# v104 plus every FLAT load/store/atomic turned into its GLOBAL twin (all pointers are global memory): lgkmcnt waits in front of LDS consumers and barriers no longer wait for global traffic
# baseline (speedup 1.0000x reference)
.LBB0_44:
	v_ashrrev_i32_e32 v0, 9, v8
	v_and_b32_e32 v6, 0xffffffc0, v0
	v_ashrrev_i32_e32 v7, 31, v6
	v_bfe_u32 v9, v8, 13, 2
	v_lshlrev_b64 v[2:3], 2, v[6:7]
	v_or_b32_e32 v2, v2, v9
	v_and_b32_e32 v10, 0x1fff, v8
	v_lshlrev_b64 v[4:5], 15, v[2:3]
	v_lshl_add_u64 v[4:5], s[30:31], 0, v[4:5]
	v_lshlrev_b32_e32 v0, 2, v10
	v_lshlrev_b64 v[2:3], 14, v[2:3]
	v_lshl_add_u64 v[4:5], v[4:5], 0, v[0:1]
	v_lshl_add_u64 v[2:3], s[6:7], 0, v[2:3]
	v_lshlrev_b32_e32 v0, 1, v10
	v_lshl_add_u64 v[2:3], v[2:3], 0, v[0:1]
	v_lshl_add_u64 v[6:7], v[6:7], 4, s[84:85]
	v_lshlrev_b32_e32 v0, 2, v9
	v_lshl_add_u64 v[6:7], v[6:7], 0, v[0:1]
	global_load_dword v64, v[4:5], off
	global_load_dword v70, v[6:7], off
	v_add_co_u32_e32 v10, vcc, s10, v4
	s_mov_b32 s4, 0x3e0000
	s_nop 0
	v_addc_co_u32_e32 v11, vcc, 0, v5, vcc
	global_load_dword v62, v[10:11], off
	global_load_dword v69, v[6:7], off offset:16
	v_add_co_u32_e32 v10, vcc, s29, v4
	v_add_u32_e32 v8, s3, v8
	s_nop 0
	v_addc_co_u32_e32 v11, vcc, 0, v5, vcc
	global_load_dword v60, v[10:11], off
	global_load_dword v68, v[6:7], off offset:32
	v_add_co_u32_e32 v10, vcc, s11, v4
	s_waitcnt vmcnt(0) lgkmcnt(0)
	v_fmac_f32_e32 v64, 0, v70
	v_addc_co_u32_e32 v11, vcc, 0, v5, vcc
	global_load_dword v58, v[10:11], off
	global_load_dword v67, v[6:7], off offset:48
	v_add_co_u32_e32 v10, vcc, s20, v4
	v_fmac_f32_e32 v62, v64, v69
	s_nop 0
	v_addc_co_u32_e32 v11, vcc, 0, v5, vcc
	global_load_dword v56, v[10:11], off
	global_load_dword v66, v[6:7], off offset:64
	v_add_co_u32_e32 v10, vcc, s21, v4
	v_fmac_f32_e32 v60, v62, v68
	s_nop 0
	v_addc_co_u32_e32 v11, vcc, 0, v5, vcc
	global_load_dword v54, v[10:11], off
	global_load_dword v65, v[6:7], off offset:80
	v_add_co_u32_e32 v10, vcc, s28, v4
	s_waitcnt vmcnt(0) lgkmcnt(0)
	v_fmac_f32_e32 v58, v60, v67
	v_addc_co_u32_e32 v11, vcc, 0, v5, vcc
	global_load_dword v52, v[10:11], off
	global_load_dword v63, v[6:7], off offset:96
	v_add_co_u32_e32 v10, vcc, s34, v4
	v_fmac_f32_e32 v56, v58, v66
	s_nop 0
	v_addc_co_u32_e32 v11, vcc, 0, v5, vcc
	global_load_dword v50, v[10:11], off
	global_load_dword v61, v[6:7], off offset:112
	v_add_co_u32_e32 v10, vcc, s35, v4
	v_fmac_f32_e32 v54, v56, v65
	s_nop 0
	v_addc_co_u32_e32 v11, vcc, 0, v5, vcc
	global_load_dword v48, v[10:11], off
	global_load_dword v59, v[6:7], off offset:128
	v_add_co_u32_e32 v10, vcc, s42, v4
	s_waitcnt vmcnt(0) lgkmcnt(0)
	v_fmac_f32_e32 v52, v54, v63
	v_addc_co_u32_e32 v11, vcc, 0, v5, vcc
	global_load_dword v46, v[10:11], off
	global_load_dword v57, v[6:7], off offset:144
	v_add_co_u32_e32 v10, vcc, s43, v4
	v_fmac_f32_e32 v50, v52, v61
	s_nop 0
	v_addc_co_u32_e32 v11, vcc, 0, v5, vcc
	global_load_dword v44, v[10:11], off
	global_load_dword v55, v[6:7], off offset:160
	v_add_co_u32_e32 v10, vcc, s44, v4
	v_fmac_f32_e32 v48, v50, v59
	s_nop 0
	v_addc_co_u32_e32 v11, vcc, 0, v5, vcc
	global_load_dword v42, v[10:11], off
	global_load_dword v53, v[6:7], off offset:176
	v_add_co_u32_e32 v10, vcc, s45, v4
	s_waitcnt vmcnt(0) lgkmcnt(0)
	v_fmac_f32_e32 v46, v48, v57
	v_addc_co_u32_e32 v11, vcc, 0, v5, vcc
	global_load_dword v41, v[10:11], off
	global_load_dword v51, v[6:7], off offset:192
	v_add_co_u32_e32 v10, vcc, s46, v4
	v_fmac_f32_e32 v44, v46, v55
	s_nop 0
	v_addc_co_u32_e32 v11, vcc, 0, v5, vcc
	global_load_dword v40, v[10:11], off
	global_load_dword v49, v[6:7], off offset:208
	v_add_co_u32_e32 v10, vcc, s47, v4
	v_fmac_f32_e32 v42, v44, v53
	s_nop 0
	v_addc_co_u32_e32 v11, vcc, 0, v5, vcc
	global_load_dword v39, v[10:11], off
	global_load_dword v47, v[6:7], off offset:224
	v_add_co_u32_e32 v10, vcc, s48, v4
	s_waitcnt vmcnt(0) lgkmcnt(0)
	v_fmac_f32_e32 v41, v42, v51
	v_addc_co_u32_e32 v11, vcc, 0, v5, vcc
	global_load_dword v38, v[10:11], off
	global_load_dword v45, v[6:7], off offset:240
	v_add_co_u32_e32 v10, vcc, s49, v4
	v_fmac_f32_e32 v40, v41, v49
	s_nop 0
	v_addc_co_u32_e32 v11, vcc, 0, v5, vcc
	global_load_dword v35, v[10:11], off
	global_load_dword v43, v[6:7], off offset:256
	v_add_co_u32_e32 v10, vcc, s50, v4
	v_fmac_f32_e32 v39, v40, v47
	s_nop 0
	v_addc_co_u32_e32 v11, vcc, 0, v5, vcc
	global_load_dword v34, v[10:11], off
	global_load_dword v37, v[6:7], off offset:272
	v_add_co_u32_e32 v10, vcc, s51, v4
	s_waitcnt vmcnt(0) lgkmcnt(0)
	v_fmac_f32_e32 v38, v39, v45
	v_addc_co_u32_e32 v11, vcc, 0, v5, vcc
	global_load_dword v31, v[10:11], off
	global_load_dword v36, v[6:7], off offset:288
	v_add_co_u32_e32 v10, vcc, s52, v4
	v_fmac_f32_e32 v35, v38, v43
	s_nop 0
	v_addc_co_u32_e32 v11, vcc, 0, v5, vcc
	global_load_dword v30, v[10:11], off
	global_load_dword v33, v[6:7], off offset:304
	v_add_co_u32_e32 v10, vcc, s53, v4
	v_fmac_f32_e32 v34, v35, v37
	s_nop 0
	v_addc_co_u32_e32 v11, vcc, 0, v5, vcc
	global_load_dword v27, v[10:11], off
	global_load_dword v32, v[6:7], off offset:320
	v_add_co_u32_e32 v10, vcc, s54, v4
	s_waitcnt vmcnt(0) lgkmcnt(0)
	v_fmac_f32_e32 v31, v34, v36
	v_addc_co_u32_e32 v11, vcc, 0, v5, vcc
	global_load_dword v26, v[10:11], off
	global_load_dword v29, v[6:7], off offset:336
	v_add_co_u32_e32 v10, vcc, s55, v4
	v_cvt_pk_bf16_f32 v36, v31, s0
	s_nop 0
	v_addc_co_u32_e32 v11, vcc, 0, v5, vcc
	global_load_dword v23, v[10:11], off
	global_load_dword v28, v[6:7], off offset:352
	v_add_co_u32_e32 v10, vcc, s56, v4
	v_fmac_f32_e32 v30, v31, v33
	s_nop 0
	v_addc_co_u32_e32 v11, vcc, 0, v5, vcc
	global_load_dword v22, v[10:11], off
	global_load_dword v25, v[6:7], off offset:368
	v_add_co_u32_e32 v10, vcc, s57, v4
	v_cvt_pk_bf16_f32 v31, v30, s0
	s_nop 0
	v_addc_co_u32_e32 v11, vcc, 0, v5, vcc
	global_load_dword v19, v[10:11], off
	global_load_dword v24, v[6:7], off offset:384
	v_add_co_u32_e32 v10, vcc, s58, v4
	v_fmac_f32_e32 v27, v30, v32
	s_nop 0
	v_addc_co_u32_e32 v11, vcc, 0, v5, vcc
	global_load_dword v18, v[10:11], off
	global_load_dword v21, v[6:7], off offset:400
	v_add_co_u32_e32 v10, vcc, s59, v4
	v_cvt_pk_bf16_f32 v32, v27, s0
	s_nop 0
	v_addc_co_u32_e32 v11, vcc, 0, v5, vcc
	global_load_dword v15, v[10:11], off
	global_load_dword v20, v[6:7], off offset:416
	v_add_co_u32_e32 v10, vcc, s60, v4
	s_waitcnt vmcnt(0) lgkmcnt(0)
	v_fmac_f32_e32 v26, v27, v29
	v_addc_co_u32_e32 v11, vcc, 0, v5, vcc
	global_load_dword v14, v[10:11], off
	global_load_dword v17, v[6:7], off offset:432
	v_add_co_u32_e32 v10, vcc, s61, v4
	v_cvt_pk_bf16_f32 v27, v26, s0
	s_nop 0
	v_addc_co_u32_e32 v11, vcc, 0, v5, vcc
	global_load_dword v11, v[10:11], off
	s_nop 0
	global_load_dword v16, v[6:7], off offset:448
	v_add_co_u32_e32 v12, vcc, s62, v4
	v_fmac_f32_e32 v23, v26, v28
	s_nop 0
	v_addc_co_u32_e32 v13, vcc, 0, v5, vcc
	v_add_co_u32_e32 v72, vcc, s63, v4
	global_load_dword v10, v[12:13], off
	s_nop 0
	global_load_dword v13, v[6:7], off offset:464
	v_addc_co_u32_e32 v73, vcc, 0, v5, vcc
	global_load_dword v9, v[72:73], off
	global_load_dword v12, v[6:7], off offset:480
	v_add_co_u32_e32 v72, vcc, s4, v4
	s_mov_b32 s4, 0x110000
	s_nop 0
	v_addc_co_u32_e32 v73, vcc, 0, v5, vcc
	v_add_co_u32_e32 v70, vcc, s64, v2
	global_load_dword v0, v[72:73], off
	s_nop 0
	global_load_dword v72, v[6:7], off offset:496
	v_cvt_pk_bf16_f32 v73, v64, s0
	v_addc_co_u32_e32 v71, vcc, 0, v3, vcc
	global_store_short v[70:71], v73, off
	v_add_co_u32_e32 v70, vcc, s10, v2
	v_cvt_pk_bf16_f32 v64, v62, s0
	s_nop 0
	v_addc_co_u32_e32 v71, vcc, 0, v3, vcc
	v_add_co_u32_e32 v68, vcc, s65, v2
	v_cvt_pk_bf16_f32 v62, v60, s0
	s_nop 0
	v_addc_co_u32_e32 v69, vcc, 0, v3, vcc
	global_store_short v[68:69], v62, off
	v_add_co_u32_e32 v68, vcc, s29, v2
	global_store_short v[70:71], v64, off
	s_nop 0
	v_addc_co_u32_e32 v69, vcc, 0, v3, vcc
	v_add_co_u32_e32 v66, vcc, s66, v2
	v_cvt_pk_bf16_f32 v60, v58, s0
	s_nop 0
	v_addc_co_u32_e32 v67, vcc, 0, v3, vcc
	v_add_co_u32_e32 v64, vcc, s11, v2
	global_store_short v[68:69], v60, off
	s_nop 0
	v_addc_co_u32_e32 v65, vcc, 0, v3, vcc
	v_add_co_u32_e32 v62, vcc, s67, v2
	v_cvt_pk_bf16_f32 v58, v56, s0
	s_nop 0
	v_addc_co_u32_e32 v63, vcc, 0, v3, vcc
	v_add_co_u32_e32 v60, vcc, s20, v2
	global_store_short v[66:67], v58, off
	s_nop 0
	v_addc_co_u32_e32 v61, vcc, 0, v3, vcc
	v_add_co_u32_e32 v58, vcc, s68, v2
	v_cvt_pk_bf16_f32 v56, v54, s0
	s_nop 0
	v_addc_co_u32_e32 v59, vcc, 0, v3, vcc
	global_store_short v[64:65], v56, off
	v_add_co_u32_e32 v56, vcc, s21, v2
	v_cvt_pk_bf16_f32 v54, v52, s0
	s_nop 0
	v_addc_co_u32_e32 v57, vcc, 0, v3, vcc
	global_store_short v[62:63], v54, off
	v_add_co_u32_e32 v54, vcc, s69, v2
	v_cvt_pk_bf16_f32 v52, v50, s0
	s_nop 0
	v_addc_co_u32_e32 v55, vcc, 0, v3, vcc
	global_store_short v[60:61], v52, off
	v_add_co_u32_e32 v52, vcc, s28, v2
	v_cvt_pk_bf16_f32 v50, v48, s0
	s_nop 0
	v_addc_co_u32_e32 v53, vcc, 0, v3, vcc
	global_store_short v[58:59], v50, off
	v_add_co_u32_e32 v50, vcc, s70, v2
	v_cvt_pk_bf16_f32 v48, v46, s0
	s_nop 0
	v_addc_co_u32_e32 v51, vcc, 0, v3, vcc
	global_store_short v[56:57], v48, off
	v_add_co_u32_e32 v48, vcc, s34, v2
	v_cvt_pk_bf16_f32 v46, v44, s0
	s_nop 0
	v_addc_co_u32_e32 v49, vcc, 0, v3, vcc
	v_cvt_pk_bf16_f32 v44, v42, s0
	v_cvt_pk_bf16_f32 v42, v41, s0
	v_cvt_pk_bf16_f32 v41, v40, s0
	v_add_co_u32_e32 v40, vcc, s71, v2
	global_store_short v[50:51], v42, off
	global_store_short v[48:49], v41, off
	v_cvt_pk_bf16_f32 v42, v39, s0
	v_addc_co_u32_e32 v41, vcc, 0, v3, vcc
	global_store_short v[40:41], v42, off
	v_add_co_u32_e32 v40, vcc, s35, v2
	v_cvt_pk_bf16_f32 v39, v38, s0
	s_nop 0
	v_addc_co_u32_e32 v41, vcc, 0, v3, vcc
	v_add_co_u32_e32 v38, vcc, s4, v2
	global_store_short v[40:41], v39, off
	v_cvt_pk_bf16_f32 v40, v35, s0
	v_addc_co_u32_e32 v39, vcc, 0, v3, vcc
	global_store_short v[38:39], v40, off
	v_add_co_u32_e32 v38, vcc, s42, v2
	s_mov_b32 s4, 0x130000
	s_nop 0
	v_addc_co_u32_e32 v39, vcc, 0, v3, vcc
	v_cvt_pk_bf16_f32 v35, v34, s0
	v_add_co_u32_e32 v34, vcc, s4, v2
	global_store_short v[38:39], v35, off
	s_nop 0
	v_addc_co_u32_e32 v35, vcc, 0, v3, vcc
	global_store_short v[34:35], v36, off
	v_add_co_u32_e32 v34, vcc, s43, v2
	s_mov_b32 s4, 0x150000
	s_nop 0
	v_addc_co_u32_e32 v35, vcc, 0, v3, vcc
	v_add_co_u32_e32 v30, vcc, s4, v2
	global_store_short v[34:35], v31, off
	s_nop 0
	v_addc_co_u32_e32 v31, vcc, 0, v3, vcc
	global_store_short v[30:31], v32, off
	v_add_co_u32_e32 v30, vcc, s44, v2
	s_mov_b32 s4, 0x170000
	s_nop 0
	v_addc_co_u32_e32 v31, vcc, 0, v3, vcc
	v_add_co_u32_e32 v26, vcc, s4, v2
	global_store_short v[30:31], v27, off
	v_cvt_pk_bf16_f32 v28, v23, s0
	v_addc_co_u32_e32 v27, vcc, 0, v3, vcc
	global_store_short v[26:27], v28, off
	v_add_co_u32_e32 v26, vcc, s45, v2
	v_fmac_f32_e32 v22, v23, v25
	s_nop 0
	v_addc_co_u32_e32 v27, vcc, 0, v3, vcc
	s_mov_b32 s4, 0x190000
	v_cvt_pk_bf16_f32 v23, v22, s0
	v_fmac_f32_e32 v19, v22, v24
	v_add_co_u32_e32 v22, vcc, s4, v2
	global_store_short v[26:27], v23, off
	v_cvt_pk_bf16_f32 v24, v19, s0
	v_addc_co_u32_e32 v23, vcc, 0, v3, vcc
	global_store_short v[22:23], v24, off
	v_add_co_u32_e32 v22, vcc, s46, v2
	v_fmac_f32_e32 v18, v19, v21
	s_nop 0
	v_addc_co_u32_e32 v23, vcc, 0, v3, vcc
	s_mov_b32 s4, 0x1b0000
	v_cvt_pk_bf16_f32 v19, v18, s0
	v_fmac_f32_e32 v15, v18, v20
	v_add_co_u32_e32 v18, vcc, s4, v2
	global_store_short v[22:23], v19, off
	v_cvt_pk_bf16_f32 v20, v15, s0
	v_addc_co_u32_e32 v19, vcc, 0, v3, vcc
	global_store_short v[18:19], v20, off
	v_add_co_u32_e32 v18, vcc, s47, v2
	s_waitcnt vmcnt(0) lgkmcnt(0)
	v_fmac_f32_e32 v14, v15, v17
	v_addc_co_u32_e32 v19, vcc, 0, v3, vcc
	s_mov_b32 s4, 0x1d0000
	v_cvt_pk_bf16_f32 v15, v14, s0
	v_fmac_f32_e32 v11, v14, v16
	v_add_co_u32_e32 v14, vcc, s4, v2
	global_store_short v[18:19], v15, off
	v_cvt_pk_bf16_f32 v16, v11, s0
	v_addc_co_u32_e32 v15, vcc, 0, v3, vcc
	global_store_short v[14:15], v16, off
	v_add_co_u32_e32 v14, vcc, s48, v2
	v_fmac_f32_e32 v10, v11, v13
	s_nop 0
	v_addc_co_u32_e32 v15, vcc, 0, v3, vcc
	s_mov_b32 s4, 0x1f0000
	v_cvt_pk_bf16_f32 v11, v10, s0
	v_fmac_f32_e32 v9, v10, v12
	v_add_co_u32_e32 v10, vcc, s4, v2
	global_store_short v[14:15], v11, off
	v_cvt_pk_bf16_f32 v12, v9, s0
	v_addc_co_u32_e32 v11, vcc, 0, v3, vcc
	s_mov_b32 s4, 0x400000
	global_store_short v[10:11], v12, off
	v_add_co_u32_e32 v10, vcc, s4, v4
	global_store_short v[2:3], v1, off
	global_store_short v[54:55], v46, off
	global_store_short v[52:53], v44, off
	v_addc_co_u32_e32 v11, vcc, 0, v5, vcc
	s_mov_b32 s4, 0x420000
	global_load_dword v16, v[10:11], off
	global_load_dword v17, v[6:7], off offset:512
	v_add_co_u32_e32 v10, vcc, s4, v4
	s_mov_b32 s4, 0x440000
	s_nop 0
	v_addc_co_u32_e32 v11, vcc, 0, v5, vcc
	global_load_dword v65, v[10:11], off
	global_load_dword v66, v[6:7], off offset:528
	v_add_co_u32_e32 v10, vcc, s4, v4
	s_mov_b32 s4, 0x460000
	s_nop 0
	v_addc_co_u32_e32 v11, vcc, 0, v5, vcc
	global_load_dword v58, v[10:11], off
	global_load_dword v68, v[6:7], off offset:544
	v_add_co_u32_e32 v10, vcc, s4, v4
	s_mov_b32 s4, 0x480000
	s_nop 0
	v_addc_co_u32_e32 v11, vcc, 0, v5, vcc
	global_load_dword v62, v[10:11], off
	global_load_dword v63, v[6:7], off offset:560
	v_add_co_u32_e32 v10, vcc, s4, v4
	s_mov_b32 s4, 0x4a0000
	s_nop 0
	v_addc_co_u32_e32 v11, vcc, 0, v5, vcc
	global_load_dword v54, v[10:11], off
	global_load_dword v67, v[6:7], off offset:576
	v_add_co_u32_e32 v10, vcc, s4, v4
	s_mov_b32 s4, 0x4c0000
	s_nop 0
	v_addc_co_u32_e32 v11, vcc, 0, v5, vcc
	global_load_dword v59, v[10:11], off
	global_load_dword v60, v[6:7], off offset:592
	v_add_co_u32_e32 v10, vcc, s4, v4
	s_mov_b32 s4, 0x4e0000
	s_nop 0
	v_addc_co_u32_e32 v11, vcc, 0, v5, vcc
	global_load_dword v50, v[10:11], off
	global_load_dword v64, v[6:7], off offset:608
	v_add_co_u32_e32 v10, vcc, s4, v4
	s_mov_b32 s4, 0x500000
	s_nop 0
	v_addc_co_u32_e32 v11, vcc, 0, v5, vcc
	global_load_dword v55, v[10:11], off
	global_load_dword v56, v[6:7], off offset:624
	v_add_co_u32_e32 v10, vcc, s4, v4
	s_mov_b32 s4, 0x520000
	s_nop 0
	v_addc_co_u32_e32 v11, vcc, 0, v5, vcc
	global_load_dword v47, v[10:11], off
	global_load_dword v61, v[6:7], off offset:640
	v_add_co_u32_e32 v10, vcc, s4, v4
	s_mov_b32 s4, 0x540000
	s_nop 0
	v_addc_co_u32_e32 v11, vcc, 0, v5, vcc
	global_load_dword v51, v[10:11], off
	global_load_dword v52, v[6:7], off offset:656
	v_add_co_u32_e32 v10, vcc, s4, v4
	s_mov_b32 s4, 0x560000
	s_nop 0
	v_addc_co_u32_e32 v11, vcc, 0, v5, vcc
	global_load_dword v46, v[10:11], off
	global_load_dword v57, v[6:7], off offset:672
	v_add_co_u32_e32 v10, vcc, s4, v4
	s_mov_b32 s4, 0x580000
	s_nop 0
	v_addc_co_u32_e32 v11, vcc, 0, v5, vcc
	global_load_dword v48, v[10:11], off
	global_load_dword v49, v[6:7], off offset:688
	v_add_co_u32_e32 v10, vcc, s4, v4
	s_mov_b32 s4, 0x5a0000
	s_nop 0
	v_addc_co_u32_e32 v11, vcc, 0, v5, vcc
	global_load_dword v39, v[10:11], off
	global_load_dword v53, v[6:7], off offset:704
	v_add_co_u32_e32 v10, vcc, s4, v4
	s_mov_b32 s4, 0x5c0000
	s_nop 0
	v_addc_co_u32_e32 v11, vcc, 0, v5, vcc
	global_load_dword v42, v[10:11], off
	global_load_dword v44, v[6:7], off offset:720
	v_add_co_u32_e32 v10, vcc, s4, v4
	s_mov_b32 s4, 0x5e0000
	s_nop 0
	v_addc_co_u32_e32 v11, vcc, 0, v5, vcc
	global_load_dword v36, v[10:11], off
	global_load_dword v45, v[6:7], off offset:736
	v_add_co_u32_e32 v10, vcc, s4, v4
	s_mov_b32 s4, 0x600000
	s_nop 0
	v_addc_co_u32_e32 v11, vcc, 0, v5, vcc
	global_load_dword v38, v[10:11], off
	global_load_dword v41, v[6:7], off offset:752
	v_add_co_u32_e32 v10, vcc, s4, v4
	s_mov_b32 s4, 0x620000
	s_nop 0
	v_addc_co_u32_e32 v11, vcc, 0, v5, vcc
	global_load_dword v33, v[10:11], off
	global_load_dword v43, v[6:7], off offset:768
	v_add_co_u32_e32 v10, vcc, s4, v4
	s_mov_b32 s4, 0x640000
	s_nop 0
	v_addc_co_u32_e32 v11, vcc, 0, v5, vcc
	global_load_dword v35, v[10:11], off
	global_load_dword v37, v[6:7], off offset:784
	v_add_co_u32_e32 v10, vcc, s4, v4
	s_mov_b32 s4, 0x660000
	s_nop 0
	v_addc_co_u32_e32 v11, vcc, 0, v5, vcc
	global_load_dword v28, v[10:11], off
	global_load_dword v40, v[6:7], off offset:800
	v_add_co_u32_e32 v10, vcc, s4, v4
	s_mov_b32 s4, 0x680000
	s_nop 0
	v_addc_co_u32_e32 v11, vcc, 0, v5, vcc
	global_load_dword v30, v[10:11], off
	global_load_dword v32, v[6:7], off offset:816
	v_add_co_u32_e32 v10, vcc, s4, v4
	s_mov_b32 s4, 0x6a0000
	s_nop 0
	v_addc_co_u32_e32 v11, vcc, 0, v5, vcc
	global_load_dword v25, v[10:11], off
	global_load_dword v34, v[6:7], off offset:832
	v_add_co_u32_e32 v10, vcc, s4, v4
	s_mov_b32 s4, 0x6c0000
	s_nop 0
	v_addc_co_u32_e32 v11, vcc, 0, v5, vcc
	global_load_dword v27, v[10:11], off
	global_load_dword v29, v[6:7], off offset:848
	v_add_co_u32_e32 v10, vcc, s4, v4
	s_mov_b32 s4, 0x6e0000
	s_nop 0
	v_addc_co_u32_e32 v11, vcc, 0, v5, vcc
	global_load_dword v21, v[10:11], off
	global_load_dword v31, v[6:7], off offset:864
	v_add_co_u32_e32 v10, vcc, s4, v4
	s_mov_b32 s4, 0x700000
	s_nop 0
	v_addc_co_u32_e32 v11, vcc, 0, v5, vcc
	global_load_dword v23, v[10:11], off
	global_load_dword v24, v[6:7], off offset:880
	v_add_co_u32_e32 v10, vcc, s4, v4
	s_mov_b32 s4, 0x720000
	s_nop 0
	v_addc_co_u32_e32 v11, vcc, 0, v5, vcc
	global_load_dword v18, v[10:11], off
	global_load_dword v26, v[6:7], off offset:896
	v_add_co_u32_e32 v10, vcc, s4, v4
	s_mov_b32 s4, 0x740000
	s_nop 0
	v_addc_co_u32_e32 v11, vcc, 0, v5, vcc
	global_load_dword v19, v[10:11], off
	global_load_dword v20, v[6:7], off offset:912
	v_add_co_u32_e32 v10, vcc, s4, v4
	s_mov_b32 s4, 0x760000
	s_nop 0
	v_addc_co_u32_e32 v11, vcc, 0, v5, vcc
	global_load_dword v13, v[10:11], off
	global_load_dword v22, v[6:7], off offset:928
	v_add_co_u32_e32 v10, vcc, s4, v4
	s_mov_b32 s4, 0x780000
	s_nop 0
	v_addc_co_u32_e32 v11, vcc, 0, v5, vcc
	global_load_dword v11, v[10:11], off
	s_nop 0
	global_load_dword v15, v[6:7], off offset:944
	v_add_co_u32_e32 v70, vcc, s4, v4
	s_mov_b32 s4, 0x7a0000
	s_nop 0
	v_addc_co_u32_e32 v71, vcc, 0, v5, vcc
	global_load_dword v10, v[70:71], off
	global_load_dword v14, v[6:7], off offset:960
	v_add_co_u32_e32 v70, vcc, s4, v4
	s_mov_b32 s4, 0x7c0000
	s_nop 0
	v_addc_co_u32_e32 v71, vcc, 0, v5, vcc
	v_add_co_u32_e32 v4, vcc, s4, v4
	v_fmac_f32_e32 v0, v9, v72
	global_load_dword v9, v[70:71], off
	global_load_dword v12, v[6:7], off offset:976
	v_addc_co_u32_e32 v5, vcc, 0, v5, vcc
	global_load_dword v4, v[4:5], off
	s_nop 0
	global_load_dword v5, v[6:7], off offset:992
	v_add_co_u32_e32 v6, vcc, s49, v2
	v_cvt_pk_bf16_f32 v69, v0, s0
	s_nop 0
	v_addc_co_u32_e32 v7, vcc, 0, v3, vcc
	s_mov_b32 s4, 0x210000
	global_store_short v[6:7], v69, off
	s_waitcnt vmcnt(0) lgkmcnt(0)
	v_fmac_f32_e32 v16, v0, v17
	v_add_co_u32_e32 v6, vcc, s4, v2
	v_cvt_pk_bf16_f32 v0, v16, s0
	s_nop 0
	v_addc_co_u32_e32 v7, vcc, 0, v3, vcc
	global_store_short v[6:7], v0, off
	v_fmac_f32_e32 v65, v16, v66
	v_add_co_u32_e32 v6, vcc, s50, v2
	v_cvt_pk_bf16_f32 v0, v65, s0
	s_nop 0
	v_addc_co_u32_e32 v7, vcc, 0, v3, vcc
	s_mov_b32 s4, 0x230000
	global_store_short v[6:7], v0, off
	v_fmac_f32_e32 v58, v65, v68
	v_add_co_u32_e32 v6, vcc, s4, v2
	v_cvt_pk_bf16_f32 v0, v58, s0
	s_nop 0
	v_addc_co_u32_e32 v7, vcc, 0, v3, vcc
	global_store_short v[6:7], v0, off
	v_fmac_f32_e32 v62, v58, v63
	v_add_co_u32_e32 v6, vcc, s51, v2
	v_cvt_pk_bf16_f32 v0, v62, s0
	s_nop 0
	v_addc_co_u32_e32 v7, vcc, 0, v3, vcc
	s_mov_b32 s4, 0x250000
	global_store_short v[6:7], v0, off
	v_fmac_f32_e32 v54, v62, v67
	v_add_co_u32_e32 v6, vcc, s4, v2
	v_cvt_pk_bf16_f32 v0, v54, s0
	s_nop 0
	v_addc_co_u32_e32 v7, vcc, 0, v3, vcc
	global_store_short v[6:7], v0, off
	v_fmac_f32_e32 v59, v54, v60
	v_add_co_u32_e32 v6, vcc, s52, v2
	v_cvt_pk_bf16_f32 v0, v59, s0
	s_nop 0
	v_addc_co_u32_e32 v7, vcc, 0, v3, vcc
	s_mov_b32 s4, 0x270000
	global_store_short v[6:7], v0, off
	v_fmac_f32_e32 v50, v59, v64
	v_add_co_u32_e32 v6, vcc, s4, v2
	v_cvt_pk_bf16_f32 v0, v50, s0
	s_nop 0
	v_addc_co_u32_e32 v7, vcc, 0, v3, vcc
	global_store_short v[6:7], v0, off
	v_fmac_f32_e32 v55, v50, v56
	v_add_co_u32_e32 v6, vcc, s53, v2
	v_cvt_pk_bf16_f32 v0, v55, s0
	s_nop 0
	v_addc_co_u32_e32 v7, vcc, 0, v3, vcc
	s_mov_b32 s4, 0x290000
	global_store_short v[6:7], v0, off
	v_fmac_f32_e32 v47, v55, v61
	v_add_co_u32_e32 v6, vcc, s4, v2
	v_cvt_pk_bf16_f32 v0, v47, s0
	s_nop 0
	v_addc_co_u32_e32 v7, vcc, 0, v3, vcc
	global_store_short v[6:7], v0, off
	v_fmac_f32_e32 v51, v47, v52
	v_add_co_u32_e32 v6, vcc, s54, v2
	v_cvt_pk_bf16_f32 v0, v51, s0
	s_nop 0
	v_addc_co_u32_e32 v7, vcc, 0, v3, vcc
	s_mov_b32 s4, 0x2b0000
	global_store_short v[6:7], v0, off
	v_fmac_f32_e32 v46, v51, v57
	v_add_co_u32_e32 v6, vcc, s4, v2
	v_cvt_pk_bf16_f32 v0, v46, s0
	s_nop 0
	v_addc_co_u32_e32 v7, vcc, 0, v3, vcc
	global_store_short v[6:7], v0, off
	v_fmac_f32_e32 v48, v46, v49
	v_add_co_u32_e32 v6, vcc, s55, v2
	v_cvt_pk_bf16_f32 v0, v48, s0
	s_nop 0
	v_addc_co_u32_e32 v7, vcc, 0, v3, vcc
	s_mov_b32 s4, 0x2d0000
	global_store_short v[6:7], v0, off
	v_fmac_f32_e32 v39, v48, v53
	v_add_co_u32_e32 v6, vcc, s4, v2
	v_cvt_pk_bf16_f32 v0, v39, s0
	s_nop 0
	v_addc_co_u32_e32 v7, vcc, 0, v3, vcc
	global_store_short v[6:7], v0, off
	v_fmac_f32_e32 v42, v39, v44
	v_add_co_u32_e32 v6, vcc, s56, v2
	v_cvt_pk_bf16_f32 v0, v42, s0
	s_nop 0
	v_addc_co_u32_e32 v7, vcc, 0, v3, vcc
	s_mov_b32 s4, 0x2f0000
	global_store_short v[6:7], v0, off
	v_fmac_f32_e32 v36, v42, v45
	v_add_co_u32_e32 v6, vcc, s4, v2
	v_cvt_pk_bf16_f32 v0, v36, s0
	s_nop 0
	v_addc_co_u32_e32 v7, vcc, 0, v3, vcc
	global_store_short v[6:7], v0, off
	v_fmac_f32_e32 v38, v36, v41
	v_add_co_u32_e32 v6, vcc, s57, v2
	v_cvt_pk_bf16_f32 v0, v38, s0
	s_nop 0
	v_addc_co_u32_e32 v7, vcc, 0, v3, vcc
	s_mov_b32 s4, 0x310000
	global_store_short v[6:7], v0, off
	v_fmac_f32_e32 v33, v38, v43
	v_add_co_u32_e32 v6, vcc, s4, v2
	v_cvt_pk_bf16_f32 v0, v33, s0
	s_nop 0
	v_addc_co_u32_e32 v7, vcc, 0, v3, vcc
	global_store_short v[6:7], v0, off
	v_fmac_f32_e32 v35, v33, v37
	v_add_co_u32_e32 v6, vcc, s58, v2
	v_cvt_pk_bf16_f32 v0, v35, s0
	s_nop 0
	v_addc_co_u32_e32 v7, vcc, 0, v3, vcc
	s_mov_b32 s4, 0x330000
	global_store_short v[6:7], v0, off
	v_fmac_f32_e32 v28, v35, v40
	v_add_co_u32_e32 v6, vcc, s4, v2
	v_cvt_pk_bf16_f32 v0, v28, s0
	s_nop 0
	v_addc_co_u32_e32 v7, vcc, 0, v3, vcc
	global_store_short v[6:7], v0, off
	v_fmac_f32_e32 v30, v28, v32
	v_add_co_u32_e32 v6, vcc, s59, v2
	v_cvt_pk_bf16_f32 v0, v30, s0
	s_nop 0
	v_addc_co_u32_e32 v7, vcc, 0, v3, vcc
	s_mov_b32 s4, 0x350000
	global_store_short v[6:7], v0, off
	v_fmac_f32_e32 v25, v30, v34
	v_add_co_u32_e32 v6, vcc, s4, v2
	v_cvt_pk_bf16_f32 v0, v25, s0
	s_nop 0
	v_addc_co_u32_e32 v7, vcc, 0, v3, vcc
	global_store_short v[6:7], v0, off
	v_fmac_f32_e32 v27, v25, v29
	v_add_co_u32_e32 v6, vcc, s60, v2
	v_cvt_pk_bf16_f32 v0, v27, s0
	s_nop 0
	v_addc_co_u32_e32 v7, vcc, 0, v3, vcc
	s_mov_b32 s4, 0x370000
	global_store_short v[6:7], v0, off
	v_fmac_f32_e32 v21, v27, v31
	v_add_co_u32_e32 v6, vcc, s4, v2
	v_cvt_pk_bf16_f32 v0, v21, s0
	s_nop 0
	v_addc_co_u32_e32 v7, vcc, 0, v3, vcc
	global_store_short v[6:7], v0, off
	v_fmac_f32_e32 v23, v21, v24
	v_add_co_u32_e32 v6, vcc, s61, v2
	v_cvt_pk_bf16_f32 v0, v23, s0
	s_nop 0
	v_addc_co_u32_e32 v7, vcc, 0, v3, vcc
	s_mov_b32 s4, 0x390000
	global_store_short v[6:7], v0, off
	v_fmac_f32_e32 v18, v23, v26
	v_add_co_u32_e32 v6, vcc, s4, v2
	v_cvt_pk_bf16_f32 v0, v18, s0
	s_nop 0
	v_addc_co_u32_e32 v7, vcc, 0, v3, vcc
	global_store_short v[6:7], v0, off
	v_fmac_f32_e32 v19, v18, v20
	v_add_co_u32_e32 v6, vcc, s62, v2
	v_cvt_pk_bf16_f32 v0, v19, s0
	s_nop 0
	v_addc_co_u32_e32 v7, vcc, 0, v3, vcc
	s_mov_b32 s4, 0x3b0000
	global_store_short v[6:7], v0, off
	v_fmac_f32_e32 v13, v19, v22
	v_add_co_u32_e32 v6, vcc, s4, v2
	v_cvt_pk_bf16_f32 v0, v13, s0
	s_nop 0
	v_addc_co_u32_e32 v7, vcc, 0, v3, vcc
	global_store_short v[6:7], v0, off
	v_fmac_f32_e32 v11, v13, v15
	v_add_co_u32_e32 v6, vcc, s63, v2
	v_cvt_pk_bf16_f32 v0, v11, s0
	s_nop 0
	v_addc_co_u32_e32 v7, vcc, 0, v3, vcc
	global_store_short v[6:7], v0, off
	v_fmac_f32_e32 v10, v11, v14
	v_add_co_u32_e32 v6, vcc, 0x3d0000, v2
	v_cvt_pk_bf16_f32 v0, v10, s0
	s_nop 0
	v_addc_co_u32_e32 v7, vcc, 0, v3, vcc
	global_store_short v[6:7], v0, off
	v_add_co_u32_e32 v6, vcc, 0x3e0000, v2
	v_fmac_f32_e32 v9, v10, v12
	s_nop 0
	v_addc_co_u32_e32 v7, vcc, 0, v3, vcc
	v_add_co_u32_e32 v2, vcc, 0x3f0000, v2
	s_mov_b32 s4, 0x1ffff
	s_nop 0
	v_addc_co_u32_e32 v3, vcc, 0, v3, vcc
	v_cvt_pk_bf16_f32 v0, v9, s0
	v_fmac_f32_e32 v4, v9, v5
	v_cmp_lt_i32_e32 vcc, s4, v8
	global_store_short v[6:7], v0, off
	v_cvt_pk_bf16_f32 v0, v4, s0
	s_or_b64 s[40:41], vcc, s[40:41]
	global_store_short v[2:3], v0, off
	s_andn2_b64 exec, exec, s[40:41]
	s_cbranch_execnz .LBB0_44

.LBB0_49:
	v_lshl_add_u64 v[76:77], s[72:73], 0, v[4:5]
	v_add_co_u32_e32 v12, vcc, 0x19600000, v76
	v_lshl_add_u64 v[78:79], s[72:73], 0, v[2:3]
	s_nop 0
	v_addc_co_u32_e32 v13, vcc, 0, v77, vcc
	v_add_co_u32_e32 v14, vcc, 0x1b600000, v78
	global_load_dword v12, v[12:13], off
	s_nop 0
	v_addc_co_u32_e32 v15, vcc, 0, v79, vcc
	v_add_co_u32_e32 v16, vcc, 0x19610000, v76
	global_load_dword v74, v[14:15], off
	s_nop 0
	v_addc_co_u32_e32 v17, vcc, 0, v77, vcc
	global_load_dword v48, v[16:17], off
	global_load_dword v72, v[14:15], off offset:1024
	v_add_co_u32_e32 v16, vcc, 0x19620000, v76
	v_cvt_pk_bf16_f32 v75, v11, s0
	s_nop 0
	v_addc_co_u32_e32 v17, vcc, 0, v77, vcc
	global_load_dword v43, v[16:17], off
	global_load_dword v69, v[14:15], off offset:2048
	v_add_co_u32_e32 v16, vcc, 0x19630000, v76
	s_mov_b64 s[4:5], 0x8000
	s_nop 0
	v_addc_co_u32_e32 v17, vcc, 0, v77, vcc
	global_load_dword v38, v[16:17], off
	global_load_dword v65, v[14:15], off offset:3072
	v_add_co_u32_e32 v14, vcc, 0x19640000, v76
	v_lshl_add_u64 v[2:3], v[2:3], 0, s[4:5]
	s_nop 0
	v_addc_co_u32_e32 v15, vcc, 0, v77, vcc
	global_load_dword v33, v[14:15], off
	v_add_co_u32_e32 v14, vcc, 0x1b601000, v78
	s_mov_b64 s[4:5], 0x200000
	s_nop 0
	v_addc_co_u32_e32 v15, vcc, 0, v79, vcc
	v_add_co_u32_e32 v16, vcc, 0x19650000, v76
	global_load_dword v73, v[14:15], off
	s_nop 0
	v_addc_co_u32_e32 v17, vcc, 0, v77, vcc
	global_load_dword v44, v[16:17], off
	global_load_dword v70, v[14:15], off offset:1024
	v_add_co_u32_e32 v16, vcc, 0x19660000, v76
	s_add_i32 s2, s2, 32
	s_nop 0
	v_addc_co_u32_e32 v17, vcc, 0, v77, vcc
	global_load_dword v39, v[16:17], off
	global_load_dword v66, v[14:15], off offset:2048
	v_add_co_u32_e32 v16, vcc, 0x19670000, v76
	v_lshl_add_u64 v[4:5], v[4:5], 0, s[4:5]
	s_nop 0
	v_addc_co_u32_e32 v17, vcc, 0, v77, vcc
	global_load_dword v34, v[16:17], off
	global_load_dword v61, v[14:15], off offset:3072
	v_add_co_u32_e32 v14, vcc, 0x19680000, v76
	s_mov_b64 s[4:5], 0x100000
	s_nop 0
	v_addc_co_u32_e32 v15, vcc, 0, v77, vcc
	global_load_dword v29, v[14:15], off
	v_add_co_u32_e32 v14, vcc, 0x1b602000, v78
	s_cmpk_gt_u32 s2, 0x5f
	s_nop 0
	v_addc_co_u32_e32 v15, vcc, 0, v79, vcc
	v_add_co_u32_e32 v16, vcc, 0x19690000, v76
	global_load_dword v71, v[14:15], off
	s_nop 0
	v_addc_co_u32_e32 v17, vcc, 0, v77, vcc
	global_load_dword v40, v[16:17], off
	global_load_dword v67, v[14:15], off offset:1024
	v_add_co_u32_e32 v16, vcc, 0x196a0000, v76
	s_waitcnt vmcnt(0) lgkmcnt(0)
	v_fmac_f32_e32 v12, v11, v74
	v_addc_co_u32_e32 v17, vcc, 0, v77, vcc
	global_load_dword v35, v[16:17], off
	global_load_dword v62, v[14:15], off offset:2048
	v_add_co_u32_e32 v16, vcc, 0x196b0000, v76
	v_cvt_pk_bf16_f32 v11, v12, s0
	s_nop 0
	v_addc_co_u32_e32 v17, vcc, 0, v77, vcc
	global_load_dword v30, v[16:17], off
	global_load_dword v57, v[14:15], off offset:3072
	v_add_co_u32_e32 v14, vcc, 0x196c0000, v76
	v_fmac_f32_e32 v48, v12, v72
	s_nop 0
	v_addc_co_u32_e32 v15, vcc, 0, v77, vcc
	global_load_dword v25, v[14:15], off
	v_add_co_u32_e32 v14, vcc, 0x1b603000, v78
	v_fmac_f32_e32 v43, v48, v69
	s_nop 0
	v_addc_co_u32_e32 v15, vcc, 0, v79, vcc
	v_add_co_u32_e32 v16, vcc, 0x196d0000, v76
	global_load_dword v68, v[14:15], off
	s_nop 0
	v_addc_co_u32_e32 v17, vcc, 0, v77, vcc
	global_load_dword v36, v[16:17], off
	global_load_dword v63, v[14:15], off offset:1024
	v_add_co_u32_e32 v16, vcc, 0x196e0000, v76
	v_fmac_f32_e32 v38, v43, v65
	s_nop 0
	v_addc_co_u32_e32 v17, vcc, 0, v77, vcc
	global_load_dword v31, v[16:17], off
	global_load_dword v58, v[14:15], off offset:2048
	v_add_co_u32_e32 v16, vcc, 0x196f0000, v76
	v_fmac_f32_e32 v33, v38, v73
	s_nop 0
	v_addc_co_u32_e32 v17, vcc, 0, v77, vcc
	global_load_dword v26, v[16:17], off
	global_load_dword v53, v[14:15], off offset:3072
	v_add_co_u32_e32 v14, vcc, 0x19700000, v76
	v_fmac_f32_e32 v44, v33, v70
	s_nop 0
	v_addc_co_u32_e32 v15, vcc, 0, v77, vcc
	global_load_dword v21, v[14:15], off
	v_add_co_u32_e32 v14, vcc, 0x1b604000, v78
	v_fmac_f32_e32 v39, v44, v66
	s_nop 0
	v_addc_co_u32_e32 v15, vcc, 0, v79, vcc
	v_add_co_u32_e32 v16, vcc, 0x19710000, v76
	global_load_dword v64, v[14:15], off
	s_nop 0
	v_addc_co_u32_e32 v17, vcc, 0, v77, vcc
	global_load_dword v32, v[16:17], off
	global_load_dword v59, v[14:15], off offset:1024
	v_add_co_u32_e32 v16, vcc, 0x19720000, v76
	v_fmac_f32_e32 v34, v39, v61
	s_nop 0
	v_addc_co_u32_e32 v17, vcc, 0, v77, vcc
	global_load_dword v27, v[16:17], off
	global_load_dword v54, v[14:15], off offset:2048
	v_add_co_u32_e32 v16, vcc, 0x19730000, v76
	v_fmac_f32_e32 v29, v34, v71
	s_nop 0
	v_addc_co_u32_e32 v17, vcc, 0, v77, vcc
	global_load_dword v22, v[16:17], off
	global_load_dword v49, v[14:15], off offset:3072
	v_add_co_u32_e32 v14, vcc, 0x19740000, v76
	v_fmac_f32_e32 v40, v29, v67
	s_nop 0
	v_addc_co_u32_e32 v15, vcc, 0, v77, vcc
	global_load_dword v17, v[14:15], off
	v_add_co_u32_e32 v14, vcc, 0x1b605000, v78
	s_waitcnt vmcnt(0) lgkmcnt(0)
	v_fmac_f32_e32 v35, v40, v62
	v_addc_co_u32_e32 v15, vcc, 0, v79, vcc
	v_add_co_u32_e32 v18, vcc, 0x19750000, v76
	global_load_dword v60, v[14:15], off
	s_nop 0
	v_addc_co_u32_e32 v19, vcc, 0, v77, vcc
	global_load_dword v28, v[18:19], off
	global_load_dword v55, v[14:15], off offset:1024
	v_add_co_u32_e32 v18, vcc, 0x19760000, v76
	v_fmac_f32_e32 v30, v35, v57
	s_nop 0
	v_addc_co_u32_e32 v19, vcc, 0, v77, vcc
	global_load_dword v23, v[18:19], off
	global_load_dword v50, v[14:15], off offset:2048
	v_add_co_u32_e32 v18, vcc, 0x19770000, v76
	v_fmac_f32_e32 v25, v30, v68
	s_nop 0
	v_addc_co_u32_e32 v19, vcc, 0, v77, vcc
	global_load_dword v18, v[18:19], off
	s_nop 0
	global_load_dword v45, v[14:15], off offset:3072
	v_add_co_u32_e32 v14, vcc, 0x19780000, v76
	v_fmac_f32_e32 v36, v25, v63
	s_nop 0
	v_addc_co_u32_e32 v15, vcc, 0, v77, vcc
	v_add_co_u32_e32 v80, vcc, 0x1b606000, v78
	global_load_dword v14, v[14:15], off
	s_nop 0
	v_addc_co_u32_e32 v81, vcc, 0, v79, vcc
	v_add_co_u32_e32 v46, vcc, 0x19790000, v76
	global_load_dword v56, v[80:81], off
	s_nop 0
	v_addc_co_u32_e32 v47, vcc, 0, v77, vcc
	global_load_dword v24, v[46:47], off
	global_load_dword v51, v[80:81], off offset:1024
	v_add_co_u32_e32 v46, vcc, 0x197a0000, v76
	v_fmac_f32_e32 v31, v36, v58
	s_nop 0
	v_addc_co_u32_e32 v47, vcc, 0, v77, vcc
	v_add_co_u32_e32 v82, vcc, 0x197b0000, v76
	global_load_dword v19, v[46:47], off
	s_nop 0
	global_load_dword v46, v[80:81], off offset:2048
	v_addc_co_u32_e32 v83, vcc, 0, v77, vcc
	global_load_dword v15, v[82:83], off
	global_load_dword v41, v[80:81], off offset:3072
	v_add_co_u32_e32 v80, vcc, 0x197c0000, v76
	v_fmac_f32_e32 v26, v31, v53
	s_nop 0
	v_addc_co_u32_e32 v81, vcc, 0, v77, vcc
	v_add_co_u32_e32 v78, vcc, 0x1b607000, v78
	global_load_dword v13, v[80:81], off
	s_nop 0
	v_addc_co_u32_e32 v79, vcc, 0, v79, vcc
	global_load_dword v52, v[78:79], off
	v_add_co_u32_e32 v80, vcc, 0x197d0000, v76
	v_fmac_f32_e32 v21, v26, v64
	s_nop 0
	v_addc_co_u32_e32 v81, vcc, 0, v77, vcc
	global_load_dword v20, v[80:81], off
	global_load_dword v47, v[78:79], off offset:1024
	v_add_co_u32_e32 v80, vcc, 0x197e0000, v76
	v_fmac_f32_e32 v32, v21, v59
	s_nop 0
	v_addc_co_u32_e32 v81, vcc, 0, v77, vcc
	v_add_co_u32_e32 v76, vcc, 0x197f0000, v76
	global_load_dword v16, v[80:81], off
	global_load_dword v42, v[78:79], off offset:2048
	v_addc_co_u32_e32 v77, vcc, 0, v77, vcc
	global_load_dword v10, v[76:77], off
	global_load_dword v37, v[78:79], off offset:3072
	v_add_co_u32_e32 v74, vcc, 0x8000, v6
	global_store_short v[6:7], v75, off
	s_nop 0
	v_addc_co_u32_e32 v75, vcc, 0, v7, vcc
	global_store_short v[74:75], v11, off
	v_add_co_u32_e32 v74, vcc, s28, v6
	v_cvt_pk_bf16_f32 v11, v48, s0
	s_nop 0
	v_addc_co_u32_e32 v75, vcc, 0, v7, vcc
	global_store_short v[74:75], v11, off
	v_add_co_u32_e32 v74, vcc, 0x18000, v6
	v_cvt_pk_bf16_f32 v11, v43, s0
	s_nop 0
	v_addc_co_u32_e32 v75, vcc, 0, v7, vcc
	global_store_short v[74:75], v11, off
	v_add_co_u32_e32 v74, vcc, s6, v6
	v_cvt_pk_bf16_f32 v11, v38, s0
	s_nop 0
	v_addc_co_u32_e32 v75, vcc, 0, v7, vcc
	v_add_co_u32_e32 v72, vcc, 0x28000, v6
	global_store_short v[74:75], v11, off
	v_cvt_pk_bf16_f32 v11, v33, s0
	v_addc_co_u32_e32 v73, vcc, 0, v7, vcc
	global_store_short v[72:73], v11, off
	v_add_co_u32_e32 v72, vcc, s34, v6
	v_cvt_pk_bf16_f32 v11, v44, s0
	s_nop 0
	v_addc_co_u32_e32 v73, vcc, 0, v7, vcc
	global_store_short v[72:73], v11, off
	v_add_co_u32_e32 v72, vcc, 0x38000, v6
	v_cvt_pk_bf16_f32 v11, v39, s0
	s_nop 0
	v_addc_co_u32_e32 v73, vcc, 0, v7, vcc
	v_add_co_u32_e32 v38, vcc, s29, v6
	global_store_short v[72:73], v11, off
	v_cvt_pk_bf16_f32 v11, v34, s0
	v_addc_co_u32_e32 v39, vcc, 0, v7, vcc
	global_store_short v[38:39], v11, off
	v_add_co_u32_e32 v38, vcc, 0x48000, v6
	v_cvt_pk_bf16_f32 v11, v29, s0
	s_nop 0
	v_addc_co_u32_e32 v39, vcc, 0, v7, vcc
	global_store_short v[38:39], v11, off
	v_add_co_u32_e32 v38, vcc, s35, v6
	v_cvt_pk_bf16_f32 v11, v40, s0
	s_nop 0
	v_addc_co_u32_e32 v39, vcc, 0, v7, vcc
	global_store_short v[38:39], v11, off
	v_add_co_u32_e32 v38, vcc, 0x58000, v6
	v_cvt_pk_bf16_f32 v11, v35, s0
	s_nop 0
	v_addc_co_u32_e32 v39, vcc, 0, v7, vcc
	v_add_co_u32_e32 v34, vcc, s7, v6
	global_store_short v[38:39], v11, off
	v_cvt_pk_bf16_f32 v11, v30, s0
	v_addc_co_u32_e32 v35, vcc, 0, v7, vcc
	global_store_short v[34:35], v11, off
	v_add_co_u32_e32 v34, vcc, 0x68000, v6
	v_cvt_pk_bf16_f32 v11, v25, s0
	s_nop 0
	v_addc_co_u32_e32 v35, vcc, 0, v7, vcc
	global_store_short v[34:35], v11, off
	v_add_co_u32_e32 v34, vcc, s42, v6
	v_cvt_pk_bf16_f32 v11, v36, s0
	s_nop 0
	v_addc_co_u32_e32 v35, vcc, 0, v7, vcc
	global_store_short v[34:35], v11, off
	v_add_co_u32_e32 v34, vcc, 0x78000, v6
	v_cvt_pk_bf16_f32 v11, v31, s0
	s_nop 0
	v_addc_co_u32_e32 v35, vcc, 0, v7, vcc
	v_add_co_u32_e32 v30, vcc, s10, v6
	global_store_short v[34:35], v11, off
	v_cvt_pk_bf16_f32 v11, v26, s0
	v_addc_co_u32_e32 v31, vcc, 0, v7, vcc
	global_store_short v[30:31], v11, off
	v_add_co_u32_e32 v30, vcc, 0x88000, v6
	v_cvt_pk_bf16_f32 v11, v21, s0
	s_nop 0
	v_addc_co_u32_e32 v31, vcc, 0, v7, vcc
	global_store_short v[30:31], v11, off
	v_add_co_u32_e32 v30, vcc, s43, v6
	v_cvt_pk_bf16_f32 v11, v32, s0
	s_nop 0
	v_addc_co_u32_e32 v31, vcc, 0, v7, vcc
	global_store_short v[30:31], v11, off
	v_add_co_u32_e32 v30, vcc, 0x98000, v6
	v_fmac_f32_e32 v27, v32, v54
	s_nop 0
	v_addc_co_u32_e32 v31, vcc, 0, v7, vcc
	v_cvt_pk_bf16_f32 v11, v27, s0
	v_fmac_f32_e32 v22, v27, v49
	v_add_co_u32_e32 v26, vcc, s11, v6
	global_store_short v[30:31], v11, off
	v_cvt_pk_bf16_f32 v11, v22, s0
	v_addc_co_u32_e32 v27, vcc, 0, v7, vcc
	global_store_short v[26:27], v11, off
	s_waitcnt vmcnt(0) lgkmcnt(0)
	v_fmac_f32_e32 v17, v22, v60
	v_add_co_u32_e32 v26, vcc, 0xa8000, v6
	v_cvt_pk_bf16_f32 v11, v17, s0
	s_nop 0
	v_addc_co_u32_e32 v27, vcc, 0, v7, vcc
	global_store_short v[26:27], v11, off
	v_fmac_f32_e32 v28, v17, v55
	v_add_co_u32_e32 v26, vcc, s44, v6
	v_cvt_pk_bf16_f32 v11, v28, s0
	s_nop 0
	v_addc_co_u32_e32 v27, vcc, 0, v7, vcc
	global_store_short v[26:27], v11, off
	v_add_co_u32_e32 v26, vcc, 0xb8000, v6
	v_fmac_f32_e32 v23, v28, v50
	s_nop 0
	v_addc_co_u32_e32 v27, vcc, 0, v7, vcc
	v_cvt_pk_bf16_f32 v11, v23, s0
	v_fmac_f32_e32 v18, v23, v45
	v_add_co_u32_e32 v22, vcc, s20, v6
	global_store_short v[26:27], v11, off
	v_cvt_pk_bf16_f32 v11, v18, s0
	v_addc_co_u32_e32 v23, vcc, 0, v7, vcc
	global_store_short v[22:23], v11, off
	v_fmac_f32_e32 v14, v18, v56
	v_add_co_u32_e32 v22, vcc, 0xc8000, v6
	v_cvt_pk_bf16_f32 v11, v14, s0
	s_nop 0
	v_addc_co_u32_e32 v23, vcc, 0, v7, vcc
	global_store_short v[22:23], v11, off
	v_fmac_f32_e32 v24, v14, v51
	v_add_co_u32_e32 v22, vcc, s45, v6
	v_cvt_pk_bf16_f32 v11, v24, s0
	s_nop 0
	v_addc_co_u32_e32 v23, vcc, 0, v7, vcc
	global_store_short v[22:23], v11, off
	v_add_co_u32_e32 v22, vcc, 0xd8000, v6
	v_fmac_f32_e32 v19, v24, v46
	s_nop 0
	v_addc_co_u32_e32 v23, vcc, 0, v7, vcc
	v_add_co_u32_e32 v18, vcc, s21, v6
	v_cvt_pk_bf16_f32 v11, v19, s0
	v_fmac_f32_e32 v15, v19, v41
	v_addc_co_u32_e32 v19, vcc, 0, v7, vcc
	v_add_co_u32_e32 v14, vcc, 0xe8000, v6
	global_store_short v[22:23], v11, off
	v_cvt_pk_bf16_f32 v11, v15, s0
	v_fmac_f32_e32 v13, v15, v52
	v_addc_co_u32_e32 v15, vcc, 0, v7, vcc
	global_store_short v[18:19], v11, off
	v_cvt_pk_bf16_f32 v11, v13, s0
	v_fmac_f32_e32 v20, v13, v47
	v_add_co_u32_e32 v12, vcc, s46, v6
	global_store_short v[14:15], v11, off
	v_cvt_pk_bf16_f32 v11, v20, s0
	v_addc_co_u32_e32 v13, vcc, 0, v7, vcc
	global_store_short v[12:13], v11, off
	v_fmac_f32_e32 v16, v20, v42
	v_add_co_u32_e32 v12, vcc, 0xf8000, v6
	v_cvt_pk_bf16_f32 v11, v16, s0
	s_nop 0
	v_addc_co_u32_e32 v13, vcc, 0, v7, vcc
	v_fmac_f32_e32 v10, v16, v37
	global_store_short v[12:13], v11, off
	v_lshl_add_u64 v[6:7], v[6:7], 0, s[4:5]
	v_mov_b32_e32 v11, v10
	s_cbranch_scc0 .LBB0_49
	v_add_u32_e32 v8, s3, v8
	s_mov_b32 s2, 0xffff
	v_cmp_lt_i32_e32 vcc, s2, v8
	s_mov_b32 s28, 0x10000
	s_or_b64 s[40:41], vcc, s[40:41]
	v_add_u16_e32 v9, s3, v9
	s_andn2_b64 exec, exec, s[40:41]
	s_cbranch_execnz .LBB0_48

.LBB0_54:
	s_lshl_b64 s[6:7], s[4:5], 13
	v_lshl_add_u64 v[28:29], s[6:7], 2, v[4:5]
	v_pk_add_f32 v[30:31], v[20:21], v[0:1] op_sel_hi:[1,0]
	v_pk_add_f32 v[18:19], v[18:19], v[0:1] op_sel_hi:[1,0]
	s_mov_b32 s6, 0x3fb8aa3b
	v_pk_mul_f32 v[20:21], v[18:19], s[6:7] op_sel_hi:[1,0]
	v_pk_mul_f32 v[18:19], v[30:31], s[6:7] op_sel_hi:[1,0]
	global_store_dwordx4 v[28:29], v[18:21], off
	v_pk_add_f32 v[14:15], v[14:15], v[0:1] op_sel_hi:[1,0]
	v_pk_add_f32 v[10:11], v[10:11], v[0:1] op_sel_hi:[1,0]
	v_pk_add_f32 v[18:19], v[16:17], v[0:1] op_sel_hi:[1,0]
	v_pk_mul_f32 v[16:17], v[14:15], s[6:7] op_sel_hi:[1,0]
	v_pk_mul_f32 v[14:15], v[18:19], s[6:7] op_sel_hi:[1,0]
	global_store_dwordx4 v[28:29], v[14:17], off offset:16
	v_pk_add_f32 v[6:7], v[6:7], v[0:1] op_sel_hi:[1,0]
	s_add_i32 s4, s4, s16
	v_pk_add_f32 v[14:15], v[12:13], v[0:1] op_sel_hi:[1,0]
	v_pk_mul_f32 v[12:13], v[10:11], s[6:7] op_sel_hi:[1,0]
	v_pk_mul_f32 v[10:11], v[14:15], s[6:7] op_sel_hi:[1,0]
	global_store_dwordx4 v[28:29], v[10:13], off offset:32
	s_cmp_gt_i32 s4, 15
	s_nop 0
	v_pk_add_f32 v[10:11], v[8:9], v[0:1] op_sel_hi:[1,0]
	v_pk_mul_f32 v[8:9], v[6:7], s[6:7] op_sel_hi:[1,0]
	v_pk_mul_f32 v[6:7], v[10:11], s[6:7] op_sel_hi:[1,0]
	global_store_dwordx4 v[28:29], v[6:9], off offset:48
	s_cbranch_scc1 .LBB0_60
.LBB0_55:
	s_ashr_i32 s5, s4, 31
	s_lshl_b64 s[6:7], s[4:5], 15
	v_lshl_add_u64 v[14:15], v[2:3], 0, s[6:7]
	s_barrier
	global_load_dwordx4 v[6:9], v[14:15], off
	global_load_dwordx4 v[10:13], v[14:15], off offset:16
	global_load_dwordx4 v[28:31], v[14:15], off offset:32
	global_load_dwordx4 v[32:35], v[14:15], off offset:48
	s_waitcnt vmcnt(0) lgkmcnt(0)
	v_add_f32_e32 v20, 0, v6
	v_add_f32_e32 v21, v7, v20
	v_add_f32_e32 v18, v8, v21
	v_add_f32_e32 v19, v9, v18
	v_add_f32_e32 v16, v10, v19
	v_add_f32_e32 v17, v11, v16
	v_add_f32_e32 v14, v12, v17
	v_add_f32_e32 v15, v13, v14
	v_add_f32_e32 v12, v28, v15
	v_add_f32_e32 v13, v29, v12
	v_add_f32_e32 v10, v30, v13
	v_add_f32_e32 v11, v31, v10
	v_add_f32_e32 v8, v32, v11
	v_add_f32_e32 v9, v33, v8
	v_add_f32_e32 v6, v34, v9
	v_add_f32_e32 v7, v35, v6
	ds_bpermute_b32 v0, v22, v7
	s_waitcnt lgkmcnt(0)
	v_add_f32_e32 v0, v7, v0
	v_cndmask_b32_e64 v0, v0, v7, s[38:39]
	ds_bpermute_b32 v28, v23, v0
	s_waitcnt lgkmcnt(0)
	v_add_f32_e32 v28, v0, v28
	v_cndmask_b32_e64 v0, v28, v0, s[40:41]
	ds_bpermute_b32 v28, v24, v0
	s_waitcnt lgkmcnt(0)
	v_add_f32_e32 v28, v0, v28
	v_cndmask_b32_e64 v0, v28, v0, s[42:43]
	ds_bpermute_b32 v28, v25, v0
	s_waitcnt lgkmcnt(0)
	v_add_f32_e32 v28, v0, v28
	v_cndmask_b32_e64 v0, v28, v0, s[44:45]
	ds_bpermute_b32 v28, v26, v0
	s_waitcnt lgkmcnt(0)
	v_add_f32_e32 v28, v0, v28
	v_cndmask_b32_e64 v0, v28, v0, s[46:47]
	ds_bpermute_b32 v28, v27, v0
	s_waitcnt lgkmcnt(0)
	v_add_f32_e32 v28, v0, v28
	s_and_saveexec_b64 s[6:7], s[50:51]
	v_mov_b32_e32 v29, s10
	ds_write_b32 v29, v28
	s_or_b64 exec, exec, s[6:7]
	v_cndmask_b32_e64 v0, v28, v0, s[48:49]
	s_andn2_b64 vcc, exec, s[2:3]
	v_sub_f32_e32 v0, v0, v7
	s_waitcnt lgkmcnt(0)
	s_barrier
	s_cbranch_vccnz .LBB0_53
	s_mov_b32 s6, 0
	v_readlane_b32 s7, v255, 2
	v_readlane_b32 s11, v255, 11

.LBB0_69:
	v_lshl_add_u64 v[34:35], v[0:1], 2, s[2:3]
	v_lshl_add_u64 v[36:37], v[34:35], 0, s[52:53]
	s_nop 4
	global_store_dword v[34:35], v18, off
	global_store_dword v[36:37], v19, off
	v_lshl_add_u64 v[18:19], v[34:35], 0, s[38:39]
	global_store_dword v[18:19], v20, off
	v_lshl_add_u64 v[18:19], v[34:35], 0, s[20:21]
	global_store_dword v[18:19], v21, off
	v_lshl_add_u64 v[18:19], v[34:35], 0, s[60:61]
	global_store_dword v[18:19], v22, off
	v_lshl_add_u64 v[18:19], v[34:35], 0, s[58:59]
	global_store_dword v[18:19], v23, off
	v_lshl_add_u64 v[18:19], v[34:35], 0, s[56:57]
	global_store_dword v[18:19], v24, off
	v_lshl_add_u64 v[18:19], v[34:35], 0, s[54:55]
	global_store_dword v[18:19], v25, off
	v_lshl_add_u64 v[18:19], v[34:35], 0, s[68:69]
	global_store_dword v[18:19], v26, off
	v_lshl_add_u64 v[18:19], v[34:35], 0, s[66:67]
	global_store_dword v[18:19], v27, off
	v_lshl_add_u64 v[18:19], v[34:35], 0, s[64:65]
	global_store_dword v[18:19], v28, off
	v_lshl_add_u64 v[18:19], v[34:35], 0, s[62:63]
	global_store_dword v[18:19], v29, off
	v_lshl_add_u64 v[18:19], v[34:35], 0, s[48:49]
	global_store_dword v[18:19], v30, off
	v_lshl_add_u64 v[18:19], v[34:35], 0, s[46:47]
	global_store_dword v[18:19], v31, off
	v_lshl_add_u64 v[18:19], v[34:35], 0, s[44:45]
	global_store_dword v[18:19], v32, off
	v_lshl_add_u64 v[18:19], v[34:35], 0, s[42:43]
	global_store_dword v[18:19], v33, off
	v_lshl_add_u64 v[18:19], v[34:35], 0, s[36:37]
	global_store_dword v[18:19], v2, off
	v_lshl_add_u64 v[18:19], v[34:35], 0, s[88:89]
	global_store_dword v[18:19], v3, off
	v_lshl_add_u64 v[2:3], v[34:35], 0, s[86:87]
	global_store_dword v[2:3], v4, off
	v_lshl_add_u64 v[2:3], v[34:35], 0, s[84:85]
	global_store_dword v[2:3], v5, off
	v_lshl_add_u64 v[2:3], v[34:35], 0, s[82:83]
	global_store_dword v[2:3], v6, off
	v_lshl_add_u64 v[2:3], v[34:35], 0, s[6:7]
	global_store_dword v[2:3], v7, off
	v_lshl_add_u64 v[2:3], v[34:35], 0, s[10:11]
	global_store_dword v[2:3], v8, off
	v_lshl_add_u64 v[2:3], v[34:35], 0, s[94:95]
	global_store_dword v[2:3], v9, off
	v_lshl_add_u64 v[2:3], v[34:35], 0, s[4:5]
	global_store_dword v[2:3], v10, off
	v_lshl_add_u64 v[2:3], v[34:35], 0, s[78:79]
	global_store_dword v[2:3], v11, off
	v_lshl_add_u64 v[2:3], v[34:35], 0, s[40:41]
	global_store_dword v[2:3], v12, off
	v_lshl_add_u64 v[2:3], v[34:35], 0, vcc
	global_store_dword v[2:3], v13, off
	v_lshl_add_u64 v[2:3], v[34:35], 0, s[92:93]
	global_store_dword v[2:3], v14, off
	v_lshl_add_u64 v[2:3], v[34:35], 0, s[90:91]
	v_readlane_b32 s2, v255, 22
	global_store_dword v[2:3], v15, off
	v_lshl_add_u64 v[2:3], v[34:35], 0, s[76:77]
	s_add_i32 s50, s50, s16
	s_add_i32 s51, s51, s2
	s_add_i32 s34, s34, s35
	global_store_dword v[2:3], v16, off
	v_lshl_add_u64 v[2:3], v[34:35], 0, s[70:71]
	s_cmpk_gt_i32 s50, 0x3ff
	s_movk_i32 s89, 0x90
	global_store_dword v[2:3], v17, off
	s_cbranch_scc1 .LBB0_112
.LBB0_70:
	s_cmpk_lt_i32 s50, 0x200
	s_mov_b64 s[4:5], -1
	s_cbranch_scc1 .LBB0_106
	s_add_i32 s2, s50, 0xfffffe00
	s_lshr_b32 s37, s2, 7
	s_bfe_u32 s40, s50, 0x60001
	s_lshl_b32 s2, s37, 13
	s_lshl_b32 s3, s40, 7
	s_or_b32 s41, s3, s2
	s_mov_b32 s2, 14
	s_and_b32 s42, s50, 1
	s_sub_i32 s43, 0, s3
	s_ashr_i32 s3, s2, 31
	s_lshl_b32 s45, s42, 7
	s_add_i32 s44, s41, -3
	s_lshl_b64 s[2:3], s[2:3], 3
	v_readlane_b32 s20, v254, 53
	s_add_u32 s2, s0, s2
	s_mov_b32 s4, 15
	s_mov_b32 s6, 16
	s_mov_b32 s10, 17
	v_mov_b32_e32 v2, v183
	v_mov_b32_e32 v36, v1
	v_mov_b32_e32 v0, s20
	s_addc_u32 s3, s1, s3
	s_ashr_i32 s5, s4, 31
	s_waitcnt lgkmcnt(0)
	s_barrier
	v_ashrrev_i32_e32 v3, 31, v2
	s_lshl_b64 s[4:5], s[4:5], 3
	v_add_u32_sdwa v0, v2, v3 dst_sel:DWORD dst_unused:UNUSED_PAD src0_sel:DWORD src1_sel:BYTE_3
	s_add_u32 s4, s0, s4
	v_ashrrev_i32_e32 v91, 8, v0
	s_addc_u32 s5, s1, s5
	s_ashr_i32 s7, s6, 31
	v_mul_i32_i24_e32 v0, 0x100, v91
	s_lshl_b64 s[6:7], s[6:7], 3
	v_sub_u32_e32 v15, v2, v0
	s_add_u32 s6, s0, s6
	v_lshlrev_b32_e32 v18, 1, v15
	s_addc_u32 s7, s1, s7
	s_ashr_i32 s11, s10, 31
	v_readlane_b32 s20, v254, 54
	v_and_b32_e32 v92, 0x7f, v15
	v_and_b32_e32 v0, 0xffffff00, v18
	v_lshlrev_b32_e32 v67, 5, v91
	s_lshl_b64 s[10:11], s[10:11], 3
	v_mov_b32_e32 v37, s20
	v_readlane_b32 s20, v254, 55
	v_or3_b32 v10, s45, v0, v92
	v_add_u32_e32 v0, s44, v67
	v_mov_b64_e32 v[4:5], s[26:27]
	s_add_u32 s10, s0, s10
	v_mov_b32_e32 v38, s20
	v_mad_i64_i32 v[4:5], s[20:21], v0, s18, v[4:5]
	v_ashrrev_i32_e32 v11, 31, v10
	s_addc_u32 s11, s1, s11
	v_readfirstlane_b32 s36, v2
	v_lshl_add_u64 v[4:5], v[10:11], 1, v[4:5]
	v_cmp_lt_i32_e64 s[38:39], s43, v67
	v_mov_b32_e32 v19, 0
	v_mov_b32_e32 v20, 0
	v_mov_b32_e32 v21, 0
	v_mov_b32_e32 v228, 0
	v_mov_b32_e32 v229, 0
	s_and_saveexec_b64 s[20:21], s[38:39]
	s_mov_b32 s48, 0x3f2aaaab
	s_mov_b32 s49, 0x3f317218
	s_mov_b32 s60, 0x33800000
	s_cbranch_execz .LBB0_73
	v_add_co_u32_e32 v6, vcc, 0x2000, v4
	s_nop 1
	v_addc_co_u32_e32 v7, vcc, 0, v5, vcc
	global_load_ushort v228, v[6:7], off offset:3584
	v_add_co_u32_e32 v6, vcc, 0x1000, v4
	s_nop 0
	s_nop 0
	v_addc_co_u32_e32 v7, vcc, 0, v5, vcc
	global_load_ushort v229, v[6:7], off
	s_nop 0
	s_nop 0
.LBB0_73:
	s_or_b64 exec, exec, s[20:21]
	s_load_dwordx2 s[52:53], s[2:3], 0x0
	s_load_dwordx2 s[20:21], s[4:5], 0x0
	s_load_dwordx2 s[56:57], s[6:7], 0x0
	s_load_dwordx2 s[58:59], s[10:11], 0x0
	v_mov_b32_e32 v230, 0
	s_and_saveexec_b64 s[2:3], s[38:39]
	s_cbranch_execz .LBB0_75
	v_add_co_u32_e32 v6, vcc, 0x4000, v4
	s_nop 1
	v_addc_co_u32_e32 v7, vcc, 0, v5, vcc
	global_load_ushort v230, v[6:7], off offset:3072
	s_nop 0
	s_nop 0
.LBB0_75:
	s_or_b64 exec, exec, s[2:3]
	v_add_co_u32_e32 v6, vcc, 0x6000, v4
	s_mov_b32 s2, 0xc000
	s_nop 0
	v_addc_co_u32_e32 v7, vcc, 0, v5, vcc
	global_load_ushort v22, v[6:7], off offset:2560
	v_add_co_u32_e32 v6, vcc, 0x8000, v4
	v_add_u32_e32 v0, 0x200, v2
	s_nop 0
	v_addc_co_u32_e32 v7, vcc, 0, v5, vcc
	global_load_ushort v26, v[6:7], off offset:2048
	v_add_co_u32_e32 v6, vcc, 0xa000, v4
	s_nop 1
	v_addc_co_u32_e32 v7, vcc, 0, v5, vcc
	global_load_ushort v27, v[6:7], off offset:1536
	v_add_co_u32_e32 v6, vcc, s2, v4
	s_mov_b32 s2, 0x11000
	s_nop 0
	v_addc_co_u32_e32 v7, vcc, 0, v5, vcc
	global_load_ushort v28, v[6:7], off offset:1024
	v_add_co_u32_e32 v6, vcc, 0xe000, v4
	s_nop 1
	v_addc_co_u32_e32 v7, vcc, 0, v5, vcc
	global_load_ushort v29, v[6:7], off offset:512
	v_add_co_u32_e32 v6, vcc, s28, v4
	s_nop 1
	v_addc_co_u32_e32 v7, vcc, 0, v5, vcc
	global_load_ushort v23, v[6:7], off
	v_add_co_u32_e32 v6, vcc, s2, v4
	s_mov_b32 s2, 0x20000
	s_nop 0
	v_addc_co_u32_e32 v7, vcc, 0, v5, vcc
	global_load_ushort v24, v[6:7], off offset:3584
	v_add_co_u32_e32 v6, vcc, 0x13000, v4
	s_nop 1
	v_addc_co_u32_e32 v7, vcc, 0, v5, vcc
	global_load_ushort v30, v[6:7], off offset:3072
	v_add_co_u32_e32 v6, vcc, 0x15000, v4
	s_nop 1
	v_addc_co_u32_e32 v7, vcc, 0, v5, vcc
	global_load_ushort v95, v[6:7], off offset:2560
	v_add_co_u32_e32 v6, vcc, 0x17000, v4
	s_nop 1
	v_addc_co_u32_e32 v7, vcc, 0, v5, vcc
	global_load_ushort v94, v[6:7], off offset:2048
	v_add_co_u32_e32 v6, vcc, 0x19000, v4
	s_nop 1
	v_addc_co_u32_e32 v7, vcc, 0, v5, vcc
	global_load_ushort v96, v[6:7], off offset:1536
	v_add_co_u32_e32 v6, vcc, 0x1b000, v4
	s_nop 1
	v_addc_co_u32_e32 v7, vcc, 0, v5, vcc
	global_load_ushort v97, v[6:7], off offset:1024
	v_add_co_u32_e32 v6, vcc, 0x1d000, v4
	s_nop 1
	v_addc_co_u32_e32 v7, vcc, 0, v5, vcc
	global_load_ushort v98, v[6:7], off offset:512
	v_add_co_u32_e32 v6, vcc, 0x1f000, v4
	s_nop 1
	v_addc_co_u32_e32 v7, vcc, 0, v5, vcc
	global_load_ushort v99, v[6:7], off
	v_add_co_u32_e32 v6, vcc, s2, v4
	s_mov_b32 s2, 0x28000
	s_nop 0
	v_addc_co_u32_e32 v7, vcc, 0, v5, vcc
	global_load_ushort v100, v[6:7], off offset:3584
	v_add_co_u32_e32 v6, vcc, 0x22000, v4
	s_nop 1
	v_addc_co_u32_e32 v7, vcc, 0, v5, vcc
	global_load_ushort v101, v[6:7], off offset:3072
	v_add_co_u32_e32 v6, vcc, 0x24000, v4
	s_nop 1
	v_addc_co_u32_e32 v7, vcc, 0, v5, vcc
	global_load_ushort v84, v[6:7], off offset:2560
	v_add_co_u32_e32 v6, vcc, 0x26000, v4
	s_nop 1
	v_addc_co_u32_e32 v7, vcc, 0, v5, vcc
	global_load_ushort v83, v[6:7], off offset:2048
	v_add_co_u32_e32 v6, vcc, s2, v4
	s_nop 1
	v_addc_co_u32_e32 v7, vcc, 0, v5, vcc
	global_load_ushort v85, v[6:7], off offset:1536
	v_add_co_u32_e32 v6, vcc, 0x2a000, v4
	s_nop 1
	v_addc_co_u32_e32 v7, vcc, 0, v5, vcc
	global_load_ushort v86, v[6:7], off offset:1024
	v_add_co_u32_e32 v6, vcc, 0x2c000, v4
	s_nop 1
	v_addc_co_u32_e32 v7, vcc, 0, v5, vcc
	global_load_ushort v87, v[6:7], off offset:512
	v_add_co_u32_e32 v6, vcc, 0x2e000, v4
	s_nop 1
	v_addc_co_u32_e32 v7, vcc, 0, v5, vcc
	global_load_ushort v88, v[6:7], off
	v_add_co_u32_e32 v6, vcc, 0x2f000, v4
	s_nop 1
	v_addc_co_u32_e32 v7, vcc, 0, v5, vcc
	global_load_ushort v89, v[6:7], off offset:3584
	v_add_co_u32_e32 v6, vcc, 0x31000, v4
	s_nop 1
	v_addc_co_u32_e32 v7, vcc, 0, v5, vcc
	global_load_ushort v90, v[6:7], off offset:3072
	v_add_co_u32_e32 v6, vcc, 0x33000, v4
	s_nop 1
	v_addc_co_u32_e32 v7, vcc, 0, v5, vcc
	global_load_ushort v35, v[6:7], off offset:2560
	v_add_co_u32_e32 v6, vcc, 0x35000, v4
	s_nop 1
	v_addc_co_u32_e32 v7, vcc, 0, v5, vcc
	global_load_ushort v34, v[6:7], off offset:2048
	v_add_co_u32_e32 v6, vcc, 0x37000, v4
	s_nop 1
	v_addc_co_u32_e32 v7, vcc, 0, v5, vcc
	global_load_ushort v77, v[6:7], off offset:1536
	v_add_co_u32_e32 v6, vcc, 0x39000, v4
	s_nop 1
	v_addc_co_u32_e32 v7, vcc, 0, v5, vcc
	global_load_ushort v78, v[6:7], off offset:1024
	v_add_co_u32_e32 v6, vcc, 0x3b000, v4
	s_nop 1
	v_addc_co_u32_e32 v7, vcc, 0, v5, vcc
	global_load_ushort v79, v[6:7], off offset:512
	v_add_co_u32_e32 v6, vcc, 0x3d000, v4
	s_nop 1
	v_addc_co_u32_e32 v7, vcc, 0, v5, vcc
	global_load_ushort v80, v[6:7], off
	v_add_co_u32_e32 v6, vcc, 0x3e000, v4
	s_nop 1
	v_addc_co_u32_e32 v7, vcc, 0, v5, vcc
	v_add_co_u32_e32 v4, vcc, s29, v4
	global_load_ushort v81, v[6:7], off offset:3584
	s_nop 0
	v_addc_co_u32_e32 v5, vcc, 0, v5, vcc
	global_load_ushort v82, v[4:5], off offset:3072
	v_ashrrev_i32_e32 v4, 31, v0
	v_add_u32_sdwa v4, v0, v4 dst_sel:DWORD dst_unused:UNUSED_PAD src0_sel:DWORD src1_sel:BYTE_3
	v_ashrrev_i32_e32 v57, 8, v4
	v_mul_i32_i24_e32 v4, 0x100, v57
	v_sub_u32_e32 v4, v0, v4
	v_lshlrev_b32_e32 v68, 1, v4
	v_and_b32_e32 v58, 0x7f, v4
	v_and_b32_e32 v0, 0xffffff00, v68
	v_lshlrev_b32_e32 v39, 5, v57
	v_or3_b32 v8, s45, v0, v58
	v_add_u32_e32 v0, s44, v39
	v_mov_b64_e32 v[6:7], s[26:27]
	v_mad_i64_i32 v[6:7], s[2:3], v0, s18, v[6:7]
	v_ashrrev_i32_e32 v9, 31, v8
	v_lshl_add_u64 v[12:13], v[8:9], 1, v[6:7]
	v_cmp_lt_i32_e64 s[38:39], s43, v39
	v_mov_b32_e32 v5, 0
	v_mov_b32_e32 v6, 0
	v_mov_b32_e32 v7, 0
	v_mov_b32_e32 v231, 0
	v_mov_b32_e32 v232, 0
	s_and_saveexec_b64 s[2:3], s[38:39]
	s_cbranch_execz .LBB0_77
	v_add_co_u32_e32 v6, vcc, 0x2000, v12
	s_nop 1
	v_addc_co_u32_e32 v7, vcc, 0, v13, vcc
	global_load_ushort v231, v[6:7], off offset:3584
	v_add_co_u32_e32 v6, vcc, 0x1000, v12
	s_nop 1
	v_addc_co_u32_e32 v7, vcc, 0, v13, vcc
	global_load_ushort v232, v[6:7], off
	s_nop 0
	s_nop 0
	s_nop 0
.LBB0_77:
	s_or_b64 exec, exec, s[2:3]
	v_mov_b32_e32 v233, 0
	s_and_saveexec_b64 s[2:3], s[38:39]
	s_cbranch_execz .LBB0_79
	v_add_co_u32_e32 v16, vcc, 0x4000, v12
	s_nop 1
	v_addc_co_u32_e32 v17, vcc, 0, v13, vcc
	global_load_ushort v233, v[16:17], off offset:3072
	s_nop 0
	s_nop 0
.LBB0_79:
	s_or_b64 exec, exec, s[2:3]
	v_add_co_u32_e32 v16, vcc, 0x6000, v12
	s_mov_b32 s2, 0xc000
	s_nop 0
	v_addc_co_u32_e32 v17, vcc, 0, v13, vcc
	global_load_ushort v70, v[16:17], off offset:2560
	v_add_co_u32_e32 v16, vcc, 0x8000, v12
	v_lshlrev_b32_e32 v0, 2, v2
	s_nop 0
	v_addc_co_u32_e32 v17, vcc, 0, v13, vcc
	global_load_ushort v69, v[16:17], off offset:2048
	v_add_co_u32_e32 v16, vcc, 0xa000, v12
	s_lshl_b32 s6, s42, 1
	s_nop 0
	v_addc_co_u32_e32 v17, vcc, 0, v13, vcc
	global_load_ushort v71, v[16:17], off offset:1536
	v_add_co_u32_e32 v16, vcc, s2, v12
	s_mov_b32 s2, 0x11000
	s_nop 0
	v_addc_co_u32_e32 v17, vcc, 0, v13, vcc
	global_load_ushort v72, v[16:17], off offset:1024
	v_add_co_u32_e32 v16, vcc, 0xe000, v12
	v_and_b32_e32 v14, 0x7f, v2
	s_nop 0
	v_addc_co_u32_e32 v17, vcc, 0, v13, vcc
	global_load_ushort v73, v[16:17], off offset:512
	v_add_co_u32_e32 v16, vcc, s28, v12
	s_nop 1
	v_addc_co_u32_e32 v17, vcc, 0, v13, vcc
	global_load_ushort v74, v[16:17], off
	v_add_co_u32_e32 v16, vcc, s2, v12
	s_mov_b32 s2, 0x20000
	s_nop 0
	v_addc_co_u32_e32 v17, vcc, 0, v13, vcc
	global_load_ushort v75, v[16:17], off offset:3584
	v_add_co_u32_e32 v16, vcc, 0x13000, v12
	s_nop 1
	v_addc_co_u32_e32 v17, vcc, 0, v13, vcc
	global_load_ushort v76, v[16:17], off offset:3072
	v_add_co_u32_e32 v16, vcc, 0x15000, v12
	s_nop 1
	v_addc_co_u32_e32 v17, vcc, 0, v13, vcc
	global_load_ushort v60, v[16:17], off offset:2560
	v_add_co_u32_e32 v16, vcc, 0x17000, v12
	s_nop 1
	v_addc_co_u32_e32 v17, vcc, 0, v13, vcc
	global_load_ushort v59, v[16:17], off offset:2048
	v_add_co_u32_e32 v16, vcc, 0x19000, v12
	s_nop 1
	v_addc_co_u32_e32 v17, vcc, 0, v13, vcc
	global_load_ushort v61, v[16:17], off offset:1536
	v_add_co_u32_e32 v16, vcc, 0x1b000, v12
	s_nop 1
	v_addc_co_u32_e32 v17, vcc, 0, v13, vcc
	global_load_ushort v62, v[16:17], off offset:1024
	v_add_co_u32_e32 v16, vcc, 0x1d000, v12
	s_nop 1
	v_addc_co_u32_e32 v17, vcc, 0, v13, vcc
	global_load_ushort v63, v[16:17], off offset:512
	v_add_co_u32_e32 v16, vcc, 0x1f000, v12
	s_nop 1
	v_addc_co_u32_e32 v17, vcc, 0, v13, vcc
	global_load_ushort v64, v[16:17], off
	v_add_co_u32_e32 v16, vcc, s2, v12
	s_mov_b32 s2, 0x28000
	s_nop 0
	v_addc_co_u32_e32 v17, vcc, 0, v13, vcc
	global_load_ushort v65, v[16:17], off offset:3584
	v_add_co_u32_e32 v16, vcc, 0x22000, v12
	s_nop 1
	v_addc_co_u32_e32 v17, vcc, 0, v13, vcc
	global_load_ushort v66, v[16:17], off offset:3072
	v_add_co_u32_e32 v16, vcc, 0x24000, v12
	s_nop 1
	v_addc_co_u32_e32 v17, vcc, 0, v13, vcc
	global_load_ushort v50, v[16:17], off offset:2560
	v_add_co_u32_e32 v16, vcc, 0x26000, v12
	s_nop 1
	v_addc_co_u32_e32 v17, vcc, 0, v13, vcc
	global_load_ushort v49, v[16:17], off offset:2048
	v_add_co_u32_e32 v16, vcc, s2, v12
	s_movk_i32 s2, 0x100
	s_nop 0
	v_addc_co_u32_e32 v17, vcc, 0, v13, vcc
	global_load_ushort v51, v[16:17], off offset:1536
	v_add_co_u32_e32 v16, vcc, 0x2a000, v12
	s_nop 1
	v_addc_co_u32_e32 v17, vcc, 0, v13, vcc
	global_load_ushort v52, v[16:17], off offset:1024
	v_add_co_u32_e32 v16, vcc, 0x2c000, v12
	s_nop 1
	v_addc_co_u32_e32 v17, vcc, 0, v13, vcc
	global_load_ushort v53, v[16:17], off offset:512
	v_add_co_u32_e32 v16, vcc, 0x2e000, v12
	s_nop 1
	v_addc_co_u32_e32 v17, vcc, 0, v13, vcc
	global_load_ushort v54, v[16:17], off
	v_add_co_u32_e32 v16, vcc, 0x2f000, v12
	s_nop 1
	v_addc_co_u32_e32 v17, vcc, 0, v13, vcc
	global_load_ushort v55, v[16:17], off offset:3584
	v_add_co_u32_e32 v16, vcc, 0x31000, v12
	s_nop 1
	v_addc_co_u32_e32 v17, vcc, 0, v13, vcc
	global_load_ushort v56, v[16:17], off offset:3072
	v_add_co_u32_e32 v16, vcc, 0x33000, v12
	s_nop 1
	v_addc_co_u32_e32 v17, vcc, 0, v13, vcc
	global_load_ushort v41, v[16:17], off offset:2560
	v_add_co_u32_e32 v16, vcc, 0x35000, v12
	s_nop 1
	v_addc_co_u32_e32 v17, vcc, 0, v13, vcc
	global_load_ushort v40, v[16:17], off offset:2048
	v_add_co_u32_e32 v16, vcc, 0x37000, v12
	s_nop 1
	v_addc_co_u32_e32 v17, vcc, 0, v13, vcc
	global_load_ushort v42, v[16:17], off offset:1536
	v_add_co_u32_e32 v16, vcc, 0x39000, v12
	s_nop 1
	v_addc_co_u32_e32 v17, vcc, 0, v13, vcc
	global_load_ushort v43, v[16:17], off offset:1024
	v_add_co_u32_e32 v16, vcc, 0x3b000, v12
	s_nop 1
	v_addc_co_u32_e32 v17, vcc, 0, v13, vcc
	global_load_ushort v44, v[16:17], off offset:512
	v_add_co_u32_e32 v16, vcc, 0x3d000, v12
	s_nop 1
	v_addc_co_u32_e32 v17, vcc, 0, v13, vcc
	global_load_ushort v45, v[16:17], off
	v_add_co_u32_e32 v16, vcc, 0x3e000, v12
	s_nop 1
	v_addc_co_u32_e32 v17, vcc, 0, v13, vcc
	v_add_co_u32_e32 v12, vcc, 0x40000, v12
	global_load_ushort v46, v[16:17], off offset:3584
	s_nop 0
	v_addc_co_u32_e32 v13, vcc, 0, v13, vcc
	global_load_ushort v47, v[12:13], off offset:3072
	v_bfe_u32 v12, v2, 7, 1
	v_cmp_gt_i32_e32 vcc, s2, v2
	v_and_b32_e32 v13, 0x3fc, v0
	s_and_saveexec_b64 s[54:55], vcc
	s_cbranch_execz .LBB0_81
	v_readlane_b32 s4, v255, 23
	v_readlane_b32 s5, v255, 24
	s_waitcnt lgkmcnt(0)
	s_add_u32 s2, s56, s4
	s_addc_u32 s3, s57, s5
	s_add_u32 s56, s58, s4
	v_or_b32_e32 v0, s41, v14
	s_movk_i32 s4, 0xf00
	v_or_b32_e32 v25, s6, v12
	v_mul_lo_u32 v0, v0, s4
	v_or_b32_e32 v0, v0, v25
	v_add_u32_e32 v0, 0xe14, v0
	v_lshl_add_u64 v[16:17], v[0:1], 1, s[26:27]
	global_load_ushort v0, v[16:17], off
	v_lshlrev_b32_e32 v17, 2, v25
	global_load_dword v16, v17, s[2:3]
	s_addc_u32 s57, s59, s5
	global_load_dword v17, v17, s[56:57]
	s_waitcnt vmcnt(0) lgkmcnt(0)
	v_lshlrev_b32_e32 v0, 16, v0
	v_add_f32_e32 v0, v16, v0
	v_max_f32_e32 v16, 0, v0
	v_mul_f32_e64 v0, |v0|, s19
	v_exp_f32_e32 v0, v0
	v_mul_f32_e32 v17, 0x3fb8aa3b, v17
	v_exp_f32_e32 v17, v17
	v_add_f32_e32 v25, 1.0, v0
	v_add_f32_e32 v31, -1.0, v25
	v_sub_f32_e32 v32, v31, v25
	v_add_f32_e32 v32, 1.0, v32
	v_sub_f32_e32 v31, v0, v31
	v_add_f32_e32 v31, v31, v32
	v_frexp_mant_f32_e32 v32, v25
	v_cmp_gt_f32_e64 s[38:39], s48, v32
	v_cvt_f64_f32_e32 v[32:33], v25
	v_frexp_exp_i32_f64_e32 v32, v[32:33]
	v_subbrev_co_u32_e64 v32, s[38:39], 0, v32, s[38:39]
	v_sub_u32_e32 v33, 0, v32
	v_ldexp_f32 v25, v25, v33
	v_ldexp_f32 v31, v31, v33
	v_add_f32_e32 v33, -1.0, v25
	v_add_f32_e32 v48, 1.0, v33
	v_sub_f32_e32 v48, v25, v48
	v_add_f32_e32 v48, v31, v48
	v_add_f32_e32 v93, v33, v48
	v_sub_f32_e32 v33, v93, v33
	v_sub_f32_e32 v33, v48, v33
	v_add_f32_e32 v48, 1.0, v25
	v_add_f32_e32 v102, -1.0, v48
	v_sub_f32_e32 v25, v25, v102
	v_add_f32_e32 v25, v31, v25
	v_add_f32_e32 v31, v48, v25
	v_sub_f32_e32 v48, v31, v48
	v_sub_f32_e32 v25, v25, v48
	v_rcp_f32_e32 v48, v31
	v_cvt_f32_i32_e32 v32, v32
	v_cmp_neq_f32_e64 s[38:39], s15, v0
	v_mul_f32_e32 v102, v93, v48
	v_mul_f32_e32 v103, v31, v102
	v_fma_f32 v104, v102, v31, -v103
	v_fmac_f32_e32 v104, v102, v25
	v_add_f32_e32 v105, v103, v104
	v_sub_f32_e32 v106, v93, v105
	v_sub_f32_e32 v93, v93, v106
	v_sub_f32_e32 v103, v105, v103
	v_sub_f32_e32 v93, v93, v105
	v_add_f32_e32 v33, v33, v93
	v_sub_f32_e32 v93, v103, v104
	v_add_f32_e32 v33, v93, v33
	v_add_f32_e32 v93, v106, v33
	v_mul_f32_e32 v103, v48, v93
	v_mul_f32_e32 v104, v31, v103
	v_fma_f32 v31, v103, v31, -v104
	v_fmac_f32_e32 v31, v103, v25
	v_sub_f32_e32 v25, v106, v93
	v_add_f32_e32 v25, v33, v25
	v_add_f32_e32 v33, v104, v31
	v_sub_f32_e32 v105, v93, v33
	v_sub_f32_e32 v93, v93, v105
	v_sub_f32_e32 v104, v33, v104
	v_sub_f32_e32 v33, v93, v33
	v_add_f32_e32 v25, v25, v33
	v_sub_f32_e32 v31, v104, v31
	v_add_f32_e32 v25, v31, v25
	v_add_f32_e32 v31, v102, v103
	v_add_f32_e32 v25, v105, v25
	v_sub_f32_e32 v33, v31, v102
	v_mul_f32_e32 v25, v48, v25
	v_sub_f32_e32 v33, v103, v33
	v_add_f32_e32 v25, v33, v25
	v_mul_f32_e32 v102, 0x3f317218, v32
	v_add_f32_e32 v33, v31, v25
	v_fma_f32 v103, v32, s49, -v102
	v_mul_f32_e32 v48, v33, v33
	v_fmac_f32_e32 v103, 0xb102e308, v32
	v_sub_f32_e32 v31, v33, v31
	v_fmamk_f32 v93, v48, 0x3e9b6dac, v172
	v_sub_f32_e32 v25, v25, v31
	v_add_f32_e32 v31, v102, v103
	v_fmaak_f32 v93, v48, v93, 0x3f2aaada
	v_sub_f32_e32 v32, v31, v102
	v_ldexp_f32 v102, v33, 1
	v_mul_f32_e32 v33, v33, v48
	v_mul_f32_e32 v33, v33, v93
	v_add_f32_e32 v48, v102, v33
	v_sub_f32_e32 v93, v48, v102
	v_ldexp_f32 v25, v25, 1
	v_sub_f32_e32 v33, v33, v93
	v_add_f32_e32 v25, v25, v33
	v_add_f32_e32 v33, v48, v25
	v_sub_f32_e32 v48, v33, v48
	v_sub_f32_e32 v25, v25, v48
	v_add_f32_e32 v48, v31, v33
	v_sub_f32_e32 v93, v48, v31
	v_sub_f32_e32 v102, v48, v93
	v_sub_f32_e32 v32, v103, v32
	v_sub_f32_e32 v31, v31, v102
	v_sub_f32_e32 v33, v33, v93
	v_add_f32_e32 v31, v33, v31
	v_add_f32_e32 v33, v32, v25
	v_sub_f32_e32 v93, v33, v32
	v_sub_f32_e32 v102, v33, v93
	v_sub_f32_e32 v32, v32, v102
	v_sub_f32_e32 v25, v25, v93
	v_add_f32_e32 v31, v33, v31
	v_add_f32_e32 v25, v25, v32
	v_add_f32_e32 v32, v48, v31
	v_sub_f32_e32 v33, v32, v48
	v_sub_f32_e32 v31, v31, v33
	v_add_f32_e32 v25, v25, v31
	v_add_f32_e32 v25, v32, v25
	v_cndmask_b32_e64 v25, v175, v25, s[38:39]
	v_cmp_ngt_f32_e64 s[38:39], -1.0, v0
	s_nop 1
	v_cndmask_b32_e64 v25, v176, v25, s[38:39]
	v_cmp_neq_f32_e64 s[38:39], -1.0, v0
	s_nop 1
	v_cndmask_b32_e64 v25, v177, v25, s[38:39]
	v_cmp_lt_f32_e64 s[38:39], |v0|, s60
	s_nop 1
	v_cndmask_b32_e64 v0, v25, v0, s[38:39]
	v_add_f32_e32 v0, v16, v0
	v_add_u32_e32 v16, v38, v13
	v_mul_f32_e64 v17, v0, -v17
	ds_write2st64_b32 v16, v17, v0 offset1:4

.LBB0_103:
	s_or_b64 exec, exec, s[20:21]
	s_lshl_b32 s2, s37, 8
	v_lshlrev_b32_e32 v6, 1, v6
	s_lshl_b32 s4, s40, 2
	s_or_b32 s5, s2, s6
	v_cvt_pk_bf16_f32 v8, v18, v19
	v_cvt_pk_bf16_f32 v9, v14, v15
	v_cvt_pk_bf16_f32 v10, v16, v17
	v_cvt_pk_bf16_f32 v11, v4, v5
	v_add3_u32 v0, v7, v0, v6
	v_cmp_gt_i32_e32 vcc, 2, v2
	ds_write_b128 v0, v[8:11]
	s_and_saveexec_b64 s[2:3], vcc
	s_cbranch_execz .LBB0_105
	v_lshl_add_u32 v0, v2, 9, v38
	ds_read_b32 v0, v0 offset:2556
	s_mov_b32 s10, s80
	s_or_b32 s80, s5, s4
	s_lshl_b64 s[6:7], s[80:81], 2
	s_mov_b32 s80, s10
	s_waitcnt lgkmcnt(0)
	v_mul_f32_e32 v0, 0x3fb8aa3b, v0
	v_exp_f32_e32 v0, v0
	v_readlane_b32 s10, v255, 17
	v_readlane_b32 s11, v255, 18
	s_add_u32 s6, s10, s6
	s_addc_u32 s7, s11, s7
	v_lshl_add_u64 v[4:5], v[2:3], 2, s[6:7]
	global_store_dword v[4:5], v0, off

.LBB0_106:
	s_and_b64 vcc, exec, s[4:5]
	s_cbranch_vccz .LBB0_111
	s_mov_b32 s2, 7
	s_ashr_i32 s3, s2, 31
	s_lshl_b64 s[2:3], s[2:3], 3
	s_add_u32 s2, s0, s2
	s_addc_u32 s3, s1, s3
	s_load_dwordx2 s[2:3], s[2:3], 0x0
	v_readlane_b32 s6, v255, 29
	s_mov_b32 s4, 8
	v_readlane_b32 s7, v255, 30
	s_waitcnt lgkmcnt(0)
	s_add_u32 s38, s2, s6
	s_addc_u32 s39, s3, s7
	s_ashr_i32 s5, s4, 31
	s_lshl_b64 s[2:3], s[4:5], 3
	s_add_u32 s2, s0, s2
	s_addc_u32 s3, s1, s3
	s_load_dwordx2 s[2:3], s[2:3], 0x0
	v_readlane_b32 s6, v255, 31
	v_mov_b32_e32 v40, v183
	v_readlane_b32 s7, v255, 32
	s_waitcnt lgkmcnt(0)
	s_add_u32 s20, s2, s6
	v_readlane_b32 s2, v254, 56
	v_ashrrev_i32_e32 v53, 8, v40
	v_mov_b32_e32 v38, v1
	v_mov_b32_e32 v0, s2
	v_readlane_b32 s2, v254, 57
	s_addc_u32 s21, s3, s7
	s_barrier
	v_mov_b32_e32 v39, s2
	s_add_i32 s2, 0, 0x1b000
	v_lshl_add_u32 v32, v53, 5, s51
	v_and_b32_e32 v49, 0xff, v40
	v_mov_b32_e32 v37, s2
	v_readlane_b32 s2, v254, 58
	v_subrev_u32_e32 v0, 32, v32
	v_mov_b64_e32 v[2:3], s[26:27]
	v_mov_b32_e32 v36, s2
	v_mad_i64_i32 v[4:5], s[2:3], v0, s18, v[2:3]
	v_lshlrev_b32_e32 v0, 1, v49
	v_subrev_u32_e32 v6, 31, v32
	v_subrev_u32_e32 v8, 30, v32
	v_subrev_u32_e32 v10, 29, v32
	v_lshl_add_u64 v[4:5], v[4:5], 0, v[0:1]
	v_mad_i64_i32 v[6:7], s[2:3], v6, s18, v[2:3]
	v_mad_i64_i32 v[8:9], s[2:3], v8, s18, v[2:3]
	v_mad_i64_i32 v[10:11], s[2:3], v10, s18, v[2:3]
	v_lshl_add_u64 v[6:7], v[6:7], 0, v[0:1]
	v_lshl_add_u64 v[8:9], v[8:9], 0, v[0:1]
	v_lshl_add_u64 v[10:11], v[10:11], 0, v[0:1]
	global_load_ushort v74, v[4:5], off offset:512
	global_load_ushort v75, v[4:5], off offset:1024
	global_load_ushort v76, v[6:7], off offset:512
	global_load_ushort v71, v[6:7], off offset:1024
	global_load_ushort v66, v[8:9], off offset:512
	global_load_ushort v67, v[8:9], off offset:1024
	global_load_ushort v68, v[10:11], off offset:512
	global_load_ushort v63, v[10:11], off offset:1024
	v_subrev_u32_e32 v4, 28, v32
	v_mad_i64_i32 v[4:5], s[2:3], v4, s18, v[2:3]
	v_subrev_u32_e32 v6, 27, v32
	v_subrev_u32_e32 v8, 26, v32
	v_subrev_u32_e32 v10, 25, v32
	v_lshl_add_u64 v[4:5], v[4:5], 0, v[0:1]
	v_mad_i64_i32 v[6:7], s[2:3], v6, s18, v[2:3]
	v_mad_i64_i32 v[8:9], s[2:3], v8, s18, v[2:3]
	v_mad_i64_i32 v[10:11], s[2:3], v10, s18, v[2:3]
	v_lshl_add_u64 v[6:7], v[6:7], 0, v[0:1]
	v_lshl_add_u64 v[8:9], v[8:9], 0, v[0:1]
	v_lshl_add_u64 v[10:11], v[10:11], 0, v[0:1]
	global_load_ushort v70, v[4:5], off offset:512
	global_load_ushort v72, v[4:5], off offset:1024
	global_load_ushort v73, v[6:7], off offset:512
	global_load_ushort v69, v[6:7], off offset:1024
	global_load_ushort v62, v[8:9], off offset:512
	global_load_ushort v64, v[8:9], off offset:1024
	global_load_ushort v65, v[10:11], off offset:512
	global_load_ushort v61, v[10:11], off offset:1024
	v_subrev_u32_e32 v4, 24, v32
	v_mad_i64_i32 v[4:5], s[2:3], v4, s18, v[2:3]
	v_subrev_u32_e32 v6, 23, v32
	v_subrev_u32_e32 v8, 22, v32
	v_subrev_u32_e32 v10, 21, v32
	v_lshl_add_u64 v[4:5], v[4:5], 0, v[0:1]
	v_mad_i64_i32 v[6:7], s[2:3], v6, s18, v[2:3]
	v_mad_i64_i32 v[8:9], s[2:3], v8, s18, v[2:3]
	v_mad_i64_i32 v[10:11], s[2:3], v10, s18, v[2:3]
	v_lshl_add_u64 v[6:7], v[6:7], 0, v[0:1]
	v_lshl_add_u64 v[8:9], v[8:9], 0, v[0:1]
	v_lshl_add_u64 v[10:11], v[10:11], 0, v[0:1]
	global_load_ushort v58, v[4:5], off offset:512
	global_load_ushort v59, v[4:5], off offset:1024
	global_load_ushort v60, v[6:7], off offset:512
	global_load_ushort v55, v[6:7], off offset:1024
	global_load_ushort v48, v[8:9], off offset:512
	global_load_ushort v50, v[8:9], off offset:1024
	global_load_ushort v51, v[10:11], off offset:512
	global_load_ushort v45, v[10:11], off offset:1024
	v_subrev_u32_e32 v4, 20, v32
	v_mad_i64_i32 v[4:5], s[2:3], v4, s18, v[2:3]
	v_subrev_u32_e32 v6, 19, v32
	v_subrev_u32_e32 v8, 18, v32
	v_subrev_u32_e32 v10, 17, v32
	v_lshl_add_u64 v[4:5], v[4:5], 0, v[0:1]
	v_mad_i64_i32 v[6:7], s[2:3], v6, s18, v[2:3]
	v_mad_i64_i32 v[8:9], s[2:3], v8, s18, v[2:3]
	v_mad_i64_i32 v[10:11], s[2:3], v10, s18, v[2:3]
	v_lshl_add_u64 v[6:7], v[6:7], 0, v[0:1]
	v_lshl_add_u64 v[8:9], v[8:9], 0, v[0:1]
	v_lshl_add_u64 v[10:11], v[10:11], 0, v[0:1]
	global_load_ushort v54, v[4:5], off offset:512
	global_load_ushort v56, v[4:5], off offset:1024
	global_load_ushort v57, v[6:7], off offset:512
	global_load_ushort v52, v[6:7], off offset:1024
	global_load_ushort v44, v[8:9], off offset:512
	global_load_ushort v46, v[8:9], off offset:1024
	global_load_ushort v47, v[10:11], off offset:512
	global_load_ushort v43, v[10:11], off offset:1024
	v_add_u32_e32 v4, -16, v32
	v_mad_i64_i32 v[4:5], s[2:3], v4, s18, v[2:3]
	v_lshl_add_u64 v[8:9], v[4:5], 0, v[0:1]
	v_add_u32_e32 v4, -15, v32
	v_mad_i64_i32 v[4:5], s[2:3], v4, s18, v[2:3]
	v_lshl_add_u64 v[10:11], v[4:5], 0, v[0:1]
	v_add_u32_e32 v4, -14, v32
	v_mad_i64_i32 v[4:5], s[2:3], v4, s18, v[2:3]
	v_readfirstlane_b32 s4, v40
	v_lshl_add_u64 v[12:13], v[4:5], 0, v[0:1]
	v_add_u32_e32 v4, -13, v32
	v_mad_i64_i32 v[4:5], s[2:3], v4, s18, v[2:3]
	v_and_b32_e32 v41, 31, v40
	s_ashr_i32 s5, s4, 1
	v_lshl_add_u64 v[14:15], v[4:5], 0, v[0:1]
	v_mov_b32_e32 v4, s5
	s_movk_i32 s2, 0xffe0
	v_add_u32_e32 v16, s51, v41
	v_bfe_u32 v42, v40, 5, 1
	v_bfi_b32 v108, s2, v4, v40
	v_subrev_u32_e32 v4, 32, v16
	v_mad_i64_i32 v[4:5], s[2:3], v4, s18, v[2:3]
	v_lshlrev_b32_e32 v34, 4, v42
	v_mov_b32_e32 v35, v1
	v_lshl_add_u64 v[4:5], v[4:5], 0, v[34:35]
	s_movk_i32 s6, 0x1000
	v_add_co_u32_e32 v4, vcc, s6, v4
	v_lshl_add_u32 v18, v42, 11, v108
	s_nop 0
	v_addc_co_u32_e32 v5, vcc, 0, v5, vcc
	global_load_dwordx4 v[4:7], v[4:5], off offset:3072
	v_ashrrev_i32_e32 v19, 31, v18
	v_mad_i64_i32 v[16:17], s[2:3], v16, s18, v[2:3]
	v_lshl_add_u64 v[20:21], v[18:19], 2, s[38:39]
	v_add_u32_e32 v22, 0x400, v18
	v_add_u32_e32 v24, 0x500, v18
	v_add_u32_e32 v26, 0x600, v18
	v_add_u32_e32 v18, 0x700, v18
	v_lshl_add_u64 v[16:17], v[16:17], 0, v[34:35]
	v_ashrrev_i32_e32 v25, 31, v24
	v_ashrrev_i32_e32 v19, 31, v18
	v_add_co_u32_e32 v16, vcc, s6, v16
	v_ashrrev_i32_e32 v23, 31, v22
	v_lshl_add_u64 v[24:25], v[24:25], 2, s[38:39]
	v_ashrrev_i32_e32 v27, 31, v26
	v_lshl_add_u64 v[18:19], v[18:19], 2, s[38:39]
	v_ashrrev_i32_e32 v109, 31, v108
	v_addc_co_u32_e32 v17, vcc, 0, v17, vcc
	v_lshl_add_u64 v[22:23], v[22:23], 2, s[38:39]
	v_lshl_add_u64 v[26:27], v[26:27], 2, s[38:39]
	global_load_dword v35, v[20:21], off
	global_load_dword v77, v[20:21], off offset:1024
	global_load_dword v78, v[20:21], off offset:2048
	global_load_dword v79, v[20:21], off offset:3072
	global_load_dword v82, v[22:23], off
	s_nop 0
	global_load_dword v24, v[24:25], off
	s_nop 0
	global_load_dword v25, v[26:27], off
	global_load_dword v85, v[18:19], off
	s_nop 0
	global_load_dwordx4 v[18:21], v[16:17], off offset:3072
	global_load_ushort v102, v[8:9], off offset:512
	global_load_ushort v104, v[8:9], off offset:1024
	global_load_ushort v105, v[10:11], off offset:512
	global_load_ushort v100, v[10:11], off offset:1024
	global_load_ushort v94, v[12:13], off offset:512
	global_load_ushort v96, v[12:13], off offset:1024
	global_load_ushort v97, v[14:15], off offset:512
	global_load_ushort v92, v[14:15], off offset:1024
	v_lshl_add_u64 v[8:9], v[108:109], 2, s[20:21]
	global_load_dword v109, v[8:9], off
	v_add_u32_e32 v10, -12, v32
	v_mad_i64_i32 v[8:9], s[2:3], v10, s18, v[2:3]
	v_add_u32_e32 v10, -11, v32
	v_add_u32_e32 v12, -10, v32
	v_add_u32_e32 v14, -9, v32
	v_lshl_add_u64 v[8:9], v[8:9], 0, v[0:1]
	v_mad_i64_i32 v[10:11], s[2:3], v10, s18, v[2:3]
	v_mad_i64_i32 v[12:13], s[2:3], v12, s18, v[2:3]
	v_mad_i64_i32 v[14:15], s[2:3], v14, s18, v[2:3]
	v_lshl_add_u64 v[10:11], v[10:11], 0, v[0:1]
	v_lshl_add_u64 v[12:13], v[12:13], 0, v[0:1]
	v_lshl_add_u64 v[14:15], v[14:15], 0, v[0:1]
	global_load_ushort v103, v[8:9], off offset:512
	global_load_ushort v106, v[8:9], off offset:1024
	global_load_ushort v107, v[10:11], off offset:512
	global_load_ushort v101, v[10:11], off offset:1024
	global_load_ushort v95, v[12:13], off offset:512
	global_load_ushort v98, v[12:13], off offset:1024
	global_load_ushort v99, v[14:15], off offset:512
	global_load_ushort v93, v[14:15], off offset:1024
	v_add_u32_e32 v8, -8, v32
	v_mad_i64_i32 v[8:9], s[2:3], v8, s18, v[2:3]
	v_add_u32_e32 v10, -7, v32
	v_add_u32_e32 v12, -6, v32
	v_add_u32_e32 v14, -5, v32
	v_lshl_add_u64 v[8:9], v[8:9], 0, v[0:1]
	v_mad_i64_i32 v[10:11], s[2:3], v10, s18, v[2:3]
	v_mad_i64_i32 v[12:13], s[2:3], v12, s18, v[2:3]
	v_mad_i64_i32 v[14:15], s[2:3], v14, s18, v[2:3]
	v_lshl_add_u64 v[10:11], v[10:11], 0, v[0:1]
	v_lshl_add_u64 v[12:13], v[12:13], 0, v[0:1]
	v_lshl_add_u64 v[14:15], v[14:15], 0, v[0:1]
	global_load_ushort v89, v[8:9], off offset:512
	global_load_ushort v90, v[8:9], off offset:1024
	global_load_ushort v91, v[10:11], off offset:512
	global_load_ushort v88, v[10:11], off offset:1024
	global_load_ushort v81, v[12:13], off offset:512
	global_load_ushort v83, v[12:13], off offset:1024
	global_load_ushort v84, v[14:15], off offset:512
	global_load_ushort v80, v[14:15], off offset:1024
	v_add_u32_e32 v8, -4, v32
	v_mad_i64_i32 v[8:9], s[2:3], v8, s18, v[2:3]
	v_lshl_add_u64 v[26:27], v[8:9], 0, v[0:1]
	v_add_u32_e32 v8, -3, v32
	v_mad_i64_i32 v[8:9], s[2:3], v8, s18, v[2:3]
	v_lshl_add_u64 v[28:29], v[8:9], 0, v[0:1]
	v_add_u32_e32 v8, -2, v32
	v_mad_i64_i32 v[8:9], s[2:3], v8, s18, v[2:3]
	v_lshl_add_u64 v[30:31], v[8:9], 0, v[0:1]
	v_add_u32_e32 v8, -1, v32
	v_mad_i64_i32 v[2:3], s[2:3], v8, s18, v[2:3]
	v_lshl_add_u64 v[32:33], v[2:3], 0, v[0:1]
	v_lshlrev_b32_e32 v108, 1, v108
	v_mul_u32_u24_e32 v110, 0x840, v42
	v_add3_u32 v111, v37, v108, v110
	s_mov_b32 s2, 0x3d800000
	s_waitcnt vmcnt(0)
	v_cvt_pk_bf16_f32 v22, v35, v77
	v_cvt_pk_bf16_f32 v23, v78, v79
	v_cvt_pk_bf16_f32 v24, v82, v24
	v_cvt_pk_bf16_f32 v25, v25, v85
	global_load_ushort v85, v[26:27], off offset:512
	global_load_ushort v86, v[26:27], off offset:1024
	global_load_ushort v87, v[28:29], off offset:512
	global_load_ushort v82, v[28:29], off offset:1024
	global_load_ushort v77, v[30:31], off offset:512
	global_load_ushort v78, v[30:31], off offset:1024
	global_load_ushort v79, v[32:33], off offset:512
	global_load_ushort v35, v[32:33], off offset:1024
	s_waitcnt lgkmcnt(0)
	v_mfma_f32_32x32x16_bf16 v[2:17], v[4:7], v[22:25], 0
	v_mfma_f32_32x32x16_bf16 v[18:33], v[18:21], v[22:25], 0
	s_nop 10
	v_add_f32_e32 v2, v109, v2
	v_cvt_pk_bf16_f32 v2, v2, s0
	ds_write_b16 v111, v2
	v_add_f32_e32 v2, v109, v18
	v_cvt_pk_bf16_f32 v2, v2, s0
	v_add3_u32 v18, v37, v110, v108
	ds_write_b16 v18, v2 offset:16896
	v_add_f32_e32 v2, v109, v3
	v_cvt_pk_bf16_f32 v2, v2, s0
	ds_write_b16 v111, v2 offset:528
	v_add_f32_e32 v2, v109, v19
	v_cvt_pk_bf16_f32 v2, v2, s0
	ds_write_b16 v18, v2 offset:17424
	v_add_f32_e32 v2, v109, v4
	v_cvt_pk_bf16_f32 v2, v2, s0
	ds_write_b16 v111, v2 offset:1056
	v_add_f32_e32 v2, v109, v20
	v_cvt_pk_bf16_f32 v2, v2, s0
	ds_write_b16 v18, v2 offset:17952
	v_add_f32_e32 v2, v109, v5
	v_cvt_pk_bf16_f32 v2, v2, s0
	ds_write_b16 v111, v2 offset:1584
	v_add_f32_e32 v2, v109, v21
	v_cvt_pk_bf16_f32 v2, v2, s0
	ds_write_b16 v18, v2 offset:18480
	v_add_f32_e32 v2, v109, v6
	v_cvt_pk_bf16_f32 v2, v2, s0
	ds_write_b16 v111, v2 offset:4224
	v_add_f32_e32 v2, v109, v22
	v_cvt_pk_bf16_f32 v2, v2, s0
	ds_write_b16 v18, v2 offset:21120
	v_add_f32_e32 v2, v109, v7
	v_cvt_pk_bf16_f32 v2, v2, s0
	ds_write_b16 v111, v2 offset:4752
	v_add_f32_e32 v2, v109, v23
	v_cvt_pk_bf16_f32 v2, v2, s0
	ds_write_b16 v18, v2 offset:21648
	v_add_f32_e32 v2, v109, v8
	v_cvt_pk_bf16_f32 v2, v2, s0
	ds_write_b16 v111, v2 offset:5280
	v_add_f32_e32 v2, v109, v24
	v_cvt_pk_bf16_f32 v2, v2, s0
	ds_write_b16 v18, v2 offset:22176
	v_add_f32_e32 v2, v109, v9
	v_cvt_pk_bf16_f32 v2, v2, s0
	ds_write_b16 v111, v2 offset:5808
	v_add_f32_e32 v2, v109, v25
	v_cvt_pk_bf16_f32 v2, v2, s0
	ds_write_b16 v18, v2 offset:22704
	v_add_f32_e32 v2, v109, v10
	v_cvt_pk_bf16_f32 v2, v2, s0
	ds_write_b16 v111, v2 offset:8448
	v_add_f32_e32 v2, v109, v26
	v_cvt_pk_bf16_f32 v2, v2, s0
	ds_write_b16 v18, v2 offset:25344
	v_add_f32_e32 v2, v109, v11
	v_cvt_pk_bf16_f32 v2, v2, s0
	ds_write_b16 v111, v2 offset:8976
	v_add_f32_e32 v2, v109, v27
	v_cvt_pk_bf16_f32 v2, v2, s0
	ds_write_b16 v18, v2 offset:25872
	v_add_f32_e32 v2, v109, v12
	v_cvt_pk_bf16_f32 v2, v2, s0
	ds_write_b16 v111, v2 offset:9504
	v_add_f32_e32 v2, v109, v28
	v_cvt_pk_bf16_f32 v2, v2, s0
	ds_write_b16 v18, v2 offset:26400
	v_add_f32_e32 v2, v109, v13
	v_cvt_pk_bf16_f32 v2, v2, s0
	ds_write_b16 v111, v2 offset:10032
	v_add_f32_e32 v2, v109, v29
	v_cvt_pk_bf16_f32 v2, v2, s0
	ds_write_b16 v18, v2 offset:26928
	v_add_f32_e32 v2, v109, v14
	v_cvt_pk_bf16_f32 v2, v2, s0
	ds_write_b16 v111, v2 offset:12672
	v_add_f32_e32 v2, v109, v30
	v_cvt_pk_bf16_f32 v2, v2, s0
	ds_write_b16 v18, v2 offset:29568
	v_add_f32_e32 v2, v109, v15
	v_cvt_pk_bf16_f32 v2, v2, s0
	ds_write_b16 v111, v2 offset:13200
	v_add_f32_e32 v2, v109, v31
	v_cvt_pk_bf16_f32 v2, v2, s0
	ds_write_b16 v18, v2 offset:30096
	v_add_f32_e32 v2, v109, v16
	v_cvt_pk_bf16_f32 v2, v2, s0
	ds_write_b16 v111, v2 offset:13728
	v_add_f32_e32 v2, v109, v32
	v_cvt_pk_bf16_f32 v2, v2, s0
	ds_write_b16 v18, v2 offset:30624
	v_add_f32_e32 v2, v109, v17
	v_cvt_pk_bf16_f32 v2, v2, s0
	ds_write_b16 v111, v2 offset:14256
	v_add_f32_e32 v2, v109, v33
	v_cvt_pk_bf16_f32 v2, v2, s0
	ds_write_b16 v18, v2 offset:31152
	v_mul_i32_i24_e32 v2, 0x4200, v53
	v_add3_u32 v0, v37, v0, v2
	s_waitcnt lgkmcnt(0)
	s_barrier
	ds_read_u16 v2, v0
	ds_read_u16 v3, v0 offset:528
	ds_read_u16 v4, v0 offset:1056
	ds_read_u16 v5, v0 offset:1584
	ds_read_u16 v6, v0 offset:2112
	ds_read_u16 v7, v0 offset:2640
	ds_read_u16 v8, v0 offset:3168
	ds_read_u16 v9, v0 offset:3696
	s_waitcnt lgkmcnt(0)
	v_lshlrev_b32_e32 v2, 16, v2
	v_mul_f32_e64 v10, |v2|, s19
	v_exp_f32_e32 v10, v10
	v_lshlrev_b32_e32 v3, 16, v3
	v_mul_f32_e64 v12, |v3|, s19
	v_exp_f32_e32 v12, v12
	v_add_f32_e32 v10, 1.0, v10
	v_cmp_gt_f32_e32 vcc, s96, v10
	v_max_f32_e32 v2, v2, v2
	v_min_f32_e32 v2, 0, v2
	v_cndmask_b32_e64 v11, 0, 32, vcc
	v_ldexp_f32 v10, v10, v11
	v_log_f32_e32 v10, v10
	v_lshlrev_b32_e32 v4, 16, v4
	v_max_f32_e32 v3, v3, v3
	v_min_f32_e32 v3, 0, v3
	v_mul_f32_e32 v11, 0x3f317217, v10
	v_fma_f32 v11, v10, s97, -v11
	v_fmac_f32_e32 v11, 0x3377d1cf, v10
	v_fmac_f32_e32 v11, 0x3f317217, v10
	v_cmp_lt_f32_e64 s[38:39], |v10|, s15
	v_lshlrev_b32_e32 v5, 16, v5
	v_lshlrev_b32_e32 v6, 16, v6
	v_cndmask_b32_e64 v10, v10, v11, s[38:39]
	v_cndmask_b32_e32 v11, 0, v179, vcc
	v_sub_f32_e32 v10, v10, v11
	v_add_f32_e32 v11, 1.0, v12
	v_cmp_gt_f32_e32 vcc, s96, v11
	v_sub_f32_e32 v2, v2, v10
	v_lshlrev_b32_e32 v7, 16, v7
	v_cndmask_b32_e64 v12, 0, 32, vcc
	v_ldexp_f32 v11, v11, v12
	v_log_f32_e32 v11, v11
	v_mul_f32_e64 v12, |v4|, s19
	v_exp_f32_e32 v12, v12
	v_max_f32_e32 v4, v4, v4
	v_mul_f32_e32 v10, 0x3f317217, v11
	v_fma_f32 v10, v11, s97, -v10
	v_fmac_f32_e32 v10, 0x3377d1cf, v11
	v_fmac_f32_e32 v10, 0x3f317217, v11
	v_cmp_lt_f32_e64 s[38:39], |v11|, s15
	v_min_f32_e32 v4, 0, v4
	v_lshlrev_b32_e32 v8, 16, v8
	v_cndmask_b32_e64 v10, v11, v10, s[38:39]
	v_cndmask_b32_e32 v11, 0, v179, vcc
	v_sub_f32_e32 v10, v10, v11
	v_sub_f32_e32 v3, v3, v10
	v_add_f32_e32 v10, 1.0, v12
	v_cmp_gt_f32_e32 vcc, s96, v10
	v_mul_f32_e64 v12, |v5|, s19
	v_exp_f32_e32 v12, v12
	v_cndmask_b32_e64 v11, 0, 32, vcc
	v_ldexp_f32 v10, v10, v11
	v_log_f32_e32 v10, v10
	v_max_f32_e32 v5, v5, v5
	v_min_f32_e32 v5, 0, v5
	v_lshlrev_b32_e32 v9, 16, v9
	v_mul_f32_e32 v11, 0x3f317217, v10
	v_fma_f32 v11, v10, s97, -v11
	v_fmac_f32_e32 v11, 0x3377d1cf, v10
	v_fmac_f32_e32 v11, 0x3f317217, v10
	v_cmp_lt_f32_e64 s[38:39], |v10|, s15
	v_fma_f32 v2, v2, s2, 0
	v_fmamk_f32 v3, v3, 0x3d800000, v2
	v_cndmask_b32_e64 v10, v10, v11, s[38:39]
	v_cndmask_b32_e32 v11, 0, v179, vcc
	v_sub_f32_e32 v10, v10, v11
	v_add_f32_e32 v11, 1.0, v12
	v_cmp_gt_f32_e32 vcc, s96, v11
	v_sub_f32_e32 v4, v4, v10
	v_fmamk_f32 v4, v4, 0x3d800000, v3
	v_cndmask_b32_e64 v12, 0, 32, vcc
	v_ldexp_f32 v11, v11, v12
	v_log_f32_e32 v11, v11
	v_mul_f32_e64 v12, |v6|, s19
	v_exp_f32_e32 v12, v12
	v_max_f32_e32 v6, v6, v6
	v_mul_f32_e32 v10, 0x3f317217, v11
	v_fma_f32 v10, v11, s97, -v10
	v_fmac_f32_e32 v10, 0x3377d1cf, v11
	v_fmac_f32_e32 v10, 0x3f317217, v11
	v_cmp_lt_f32_e64 s[38:39], |v11|, s15
	v_min_f32_e32 v6, 0, v6
	s_movk_i32 s2, 0x100
	v_cndmask_b32_e64 v10, v11, v10, s[38:39]
	v_cndmask_b32_e32 v11, 0, v179, vcc
	v_sub_f32_e32 v10, v10, v11
	v_sub_f32_e32 v5, v5, v10
	v_add_f32_e32 v10, 1.0, v12
	v_cmp_gt_f32_e32 vcc, s96, v10
	v_mul_f32_e64 v12, |v7|, s19
	v_exp_f32_e32 v12, v12
	v_cndmask_b32_e64 v11, 0, 32, vcc
	v_ldexp_f32 v10, v10, v11
	v_log_f32_e32 v10, v10
	v_max_f32_e32 v7, v7, v7
	v_min_f32_e32 v7, 0, v7
	v_fmamk_f32 v5, v5, 0x3d800000, v4
	v_mul_f32_e32 v11, 0x3f317217, v10
	v_fma_f32 v11, v10, s97, -v11
	v_fmac_f32_e32 v11, 0x3377d1cf, v10
	v_fmac_f32_e32 v11, 0x3f317217, v10
	v_cmp_lt_f32_e64 s[38:39], |v10|, s15
	s_nop 1
	v_cndmask_b32_e64 v10, v10, v11, s[38:39]
	v_cndmask_b32_e32 v11, 0, v179, vcc
	v_sub_f32_e32 v10, v10, v11
	v_add_f32_e32 v11, 1.0, v12
	v_cmp_gt_f32_e32 vcc, s96, v11
	v_sub_f32_e32 v6, v6, v10
	v_fmamk_f32 v6, v6, 0x3d800000, v5
	v_cndmask_b32_e64 v12, 0, 32, vcc
	v_ldexp_f32 v11, v11, v12
	v_log_f32_e32 v11, v11
	v_mul_f32_e64 v12, |v8|, s19
	v_exp_f32_e32 v12, v12
	v_max_f32_e32 v8, v8, v8
	v_mul_f32_e32 v10, 0x3f317217, v11
	v_fma_f32 v10, v11, s97, -v10
	v_fmac_f32_e32 v10, 0x3377d1cf, v11
	v_fmac_f32_e32 v10, 0x3f317217, v11
	v_cmp_lt_f32_e64 s[38:39], |v11|, s15
	v_min_f32_e32 v8, 0, v8
	s_nop 0
	v_cndmask_b32_e64 v10, v11, v10, s[38:39]
	v_cndmask_b32_e32 v11, 0, v179, vcc
	v_sub_f32_e32 v10, v10, v11
	v_sub_f32_e32 v7, v7, v10
	v_add_f32_e32 v10, 1.0, v12
	v_cmp_gt_f32_e32 vcc, s96, v10
	v_mul_f32_e64 v12, |v9|, s19
	v_exp_f32_e32 v12, v12
	v_cndmask_b32_e64 v11, 0, 32, vcc
	v_ldexp_f32 v10, v10, v11
	v_log_f32_e32 v10, v10
	v_max_f32_e32 v9, v9, v9
	v_min_f32_e32 v9, 0, v9
	v_fmamk_f32 v7, v7, 0x3d800000, v6
	v_mul_f32_e32 v11, 0x3f317217, v10
	v_fma_f32 v11, v10, s97, -v11
	v_fmac_f32_e32 v11, 0x3377d1cf, v10
	v_fmac_f32_e32 v11, 0x3f317217, v10
	v_cmp_lt_f32_e64 s[38:39], |v10|, s15
	s_nop 1
	v_cndmask_b32_e64 v10, v10, v11, s[38:39]
	v_cndmask_b32_e32 v11, 0, v179, vcc
	v_sub_f32_e32 v10, v10, v11
	v_add_f32_e32 v11, 1.0, v12
	v_cmp_gt_f32_e32 vcc, s96, v11
	v_sub_f32_e32 v8, v8, v10
	v_fmamk_f32 v8, v8, 0x3d800000, v7
	v_cndmask_b32_e64 v12, 0, 32, vcc
	v_ldexp_f32 v11, v11, v12
	v_log_f32_e32 v11, v11
	ds_read_u16 v12, v0 offset:4224
	ds_read_u16 v13, v0 offset:4752
	ds_read_u16 v14, v0 offset:5280
	ds_read_u16 v15, v0 offset:5808
	ds_read_u16 v16, v0 offset:6336
	ds_read_u16 v17, v0 offset:6864
	ds_read_u16 v18, v0 offset:7392
	ds_read_u16 v19, v0 offset:7920
	s_waitcnt lgkmcnt(0)
	v_lshlrev_b32_e32 v12, 16, v12
	v_mul_f32_e64 v20, |v12|, s19
	v_mul_f32_e32 v10, 0x3f317217, v11
	v_fma_f32 v10, v11, s97, -v10
	v_fmac_f32_e32 v10, 0x3377d1cf, v11
	v_exp_f32_e32 v20, v20
	v_fmac_f32_e32 v10, 0x3f317217, v11
	v_cmp_lt_f32_e64 s[38:39], |v11|, s15
	v_lshlrev_b32_e32 v13, 16, v13
	v_lshlrev_b32_e32 v14, 16, v14
	v_cndmask_b32_e64 v10, v11, v10, s[38:39]
	v_cndmask_b32_e32 v11, 0, v179, vcc
	v_sub_f32_e32 v10, v10, v11
	v_sub_f32_e32 v9, v9, v10
	v_add_f32_e32 v10, 1.0, v20
	v_cmp_gt_f32_e32 vcc, s96, v10
	v_mul_f32_e64 v20, |v13|, s19
	v_exp_f32_e32 v20, v20
	v_cndmask_b32_e64 v11, 0, 32, vcc
	v_ldexp_f32 v10, v10, v11
	v_log_f32_e32 v10, v10
	v_max_f32_e32 v11, v12, v12
	v_min_f32_e32 v11, 0, v11
	v_lshlrev_b32_e32 v15, 16, v15
	v_mul_f32_e32 v12, 0x3f317217, v10
	v_fma_f32 v12, v10, s97, -v12
	v_fmac_f32_e32 v12, 0x3377d1cf, v10
	v_fmac_f32_e32 v12, 0x3f317217, v10
	v_cmp_lt_f32_e64 s[38:39], |v10|, s15
	v_lshlrev_b32_e32 v16, 16, v16
	v_lshlrev_b32_e32 v17, 16, v17
	v_cndmask_b32_e64 v10, v10, v12, s[38:39]
	v_cndmask_b32_e32 v12, 0, v179, vcc
	v_sub_f32_e32 v10, v10, v12
	v_add_f32_e32 v12, 1.0, v20
	v_cmp_gt_f32_e32 vcc, s96, v12
	v_sub_f32_e32 v10, v11, v10
	v_max_f32_e32 v11, v13, v13
	v_cndmask_b32_e64 v20, 0, 32, vcc
	v_ldexp_f32 v12, v12, v20
	v_log_f32_e32 v12, v12
	v_mul_f32_e64 v20, |v14|, s19
	v_exp_f32_e32 v20, v20
	v_min_f32_e32 v11, 0, v11
	v_mul_f32_e32 v13, 0x3f317217, v12
	v_fma_f32 v13, v12, s97, -v13
	v_fmac_f32_e32 v13, 0x3377d1cf, v12
	v_fmac_f32_e32 v13, 0x3f317217, v12
	v_cmp_lt_f32_e64 s[38:39], |v12|, s15
	v_lshlrev_b32_e32 v18, 16, v18
	v_lshlrev_b32_e32 v19, 16, v19
	v_cndmask_b32_e64 v12, v12, v13, s[38:39]
	v_cndmask_b32_e32 v13, 0, v179, vcc
	v_sub_f32_e32 v12, v12, v13
	v_sub_f32_e32 v11, v11, v12
	v_add_f32_e32 v12, 1.0, v20
	v_cmp_gt_f32_e32 vcc, s96, v12
	v_mul_f32_e64 v20, |v15|, s19
	v_exp_f32_e32 v20, v20
	v_cndmask_b32_e64 v13, 0, 32, vcc
	v_ldexp_f32 v12, v12, v13
	v_log_f32_e32 v12, v12
	v_max_f32_e32 v13, v14, v14
	v_min_f32_e32 v13, 0, v13
	v_fmamk_f32 v9, v9, 0x3d800000, v8
	v_mul_f32_e32 v14, 0x3f317217, v12
	v_fma_f32 v14, v12, s97, -v14
	v_fmac_f32_e32 v14, 0x3377d1cf, v12
	v_fmac_f32_e32 v14, 0x3f317217, v12
	v_cmp_lt_f32_e64 s[38:39], |v12|, s15
	v_fmamk_f32 v10, v10, 0x3d800000, v9
	v_fmamk_f32 v11, v11, 0x3d800000, v10
	v_cndmask_b32_e64 v12, v12, v14, s[38:39]
	v_cndmask_b32_e32 v14, 0, v179, vcc
	v_sub_f32_e32 v12, v12, v14
	v_add_f32_e32 v14, 1.0, v20
	v_cmp_gt_f32_e32 vcc, s96, v14
	v_sub_f32_e32 v12, v13, v12
	v_max_f32_e32 v13, v15, v15
	v_cndmask_b32_e64 v20, 0, 32, vcc
	v_ldexp_f32 v14, v14, v20
	v_log_f32_e32 v14, v14
	v_mul_f32_e64 v20, |v16|, s19
	v_exp_f32_e32 v20, v20
	v_min_f32_e32 v13, 0, v13
	v_mul_f32_e32 v15, 0x3f317217, v14
	v_fma_f32 v15, v14, s97, -v15
	v_fmac_f32_e32 v15, 0x3377d1cf, v14
	v_fmac_f32_e32 v15, 0x3f317217, v14
	v_cmp_lt_f32_e64 s[38:39], |v14|, s15
	v_fmamk_f32 v12, v12, 0x3d800000, v11
	s_nop 0
	v_cndmask_b32_e64 v14, v14, v15, s[38:39]
	v_cndmask_b32_e32 v15, 0, v179, vcc
	v_sub_f32_e32 v14, v14, v15
	v_sub_f32_e32 v13, v13, v14
	v_add_f32_e32 v14, 1.0, v20
	v_cmp_gt_f32_e32 vcc, s96, v14
	v_mul_f32_e64 v20, |v17|, s19
	v_exp_f32_e32 v20, v20
	v_cndmask_b32_e64 v15, 0, 32, vcc
	v_ldexp_f32 v14, v14, v15
	v_log_f32_e32 v14, v14
	v_max_f32_e32 v15, v16, v16
	v_min_f32_e32 v15, 0, v15
	v_fmamk_f32 v13, v13, 0x3d800000, v12
	v_mul_f32_e32 v16, 0x3f317217, v14
	v_fma_f32 v16, v14, s97, -v16
	v_fmac_f32_e32 v16, 0x3377d1cf, v14
	v_fmac_f32_e32 v16, 0x3f317217, v14
	v_cmp_lt_f32_e64 s[38:39], |v14|, s15
	s_nop 1
	v_cndmask_b32_e64 v14, v14, v16, s[38:39]
	v_cndmask_b32_e32 v16, 0, v179, vcc
	v_sub_f32_e32 v14, v14, v16
	v_add_f32_e32 v16, 1.0, v20
	v_cmp_gt_f32_e32 vcc, s96, v16
	v_sub_f32_e32 v14, v15, v14
	v_max_f32_e32 v15, v17, v17
	v_cndmask_b32_e64 v20, 0, 32, vcc
	v_ldexp_f32 v16, v16, v20
	v_log_f32_e32 v16, v16
	v_mul_f32_e64 v20, |v18|, s19
	v_exp_f32_e32 v20, v20
	v_min_f32_e32 v15, 0, v15
	v_mul_f32_e32 v17, 0x3f317217, v16
	v_fma_f32 v17, v16, s97, -v17
	v_fmac_f32_e32 v17, 0x3377d1cf, v16
	v_fmac_f32_e32 v17, 0x3f317217, v16
	v_cmp_lt_f32_e64 s[38:39], |v16|, s15
	v_fmamk_f32 v14, v14, 0x3d800000, v13
	s_nop 0
	v_cndmask_b32_e64 v16, v16, v17, s[38:39]
	v_cndmask_b32_e32 v17, 0, v179, vcc
	v_sub_f32_e32 v16, v16, v17
	v_sub_f32_e32 v15, v15, v16
	v_add_f32_e32 v16, 1.0, v20
	v_cmp_gt_f32_e32 vcc, s96, v16
	v_mul_f32_e64 v20, |v19|, s19
	v_exp_f32_e32 v20, v20
	v_cndmask_b32_e64 v17, 0, 32, vcc
	v_ldexp_f32 v16, v16, v17
	v_log_f32_e32 v16, v16
	v_max_f32_e32 v17, v18, v18
	v_min_f32_e32 v17, 0, v17
	v_fmamk_f32 v15, v15, 0x3d800000, v14
	v_mul_f32_e32 v18, 0x3f317217, v16
	v_fma_f32 v18, v16, s97, -v18
	v_fmac_f32_e32 v18, 0x3377d1cf, v16
	v_fmac_f32_e32 v18, 0x3f317217, v16
	v_cmp_lt_f32_e64 s[38:39], |v16|, s15
	s_nop 1
	v_cndmask_b32_e64 v16, v16, v18, s[38:39]
	v_cndmask_b32_e32 v18, 0, v179, vcc
	v_sub_f32_e32 v16, v16, v18
	v_add_f32_e32 v18, 1.0, v20
	v_cmp_gt_f32_e32 vcc, s96, v18
	v_sub_f32_e32 v16, v17, v16
	v_max_f32_e32 v17, v19, v19
	v_cndmask_b32_e64 v20, 0, 32, vcc
	v_ldexp_f32 v18, v18, v20
	v_log_f32_e32 v18, v18
	ds_read_u16 v20, v0 offset:8448
	ds_read_u16 v21, v0 offset:8976
	ds_read_u16 v22, v0 offset:9504
	ds_read_u16 v23, v0 offset:10032
	ds_read_u16 v24, v0 offset:10560
	ds_read_u16 v25, v0 offset:11088
	ds_read_u16 v26, v0 offset:11616
	ds_read_u16 v27, v0 offset:12144
	s_waitcnt lgkmcnt(0)
	v_lshlrev_b32_e32 v20, 16, v20
	v_mul_f32_e64 v28, |v20|, s19
	v_mul_f32_e32 v19, 0x3f317217, v18
	v_fma_f32 v19, v18, s97, -v19
	v_fmac_f32_e32 v19, 0x3377d1cf, v18
	v_exp_f32_e32 v28, v28
	v_fmac_f32_e32 v19, 0x3f317217, v18
	v_cmp_lt_f32_e64 s[38:39], |v18|, s15
	v_min_f32_e32 v17, 0, v17
	v_lshlrev_b32_e32 v21, 16, v21
	v_cndmask_b32_e64 v18, v18, v19, s[38:39]
	v_cndmask_b32_e32 v19, 0, v179, vcc
	v_sub_f32_e32 v18, v18, v19
	v_sub_f32_e32 v17, v17, v18
	v_add_f32_e32 v18, 1.0, v28
	v_cmp_gt_f32_e32 vcc, s96, v18
	v_mul_f32_e64 v28, |v21|, s19
	v_exp_f32_e32 v28, v28
	v_cndmask_b32_e64 v19, 0, 32, vcc
	v_ldexp_f32 v18, v18, v19
	v_log_f32_e32 v18, v18
	v_max_f32_e32 v19, v20, v20
	v_min_f32_e32 v19, 0, v19
	v_lshlrev_b32_e32 v22, 16, v22
	v_mul_f32_e32 v20, 0x3f317217, v18
	v_fma_f32 v20, v18, s97, -v20
	v_fmac_f32_e32 v20, 0x3377d1cf, v18
	v_fmac_f32_e32 v20, 0x3f317217, v18
	v_cmp_lt_f32_e64 s[38:39], |v18|, s15
	v_lshlrev_b32_e32 v23, 16, v23
	v_lshlrev_b32_e32 v24, 16, v24
	v_cndmask_b32_e64 v18, v18, v20, s[38:39]
	v_cndmask_b32_e32 v20, 0, v179, vcc
	v_sub_f32_e32 v18, v18, v20
	v_add_f32_e32 v20, 1.0, v28
	v_cmp_gt_f32_e32 vcc, s96, v20
	v_sub_f32_e32 v18, v19, v18
	v_max_f32_e32 v19, v21, v21
	v_cndmask_b32_e64 v28, 0, 32, vcc
	v_ldexp_f32 v20, v20, v28
	v_log_f32_e32 v20, v20
	v_mul_f32_e64 v28, |v22|, s19
	v_exp_f32_e32 v28, v28
	v_min_f32_e32 v19, 0, v19
	v_mul_f32_e32 v21, 0x3f317217, v20
	v_fma_f32 v21, v20, s97, -v21
	v_fmac_f32_e32 v21, 0x3377d1cf, v20
	v_fmac_f32_e32 v21, 0x3f317217, v20
	v_cmp_lt_f32_e64 s[38:39], |v20|, s15
	v_lshlrev_b32_e32 v25, 16, v25
	v_lshlrev_b32_e32 v26, 16, v26
	v_cndmask_b32_e64 v20, v20, v21, s[38:39]
	v_cndmask_b32_e32 v21, 0, v179, vcc
	v_sub_f32_e32 v20, v20, v21
	v_sub_f32_e32 v19, v19, v20
	v_add_f32_e32 v20, 1.0, v28
	v_cmp_gt_f32_e32 vcc, s96, v20
	v_mul_f32_e64 v28, |v23|, s19
	v_exp_f32_e32 v28, v28
	v_cndmask_b32_e64 v21, 0, 32, vcc
	v_ldexp_f32 v20, v20, v21
	v_log_f32_e32 v20, v20
	v_max_f32_e32 v21, v22, v22
	v_min_f32_e32 v21, 0, v21
	v_lshlrev_b32_e32 v27, 16, v27
	v_mul_f32_e32 v22, 0x3f317217, v20
	v_fma_f32 v22, v20, s97, -v22
	v_fmac_f32_e32 v22, 0x3377d1cf, v20
	v_fmac_f32_e32 v22, 0x3f317217, v20
	v_cmp_lt_f32_e64 s[38:39], |v20|, s15
	v_fmamk_f32 v16, v16, 0x3d800000, v15
	v_fmamk_f32 v17, v17, 0x3d800000, v16
	v_cndmask_b32_e64 v20, v20, v22, s[38:39]
	v_cndmask_b32_e32 v22, 0, v179, vcc
	v_sub_f32_e32 v20, v20, v22
	v_add_f32_e32 v22, 1.0, v28
	v_cmp_gt_f32_e32 vcc, s96, v22
	v_sub_f32_e32 v20, v21, v20
	v_max_f32_e32 v21, v23, v23
	v_cndmask_b32_e64 v28, 0, 32, vcc
	v_ldexp_f32 v22, v22, v28
	v_log_f32_e32 v22, v22
	v_mul_f32_e64 v28, |v24|, s19
	v_exp_f32_e32 v28, v28
	v_min_f32_e32 v21, 0, v21
	v_mul_f32_e32 v23, 0x3f317217, v22
	v_fma_f32 v23, v22, s97, -v23
	v_fmac_f32_e32 v23, 0x3377d1cf, v22
	v_fmac_f32_e32 v23, 0x3f317217, v22
	v_cmp_lt_f32_e64 s[38:39], |v22|, s15
	v_fmamk_f32 v18, v18, 0x3d800000, v17
	v_fmamk_f32 v19, v19, 0x3d800000, v18
	v_cndmask_b32_e64 v22, v22, v23, s[38:39]
	v_cndmask_b32_e32 v23, 0, v179, vcc
	v_sub_f32_e32 v22, v22, v23
	v_sub_f32_e32 v21, v21, v22
	v_add_f32_e32 v22, 1.0, v28
	v_cmp_gt_f32_e32 vcc, s96, v22
	v_mul_f32_e64 v28, |v25|, s19
	v_exp_f32_e32 v28, v28
	v_cndmask_b32_e64 v23, 0, 32, vcc
	v_ldexp_f32 v22, v22, v23
	v_log_f32_e32 v22, v22
	v_max_f32_e32 v23, v24, v24
	v_min_f32_e32 v23, 0, v23
	v_fmamk_f32 v20, v20, 0x3d800000, v19
	v_mul_f32_e32 v24, 0x3f317217, v22
	v_fma_f32 v24, v22, s97, -v24
	v_fmac_f32_e32 v24, 0x3377d1cf, v22
	v_fmac_f32_e32 v24, 0x3f317217, v22
	v_cmp_lt_f32_e64 s[38:39], |v22|, s15
	v_fmamk_f32 v21, v21, 0x3d800000, v20
	s_nop 0
	v_cndmask_b32_e64 v22, v22, v24, s[38:39]
	v_cndmask_b32_e32 v24, 0, v179, vcc
	v_sub_f32_e32 v22, v22, v24
	v_add_f32_e32 v24, 1.0, v28
	v_cmp_gt_f32_e32 vcc, s96, v24
	v_sub_f32_e32 v22, v23, v22
	v_max_f32_e32 v23, v25, v25
	v_cndmask_b32_e64 v28, 0, 32, vcc
	v_ldexp_f32 v24, v24, v28
	v_log_f32_e32 v24, v24
	v_mul_f32_e64 v28, |v26|, s19
	v_exp_f32_e32 v28, v28
	v_min_f32_e32 v23, 0, v23
	v_mul_f32_e32 v25, 0x3f317217, v24
	v_fma_f32 v25, v24, s97, -v25
	v_fmac_f32_e32 v25, 0x3377d1cf, v24
	v_fmac_f32_e32 v25, 0x3f317217, v24
	v_cmp_lt_f32_e64 s[38:39], |v24|, s15
	v_fmamk_f32 v22, v22, 0x3d800000, v21
	s_nop 0
	v_cndmask_b32_e64 v24, v24, v25, s[38:39]
	v_cndmask_b32_e32 v25, 0, v179, vcc
	v_sub_f32_e32 v24, v24, v25
	v_sub_f32_e32 v23, v23, v24
	v_add_f32_e32 v24, 1.0, v28
	v_cmp_gt_f32_e32 vcc, s96, v24
	v_mul_f32_e64 v28, |v27|, s19
	v_exp_f32_e32 v28, v28
	v_cndmask_b32_e64 v25, 0, 32, vcc
	v_ldexp_f32 v24, v24, v25
	v_log_f32_e32 v24, v24
	v_max_f32_e32 v25, v26, v26
	v_min_f32_e32 v25, 0, v25
	v_fmamk_f32 v23, v23, 0x3d800000, v22
	v_mul_f32_e32 v26, 0x3f317217, v24
	v_fma_f32 v26, v24, s97, -v26
	v_fmac_f32_e32 v26, 0x3377d1cf, v24
	v_fmac_f32_e32 v26, 0x3f317217, v24
	v_cmp_lt_f32_e64 s[38:39], |v24|, s15
	s_nop 1
	v_cndmask_b32_e64 v24, v24, v26, s[38:39]
	v_cndmask_b32_e32 v26, 0, v179, vcc
	v_sub_f32_e32 v24, v24, v26
	v_add_f32_e32 v26, 1.0, v28
	v_cmp_gt_f32_e32 vcc, s96, v26
	v_sub_f32_e32 v24, v25, v24
	v_max_f32_e32 v25, v27, v27
	v_cndmask_b32_e64 v28, 0, 32, vcc
	v_ldexp_f32 v26, v26, v28
	v_log_f32_e32 v26, v26
	ds_read_u16 v28, v0 offset:12672
	ds_read_u16 v29, v0 offset:13200
	ds_read_u16 v30, v0 offset:13728
	ds_read_u16 v31, v0 offset:14256
	ds_read_u16 v32, v0 offset:14784
	ds_read_u16 v33, v0 offset:15312
	ds_read_u16 v37, v0 offset:15840
	ds_read_u16 v0, v0 offset:16368
	s_waitcnt lgkmcnt(0)
	v_lshlrev_b32_e32 v28, 16, v28
	v_mul_f32_e64 v108, |v28|, s19
	v_mul_f32_e32 v27, 0x3f317217, v26
	v_fma_f32 v27, v26, s97, -v27
	v_fmac_f32_e32 v27, 0x3377d1cf, v26
	v_exp_f32_e32 v108, v108
	v_fmac_f32_e32 v27, 0x3f317217, v26
	v_cmp_lt_f32_e64 s[38:39], |v26|, s15
	v_min_f32_e32 v25, 0, v25
	v_lshlrev_b32_e32 v29, 16, v29
	v_cndmask_b32_e64 v26, v26, v27, s[38:39]
	v_cndmask_b32_e32 v27, 0, v179, vcc
	v_sub_f32_e32 v26, v26, v27
	v_sub_f32_e32 v25, v25, v26
	v_add_f32_e32 v26, 1.0, v108
	v_cmp_gt_f32_e32 vcc, s96, v26
	v_mul_f32_e64 v108, |v29|, s19
	v_exp_f32_e32 v108, v108
	v_cndmask_b32_e64 v27, 0, 32, vcc
	v_ldexp_f32 v26, v26, v27
	v_log_f32_e32 v26, v26
	v_max_f32_e32 v27, v28, v28
	v_min_f32_e32 v27, 0, v27
	v_lshlrev_b32_e32 v30, 16, v30
	v_mul_f32_e32 v28, 0x3f317217, v26
	v_fma_f32 v28, v26, s97, -v28
	v_fmac_f32_e32 v28, 0x3377d1cf, v26
	v_fmac_f32_e32 v28, 0x3f317217, v26
	v_cmp_lt_f32_e64 s[38:39], |v26|, s15
	v_lshlrev_b32_e32 v31, 16, v31
	v_lshlrev_b32_e32 v32, 16, v32
	v_cndmask_b32_e64 v26, v26, v28, s[38:39]
	v_cndmask_b32_e32 v28, 0, v179, vcc
	v_sub_f32_e32 v26, v26, v28
	v_add_f32_e32 v28, 1.0, v108
	v_cmp_gt_f32_e32 vcc, s96, v28
	v_sub_f32_e32 v26, v27, v26
	v_max_f32_e32 v27, v29, v29
	v_cndmask_b32_e64 v108, 0, 32, vcc
	v_ldexp_f32 v28, v28, v108
	v_log_f32_e32 v28, v28
	v_mul_f32_e64 v108, |v30|, s19
	v_exp_f32_e32 v108, v108
	v_min_f32_e32 v27, 0, v27
	v_mul_f32_e32 v29, 0x3f317217, v28
	v_fma_f32 v29, v28, s97, -v29
	v_fmac_f32_e32 v29, 0x3377d1cf, v28
	v_fmac_f32_e32 v29, 0x3f317217, v28
	v_cmp_lt_f32_e64 s[38:39], |v28|, s15
	v_lshlrev_b32_e32 v33, 16, v33
	v_lshlrev_b32_e32 v37, 16, v37
	v_cndmask_b32_e64 v28, v28, v29, s[38:39]
	v_cndmask_b32_e32 v29, 0, v179, vcc
	v_sub_f32_e32 v28, v28, v29
	v_sub_f32_e32 v27, v27, v28
	v_add_f32_e32 v28, 1.0, v108
	v_cmp_gt_f32_e32 vcc, s96, v28
	v_mul_f32_e64 v108, |v31|, s19
	v_exp_f32_e32 v108, v108
	v_cndmask_b32_e64 v29, 0, 32, vcc
	v_ldexp_f32 v28, v28, v29
	v_log_f32_e32 v28, v28
	v_max_f32_e32 v29, v30, v30
	v_min_f32_e32 v29, 0, v29
	v_lshlrev_b32_e32 v0, 16, v0
	v_mul_f32_e32 v30, 0x3f317217, v28
	v_fma_f32 v30, v28, s97, -v30
	v_fmac_f32_e32 v30, 0x3377d1cf, v28
	v_fmac_f32_e32 v30, 0x3f317217, v28
	v_cmp_lt_f32_e64 s[38:39], |v28|, s15
	v_fmamk_f32 v24, v24, 0x3d800000, v23
	v_fmamk_f32 v25, v25, 0x3d800000, v24
	v_cndmask_b32_e64 v28, v28, v30, s[38:39]
	v_cndmask_b32_e32 v30, 0, v179, vcc
	v_sub_f32_e32 v28, v28, v30
	v_add_f32_e32 v30, 1.0, v108
	v_cmp_gt_f32_e32 vcc, s96, v30
	v_sub_f32_e32 v28, v29, v28
	v_max_f32_e32 v29, v31, v31
	v_cndmask_b32_e64 v108, 0, 32, vcc
	v_ldexp_f32 v30, v30, v108
	v_log_f32_e32 v30, v30
	v_mul_f32_e64 v108, |v32|, s19
	v_exp_f32_e32 v108, v108
	v_min_f32_e32 v29, 0, v29
	v_mul_f32_e32 v31, 0x3f317217, v30
	v_fma_f32 v31, v30, s97, -v31
	v_fmac_f32_e32 v31, 0x3377d1cf, v30
	v_fmac_f32_e32 v31, 0x3f317217, v30
	v_cmp_lt_f32_e64 s[38:39], |v30|, s15
	v_fmamk_f32 v26, v26, 0x3d800000, v25
	v_fmamk_f32 v27, v27, 0x3d800000, v26
	v_cndmask_b32_e64 v30, v30, v31, s[38:39]
	v_cndmask_b32_e32 v31, 0, v179, vcc
	v_sub_f32_e32 v30, v30, v31
	v_sub_f32_e32 v29, v29, v30
	v_add_f32_e32 v30, 1.0, v108
	v_cmp_gt_f32_e32 vcc, s96, v30
	v_mul_f32_e64 v108, |v33|, s19
	v_exp_f32_e32 v108, v108
	v_cndmask_b32_e64 v31, 0, 32, vcc
	v_ldexp_f32 v30, v30, v31
	v_log_f32_e32 v30, v30
	v_max_f32_e32 v31, v32, v32
	v_min_f32_e32 v31, 0, v31
	v_fmamk_f32 v28, v28, 0x3d800000, v27
	v_mul_f32_e32 v32, 0x3f317217, v30
	v_fma_f32 v32, v30, s97, -v32
	v_fmac_f32_e32 v32, 0x3377d1cf, v30
	v_fmac_f32_e32 v32, 0x3f317217, v30
	v_cmp_lt_f32_e64 s[38:39], |v30|, s15
	v_fmamk_f32 v29, v29, 0x3d800000, v28
	s_nop 0
	v_cndmask_b32_e64 v30, v30, v32, s[38:39]
	v_cndmask_b32_e32 v32, 0, v179, vcc
	v_sub_f32_e32 v30, v30, v32
	v_add_f32_e32 v32, 1.0, v108
	v_cmp_gt_f32_e32 vcc, s96, v32
	v_sub_f32_e32 v30, v31, v30
	v_max_f32_e32 v31, v33, v33
	v_cndmask_b32_e64 v108, 0, 32, vcc
	v_ldexp_f32 v32, v32, v108
	v_log_f32_e32 v32, v32
	v_mul_f32_e64 v108, |v37|, s19
	v_exp_f32_e32 v108, v108
	v_min_f32_e32 v31, 0, v31
	v_mul_f32_e32 v33, 0x3f317217, v32
	v_fma_f32 v33, v32, s97, -v33
	v_fmac_f32_e32 v33, 0x3377d1cf, v32
	v_fmac_f32_e32 v33, 0x3f317217, v32
	v_cmp_lt_f32_e64 s[38:39], |v32|, s15
	v_fmamk_f32 v30, v30, 0x3d800000, v29
	s_nop 0
	v_cndmask_b32_e64 v32, v32, v33, s[38:39]
	v_cndmask_b32_e32 v33, 0, v179, vcc
	v_sub_f32_e32 v32, v32, v33
	v_sub_f32_e32 v31, v31, v32
	v_add_f32_e32 v32, 1.0, v108
	v_cmp_gt_f32_e32 vcc, s96, v32
	v_mul_f32_e64 v108, |v0|, s19
	v_exp_f32_e32 v108, v108
	v_cndmask_b32_e64 v33, 0, 32, vcc
	v_ldexp_f32 v32, v32, v33
	v_log_f32_e32 v32, v32
	v_max_f32_e32 v33, v37, v37
	v_min_f32_e32 v33, 0, v33
	v_max_f32_e32 v0, v0, v0
	v_mul_f32_e32 v37, 0x3f317217, v32
	v_fma_f32 v37, v32, s97, -v37
	v_fmac_f32_e32 v37, 0x3377d1cf, v32
	v_fmac_f32_e32 v37, 0x3f317217, v32
	v_cmp_lt_f32_e64 s[38:39], |v32|, s15
	v_fmamk_f32 v31, v31, 0x3d800000, v30
	v_min_f32_e32 v0, 0, v0
	v_cndmask_b32_e64 v32, v32, v37, s[38:39]
	v_cndmask_b32_e32 v37, 0, v179, vcc
	v_sub_f32_e32 v32, v32, v37
	v_add_f32_e32 v37, 1.0, v108
	v_cmp_gt_f32_e32 vcc, s96, v37
	v_sub_f32_e32 v32, v33, v32
	v_fmamk_f32 v32, v32, 0x3d800000, v31
	v_cndmask_b32_e64 v108, 0, 32, vcc
	v_ldexp_f32 v37, v37, v108
	v_log_f32_e32 v37, v37
	s_nop 0
	v_mul_f32_e32 v33, 0x3f317217, v37
	v_fma_f32 v33, v37, s97, -v33
	v_fmac_f32_e32 v33, 0x3377d1cf, v37
	v_fmac_f32_e32 v33, 0x3f317217, v37
	v_cmp_lt_f32_e64 s[38:39], |v37|, s15
	s_nop 1
	v_cndmask_b32_e64 v33, v37, v33, s[38:39]
	v_cndmask_b32_e32 v37, 0, v179, vcc
	v_sub_f32_e32 v33, v33, v37
	v_sub_f32_e32 v0, v0, v33
	v_fmamk_f32 v33, v0, 0x3d800000, v32
	v_lshl_add_u32 v0, v49, 2, v36
	v_lshl_add_u32 v36, v53, 10, v0
	ds_write_b32 v36, v33
	s_waitcnt lgkmcnt(0)
	s_barrier
	ds_read2st64_b32 v[36:37], v0 offset1:4
	v_cmp_gt_u32_e32 vcc, s2, v40
	s_movk_i32 s2, 0xff
	v_cmp_lt_u32_e64 s[38:39], s2, v40
	s_and_saveexec_b64 s[2:3], s[38:39]
	s_cbranch_execz .LBB0_109
	s_waitcnt lgkmcnt(0)
	v_pk_add_f32 v[2:3], v[2:3], v[36:37] op_sel_hi:[1,0]
	v_pk_add_f32 v[4:5], v[4:5], v[36:37] op_sel_hi:[1,0]
	v_pk_add_f32 v[6:7], v[6:7], v[36:37] op_sel_hi:[1,0]
	v_pk_add_f32 v[8:9], v[8:9], v[36:37] op_sel_hi:[1,0]
	v_pk_add_f32 v[10:11], v[10:11], v[36:37] op_sel_hi:[1,0]
	v_pk_add_f32 v[12:13], v[12:13], v[36:37] op_sel_hi:[1,0]
	v_pk_add_f32 v[14:15], v[14:15], v[36:37] op_sel_hi:[1,0]
	v_pk_add_f32 v[16:17], v[16:17], v[36:37] op_sel_hi:[1,0]
	v_pk_add_f32 v[18:19], v[18:19], v[36:37] op_sel_hi:[1,0]
	v_pk_add_f32 v[20:21], v[20:21], v[36:37] op_sel_hi:[1,0]
	v_pk_add_f32 v[22:23], v[22:23], v[36:37] op_sel_hi:[1,0]
	v_pk_add_f32 v[24:25], v[24:25], v[36:37] op_sel_hi:[1,0]
	v_pk_add_f32 v[26:27], v[26:27], v[36:37] op_sel_hi:[1,0]
	v_pk_add_f32 v[28:29], v[36:37], v[28:29] op_sel_hi:[0,1]
	v_pk_add_f32 v[30:31], v[36:37], v[30:31] op_sel_hi:[0,1]
	v_pk_add_f32 v[32:33], v[36:37], v[32:33] op_sel_hi:[0,1]
.LBB0_109:
	s_or_b64 exec, exec, s[2:3]
	s_waitcnt lgkmcnt(0)
	v_add_f32_e32 v0, v36, v37
	v_sub_f32_e32 v2, v0, v2
	v_sub_f32_e32 v3, v0, v3
	v_mul_f32_e32 v2, 0x3fb8aa3b, v2
	v_mul_f32_e32 v3, 0x3fb8aa3b, v3
	v_sub_f32_e32 v4, v0, v4
	v_sub_f32_e32 v5, v0, v5
	v_exp_f32_e32 v2, v2
	v_exp_f32_e32 v3, v3
	v_mul_f32_e32 v4, 0x3fb8aa3b, v4
	v_mul_f32_e32 v5, 0x3fb8aa3b, v5
	v_sub_f32_e32 v6, v0, v6
	v_sub_f32_e32 v7, v0, v7
	v_exp_f32_e32 v4, v4
	v_exp_f32_e32 v5, v5
	v_mul_f32_e32 v6, 0x3fb8aa3b, v6
	v_mul_f32_e32 v7, 0x3fb8aa3b, v7
	v_sub_f32_e32 v8, v0, v8
	v_sub_f32_e32 v9, v0, v9
	v_lshlrev_b32_e32 v36, 6, v53
	v_exp_f32_e32 v6, v6
	v_exp_f32_e32 v7, v7
	v_mul_f32_e32 v8, 0x3fb8aa3b, v8
	v_mul_f32_e32 v9, 0x3fb8aa3b, v9
	v_mad_u32_u24 v49, v49, s89, v36
	v_lshlrev_b32_e32 v37, 16, v76
	v_lshlrev_b32_e32 v36, 16, v74
	v_exp_f32_e32 v8, v8
	v_exp_f32_e32 v9, v9
	v_pk_mul_f32 v[2:3], v[2:3], v[36:37]
	v_lshlrev_b32_e32 v37, 16, v68
	v_lshlrev_b32_e32 v36, 16, v66
	v_pk_mul_f32 v[4:5], v[4:5], v[36:37]
	v_lshlrev_b32_e32 v37, 16, v73
	v_lshlrev_b32_e32 v36, 16, v70
	v_pk_mul_f32 v[6:7], v[6:7], v[36:37]
	v_lshlrev_b32_e32 v37, 16, v65
	v_lshlrev_b32_e32 v36, 16, v62
	v_pk_mul_f32 v[8:9], v[8:9], v[36:37]
	v_lshlrev_b32_e32 v53, 16, v75
	v_lshlrev_b32_e32 v71, 16, v71
	v_lshlrev_b32_e32 v67, 16, v67
	v_lshlrev_b32_e32 v63, 16, v63
	v_lshlrev_b32_e32 v66, 16, v72
	v_lshlrev_b32_e32 v68, 16, v69
	v_lshlrev_b32_e32 v64, 16, v64
	v_lshlrev_b32_e32 v36, 16, v61
	v_cvt_pk_bf16_f32 v2, v2, v3
	v_cvt_pk_bf16_f32 v3, v4, v5
	v_cvt_pk_bf16_f32 v4, v6, v7
	v_cvt_pk_bf16_f32 v5, v8, v9
	v_add_u32_e32 v37, v38, v49
	ds_write_b128 v37, v[2:5]
	v_cvt_pk_bf16_f32 v2, v53, v71
	v_cvt_pk_bf16_f32 v3, v67, v63
	v_cvt_pk_bf16_f32 v4, v66, v68
	v_cvt_pk_bf16_f32 v5, v64, v36
	v_add_u32_e32 v36, v39, v49
	ds_write_b128 v36, v[2:5]
	v_sub_f32_e32 v2, v0, v10
	v_sub_f32_e32 v3, v0, v11
	v_mul_f32_e32 v2, 0x3fb8aa3b, v2
	v_mul_f32_e32 v3, 0x3fb8aa3b, v3
	v_exp_f32_e32 v2, v2
	v_exp_f32_e32 v3, v3
	v_lshlrev_b32_e32 v5, 16, v60
	v_lshlrev_b32_e32 v4, 16, v58
	v_lshlrev_b32_e32 v7, 16, v51
	v_pk_mul_f32 v[2:3], v[2:3], v[4:5]
	v_sub_f32_e32 v4, v0, v12
	v_sub_f32_e32 v5, v0, v13
	v_mul_f32_e32 v4, 0x3fb8aa3b, v4
	v_mul_f32_e32 v5, 0x3fb8aa3b, v5
	v_exp_f32_e32 v4, v4
	v_exp_f32_e32 v5, v5
	v_lshlrev_b32_e32 v6, 16, v48
	v_lshlrev_b32_e32 v9, 16, v57
	v_lshlrev_b32_e32 v8, 16, v54
	v_pk_mul_f32 v[4:5], v[4:5], v[6:7]
	v_sub_f32_e32 v6, v0, v14
	v_sub_f32_e32 v7, v0, v15
	v_mul_f32_e32 v6, 0x3fb8aa3b, v6
	v_mul_f32_e32 v7, 0x3fb8aa3b, v7
	v_exp_f32_e32 v6, v6
	v_exp_f32_e32 v7, v7
	v_lshlrev_b32_e32 v11, 16, v47
	v_lshlrev_b32_e32 v10, 16, v44
	v_lshlrev_b32_e32 v49, 16, v59
	v_pk_mul_f32 v[6:7], v[6:7], v[8:9]
	v_sub_f32_e32 v8, v0, v16
	v_sub_f32_e32 v9, v0, v17
	v_mul_f32_e32 v8, 0x3fb8aa3b, v8
	v_mul_f32_e32 v9, 0x3fb8aa3b, v9
	v_exp_f32_e32 v8, v8
	v_exp_f32_e32 v9, v9
	v_lshlrev_b32_e32 v53, 16, v55
	v_lshlrev_b32_e32 v12, 16, v50
	v_lshlrev_b32_e32 v13, 16, v45
	v_pk_mul_f32 v[8:9], v[8:9], v[10:11]
	v_lshlrev_b32_e32 v14, 16, v56
	v_lshlrev_b32_e32 v15, 16, v52
	v_lshlrev_b32_e32 v16, 16, v46
	v_lshlrev_b32_e32 v10, 16, v43
	v_cvt_pk_bf16_f32 v2, v2, v3
	v_cvt_pk_bf16_f32 v3, v4, v5
	v_cvt_pk_bf16_f32 v4, v6, v7
	v_cvt_pk_bf16_f32 v5, v8, v9
	ds_write_b128 v37, v[2:5] offset:16
	v_cvt_pk_bf16_f32 v2, v49, v53
	v_cvt_pk_bf16_f32 v3, v12, v13
	v_cvt_pk_bf16_f32 v4, v14, v15
	v_cvt_pk_bf16_f32 v5, v16, v10
	ds_write_b128 v36, v[2:5] offset:16
	v_sub_f32_e32 v2, v0, v18
	v_sub_f32_e32 v3, v0, v19
	v_mul_f32_e32 v2, 0x3fb8aa3b, v2
	v_mul_f32_e32 v3, 0x3fb8aa3b, v3
	v_exp_f32_e32 v2, v2
	v_exp_f32_e32 v3, v3
	v_lshlrev_b32_e32 v5, 16, v105
	v_lshlrev_b32_e32 v4, 16, v102
	v_lshlrev_b32_e32 v7, 16, v97
	v_pk_mul_f32 v[2:3], v[2:3], v[4:5]
	v_sub_f32_e32 v4, v0, v20
	v_sub_f32_e32 v5, v0, v21
	v_mul_f32_e32 v4, 0x3fb8aa3b, v4
	v_mul_f32_e32 v5, 0x3fb8aa3b, v5
	v_exp_f32_e32 v4, v4
	v_exp_f32_e32 v5, v5
	v_lshlrev_b32_e32 v6, 16, v94
	v_lshlrev_b32_e32 v9, 16, v107
	v_lshlrev_b32_e32 v8, 16, v103
	v_pk_mul_f32 v[4:5], v[4:5], v[6:7]
	v_sub_f32_e32 v6, v0, v22
	v_sub_f32_e32 v7, v0, v23
	v_mul_f32_e32 v6, 0x3fb8aa3b, v6
	v_mul_f32_e32 v7, 0x3fb8aa3b, v7
	v_exp_f32_e32 v6, v6
	v_exp_f32_e32 v7, v7
	v_lshlrev_b32_e32 v11, 16, v99
	v_lshlrev_b32_e32 v10, 16, v95
	v_lshlrev_b32_e32 v12, 16, v104
	v_pk_mul_f32 v[6:7], v[6:7], v[8:9]
	v_sub_f32_e32 v8, v0, v24
	v_sub_f32_e32 v9, v0, v25
	v_mul_f32_e32 v8, 0x3fb8aa3b, v8
	v_mul_f32_e32 v9, 0x3fb8aa3b, v9
	v_exp_f32_e32 v8, v8
	v_exp_f32_e32 v9, v9
	v_lshlrev_b32_e32 v13, 16, v100
	v_lshlrev_b32_e32 v14, 16, v96
	v_lshlrev_b32_e32 v15, 16, v92
	v_pk_mul_f32 v[8:9], v[8:9], v[10:11]
	v_lshlrev_b32_e32 v16, 16, v106
	v_lshlrev_b32_e32 v17, 16, v101
	v_lshlrev_b32_e32 v18, 16, v98
	v_lshlrev_b32_e32 v10, 16, v93
	v_cvt_pk_bf16_f32 v2, v2, v3
	v_cvt_pk_bf16_f32 v3, v4, v5
	v_cvt_pk_bf16_f32 v4, v6, v7
	v_cvt_pk_bf16_f32 v5, v8, v9
	ds_write_b128 v37, v[2:5] offset:32
	v_cvt_pk_bf16_f32 v2, v12, v13
	v_cvt_pk_bf16_f32 v3, v14, v15
	v_cvt_pk_bf16_f32 v4, v16, v17
	v_cvt_pk_bf16_f32 v5, v18, v10
	ds_write_b128 v36, v[2:5] offset:32
	v_sub_f32_e32 v2, v0, v26
	v_sub_f32_e32 v3, v0, v27
	v_mul_f32_e32 v2, 0x3fb8aa3b, v2
	v_mul_f32_e32 v3, 0x3fb8aa3b, v3
	v_exp_f32_e32 v2, v2
	v_exp_f32_e32 v3, v3
	v_lshlrev_b32_e32 v5, 16, v91
	v_lshlrev_b32_e32 v4, 16, v89
	v_lshlrev_b32_e32 v7, 16, v84
	v_pk_mul_f32 v[2:3], v[2:3], v[4:5]
	v_sub_f32_e32 v4, v0, v28
	v_sub_f32_e32 v5, v0, v29
	v_mul_f32_e32 v4, 0x3fb8aa3b, v4
	v_mul_f32_e32 v5, 0x3fb8aa3b, v5
	v_exp_f32_e32 v4, v4
	v_exp_f32_e32 v5, v5
	v_lshlrev_b32_e32 v6, 16, v81
	s_waitcnt vmcnt(0)
	v_lshlrev_b32_e32 v9, 16, v87
	v_lshlrev_b32_e32 v8, 16, v85
	v_pk_mul_f32 v[4:5], v[4:5], v[6:7]
	v_sub_f32_e32 v6, v0, v30
	v_sub_f32_e32 v7, v0, v31
	v_mul_f32_e32 v6, 0x3fb8aa3b, v6
	v_mul_f32_e32 v7, 0x3fb8aa3b, v7
	v_exp_f32_e32 v6, v6
	v_exp_f32_e32 v7, v7
	v_lshlrev_b32_e32 v11, 16, v79
	v_lshlrev_b32_e32 v10, 16, v77
	v_lshlrev_b32_e32 v12, 16, v90
	v_pk_mul_f32 v[6:7], v[6:7], v[8:9]
	v_sub_f32_e32 v8, v0, v32
	v_sub_f32_e32 v9, v0, v33
	v_mul_f32_e32 v8, 0x3fb8aa3b, v8
	v_mul_f32_e32 v9, 0x3fb8aa3b, v9
	v_exp_f32_e32 v8, v8
	v_exp_f32_e32 v9, v9
	v_lshlrev_b32_e32 v13, 16, v88
	v_lshlrev_b32_e32 v14, 16, v83
	v_lshlrev_b32_e32 v15, 16, v80
	v_pk_mul_f32 v[8:9], v[8:9], v[10:11]
	v_lshlrev_b32_e32 v16, 16, v86
	v_lshlrev_b32_e32 v17, 16, v82
	v_lshlrev_b32_e32 v18, 16, v78
	v_lshlrev_b32_e32 v10, 16, v35
	v_cvt_pk_bf16_f32 v2, v2, v3
	v_cvt_pk_bf16_f32 v3, v4, v5
	v_cvt_pk_bf16_f32 v4, v6, v7
	v_cvt_pk_bf16_f32 v5, v8, v9
	ds_write_b128 v37, v[2:5] offset:48
	v_cvt_pk_bf16_f32 v2, v12, v13
	v_cvt_pk_bf16_f32 v3, v14, v15
	v_cvt_pk_bf16_f32 v4, v16, v17
	v_cvt_pk_bf16_f32 v5, v18, v10
	ds_write_b128 v36, v[2:5] offset:48
	s_and_saveexec_b64 s[2:3], vcc
	s_cbranch_execz .LBB0_68
	v_mul_f32_e32 v0, 0x3fb8aa3b, v0
	v_exp_f32_e32 v5, v0
	v_lshrrev_b32_e32 v0, 6, v40
	v_add_u32_e32 v2, s34, v0
	v_ashrrev_i32_e32 v3, 31, v2
	v_readlane_b32 s6, v255, 20
	v_and_b32_e32 v4, 63, v40
	v_lshlrev_b64 v[2:3], 8, v[2:3]
	v_readlane_b32 s7, v255, 21
	v_lshlrev_b32_e32 v0, 2, v4
	s_nop 0
	v_lshl_add_u64 v[2:3], s[6:7], 0, v[2:3]
	v_lshl_add_u64 v[2:3], v[2:3], 0, v[0:1]
	global_store_dword v[2:3], v5, off
	s_branch .LBB0_68

.LBB0_118:
	v_lshl_add_u64 v[2:3], s[72:73], 0, v[22:23]
	v_lshl_add_u64 v[4:5], s[72:73], 0, v[20:21]
	v_lshl_add_u64 v[26:27], s[72:73], 0, v[18:19]
	global_load_dwordx2 v[2:3], v[2:3], off
	s_add_i32 s3, s11, s2
	global_load_dwordx2 v[4:5], v[4:5], off
	s_add_i32 s80, s3, 0xf8804b00
	global_load_dwordx2 v[38:39], v[26:27], off
	v_lshl_add_u64 v[26:27], s[72:73], 0, v[16:17]
	global_load_dwordx2 v[40:41], v[26:27], off
	v_lshl_add_u64 v[26:27], s[72:73], 0, v[14:15]
	global_load_dwordx2 v[42:43], v[26:27], off
	v_lshl_add_u64 v[26:27], s[80:81], 1, v[8:9]
	s_add_i32 s80, s3, 0xf8805a00
	global_load_dwordx2 v[44:45], v[26:27], off offset:3072
	v_lshl_add_u64 v[26:27], s[80:81], 1, v[8:9]
	s_add_i32 s80, s3, 0xf8806900
	global_load_dwordx2 v[46:47], v[26:27], off offset:3072
	v_lshl_add_u64 v[26:27], s[80:81], 1, v[8:9]
	global_load_dwordx2 v[48:49], v[26:27], off offset:3072
	v_lshl_add_u64 v[50:51], s[72:73], 0, v[12:13]
	s_mov_b32 s3, 0x18600000
	s_and_saveexec_b64 s[50:51], s[38:39]
	v_lshl_add_u64 v[56:57], s[26:27], 0, v[0:1]
	v_add_co_u32_e32 v56, vcc, v56, v24
	s_nop 1
	v_addc_co_u32_e32 v57, vcc, 0, v57, vcc
	v_add_co_u32_e32 v56, vcc, 0x1000, v56
	s_nop 1
	v_addc_co_u32_e32 v57, vcc, 0, v57, vcc
	global_load_ushort v58, v[56:57], off offset:3104
	s_or_b64 exec, exec, s[50:51]
	s_waitcnt vmcnt(0) lgkmcnt(0)
	v_and_b32_e32 v25, 0xffff, v2
	v_lshrrev_b32_e32 v2, 16, v2
	v_and_or_b32 v30, v4, s33, v2
	v_lshl_or_b32 v26, v4, 16, v25
	v_lshrrev_b32_e32 v2, 16, v38
	v_and_b32_e32 v25, 0xffff, v38
	v_and_or_b32 v31, v40, s33, v2
	v_lshl_or_b32 v27, v40, 16, v25
	v_lshrrev_b32_e32 v2, 16, v42
	v_and_b32_e32 v25, 0xffff, v42
	v_add_co_u32_e32 v38, vcc, s3, v50
	v_and_or_b32 v32, v44, s33, v2
	v_lshl_or_b32 v28, v44, 16, v25
	v_lshrrev_b32_e32 v2, 16, v46
	v_and_b32_e32 v25, 0xffff, v46
	v_and_or_b32 v33, v48, s33, v2
	v_and_b32_e32 v2, 0xffff, v3
	v_lshl_or_b32 v34, v5, 16, v2
	v_and_b32_e32 v2, 0xffff, v39
	v_lshl_or_b32 v35, v41, 16, v2
	v_and_b32_e32 v2, 0xffff, v43
	v_lshl_or_b32 v36, v45, 16, v2
	v_and_b32_e32 v2, 0xffff, v47
	v_lshl_or_b32 v29, v48, 16, v25
	v_lshl_or_b32 v37, v49, 16, v2
	v_lshrrev_b32_e32 v2, 16, v3
	v_lshrrev_b32_e32 v3, 16, v39
	v_addc_co_u32_e32 v39, vcc, 0, v51, vcc
	s_mov_b32 s3, 0x18604000
	global_store_dwordx4 v[38:39], v[26:29], off
	v_and_or_b32 v2, v5, s33, v2
	v_lshrrev_b32_e32 v4, 16, v43
	v_add_co_u32_e32 v26, vcc, s3, v50
	v_lshrrev_b32_e32 v5, 16, v47
	s_nop 0
	v_addc_co_u32_e32 v27, vcc, 0, v51, vcc
	global_store_dwordx4 v[26:27], v[30:33], off
	v_add_co_u32_e32 v26, vcc, 0x18608000, v50
	v_and_or_b32 v3, v41, s33, v3
	s_nop 0
	v_addc_co_u32_e32 v27, vcc, 0, v51, vcc
	global_store_dwordx4 v[26:27], v[34:37], off
	v_add_co_u32_e32 v26, vcc, 0x1860c000, v50
	v_and_or_b32 v4, v45, s33, v4
	v_and_or_b32 v5, v49, s33, v5
	v_addc_co_u32_e32 v27, vcc, 0, v51, vcc
	global_store_dwordx4 v[26:27], v[2:5], off
	s_and_saveexec_b64 s[50:51], s[38:39]
	s_cbranch_execz .LBB0_117
	v_lshlrev_b32_e32 v2, 16, v58
	v_add_f32_e32 v3, v55, v2
	v_min_f32_e32 v2, 0, v3
	v_mul_f32_e64 v3, |v3|, s19
	v_exp_f32_e32 v3, v3
	s_nop 0
	v_add_f32_e32 v25, 1.0, v3
	v_add_f32_e32 v4, -1.0, v25
	v_sub_f32_e32 v5, v4, v25
	v_add_f32_e32 v5, 1.0, v5
	v_sub_f32_e32 v4, v3, v4
	v_add_f32_e32 v26, v4, v5
	v_frexp_mant_f32_e32 v4, v25
	v_cmp_gt_f32_e32 vcc, s86, v4
	v_cvt_f64_f32_e32 v[4:5], v25
	v_frexp_exp_i32_f64_e32 v4, v[4:5]
	v_subbrev_co_u32_e32 v32, vcc, 0, v4, vcc
	v_sub_u32_e32 v4, 0, v32
	v_ldexp_f32 v5, v25, v4
	v_add_f32_e32 v25, -1.0, v5
	v_add_f32_e32 v27, 1.0, v5
	v_ldexp_f32 v4, v26, v4
	v_add_f32_e32 v26, 1.0, v25
	v_add_f32_e32 v28, -1.0, v27
	v_sub_f32_e32 v26, v5, v26
	v_sub_f32_e32 v5, v5, v28
	v_add_f32_e32 v26, v4, v26
	v_add_f32_e32 v4, v4, v5
	v_add_f32_e32 v33, v27, v4
	v_rcp_f32_e32 v35, v33
	v_sub_f32_e32 v5, v33, v27
	v_sub_f32_e32 v34, v4, v5
	v_add_f32_e32 v5, v25, v26
	v_sub_f32_e32 v4, v5, v25
	v_mul_f32_e32 v36, v5, v35
	v_sub_f32_e32 v25, v26, v4
	v_mul_f32_e32 v26, v33, v36
	v_fma_f32 v28, v36, v33, -v26
	v_fmac_f32_e32 v28, v36, v34
	v_add_f32_e32 v4, v26, v28
	v_sub_f32_e32 v27, v5, v4
	v_pk_add_f32 v[30:31], v[4:5], v[26:27] neg_lo:[0,1] neg_hi:[0,1]
	v_mov_b32_e32 v29, v4
	v_pk_add_f32 v[4:5], v[30:31], v[28:29] neg_lo:[0,1] neg_hi:[0,1]
	v_cmp_neq_f32_e32 vcc, s15, v3
	v_add_f32_e32 v5, v25, v5
	v_add_f32_e32 v4, v4, v5
	v_add_f32_e32 v5, v27, v4
	v_mul_f32_e32 v25, v35, v5
	v_mul_f32_e32 v26, v33, v25
	v_fma_f32 v28, v25, v33, -v26
	v_fmac_f32_e32 v28, v25, v34
	v_sub_f32_e32 v27, v27, v5
	v_add_f32_e32 v33, v4, v27
	v_add_f32_e32 v4, v26, v28
	v_sub_f32_e32 v27, v5, v4
	v_pk_add_f32 v[30:31], v[4:5], v[26:27] neg_lo:[0,1] neg_hi:[0,1]
	v_mov_b32_e32 v29, v4
	v_pk_add_f32 v[4:5], v[30:31], v[28:29] neg_lo:[0,1] neg_hi:[0,1]
	s_nop 0
	v_add_f32_e32 v5, v33, v5
	v_add_f32_e32 v4, v4, v5
	v_add_f32_e32 v5, v36, v25
	v_add_f32_e32 v4, v27, v4
	v_sub_f32_e32 v26, v5, v36
	v_mul_f32_e32 v4, v35, v4
	v_sub_f32_e32 v25, v25, v26
	v_add_f32_e32 v25, v25, v4
	v_add_f32_e32 v26, v5, v25
	v_mul_f32_e32 v28, v26, v26
	v_fmamk_f32 v4, v28, 0x3e9b6dac, v172
	v_fmaak_f32 v147, v28, v4, 0x3f2aaada
	v_cvt_f32_i32_e32 v4, v32
	v_sub_f32_e32 v5, v26, v5
	v_sub_f32_e32 v5, v25, v5
	v_ldexp_f32 v25, v5, 1
	v_mul_f32_e32 v5, v26, v28
	v_pk_mul_f32 v[28:29], v[4:5], v[146:147]
	v_ldexp_f32 v27, v26, 1
	v_fma_f32 v26, v4, s87, -v28
	v_fmac_f32_e32 v26, 0xb102e308, v4
	v_pk_add_f32 v[4:5], v[28:29], v[26:27]
	v_mov_b32_e32 v30, v28
	v_sub_f32_e32 v27, v5, v27
	v_sub_f32_e32 v27, v29, v27
	v_add_f32_e32 v31, v25, v27
	v_pk_add_f32 v[28:29], v[4:5], v[28:29] neg_lo:[0,1] neg_hi:[0,1]
	v_pk_add_f32 v[32:33], v[4:5], v[30:31]
	v_mov_b32_e32 v27, v4
	v_mov_b32_e32 v29, v33
	v_pk_add_f32 v[34:35], v[26:27], v[28:29] neg_lo:[0,1] neg_hi:[0,1]
	v_pk_add_f32 v[26:27], v[26:27], v[28:29]
	v_mov_b32_e32 v30, v31
	v_pk_add_f32 v[28:29], v[26:27], v[4:5] op_sel:[1,0] op_sel_hi:[0,1] neg_lo:[0,1] neg_hi:[0,1]
	v_pk_add_f32 v[36:37], v[32:33], v[28:29] op_sel_hi:[1,0] neg_lo:[0,1] neg_hi:[0,1]
	v_mov_b32_e32 v32, v33
	v_mov_b32_e32 v33, v27
	v_pk_mov_b32 v[28:29], v[4:5], v[28:29] op_sel:[1,0]
	v_mov_b32_e32 v31, v4
	v_pk_add_f32 v[28:29], v[32:33], v[28:29] neg_lo:[0,1] neg_hi:[0,1]
	v_mov_b32_e32 v36, v34
	v_pk_add_f32 v[4:5], v[30:31], v[28:29] neg_lo:[0,1] neg_hi:[0,1]
	v_mov_b32_e32 v35, v27
	v_pk_add_f32 v[28:29], v[36:37], v[4:5]
	s_nop 0
	v_pk_add_f32 v[30:31], v[28:29], v[28:29] op_sel:[0,1] op_sel_hi:[1,0]
	s_nop 0
	v_pk_add_f32 v[26:27], v[26:27], v[30:31] op_sel:[1,0] op_sel_hi:[0,1]
	v_mov_b32_e32 v29, v26
	v_pk_add_f32 v[32:33], v[28:29], v[34:35] neg_lo:[0,1] neg_hi:[0,1]
	v_mov_b32_e32 v5, v30
	v_sub_f32_e32 v25, v28, v32
	v_pk_add_f32 v[4:5], v[4:5], v[32:33] neg_lo:[0,1] neg_hi:[0,1]
	v_sub_f32_e32 v25, v34, v25
	v_add_f32_e32 v4, v4, v25
	v_add_f32_e32 v4, v4, v5
	v_add_f32_e32 v4, v26, v4
	v_cndmask_b32_e32 v4, v175, v4, vcc
	v_cmp_ngt_f32_e32 vcc, -1.0, v3
	s_nop 1
	v_cndmask_b32_e32 v4, v176, v4, vcc
	v_cmp_neq_f32_e32 vcc, -1.0, v3
	s_nop 1
	v_cndmask_b32_e32 v4, v177, v4, vcc
	v_cmp_lt_f32_e64 vcc, |v3|, s88
	s_nop 1
	v_cndmask_b32_e32 v3, v4, v3, vcc
	v_sub_f32_e32 v4, v2, v3
	v_lshl_add_u64 v[2:3], s[72:73], 0, v[10:11]
	global_store_dword v[2:3], v4, off
	s_branch .LBB0_117

.LBB0_121:
	s_and_b64 vcc, exec, s[2:3]
	s_cbranch_vccz .LBB0_114
	s_mov_b32 s2, 20
	s_ashr_i32 s3, s2, 31
	s_and_b32 s21, s4, 0xff
	s_lshl_b64 s[2:3], s[2:3], 3
	s_add_u32 s2, s0, s2
	s_addc_u32 s3, s1, s3
	s_load_dwordx2 s[2:3], s[2:3], 0x0
	s_mov_b32 s38, 21
	v_mov_b32_e32 v0, v183
	s_waitcnt lgkmcnt(0)
	s_add_u32 s2, s2, s46
	s_addc_u32 s3, s3, s47
	s_ashr_i32 s39, s38, 31
	s_lshl_b64 s[38:39], s[38:39], 3
	s_add_u32 s38, s0, s38
	s_addc_u32 s39, s1, s39
	s_load_dwordx2 s[38:39], s[38:39], 0x0
	s_waitcnt lgkmcnt(0)
	s_add_u32 s38, s38, s48
	v_lshlrev_b32_e32 v0, 2, v0
	v_and_b32_e32 v0, 0xfc, v0
	v_lshlrev_b32_e32 v14, 2, v0
	s_addc_u32 s39, s39, s49
	global_load_dwordx4 v[2:5], v14, s[2:3]
	global_load_dwordx4 v[6:9], v14, s[2:3] offset:1024
	global_load_dwordx4 v[10:13], v14, s[2:3] offset:2048
	s_nop 0
	global_load_dwordx4 v[14:17], v14, s[38:39]
	s_cmp_eq_u32 s21, 0
	v_lshlrev_b32_e32 v0, 1, v0
	s_cbranch_scc1 .LBB0_124
	s_lshl_b32 s21, s4, 5
	s_mul_i32 s3, s4, 0x3c000
	s_add_i32 s2, s21, -1
	s_addk_i32 s3, 0xe200
	s_mul_hi_i32 s31, s2, 0x1e00
	s_add_u32 s2, s26, s3
	s_addc_u32 s3, s27, s31
	s_add_i32 s21, s21, -2
	s_mul_hi_i32 s31, s21, 0x1e00
	s_mulk_i32 s21, 0x1e00
	s_add_u32 s38, s26, s21
	s_addc_u32 s39, s27, s31
	v_lshl_add_u64 v[18:19], s[38:39], 0, v[0:1]
	s_movk_i32 s21, 0x1000
	v_add_co_u32_e32 v18, vcc, s21, v18
	s_nop 1
	v_addc_co_u32_e32 v19, vcc, 0, v19, vcc
	global_load_dwordx2 v[20:21], v[18:19], off offset:2048
	s_nop 0
	global_load_dwordx2 v[18:19], v[18:19], off offset:2560
	s_waitcnt vmcnt(0) lgkmcnt(0)
	v_lshlrev_b32_e32 v22, 16, v20
	v_and_b32_e32 v23, 0xffff0000, v20
	v_lshlrev_b32_e32 v24, 16, v18
	v_and_b32_e32 v25, 0xffff0000, v18
	v_lshlrev_b32_e32 v18, 16, v21
	v_lshlrev_b32_e32 v26, 16, v19
	v_and_b32_e32 v27, 0xffff0000, v19
	v_and_b32_e32 v19, 0xffff0000, v21
	v_pk_mul_f32 v[20:21], v[18:19], v[26:27]
	v_pk_mul_f32 v[18:19], v[22:23], v[24:25]
	v_lshl_add_u64 v[22:23], s[2:3], 0, v[0:1]
	v_add_co_u32_e32 v22, vcc, s21, v22
	s_nop 1
	v_addc_co_u32_e32 v23, vcc, 0, v23, vcc
	global_load_dwordx2 v[24:25], v[22:23], off offset:2048
	s_nop 0
	global_load_dwordx2 v[22:23], v[22:23], off offset:2560
	s_waitcnt vmcnt(0) lgkmcnt(0)
	v_lshlrev_b32_e32 v26, 16, v24
	v_and_b32_e32 v27, 0xffff0000, v24
	v_lshlrev_b32_e32 v28, 16, v22
	v_and_b32_e32 v29, 0xffff0000, v22
	v_lshlrev_b32_e32 v22, 16, v25
	v_lshlrev_b32_e32 v30, 16, v23
	v_and_b32_e32 v31, 0xffff0000, v23
	v_and_b32_e32 v23, 0xffff0000, v25
	v_pk_mul_f32 v[24:25], v[22:23], v[30:31]
	v_pk_mul_f32 v[22:23], v[26:27], v[28:29]
	s_branch .LBB0_125

.LBB0_128:
	s_and_b64 vcc, exec, s[2:3]
	s_cbranch_vccz .LBB0_152
	v_readlane_b32 s2, v255, 4
	s_add_u32 s30, s2, 0x1080000
	v_readlane_b32 s2, v255, 5
	s_addc_u32 s31, s2, 0
	v_readlane_b32 s2, v255, 3
	s_mul_i32 s2, s2, 3
	s_ashr_i32 s3, s2, 31
	s_lshl_b64 s[2:3], s[2:3], 18
	v_readlane_b32 s4, v255, 6
	s_add_u32 s2, s4, s2
	v_readlane_b32 s4, v255, 7
	s_addc_u32 s3, s4, s3
	s_add_u32 s34, s2, 0x40000
	s_addc_u32 s35, s3, 0
	v_readlane_b32 s11, v255, 16
	v_mov_b32_e32 v12, v170
	s_cmpk_lt_i32 s11, 0x700
	s_nop 0
	v_readfirstlane_b32 s3, v12
	s_cbranch_scc0 .LBB0_145
	v_lshlrev_b32_e32 v0, 4, v12
	v_add_u32_e32 v2, 0x2000, v0
	v_ashrrev_i32_e32 v3, 31, v2
	v_lshrrev_b32_e32 v3, 22, v3
	v_add_u32_e32 v3, v2, v3
	v_ashrrev_i32_e32 v10, 10, v3
	v_mul_i32_i24_e32 v3, 0x400, v10
	v_sub_u32_e32 v2, v2, v3
	v_lshrrev_b32_e32 v3, 4, v2
	v_bitop3_b32 v2, v3, v2, 32 bitop3:0x6c
	v_ashrrev_i32_e32 v3, 31, v2
	v_lshrrev_b32_e32 v3, 26, v3
	v_add_u32_e32 v3, v2, v3
	v_lshlrev_b32_e32 v4, 3, v10
	v_ashrrev_i32_e32 v13, 6, v3
	v_and_b32_e32 v4, -16, v4
	v_add_u32_e32 v4, v13, v4
	v_and_b32_e32 v5, 3, v13
	s_mov_b32 s2, 0x1fffe0
	v_lshrrev_b32_e32 v6, 2, v4
	v_lshlrev_b32_e32 v7, 1, v4
	v_and_b32_e32 v3, 0xc0, v3
	v_and_or_b32 v5, v4, s2, v5
	v_and_b32_e32 v6, 4, v6
	v_and_b32_e32 v7, 24, v7
	v_sub_u32_e32 v2, v2, v3
	v_or3_b32 v5, v5, v6, v7
	v_lshlrev_b32_e32 v6, 5, v10
	v_ashrrev_i16_sdwa v2, v180, sext(v2) dst_sel:DWORD dst_unused:UNUSED_PAD src0_sel:DWORD src1_sel:BYTE_0
	v_and_b32_e32 v6, 32, v6
	v_bfe_i32 v14, v2, 0, 16
	v_add_lshl_u32 v2, v6, v14, 1
	v_lshl_add_u32 v130, v5, 11, v2
	v_lshl_add_u32 v132, v4, 11, v2
	v_bfe_i32 v2, v12, 27, 1
	v_lshrrev_b32_e32 v2, 22, v2
	v_add_u32_e32 v2, v0, v2
	v_and_b32_e32 v2, 0xfffffc00, v2
	v_sub_u32_e32 v0, v0, v2
	v_lshrrev_b32_e32 v2, 4, v0
	v_ashrrev_i32_e32 v3, 31, v12
	v_bitop3_b32 v0, v2, v0, 32 bitop3:0x6c
	v_lshrrev_b32_e32 v3, 26, v3
	v_ashrrev_i32_e32 v2, 31, v0
	v_add_u32_e32 v3, v12, v3
	v_lshrrev_b32_e32 v2, 26, v2
	v_ashrrev_i32_e32 v16, 6, v3
	v_add_u32_e32 v2, v0, v2
	v_lshlrev_b32_e32 v3, 3, v16
	v_ashrrev_i32_e32 v15, 6, v2
	v_and_b32_e32 v3, -16, v3
	v_add_u32_e32 v3, v15, v3
	v_and_b32_e32 v4, 3, v15
	s_ashr_i32 s7, s11, 31
	v_and_or_b32 v4, v3, s2, v4
	s_lshr_b32 s2, s7, 29
	s_add_i32 s2, s11, s2
	s_ashr_i32 s38, s3, 8
	s_ashr_i32 s5, s3, 6
	s_ashr_i32 s10, s2, 3
	s_and_b32 s2, s2, -8
	s_lshl_b32 s6, s5, 10
	s_lshl_b32 s4, s38, 6
	s_sub_i32 s2, s11, s2
	s_cmp_lt_i32 s2, 0
	s_movk_i32 s11, 0xe1
	s_cselect_b32 s11, s11, 0xe0
	s_mul_i32 s2, s2, s11
	s_add_i32 s2, s2, s10
	s_mul_hi_i32 s10, s2, 0x92492493
	s_add_i32 s10, s10, s2
	s_lshr_b32 s11, s10, 31
	s_ashr_i32 s10, s10, 6
	s_add_i32 s10, s10, s11
	s_lshl_b32 s11, s10, 3
	s_mulk_i32 s10, 0x70
	s_sub_i32 s10, s2, s10
	s_bfe_i32 s2, s10, 0x80000
	s_bfe_u32 s2, s2, 0x3000c
	s_add_i32 s20, s10, s2
	s_bfe_i32 s2, s20, 0x80000
	s_and_b32 s20, s20, 0xf8
	v_lshrrev_b32_e32 v5, 2, v3
	v_lshlrev_b32_e32 v6, 1, v3
	v_and_b32_e32 v2, 0xc0, v2
	s_sub_i32 s10, s10, s20
	v_and_b32_e32 v5, 4, v5
	v_and_b32_e32 v6, 24, v6
	v_sub_u32_e32 v0, v0, v2
	s_sext_i32_i8 s10, s10
	v_or3_b32 v4, v4, v5, v6
	v_lshlrev_b32_e32 v5, 5, v16
	v_ashrrev_i16_sdwa v0, v180, sext(v0) dst_sel:DWORD dst_unused:UNUSED_PAD src0_sel:DWORD src1_sel:BYTE_0
	s_add_i32 s50, s11, s10
	v_and_b32_e32 v5, 32, v5
	v_bfe_i32 v17, v0, 0, 16
	s_sext_i32_i16 s2, s2
	s_lshl_b32 s10, s50, 8
	v_and_b32_e32 v11, 15, v12
	v_add_lshl_u32 v2, v5, v17, 1
	s_lshr_b32 s2, s2, 3
	s_add_i32 s10, s10, s4
	v_lshl_add_u32 v0, v4, 11, v2
	v_lshl_add_u32 v134, v3, 11, v2
	v_or_b32_e32 v2, s10, v11
	s_ashr_i32 s51, s50, 31
	s_bfe_i64 s[10:11], s[2:3], 0x100000
	s_lshl_b64 s[20:21], s[50:51], 19
	s_lshl_b64 s[10:11], s[10:11], 19
	s_add_u32 s52, s30, s10
	v_ashrrev_i32_e32 v3, 31, v2
	s_addc_u32 s53, s31, s11
	s_add_i32 s10, s6, 0
	v_lshl_add_u64 v[2:3], v[2:3], 3, s[34:35]
	s_add_i32 m0, s10, 0x10000
	s_waitcnt vmcnt(0)
	global_load_dwordx2 v[158:159], v[2:3], off
	global_load_dwordx2 v[156:157], v[2:3], off offset:128
	global_load_dwordx2 v[154:155], v[2:3], off offset:256
	global_load_dwordx2 v[152:153], v[2:3], off offset:384
	global_load_dwordx2 v[150:151], v[2:3], off offset:1024
	global_load_dwordx2 v[148:149], v[2:3], off offset:1152
	global_load_dwordx2 v[142:143], v[2:3], off offset:1280
	global_load_dwordx2 v[140:141], v[2:3], off offset:1408
	v_mov_b32_e32 v131, v1
	global_load_lds_dwordx4 v0, s[52:53]
	s_add_i32 m0, s10, 0x12000
	s_add_u32 s36, s52, 0x40000
	global_load_lds_dwordx4 v130, s[52:53]
	s_addc_u32 s37, s53, 0
	s_add_i32 m0, s10, 0x14000
	v_mov_b32_e32 v135, v1
	global_load_lds_dwordx4 v0, s[36:37]
	s_add_i32 m0, s10, 0x16000
	s_add_u32 s54, s24, s20
	s_addc_u32 s55, s25, s21
	s_add_i32 s11, s10, 0x2000
	global_load_lds_dwordx4 v130, s[36:37]
	s_mov_b32 m0, s10
	s_add_u32 s20, s54, 0x40000
	global_load_lds_dwordx4 v134, s[54:55]
	s_mov_b32 m0, s11
	s_addc_u32 s21, s55, 0
	s_add_i32 s36, s10, 0x4000
	global_load_lds_dwordx4 v132, s[54:55]
	s_mov_b32 m0, s36
	s_add_i32 s37, s10, 0x6000
	global_load_lds_dwordx4 v134, s[20:21]
	s_mov_b32 m0, s37
	v_mov_b32_e32 v133, v1
	global_load_lds_dwordx4 v132, s[20:21]
	s_cmp_eq_u32 s38, 1
	v_lshl_add_u64 v[8:9], s[52:53], 0, v[0:1]
	v_lshl_add_u64 v[6:7], s[52:53], 0, v[130:131]
	v_lshl_add_u64 v[2:3], s[54:55], 0, v[134:135]
	s_cselect_b64 s[20:21], -1, 0
	s_cmp_lg_u32 s38, 1
	v_lshl_add_u64 v[4:5], s[54:55], 0, v[132:133]
	s_cbranch_scc1 .LBB0_132
	s_barrier

.LBB0_141:
	s_waitcnt vmcnt(8)
	v_ffbh_u32_e32 v162, v159
	v_min_u32_e32 v162, 32, v162
	v_lshlrev_b64 v[158:159], v162, v[158:159]
	v_min_u32_e32 v158, 1, v158
	v_or_b32_e32 v158, v159, v158
	v_ffbh_u32_e32 v159, v157
	v_min_u32_e32 v159, 32, v159
	v_lshlrev_b64 v[156:157], v159, v[156:157]
	v_min_u32_e32 v156, 1, v156
	v_cvt_f32_u32_e32 v158, v158
	v_or_b32_e32 v156, v157, v156
	v_cvt_f32_u32_e32 v156, v156
	v_sub_u32_e32 v157, 32, v162
	v_ldexp_f32 v157, v158, v157
	v_sub_u32_e32 v158, 32, v159
	v_ldexp_f32 v156, v156, v158
	v_ffbh_u32_e32 v158, v155
	v_min_u32_e32 v158, 32, v158
	v_lshlrev_b64 v[154:155], v158, v[154:155]
	v_min_u32_e32 v154, 1, v154
	v_or_b32_e32 v154, v155, v154
	v_ffbh_u32_e32 v155, v153
	v_min_u32_e32 v155, 32, v155
	v_lshlrev_b64 v[152:153], v155, v[152:153]
	v_min_u32_e32 v152, 1, v152
	v_cvt_f32_u32_e32 v154, v154
	v_or_b32_e32 v152, v153, v152
	v_cvt_f32_u32_e32 v152, v152
	v_sub_u32_e32 v153, 32, v158
	v_ldexp_f32 v153, v154, v153
	v_sub_u32_e32 v154, 32, v155
	s_mov_b32 s2, 0x35800000
	v_ldexp_f32 v152, v152, v154
	v_pk_mul_f32 v[154:155], v[152:153], s[2:3] op_sel_hi:[1,0]
	v_ffbh_u32_e32 v152, v151
	v_min_u32_e32 v152, 32, v152
	v_lshlrev_b64 v[150:151], v152, v[150:151]
	v_min_u32_e32 v150, 1, v150
	v_or_b32_e32 v150, v151, v150
	v_ffbh_u32_e32 v151, v149
	v_min_u32_e32 v151, 32, v151
	v_lshlrev_b64 v[148:149], v151, v[148:149]
	v_min_u32_e32 v148, 1, v148
	v_cvt_f32_u32_e32 v150, v150
	v_or_b32_e32 v148, v149, v148
	v_cvt_f32_u32_e32 v148, v148
	v_sub_u32_e32 v149, 32, v152
	v_ldexp_f32 v149, v150, v149
	v_sub_u32_e32 v150, 32, v151
	v_ldexp_f32 v148, v148, v150
	v_pk_mul_f32 v[152:153], v[148:149], s[2:3] op_sel_hi:[1,0]
	v_ffbh_u32_e32 v148, v143
	v_min_u32_e32 v148, 32, v148
	v_lshlrev_b64 v[142:143], v148, v[142:143]
	v_min_u32_e32 v142, 1, v142
	v_or_b32_e32 v142, v143, v142
	v_ffbh_u32_e32 v143, v141
	v_min_u32_e32 v143, 32, v143
	v_lshlrev_b64 v[140:141], v143, v[140:141]
	v_min_u32_e32 v140, 1, v140
	v_cvt_f32_u32_e32 v142, v142
	v_or_b32_e32 v140, v141, v140
	v_cvt_f32_u32_e32 v140, v140
	v_sub_u32_e32 v141, 32, v148
	v_ldexp_f32 v141, v142, v141
	v_sub_u32_e32 v142, 32, v143
	v_ldexp_f32 v140, v140, v142
	v_lshl_add_u32 v165, s50, 8, v144
	v_lshl_or_b32 v148, s59, 8, v160
	v_mov_b64_e32 v[142:143], s[26:27]
	v_pk_mul_f32 v[156:157], v[156:157], s[2:3] op_sel_hi:[1,0]
	v_pk_mul_f32 v[140:141], v[140:141], s[2:3] op_sel_hi:[1,0]
	v_ashrrev_i32_e32 v149, 31, v148
	v_mad_i64_i32 v[150:151], s[2:3], v165, s18, v[142:143]
	v_lshlrev_b64 v[148:149], 1, v[148:149]
	s_mov_b32 s2, 0x358637bd
	v_lshl_add_u64 v[158:159], v[150:151], 0, v[148:149]
	v_mov_b64_e32 v[150:151], s[2:3]
	s_mov_b32 s4, 0x3a800000
	v_pk_fma_f32 v[156:157], v[156:157], s[4:5], v[150:151] op_sel_hi:[1,0,0]
	v_or_b32_e32 v162, 16, v165
	v_mul_f32_e32 v163, 0x4b800000, v157
	v_cmp_gt_f32_e32 vcc, s96, v157
	s_nop 1
	v_cndmask_b32_e32 v157, v157, v163, vcc
	v_rsq_f32_e32 v157, v157
	v_mad_i64_i32 v[162:163], s[2:3], v162, s18, v[142:143]
	v_lshl_add_u64 v[162:163], v[162:163], 0, v[148:149]
	v_mul_f32_e32 v164, 0x45800000, v157
	v_cndmask_b32_e32 v164, v157, v164, vcc
	v_pk_mul_f32 v[128:129], v[164:165], v[128:129] op_sel_hi:[0,1]
	v_pk_mul_f32 v[126:127], v[164:165], v[126:127] op_sel_hi:[0,1]
	v_pk_mul_f32 v[166:167], v[164:165], v[124:125] op_sel_hi:[0,1]
	v_pk_mul_f32 v[124:125], v[164:165], v[122:123] op_sel_hi:[0,1]
	v_cvt_pk_bf16_f32 v122, v126, v127
	v_cvt_pk_bf16_f32 v123, v128, v129
	v_pk_mul_f32 v[118:119], v[164:165], v[118:119] op_sel_hi:[0,1]
	v_cvt_pk_bf16_f32 v124, v124, v125
	v_cvt_pk_bf16_f32 v125, v166, v167
	global_store_dwordx4 v[158:159], v[122:125], off
	v_cmp_gt_f32_e32 vcc, s96, v156
	v_pk_mul_f32 v[120:121], v[164:165], v[120:121] op_sel_hi:[0,1]
	v_pk_mul_f32 v[122:123], v[164:165], v[116:117] op_sel_hi:[0,1]
	v_pk_mul_f32 v[116:117], v[164:165], v[114:115] op_sel_hi:[0,1]
	v_cvt_pk_bf16_f32 v114, v118, v119
	v_mul_f32_e32 v118, 0x4b800000, v156
	v_cndmask_b32_e32 v118, v156, v118, vcc
	v_rsq_f32_e32 v118, v118
	v_cvt_pk_bf16_f32 v115, v120, v121
	v_cvt_pk_bf16_f32 v116, v116, v117
	v_cvt_pk_bf16_f32 v117, v122, v123
	global_store_dwordx4 v[158:159], v[114:117], off offset:256
	s_nop 1
	v_mul_f32_e32 v114, 0x45800000, v118
	v_cndmask_b32_e32 v114, v118, v114, vcc
	v_pk_mul_f32 v[112:113], v[114:115], v[112:113] op_sel_hi:[0,1]
	v_pk_mul_f32 v[110:111], v[114:115], v[110:111] op_sel_hi:[0,1]
	v_pk_mul_f32 v[116:117], v[114:115], v[108:109] op_sel_hi:[0,1]
	v_pk_mul_f32 v[108:109], v[114:115], v[106:107] op_sel_hi:[0,1]
	v_cvt_pk_bf16_f32 v106, v110, v111
	v_cvt_pk_bf16_f32 v107, v112, v113
	v_cvt_pk_bf16_f32 v108, v108, v109
	v_cvt_pk_bf16_f32 v109, v116, v117
	global_store_dwordx4 v[162:163], v[106:109], off
	v_pk_mul_f32 v[104:105], v[114:115], v[104:105] op_sel_hi:[0,1]
	v_pk_mul_f32 v[102:103], v[114:115], v[102:103] op_sel_hi:[0,1]
	v_pk_mul_f32 v[106:107], v[114:115], v[100:101] op_sel_hi:[0,1]
	v_pk_mul_f32 v[100:101], v[114:115], v[98:99] op_sel_hi:[0,1]
	v_cvt_pk_bf16_f32 v98, v102, v103
	v_cvt_pk_bf16_f32 v99, v104, v105
	v_cvt_pk_bf16_f32 v100, v100, v101
	v_cvt_pk_bf16_f32 v101, v106, v107
	global_store_dwordx4 v[162:163], v[98:101], off offset:256
	v_or_b32_e32 v102, 48, v165
	s_nop 0
	v_pk_fma_f32 v[100:101], v[154:155], s[4:5], v[150:151] op_sel_hi:[1,0,0]
	v_or_b32_e32 v98, 32, v165
	v_mul_f32_e32 v103, 0x4b800000, v101
	v_cmp_gt_f32_e32 vcc, s96, v101
	v_mad_i64_i32 v[98:99], s[2:3], v98, s18, v[142:143]
	s_nop 0
	v_cndmask_b32_e32 v101, v101, v103, vcc
	v_rsq_f32_e32 v101, v101
	v_lshl_add_u64 v[98:99], v[98:99], 0, v[148:149]
	v_mad_i64_i32 v[102:103], s[2:3], v102, s18, v[142:143]
	v_mul_f32_e32 v104, 0x45800000, v101
	v_cndmask_b32_e32 v104, v101, v104, vcc
	v_pk_mul_f32 v[96:97], v[104:105], v[96:97] op_sel_hi:[0,1]
	v_pk_mul_f32 v[94:95], v[104:105], v[94:95] op_sel_hi:[0,1]
	v_pk_mul_f32 v[106:107], v[104:105], v[92:93] op_sel_hi:[0,1]
	v_pk_mul_f32 v[92:93], v[104:105], v[90:91] op_sel_hi:[0,1]
	v_cvt_pk_bf16_f32 v90, v94, v95
	v_cvt_pk_bf16_f32 v91, v96, v97
	v_pk_mul_f32 v[86:87], v[104:105], v[86:87] op_sel_hi:[0,1]
	v_cvt_pk_bf16_f32 v92, v92, v93
	v_cvt_pk_bf16_f32 v93, v106, v107
	global_store_dwordx4 v[98:99], v[90:93], off
	v_cmp_gt_f32_e32 vcc, s96, v100
	v_pk_mul_f32 v[88:89], v[104:105], v[88:89] op_sel_hi:[0,1]
	v_pk_mul_f32 v[90:91], v[104:105], v[84:85] op_sel_hi:[0,1]
	v_pk_mul_f32 v[84:85], v[104:105], v[82:83] op_sel_hi:[0,1]
	v_cvt_pk_bf16_f32 v82, v86, v87
	v_mul_f32_e32 v86, 0x4b800000, v100
	v_cndmask_b32_e32 v86, v100, v86, vcc
	v_rsq_f32_e32 v86, v86
	v_cvt_pk_bf16_f32 v83, v88, v89
	v_cvt_pk_bf16_f32 v84, v84, v85
	v_cvt_pk_bf16_f32 v85, v90, v91
	global_store_dwordx4 v[98:99], v[82:85], off offset:256
	v_lshl_add_u64 v[102:103], v[102:103], 0, v[148:149]
	s_nop 0
	v_mul_f32_e32 v82, 0x45800000, v86
	v_cndmask_b32_e32 v82, v86, v82, vcc
	v_pk_mul_f32 v[80:81], v[82:83], v[80:81] op_sel_hi:[0,1]
	v_pk_mul_f32 v[78:79], v[82:83], v[78:79] op_sel_hi:[0,1]
	v_pk_mul_f32 v[84:85], v[82:83], v[76:77] op_sel_hi:[0,1]
	v_pk_mul_f32 v[76:77], v[82:83], v[74:75] op_sel_hi:[0,1]
	v_cvt_pk_bf16_f32 v74, v78, v79
	v_cvt_pk_bf16_f32 v75, v80, v81
	v_cvt_pk_bf16_f32 v76, v76, v77
	v_cvt_pk_bf16_f32 v77, v84, v85
	global_store_dwordx4 v[102:103], v[74:77], off
	v_pk_mul_f32 v[72:73], v[82:83], v[72:73] op_sel_hi:[0,1]
	v_pk_mul_f32 v[70:71], v[82:83], v[70:71] op_sel_hi:[0,1]
	v_pk_mul_f32 v[74:75], v[82:83], v[68:69] op_sel_hi:[0,1]
	v_pk_mul_f32 v[68:69], v[82:83], v[66:67] op_sel_hi:[0,1]
	v_cvt_pk_bf16_f32 v66, v70, v71
	v_cvt_pk_bf16_f32 v67, v72, v73
	v_cvt_pk_bf16_f32 v68, v68, v69
	v_cvt_pk_bf16_f32 v69, v74, v75
	global_store_dwordx4 v[102:103], v[66:69], off offset:256
	v_add_u32_e32 v70, 0x90, v165
	s_nop 0
	v_pk_fma_f32 v[68:69], v[152:153], s[4:5], v[150:151] op_sel_hi:[1,0,0]
	v_add_u32_e32 v66, 0x80, v165
	v_mul_f32_e32 v71, 0x4b800000, v69
	v_cmp_gt_f32_e32 vcc, s96, v69
	v_mad_i64_i32 v[66:67], s[2:3], v66, s18, v[142:143]
	s_nop 0
	v_cndmask_b32_e32 v69, v69, v71, vcc
	v_rsq_f32_e32 v69, v69
	v_lshl_add_u64 v[66:67], v[66:67], 0, v[148:149]
	v_mad_i64_i32 v[70:71], s[2:3], v70, s18, v[142:143]
	v_mul_f32_e32 v72, 0x45800000, v69
	v_cndmask_b32_e32 v72, v69, v72, vcc
	v_pk_mul_f32 v[64:65], v[72:73], v[64:65] op_sel_hi:[0,1]
	v_pk_mul_f32 v[62:63], v[72:73], v[62:63] op_sel_hi:[0,1]
	v_pk_mul_f32 v[74:75], v[72:73], v[60:61] op_sel_hi:[0,1]
	v_pk_mul_f32 v[60:61], v[72:73], v[58:59] op_sel_hi:[0,1]
	v_cvt_pk_bf16_f32 v58, v62, v63
	v_cvt_pk_bf16_f32 v59, v64, v65
	v_pk_mul_f32 v[54:55], v[72:73], v[54:55] op_sel_hi:[0,1]
	v_cvt_pk_bf16_f32 v60, v60, v61
	v_cvt_pk_bf16_f32 v61, v74, v75
	global_store_dwordx4 v[66:67], v[58:61], off
	v_cmp_gt_f32_e32 vcc, s96, v68
	v_pk_mul_f32 v[56:57], v[72:73], v[56:57] op_sel_hi:[0,1]
	v_pk_mul_f32 v[58:59], v[72:73], v[52:53] op_sel_hi:[0,1]
	v_pk_mul_f32 v[52:53], v[72:73], v[50:51] op_sel_hi:[0,1]
	v_cvt_pk_bf16_f32 v50, v54, v55
	v_mul_f32_e32 v54, 0x4b800000, v68
	v_cndmask_b32_e32 v54, v68, v54, vcc
	v_rsq_f32_e32 v54, v54
	v_cvt_pk_bf16_f32 v51, v56, v57
	v_cvt_pk_bf16_f32 v52, v52, v53
	v_cvt_pk_bf16_f32 v53, v58, v59
	global_store_dwordx4 v[66:67], v[50:53], off offset:256
	v_lshl_add_u64 v[70:71], v[70:71], 0, v[148:149]
	s_nop 0
	v_mul_f32_e32 v50, 0x45800000, v54
	v_cndmask_b32_e32 v50, v54, v50, vcc
	v_pk_mul_f32 v[48:49], v[50:51], v[48:49] op_sel_hi:[0,1]
	v_pk_mul_f32 v[46:47], v[50:51], v[46:47] op_sel_hi:[0,1]
	v_pk_mul_f32 v[52:53], v[50:51], v[44:45] op_sel_hi:[0,1]
	v_pk_mul_f32 v[44:45], v[50:51], v[42:43] op_sel_hi:[0,1]
	v_cvt_pk_bf16_f32 v42, v46, v47
	v_cvt_pk_bf16_f32 v43, v48, v49
	v_cvt_pk_bf16_f32 v44, v44, v45
	v_cvt_pk_bf16_f32 v45, v52, v53
	global_store_dwordx4 v[70:71], v[42:45], off
	v_pk_mul_f32 v[40:41], v[50:51], v[40:41] op_sel_hi:[0,1]
	v_pk_mul_f32 v[38:39], v[50:51], v[38:39] op_sel_hi:[0,1]
	v_pk_mul_f32 v[42:43], v[50:51], v[36:37] op_sel_hi:[0,1]
	v_pk_mul_f32 v[36:37], v[50:51], v[34:35] op_sel_hi:[0,1]
	v_cvt_pk_bf16_f32 v34, v38, v39
	v_cvt_pk_bf16_f32 v35, v40, v41
	v_cvt_pk_bf16_f32 v36, v36, v37
	v_cvt_pk_bf16_f32 v37, v42, v43
	global_store_dwordx4 v[70:71], v[34:37], off offset:256
	v_add_u32_e32 v38, 0xb0, v165
	s_nop 0
	v_pk_fma_f32 v[36:37], v[140:141], s[4:5], v[150:151] op_sel_hi:[1,0,0]
	v_add_u32_e32 v34, 0xa0, v165
	v_mul_f32_e32 v39, 0x4b800000, v37
	v_cmp_gt_f32_e32 vcc, s96, v37
	v_mad_i64_i32 v[34:35], s[2:3], v34, s18, v[142:143]
	s_nop 0
	v_cndmask_b32_e32 v37, v37, v39, vcc
	v_rsq_f32_e32 v37, v37
	v_lshl_add_u64 v[34:35], v[34:35], 0, v[148:149]
	v_mad_i64_i32 v[38:39], s[2:3], v38, s18, v[142:143]
	v_mul_f32_e32 v40, 0x45800000, v37
	v_cndmask_b32_e32 v40, v37, v40, vcc
	v_pk_mul_f32 v[32:33], v[40:41], v[32:33] op_sel_hi:[0,1]
	v_pk_mul_f32 v[30:31], v[40:41], v[30:31] op_sel_hi:[0,1]
	v_pk_mul_f32 v[42:43], v[40:41], v[28:29] op_sel_hi:[0,1]
	v_pk_mul_f32 v[28:29], v[40:41], v[26:27] op_sel_hi:[0,1]
	v_cvt_pk_bf16_f32 v26, v30, v31
	v_cvt_pk_bf16_f32 v27, v32, v33
	v_pk_mul_f32 v[22:23], v[40:41], v[22:23] op_sel_hi:[0,1]
	v_cvt_pk_bf16_f32 v28, v28, v29
	v_cvt_pk_bf16_f32 v29, v42, v43
	global_store_dwordx4 v[34:35], v[26:29], off
	v_cmp_gt_f32_e32 vcc, s96, v36
	v_pk_mul_f32 v[24:25], v[40:41], v[24:25] op_sel_hi:[0,1]
	v_pk_mul_f32 v[26:27], v[40:41], v[20:21] op_sel_hi:[0,1]
	v_pk_mul_f32 v[20:21], v[40:41], v[18:19] op_sel_hi:[0,1]
	v_cvt_pk_bf16_f32 v18, v22, v23
	v_mul_f32_e32 v22, 0x4b800000, v36
	v_cndmask_b32_e32 v22, v36, v22, vcc
	v_rsq_f32_e32 v22, v22
	v_cvt_pk_bf16_f32 v19, v24, v25
	v_cvt_pk_bf16_f32 v20, v20, v21
	v_cvt_pk_bf16_f32 v21, v26, v27
	global_store_dwordx4 v[34:35], v[18:21], off offset:256
	v_lshl_add_u64 v[38:39], v[38:39], 0, v[148:149]
	s_mov_b64 s[2:3], -1
	v_mul_f32_e32 v18, 0x45800000, v22
	v_cndmask_b32_e32 v18, v22, v18, vcc
	v_pk_mul_f32 v[16:17], v[18:19], v[16:17] op_sel_hi:[0,1]
	v_pk_mul_f32 v[14:15], v[18:19], v[14:15] op_sel_hi:[0,1]
	v_pk_mul_f32 v[20:21], v[18:19], v[12:13] op_sel_hi:[0,1]
	v_pk_mul_f32 v[12:13], v[18:19], v[10:11] op_sel_hi:[0,1]
	v_cvt_pk_bf16_f32 v10, v14, v15
	v_cvt_pk_bf16_f32 v11, v16, v17
	v_cvt_pk_bf16_f32 v12, v12, v13
	v_cvt_pk_bf16_f32 v13, v20, v21
	global_store_dwordx4 v[38:39], v[10:13], off
	s_andn2_b64 vcc, exec, s[38:39]
	v_pk_mul_f32 v[8:9], v[18:19], v[8:9] op_sel_hi:[0,1]
	v_pk_mul_f32 v[10:11], v[18:19], v[4:5] op_sel_hi:[0,1]
	v_pk_mul_f32 v[4:5], v[18:19], v[2:3] op_sel_hi:[0,1]
	v_pk_mul_f32 v[6:7], v[18:19], v[6:7] op_sel_hi:[0,1]
	v_cvt_pk_bf16_f32 v2, v6, v7
	v_cvt_pk_bf16_f32 v3, v8, v9
	v_cvt_pk_bf16_f32 v4, v4, v5
	v_cvt_pk_bf16_f32 v5, v10, v11
	global_store_dwordx4 v[38:39], v[2:5], off offset:256
	s_cbranch_vccnz .LBB0_134
	s_nop 0
	v_lshl_add_u32 v2, s44, 8, v144
	v_ashrrev_i32_e32 v3, 31, v2
	v_lshl_add_u64 v[2:3], v[2:3], 3, s[34:35]
	global_load_dwordx2 v[158:159], v[2:3], off
	global_load_dwordx2 v[156:157], v[2:3], off offset:128
	global_load_dwordx2 v[154:155], v[2:3], off offset:256
	global_load_dwordx2 v[152:153], v[2:3], off offset:384
	global_load_dwordx2 v[150:151], v[2:3], off offset:1024
	global_load_dwordx2 v[148:149], v[2:3], off offset:1152
	global_load_dwordx2 v[142:143], v[2:3], off offset:1280
	global_load_dwordx2 v[140:141], v[2:3], off offset:1408
	s_andn2_b64 vcc, exec, s[20:21]
	s_cbranch_vccnz .LBB0_133
	s_barrier
	s_branch .LBB0_133

.LBB0_149:
	global_load_dwordx4 v[24:27], v[12:13], off offset:0
	global_load_dwordx4 v[28:31], v[16:17], off offset:0
	global_load_dwordx4 v[32:35], v[14:15], off offset:0
	global_load_dwordx4 v[36:39], v[12:13], off offset:64
	global_load_dwordx4 v[40:43], v[16:17], off offset:64
	global_load_dwordx4 v[44:47], v[14:15], off offset:64
	global_load_dwordx4 v[48:51], v[12:13], off offset:128
	global_load_dwordx4 v[52:55], v[16:17], off offset:128
	global_load_dwordx4 v[56:59], v[14:15], off offset:128
	global_load_dwordx4 v[60:63], v[12:13], off offset:192
	global_load_dwordx4 v[64:67], v[16:17], off offset:192
	global_load_dwordx4 v[68:71], v[14:15], off offset:192
	global_load_dwordx4 v[72:75], v[12:13], off offset:256
	global_load_dwordx4 v[76:79], v[16:17], off offset:256
	global_load_dwordx4 v[80:83], v[14:15], off offset:256
	global_load_dwordx4 v[84:87], v[12:13], off offset:320
	global_load_dwordx4 v[88:91], v[16:17], off offset:320
	global_load_dwordx4 v[92:95], v[14:15], off offset:320
	global_load_dwordx4 v[96:99], v[12:13], off offset:384
	global_load_dwordx4 v[100:103], v[16:17], off offset:384
	global_load_dwordx4 v[104:107], v[14:15], off offset:384
	global_load_dwordx4 v[108:111], v[12:13], off offset:448
	global_load_dwordx4 v[112:115], v[16:17], off offset:448
	global_load_dwordx4 v[116:119], v[14:15], off offset:448
	global_load_dwordx4 v[120:123], v[12:13], off offset:512
	global_load_dwordx4 v[124:127], v[16:17], off offset:512
	global_load_dwordx4 v[128:131], v[14:15], off offset:512
	global_load_dwordx4 v[132:135], v[12:13], off offset:576
	global_load_dwordx4 v[136:139], v[16:17], off offset:576
	global_load_dwordx4 v[140:143], v[14:15], off offset:576
	global_load_dwordx4 v[148:151], v[12:13], off offset:640
	global_load_dwordx4 v[152:155], v[16:17], off offset:640
	global_load_dwordx4 v[156:159], v[14:15], off offset:640
	global_load_dwordx4 v[160:163], v[12:13], off offset:704
	global_load_dwordx4 v[164:167], v[16:17], off offset:704
	global_load_dwordx4 v[184:187], v[14:15], off offset:704
	global_load_dwordx4 v[188:191], v[12:13], off offset:768
	global_load_dwordx4 v[192:195], v[16:17], off offset:768
	global_load_dwordx4 v[196:199], v[14:15], off offset:768
	global_load_dwordx4 v[200:203], v[12:13], off offset:832
	global_load_dwordx4 v[204:207], v[16:17], off offset:832
	global_load_dwordx4 v[208:211], v[14:15], off offset:832
	global_load_dwordx4 v[212:215], v[12:13], off offset:896
	global_load_dwordx4 v[216:219], v[16:17], off offset:896
	global_load_dwordx4 v[224:227], v[14:15], off offset:896
	global_load_dwordx4 v[228:231], v[12:13], off offset:960
	global_load_dwordx4 v[232:235], v[16:17], off offset:960
	global_load_dwordx4 v[236:239], v[14:15], off offset:960
	s_waitcnt vmcnt(24)
	v_mfma_f32_16x16x32_bf16 v[2:5], v[24:27], v[32:35], v[2:5]
	v_mfma_f32_16x16x32_bf16 v[6:9], v[28:31], v[32:35], v[6:9]
	v_mfma_f32_16x16x32_bf16 v[2:5], v[36:39], v[44:47], v[2:5]
	v_mfma_f32_16x16x32_bf16 v[6:9], v[40:43], v[44:47], v[6:9]
	v_mfma_f32_16x16x32_bf16 v[2:5], v[48:51], v[56:59], v[2:5]
	v_mfma_f32_16x16x32_bf16 v[6:9], v[52:55], v[56:59], v[6:9]
	v_mfma_f32_16x16x32_bf16 v[2:5], v[60:63], v[68:71], v[2:5]
	v_mfma_f32_16x16x32_bf16 v[6:9], v[64:67], v[68:71], v[6:9]
	v_mfma_f32_16x16x32_bf16 v[2:5], v[72:75], v[80:83], v[2:5]
	v_mfma_f32_16x16x32_bf16 v[6:9], v[76:79], v[80:83], v[6:9]
	v_mfma_f32_16x16x32_bf16 v[2:5], v[84:87], v[92:95], v[2:5]
	v_mfma_f32_16x16x32_bf16 v[6:9], v[88:91], v[92:95], v[6:9]
	v_mfma_f32_16x16x32_bf16 v[2:5], v[96:99], v[104:107], v[2:5]
	v_mfma_f32_16x16x32_bf16 v[6:9], v[100:103], v[104:107], v[6:9]
	v_mfma_f32_16x16x32_bf16 v[2:5], v[108:111], v[116:119], v[2:5]
	v_mfma_f32_16x16x32_bf16 v[6:9], v[112:115], v[116:119], v[6:9]
	global_load_dwordx4 v[24:27], v[12:13], off offset:1024
	global_load_dwordx4 v[28:31], v[16:17], off offset:1024
	global_load_dwordx4 v[32:35], v[14:15], off offset:1024
	global_load_dwordx4 v[36:39], v[12:13], off offset:1088
	global_load_dwordx4 v[40:43], v[16:17], off offset:1088
	global_load_dwordx4 v[44:47], v[14:15], off offset:1088
	global_load_dwordx4 v[48:51], v[12:13], off offset:1152
	global_load_dwordx4 v[52:55], v[16:17], off offset:1152
	global_load_dwordx4 v[56:59], v[14:15], off offset:1152
	global_load_dwordx4 v[60:63], v[12:13], off offset:1216
	global_load_dwordx4 v[64:67], v[16:17], off offset:1216
	global_load_dwordx4 v[68:71], v[14:15], off offset:1216
	global_load_dwordx4 v[72:75], v[12:13], off offset:1280
	global_load_dwordx4 v[76:79], v[16:17], off offset:1280
	global_load_dwordx4 v[80:83], v[14:15], off offset:1280
	global_load_dwordx4 v[84:87], v[12:13], off offset:1344
	global_load_dwordx4 v[88:91], v[16:17], off offset:1344
	global_load_dwordx4 v[92:95], v[14:15], off offset:1344
	global_load_dwordx4 v[96:99], v[12:13], off offset:1408
	global_load_dwordx4 v[100:103], v[16:17], off offset:1408
	global_load_dwordx4 v[104:107], v[14:15], off offset:1408
	global_load_dwordx4 v[108:111], v[12:13], off offset:1472
	global_load_dwordx4 v[112:115], v[16:17], off offset:1472
	global_load_dwordx4 v[116:119], v[14:15], off offset:1472
	s_waitcnt vmcnt(24)
	v_mfma_f32_16x16x32_bf16 v[2:5], v[120:123], v[128:131], v[2:5]
	v_mfma_f32_16x16x32_bf16 v[6:9], v[124:127], v[128:131], v[6:9]
	v_mfma_f32_16x16x32_bf16 v[2:5], v[132:135], v[140:143], v[2:5]
	v_mfma_f32_16x16x32_bf16 v[6:9], v[136:139], v[140:143], v[6:9]
	v_mfma_f32_16x16x32_bf16 v[2:5], v[148:151], v[156:159], v[2:5]
	v_mfma_f32_16x16x32_bf16 v[6:9], v[152:155], v[156:159], v[6:9]
	v_mfma_f32_16x16x32_bf16 v[2:5], v[160:163], v[184:187], v[2:5]
	v_mfma_f32_16x16x32_bf16 v[6:9], v[164:167], v[184:187], v[6:9]
	v_mfma_f32_16x16x32_bf16 v[2:5], v[188:191], v[196:199], v[2:5]
	v_mfma_f32_16x16x32_bf16 v[6:9], v[192:195], v[196:199], v[6:9]
	v_mfma_f32_16x16x32_bf16 v[2:5], v[200:203], v[208:211], v[2:5]
	v_mfma_f32_16x16x32_bf16 v[6:9], v[204:207], v[208:211], v[6:9]
	v_mfma_f32_16x16x32_bf16 v[2:5], v[212:215], v[224:227], v[2:5]
	v_mfma_f32_16x16x32_bf16 v[6:9], v[216:219], v[224:227], v[6:9]
	v_mfma_f32_16x16x32_bf16 v[2:5], v[228:231], v[236:239], v[2:5]
	v_mfma_f32_16x16x32_bf16 v[6:9], v[232:235], v[236:239], v[6:9]
	global_load_dwordx4 v[120:123], v[12:13], off offset:1536
	global_load_dwordx4 v[124:127], v[16:17], off offset:1536
	global_load_dwordx4 v[128:131], v[14:15], off offset:1536
	global_load_dwordx4 v[132:135], v[12:13], off offset:1600
	global_load_dwordx4 v[136:139], v[16:17], off offset:1600
	global_load_dwordx4 v[140:143], v[14:15], off offset:1600
	global_load_dwordx4 v[148:151], v[12:13], off offset:1664
	global_load_dwordx4 v[152:155], v[16:17], off offset:1664
	global_load_dwordx4 v[156:159], v[14:15], off offset:1664
	global_load_dwordx4 v[160:163], v[12:13], off offset:1728
	global_load_dwordx4 v[164:167], v[16:17], off offset:1728
	global_load_dwordx4 v[184:187], v[14:15], off offset:1728
	global_load_dwordx4 v[188:191], v[12:13], off offset:1792
	global_load_dwordx4 v[192:195], v[16:17], off offset:1792
	global_load_dwordx4 v[196:199], v[14:15], off offset:1792
	global_load_dwordx4 v[200:203], v[12:13], off offset:1856
	global_load_dwordx4 v[204:207], v[16:17], off offset:1856
	global_load_dwordx4 v[208:211], v[14:15], off offset:1856
	global_load_dwordx4 v[212:215], v[12:13], off offset:1920
	global_load_dwordx4 v[216:219], v[16:17], off offset:1920
	global_load_dwordx4 v[224:227], v[14:15], off offset:1920
	global_load_dwordx4 v[228:231], v[12:13], off offset:1984
	global_load_dwordx4 v[232:235], v[16:17], off offset:1984
	global_load_dwordx4 v[236:239], v[14:15], off offset:1984
	s_waitcnt vmcnt(24)
	v_mfma_f32_16x16x32_bf16 v[2:5], v[24:27], v[32:35], v[2:5]
	v_mfma_f32_16x16x32_bf16 v[6:9], v[28:31], v[32:35], v[6:9]
	v_mfma_f32_16x16x32_bf16 v[2:5], v[36:39], v[44:47], v[2:5]
	v_mfma_f32_16x16x32_bf16 v[6:9], v[40:43], v[44:47], v[6:9]
	v_mfma_f32_16x16x32_bf16 v[2:5], v[48:51], v[56:59], v[2:5]
	v_mfma_f32_16x16x32_bf16 v[6:9], v[52:55], v[56:59], v[6:9]
	v_mfma_f32_16x16x32_bf16 v[2:5], v[60:63], v[68:71], v[2:5]
	v_mfma_f32_16x16x32_bf16 v[6:9], v[64:67], v[68:71], v[6:9]
	v_mfma_f32_16x16x32_bf16 v[2:5], v[72:75], v[80:83], v[2:5]
	v_mfma_f32_16x16x32_bf16 v[6:9], v[76:79], v[80:83], v[6:9]
	v_mfma_f32_16x16x32_bf16 v[2:5], v[84:87], v[92:95], v[2:5]
	v_mfma_f32_16x16x32_bf16 v[6:9], v[88:91], v[92:95], v[6:9]
	v_mfma_f32_16x16x32_bf16 v[2:5], v[96:99], v[104:107], v[2:5]
	v_mfma_f32_16x16x32_bf16 v[6:9], v[100:103], v[104:107], v[6:9]
	v_mfma_f32_16x16x32_bf16 v[2:5], v[108:111], v[116:119], v[2:5]
	v_mfma_f32_16x16x32_bf16 v[6:9], v[112:115], v[116:119], v[6:9]
	s_waitcnt vmcnt(0)
	v_mfma_f32_16x16x32_bf16 v[2:5], v[120:123], v[128:131], v[2:5]
	v_mfma_f32_16x16x32_bf16 v[6:9], v[124:127], v[128:131], v[6:9]
	v_mfma_f32_16x16x32_bf16 v[2:5], v[132:135], v[140:143], v[2:5]
	v_mfma_f32_16x16x32_bf16 v[6:9], v[136:139], v[140:143], v[6:9]
	v_mfma_f32_16x16x32_bf16 v[2:5], v[148:151], v[156:159], v[2:5]
	v_mfma_f32_16x16x32_bf16 v[6:9], v[152:155], v[156:159], v[6:9]
	v_mfma_f32_16x16x32_bf16 v[2:5], v[160:163], v[184:187], v[2:5]
	v_mfma_f32_16x16x32_bf16 v[6:9], v[164:167], v[184:187], v[6:9]
	v_mfma_f32_16x16x32_bf16 v[2:5], v[188:191], v[196:199], v[2:5]
	v_mfma_f32_16x16x32_bf16 v[6:9], v[192:195], v[196:199], v[6:9]
	v_mfma_f32_16x16x32_bf16 v[2:5], v[200:203], v[208:211], v[2:5]
	v_mfma_f32_16x16x32_bf16 v[6:9], v[204:207], v[208:211], v[6:9]
	v_mfma_f32_16x16x32_bf16 v[2:5], v[212:215], v[224:227], v[2:5]
	v_mfma_f32_16x16x32_bf16 v[6:9], v[216:219], v[224:227], v[6:9]
	v_mfma_f32_16x16x32_bf16 v[2:5], v[228:231], v[236:239], v[2:5]
	v_mfma_f32_16x16x32_bf16 v[6:9], v[232:235], v[236:239], v[6:9]
	v_lshl_add_u64 v[12:13], v[10:11], 3, s[34:35]
	global_load_dwordx2 v[12:13], v[12:13], off
	v_mov_b64_e32 v[14:15], s[26:27]
	s_waitcnt vmcnt(0) lgkmcnt(0)
	v_ffbh_u32_e32 v0, v13
	v_min_u32_e32 v0, 32, v0
	v_lshlrev_b64 v[12:13], v0, v[12:13]
	v_min_u32_e32 v11, 1, v12
	v_or_b32_e32 v11, v13, v11
	v_cvt_f32_u32_e32 v11, v11
	v_sub_u32_e32 v0, 32, v0
	v_ldexp_f32 v0, v11, v0
	v_mul_f32_e32 v0, 0x35800000, v0
	v_fmamk_f32 v0, v0, 0x3a800000, v173
	v_cmp_gt_f32_e32 vcc, s96, v0
	v_mul_f32_e32 v11, 0x4b800000, v0
	s_nop 0
	v_cndmask_b32_e32 v0, v0, v11, vcc
	v_rsq_f32_e32 v0, v0
	s_nop 0
	v_mul_f32_e32 v11, 0x45800000, v0
	v_cndmask_b32_e32 v12, v0, v11, vcc
	v_mad_i64_i32 v[10:11], s[2:3], v10, s18, v[14:15]
	v_lshlrev_b32_e32 v0, 3, v23
	v_lshl_add_u64 v[10:11], v[10:11], 0, v[0:1]
	v_pk_mul_f32 v[2:3], v[2:3], v[12:13] op_sel_hi:[1,0]
	v_pk_mul_f32 v[4:5], v[4:5], v[12:13] op_sel_hi:[1,0]
	v_cvt_pk_bf16_f32 v2, v2, v3
	v_cvt_pk_bf16_f32 v3, v4, v5
	v_add_co_u32_e32 v4, vcc, 0x1000, v10
	s_nop 1
	v_addc_co_u32_e32 v5, vcc, 0, v11, vcc
	v_cmp_gt_u32_e32 vcc, 32, v22
	global_store_dwordx2 v[4:5], v[2:3], off offset:3072
	s_and_saveexec_b64 s[2:3], vcc
	s_cbranch_execz .LBB0_147
	v_mov_b32_e32 v13, v12
	s_mov_b64 s[4:5], 0x1c00
	v_pk_mul_f32 v[4:5], v[6:7], v[12:13]
	v_pk_mul_f32 v[6:7], v[8:9], v[12:13]
	v_lshl_add_u64 v[2:3], v[10:11], 0, s[4:5]
	v_cvt_pk_bf16_f32 v4, v4, v5
	v_cvt_pk_bf16_f32 v5, v6, v7
	global_store_dwordx2 v[2:3], v[4:5], off offset:32
	s_branch .LBB0_147

.LBB0_165:
	s_cmpk_lt_u32 s85, 0x400
	s_cbranch_scc1 .LBB0_173
	s_add_i32 s2, s85, 0xfffffc00
	s_lshl_b32 s42, s2, 2
	s_lshl_b32 s7, s2, 6
	s_mov_b32 s2, 7
	s_ashr_i32 s3, s2, 31
	s_lshl_b64 s[2:3], s[2:3], 3
	s_add_u32 s2, s0, s2
	s_addc_u32 s3, s1, s3
	s_load_dwordx2 s[2:3], s[2:3], 0x0
	s_mov_b32 s10, 8
	v_mov_b32_e32 v109, v183
	v_mov_b32_e32 v66, v1
	s_waitcnt lgkmcnt(0)
	s_add_u32 s40, s2, s92
	s_addc_u32 s41, s3, s93
	s_ashr_i32 s11, s10, 31
	s_lshl_b64 s[2:3], s[10:11], 3
	s_add_u32 s2, s0, s2
	s_addc_u32 s3, s1, s3
	s_load_dwordx2 s[2:3], s[2:3], 0x0
	s_lshl_b64 s[68:69], s[34:35], 2
	s_mov_b32 s10, 9
	v_mov_b32_e32 v83, v1
	s_waitcnt lgkmcnt(0)
	s_add_u32 s38, s2, s68
	s_addc_u32 s39, s3, s69
	s_ashr_i32 s11, s10, 31
	s_lshl_b64 s[2:3], s[10:11], 3
	s_add_u32 s2, s0, s2
	s_addc_u32 s3, s1, s3
	s_load_dwordx2 s[20:21], s[2:3], 0x0
	v_readlane_b32 s2, v254, 56
	s_waitcnt lgkmcnt(0)
	v_readfirstlane_b32 s11, v109
	s_bitcmp1_b32 s11, 8
	s_cselect_b32 s3, 64, 0
	s_xor_b32 s11, s11, s3
	v_mov_b32_e32 v85, s2
	v_readlane_b32 s2, v254, 57
	s_ashr_i32 s10, s11, 7
	s_ashr_i32 s6, s11, 6
	v_mov_b32_e32 v87, s2
	s_add_i32 s2, 0, 0x1b000
	v_mov_b32_e32 v189, s2
	v_readlane_b32 s2, v254, 58
	v_lshrrev_b32_e32 v0, 1, v109
	v_and_b32_e32 v0, 16, v0
	v_mov_b32_e32 v187, s2
	s_add_i32 s2, s10, s42
	s_ashr_i32 s3, s2, 31
	s_lshl_b64 s[2:3], s[2:3], 13
	v_readlane_b32 s42, v254, 3
	v_readlane_b32 s43, v254, 4
	s_add_u32 s2, s42, s2
	s_addc_u32 s3, s43, s3
	v_lshl_add_u64 v[2:3], s[2:3], 0, v[0:1]
	v_lshlrev_b32_e32 v0, 7, v109
	v_and_b32_e32 v0, 0xf80, v0
	v_and_b32_e32 v84, 63, v109
	v_lshl_add_u64 v[4:5], v[2:3], 0, v[0:1]
	v_mov_b32_e32 v0, 0x1000
	v_lshl_or_b32 v0, v84, 7, v0
	v_lshl_add_u64 v[2:3], v[2:3], 0, v[0:1]
	v_ashrrev_i32_e32 v160, 8, v109
	s_barrier
	global_load_dwordx4 v[62:65], v[4:5], off
	global_load_dwordx4 v[58:61], v[4:5], off offset:32
	global_load_dwordx4 v[54:57], v[4:5], off offset:64
	global_load_dwordx4 v[50:53], v[4:5], off offset:96
	global_load_dwordx4 v[46:49], v[2:3], off
	global_load_dwordx4 v[42:45], v[2:3], off offset:32
	global_load_dwordx4 v[38:41], v[2:3], off offset:64
	global_load_dwordx4 v[34:37], v[2:3], off offset:96
	v_lshl_add_u32 v30, v160, 5, s7
	v_mov_b64_e32 v[2:3], s[26:27]
	v_mad_i64_i32 v[4:5], s[2:3], v30, s18, v[2:3]
	v_lshlrev_b32_sdwa v0, v180, v109 dst_sel:DWORD dst_unused:UNUSED_PAD src0_sel:DWORD src1_sel:BYTE_0
	v_or_b32_e32 v6, 1, v30
	v_or_b32_e32 v8, 2, v30
	v_lshl_add_u64 v[4:5], v[4:5], 0, v[0:1]
	v_mad_i64_i32 v[6:7], s[2:3], v6, s18, v[2:3]
	v_mad_i64_i32 v[8:9], s[2:3], v8, s18, v[2:3]
	v_lshl_add_u64 v[6:7], v[6:7], 0, v[0:1]
	v_lshl_add_u64 v[8:9], v[8:9], 0, v[0:1]
	global_load_ushort v185, v[4:5], off
	global_load_ushort v169, v[4:5], off offset:512
	global_load_ushort v168, v[4:5], off offset:1024
	global_load_ushort v161, v[6:7], off
	s_nop 0
	global_load_ushort v156, v[6:7], off offset:512
	global_load_ushort v155, v[6:7], off offset:1024
	global_load_ushort v148, v[8:9], off
	global_load_ushort v144, v[8:9], off offset:512
	v_or_b32_e32 v4, 3, v30
	v_mad_i64_i32 v[4:5], s[2:3], v4, s18, v[2:3]
	v_or_b32_e32 v6, 4, v30
	v_or_b32_e32 v10, 5, v30
	v_lshl_add_u64 v[4:5], v[4:5], 0, v[0:1]
	v_mad_i64_i32 v[6:7], s[2:3], v6, s18, v[2:3]
	v_mad_i64_i32 v[10:11], s[2:3], v10, s18, v[2:3]
	v_lshl_add_u64 v[6:7], v[6:7], 0, v[0:1]
	v_lshl_add_u64 v[10:11], v[10:11], 0, v[0:1]
	global_load_ushort v163, v[8:9], off offset:1024
	global_load_ushort v152, v[4:5], off
	global_load_ushort v151, v[4:5], off offset:512
	global_load_ushort v150, v[4:5], off offset:1024
	global_load_ushort v141, v[6:7], off
	global_load_ushort v139, v[6:7], off offset:512
	global_load_ushort v137, v[6:7], off offset:1024
	global_load_ushort v132, v[10:11], off
	v_or_b32_e32 v4, 6, v30
	v_mad_i64_i32 v[4:5], s[2:3], v4, s18, v[2:3]
	v_or_b32_e32 v6, 7, v30
	v_lshl_add_u64 v[4:5], v[4:5], 0, v[0:1]
	v_mad_i64_i32 v[6:7], s[2:3], v6, s18, v[2:3]
	v_lshl_add_u64 v[6:7], v[6:7], 0, v[0:1]
	global_load_ushort v140, v[10:11], off offset:512
	global_load_ushort v138, v[10:11], off offset:1024
	global_load_ushort v133, v[4:5], off
	global_load_ushort v131, v[4:5], off offset:512
	global_load_ushort v130, v[4:5], off offset:1024
	global_load_ushort v126, v[6:7], off
	global_load_ushort v124, v[6:7], off offset:512
	global_load_ushort v123, v[6:7], off offset:1024
	v_or_b32_e32 v4, 8, v30
	v_mad_i64_i32 v[4:5], s[2:3], v4, s18, v[2:3]
	v_or_b32_e32 v6, 9, v30
	v_or_b32_e32 v8, 10, v30
	v_lshl_add_u64 v[4:5], v[4:5], 0, v[0:1]
	v_mad_i64_i32 v[6:7], s[2:3], v6, s18, v[2:3]
	v_mad_i64_i32 v[8:9], s[2:3], v8, s18, v[2:3]
	v_lshl_add_u64 v[6:7], v[6:7], 0, v[0:1]
	v_lshl_add_u64 v[8:9], v[8:9], 0, v[0:1]
	global_load_ushort v122, v[4:5], off
	global_load_ushort v120, v[4:5], off offset:512
	global_load_ushort v119, v[4:5], off offset:1024
	global_load_ushort v113, v[6:7], off
	global_load_ushort v112, v[6:7], off offset:512
	global_load_ushort v111, v[6:7], off offset:1024
	global_load_ushort v101, v[8:9], off
	global_load_ushort v100, v[8:9], off offset:512
	v_or_b32_e32 v4, 11, v30
	v_mad_i64_i32 v[4:5], s[2:3], v4, s18, v[2:3]
	v_or_b32_e32 v6, 12, v30
	v_or_b32_e32 v10, 13, v30
	v_lshl_add_u64 v[4:5], v[4:5], 0, v[0:1]
	v_mad_i64_i32 v[6:7], s[2:3], v6, s18, v[2:3]
	v_mad_i64_i32 v[10:11], s[2:3], v10, s18, v[2:3]
	v_lshl_add_u64 v[6:7], v[6:7], 0, v[0:1]
	v_lshl_add_u64 v[10:11], v[10:11], 0, v[0:1]
	global_load_ushort v114, v[8:9], off offset:1024
	global_load_ushort v106, v[4:5], off
	global_load_ushort v103, v[4:5], off offset:512
	global_load_ushort v102, v[4:5], off offset:1024
	global_load_ushort v96, v[6:7], off
	global_load_ushort v92, v[6:7], off offset:512
	global_load_ushort v90, v[6:7], off offset:1024
	global_load_ushort v81, v[10:11], off
	v_or_b32_e32 v4, 14, v30
	v_mad_i64_i32 v[4:5], s[2:3], v4, s18, v[2:3]
	v_or_b32_e32 v6, 15, v30
	v_lshl_add_u64 v[4:5], v[4:5], 0, v[0:1]
	v_mad_i64_i32 v[6:7], s[2:3], v6, s18, v[2:3]
	v_lshl_add_u64 v[6:7], v[6:7], 0, v[0:1]
	global_load_ushort v94, v[10:11], off offset:512
	global_load_ushort v91, v[10:11], off offset:1024
	global_load_ushort v86, v[4:5], off
	global_load_ushort v79, v[4:5], off offset:512
	global_load_ushort v78, v[4:5], off offset:1024
	global_load_ushort v77, v[6:7], off
	global_load_ushort v76, v[6:7], off offset:512
	global_load_ushort v75, v[6:7], off offset:1024
	v_or_b32_e32 v4, 16, v30
	v_mad_i64_i32 v[4:5], s[2:3], v4, s18, v[2:3]
	v_or_b32_e32 v6, 17, v30
	v_or_b32_e32 v8, 18, v30
	v_lshl_add_u64 v[4:5], v[4:5], 0, v[0:1]
	v_mad_i64_i32 v[6:7], s[2:3], v6, s18, v[2:3]
	v_mad_i64_i32 v[8:9], s[2:3], v8, s18, v[2:3]
	v_lshl_add_u64 v[6:7], v[6:7], 0, v[0:1]
	v_lshl_add_u64 v[8:9], v[8:9], 0, v[0:1]
	global_load_ushort v74, v[4:5], off
	global_load_ushort v73, v[4:5], off offset:512
	global_load_ushort v72, v[4:5], off offset:1024
	global_load_ushort v71, v[6:7], off
	global_load_ushort v70, v[6:7], off offset:512
	global_load_ushort v69, v[6:7], off offset:1024
	global_load_ushort v68, v[8:9], off
	global_load_ushort v67, v[8:9], off offset:512
	v_or_b32_e32 v4, 19, v30
	v_mad_i64_i32 v[4:5], s[2:3], v4, s18, v[2:3]
	v_lshl_add_u64 v[10:11], v[4:5], 0, v[0:1]
	v_or_b32_e32 v4, 20, v30
	v_mad_i64_i32 v[4:5], s[2:3], v4, s18, v[2:3]
	v_lshl_add_u64 v[12:13], v[4:5], 0, v[0:1]
	v_or_b32_e32 v4, 21, v30
	v_and_b32_e32 v89, 31, v109
	v_mad_i64_i32 v[4:5], s[2:3], v4, s18, v[2:3]
	v_bfe_u32 v93, v109, 5, 1
	v_or_b32_e32 v16, s7, v89
	v_lshl_add_u64 v[14:15], v[4:5], 0, v[0:1]
	v_mad_i64_i32 v[4:5], s[2:3], v16, s18, v[2:3]
	v_lshlrev_b32_e32 v82, 4, v93
	v_lshl_add_u64 v[4:5], v[4:5], 0, v[82:83]
	s_movk_i32 s42, 0x1000
	v_add_co_u32_e32 v4, vcc, s42, v4
	v_lshl_or_b32 v190, s6, 5, v89
	s_nop 0
	v_addc_co_u32_e32 v5, vcc, 0, v5, vcc
	global_load_dwordx4 v[4:7], v[4:5], off offset:3072
	v_lshl_add_u32 v18, v93, 11, v190
	v_or_b32_e32 v16, 32, v16
	v_ashrrev_i32_e32 v19, 31, v18
	v_mad_i64_i32 v[16:17], s[2:3], v16, s18, v[2:3]
	v_lshl_add_u64 v[20:21], v[18:19], 2, s[40:41]
	v_add_u32_e32 v22, 0x400, v18
	v_add_u32_e32 v24, 0x500, v18
	v_add_u32_e32 v26, 0x600, v18
	v_add_u32_e32 v18, 0x700, v18
	v_lshl_add_u64 v[16:17], v[16:17], 0, v[82:83]
	v_ashrrev_i32_e32 v25, 31, v24
	v_ashrrev_i32_e32 v19, 31, v18
	v_add_co_u32_e32 v16, vcc, s42, v16
	v_ashrrev_i32_e32 v23, 31, v22
	v_lshl_add_u64 v[24:25], v[24:25], 2, s[40:41]
	v_ashrrev_i32_e32 v27, 31, v26
	v_lshl_add_u64 v[18:19], v[18:19], 2, s[40:41]
	v_ashrrev_i32_e32 v191, 31, v190
	v_addc_co_u32_e32 v17, vcc, 0, v17, vcc
	v_lshl_add_u64 v[22:23], v[22:23], 2, s[40:41]
	v_lshl_add_u64 v[26:27], v[26:27], 2, s[40:41]
	global_load_dword v32, v[20:21], off
	global_load_dword v33, v[20:21], off offset:1024
	global_load_dword v80, v[20:21], off offset:2048
	global_load_dword v83, v[20:21], off offset:3072
	global_load_dword v88, v[22:23], off
	s_nop 0
	global_load_dword v24, v[24:25], off
	s_nop 0
	global_load_dword v25, v[26:27], off
	global_load_dword v95, v[18:19], off
	s_nop 0
	global_load_dwordx4 v[18:21], v[16:17], off offset:3072
	global_load_ushort v186, v[8:9], off offset:1024
	global_load_ushort v184, v[10:11], off
	global_load_ushort v167, v[10:11], off offset:512
	global_load_ushort v166, v[10:11], off offset:1024
	global_load_ushort v162, v[12:13], off
	global_load_ushort v159, v[12:13], off offset:512
	global_load_ushort v157, v[12:13], off offset:1024
	global_load_ushort v149, v[14:15], off
	v_lshl_add_u64 v[8:9], v[190:191], 2, s[38:39]
	global_load_dword v188, v[8:9], off
	v_or_b32_e32 v10, 22, v30
	v_mad_i64_i32 v[8:9], s[2:3], v10, s18, v[2:3]
	v_or_b32_e32 v10, 23, v30
	v_lshl_add_u64 v[8:9], v[8:9], 0, v[0:1]
	v_mad_i64_i32 v[10:11], s[2:3], v10, s18, v[2:3]
	v_lshl_add_u64 v[10:11], v[10:11], 0, v[0:1]
	global_load_ushort v165, v[14:15], off offset:512
	global_load_ushort v164, v[14:15], off offset:1024
	global_load_ushort v158, v[8:9], off
	global_load_ushort v154, v[8:9], off offset:512
	global_load_ushort v153, v[8:9], off offset:1024
	global_load_ushort v147, v[10:11], off
	global_load_ushort v143, v[10:11], off offset:512
	global_load_ushort v142, v[10:11], off offset:1024
	v_or_b32_e32 v8, 24, v30
	v_mad_i64_i32 v[8:9], s[2:3], v8, s18, v[2:3]
	v_or_b32_e32 v10, 25, v30
	v_or_b32_e32 v12, 26, v30
	v_lshl_add_u64 v[8:9], v[8:9], 0, v[0:1]
	v_mad_i64_i32 v[10:11], s[2:3], v10, s18, v[2:3]
	v_mad_i64_i32 v[12:13], s[2:3], v12, s18, v[2:3]
	v_lshl_add_u64 v[10:11], v[10:11], 0, v[0:1]
	v_lshl_add_u64 v[12:13], v[12:13], 0, v[0:1]
	global_load_ushort v136, v[8:9], off
	global_load_ushort v135, v[8:9], off offset:512
	global_load_ushort v134, v[8:9], off offset:1024
	global_load_ushort v129, v[10:11], off
	global_load_ushort v128, v[10:11], off offset:512
	global_load_ushort v127, v[10:11], off offset:1024
	global_load_ushort v121, v[12:13], off
	global_load_ushort v117, v[12:13], off offset:512
	v_or_b32_e32 v8, 27, v30
	v_mad_i64_i32 v[8:9], s[2:3], v8, s18, v[2:3]
	v_or_b32_e32 v10, 28, v30
	v_or_b32_e32 v14, 29, v30
	v_lshl_add_u64 v[8:9], v[8:9], 0, v[0:1]
	v_mad_i64_i32 v[10:11], s[2:3], v10, s18, v[2:3]
	v_mad_i64_i32 v[14:15], s[2:3], v14, s18, v[2:3]
	v_lshl_add_u64 v[10:11], v[10:11], 0, v[0:1]
	v_lshl_add_u64 v[26:27], v[14:15], 0, v[0:1]
	global_load_ushort v125, v[12:13], off offset:1024
	global_load_ushort v118, v[8:9], off
	global_load_ushort v116, v[8:9], off offset:512
	global_load_ushort v115, v[8:9], off offset:1024
	global_load_ushort v110, v[10:11], off
	global_load_ushort v107, v[10:11], off offset:512
	global_load_ushort v104, v[10:11], off offset:1024
	global_load_ushort v98, v[26:27], off
	v_or_b32_e32 v8, 30, v30
	v_mad_i64_i32 v[8:9], s[2:3], v8, s18, v[2:3]
	v_lshl_add_u64 v[28:29], v[8:9], 0, v[0:1]
	v_or_b32_e32 v8, 31, v30
	v_mad_i64_i32 v[2:3], s[2:3], v8, s18, v[2:3]
	v_lshl_add_u64 v[30:31], v[2:3], 0, v[0:1]
	v_lshlrev_b32_e32 v190, 1, v190
	v_mul_u32_u24_e32 v191, 0x840, v93
	v_add3_u32 v192, v189, v190, v191
	s_mov_b32 s2, 0x3d800000
	s_waitcnt vmcnt(0)
	v_cvt_pk_bf16_f32 v22, v32, v33
	v_cvt_pk_bf16_f32 v23, v80, v83
	v_cvt_pk_bf16_f32 v24, v88, v24
	v_cvt_pk_bf16_f32 v25, v25, v95
	global_load_ushort v108, v[26:27], off offset:512
	global_load_ushort v105, v[26:27], off offset:1024
	global_load_ushort v99, v[28:29], off
	global_load_ushort v97, v[28:29], off offset:512
	global_load_ushort v95, v[28:29], off offset:1024
	global_load_ushort v88, v[30:31], off
	global_load_ushort v83, v[30:31], off offset:512
	global_load_ushort v80, v[30:31], off offset:1024
	s_waitcnt lgkmcnt(0)
	v_mfma_f32_32x32x16_bf16 v[2:17], v[4:7], v[22:25], 0
	v_mfma_f32_32x32x16_bf16 v[18:33], v[18:21], v[22:25], 0
	s_nop 10
	v_add_f32_e32 v2, v188, v2
	v_cvt_pk_bf16_f32 v2, v2, s0
	ds_write_b16 v192, v2
	v_add_f32_e32 v2, v188, v18
	v_cvt_pk_bf16_f32 v2, v2, s0
	v_add3_u32 v18, v189, v191, v190
	ds_write_b16 v18, v2 offset:16896
	v_add_f32_e32 v2, v188, v3
	v_cvt_pk_bf16_f32 v2, v2, s0
	ds_write_b16 v192, v2 offset:528
	v_add_f32_e32 v2, v188, v19
	v_cvt_pk_bf16_f32 v2, v2, s0
	ds_write_b16 v18, v2 offset:17424
	v_add_f32_e32 v2, v188, v4
	v_cvt_pk_bf16_f32 v2, v2, s0
	ds_write_b16 v192, v2 offset:1056
	v_add_f32_e32 v2, v188, v20
	v_cvt_pk_bf16_f32 v2, v2, s0
	ds_write_b16 v18, v2 offset:17952
	v_add_f32_e32 v2, v188, v5
	v_cvt_pk_bf16_f32 v2, v2, s0
	ds_write_b16 v192, v2 offset:1584
	v_add_f32_e32 v2, v188, v21
	v_cvt_pk_bf16_f32 v2, v2, s0
	ds_write_b16 v18, v2 offset:18480
	v_add_f32_e32 v2, v188, v6
	v_cvt_pk_bf16_f32 v2, v2, s0
	ds_write_b16 v192, v2 offset:4224
	v_add_f32_e32 v2, v188, v22
	v_cvt_pk_bf16_f32 v2, v2, s0
	ds_write_b16 v18, v2 offset:21120
	v_add_f32_e32 v2, v188, v7
	v_cvt_pk_bf16_f32 v2, v2, s0
	ds_write_b16 v192, v2 offset:4752
	v_add_f32_e32 v2, v188, v23
	v_cvt_pk_bf16_f32 v2, v2, s0
	ds_write_b16 v18, v2 offset:21648
	v_add_f32_e32 v2, v188, v8
	v_cvt_pk_bf16_f32 v2, v2, s0
	ds_write_b16 v192, v2 offset:5280
	v_add_f32_e32 v2, v188, v24
	v_cvt_pk_bf16_f32 v2, v2, s0
	ds_write_b16 v18, v2 offset:22176
	v_add_f32_e32 v2, v188, v9
	v_cvt_pk_bf16_f32 v2, v2, s0
	ds_write_b16 v192, v2 offset:5808
	v_add_f32_e32 v2, v188, v25
	v_cvt_pk_bf16_f32 v2, v2, s0
	ds_write_b16 v18, v2 offset:22704
	v_add_f32_e32 v2, v188, v10
	v_cvt_pk_bf16_f32 v2, v2, s0
	ds_write_b16 v192, v2 offset:8448
	v_add_f32_e32 v2, v188, v26
	v_cvt_pk_bf16_f32 v2, v2, s0
	ds_write_b16 v18, v2 offset:25344
	v_add_f32_e32 v2, v188, v11
	v_cvt_pk_bf16_f32 v2, v2, s0
	ds_write_b16 v192, v2 offset:8976
	v_add_f32_e32 v2, v188, v27
	v_cvt_pk_bf16_f32 v2, v2, s0
	ds_write_b16 v18, v2 offset:25872
	v_add_f32_e32 v2, v188, v12
	v_cvt_pk_bf16_f32 v2, v2, s0
	ds_write_b16 v192, v2 offset:9504
	v_add_f32_e32 v2, v188, v28
	v_cvt_pk_bf16_f32 v2, v2, s0
	ds_write_b16 v18, v2 offset:26400
	v_add_f32_e32 v2, v188, v13
	v_cvt_pk_bf16_f32 v2, v2, s0
	ds_write_b16 v192, v2 offset:10032
	v_add_f32_e32 v2, v188, v29
	v_cvt_pk_bf16_f32 v2, v2, s0
	ds_write_b16 v18, v2 offset:26928
	v_add_f32_e32 v2, v188, v14
	v_cvt_pk_bf16_f32 v2, v2, s0
	ds_write_b16 v192, v2 offset:12672
	v_add_f32_e32 v2, v188, v30
	v_cvt_pk_bf16_f32 v2, v2, s0
	ds_write_b16 v18, v2 offset:29568
	v_add_f32_e32 v2, v188, v15
	v_cvt_pk_bf16_f32 v2, v2, s0
	ds_write_b16 v192, v2 offset:13200
	v_add_f32_e32 v2, v188, v31
	v_cvt_pk_bf16_f32 v2, v2, s0
	ds_write_b16 v18, v2 offset:30096
	v_add_f32_e32 v2, v188, v16
	v_cvt_pk_bf16_f32 v2, v2, s0
	ds_write_b16 v192, v2 offset:13728
	v_add_f32_e32 v2, v188, v32
	v_cvt_pk_bf16_f32 v2, v2, s0
	ds_write_b16 v18, v2 offset:30624
	v_add_f32_e32 v2, v188, v17
	v_cvt_pk_bf16_f32 v2, v2, s0
	ds_write_b16 v192, v2 offset:14256
	v_add_f32_e32 v2, v188, v33
	v_mul_i32_i24_e32 v188, 0x4200, v160
	v_cvt_pk_bf16_f32 v2, v2, s0
	v_add3_u32 v24, v189, v0, v188
	ds_write_b16 v18, v2 offset:31152
	s_waitcnt lgkmcnt(0)
	s_barrier
	ds_read_u16 v2, v24
	ds_read_u16 v3, v24 offset:528
	ds_read_u16 v4, v24 offset:1056
	ds_read_u16 v5, v24 offset:1584
	ds_read_u16 v6, v24 offset:2112
	ds_read_u16 v7, v24 offset:2640
	ds_read_u16 v8, v24 offset:3168
	ds_read_u16 v9, v24 offset:3696
	s_waitcnt lgkmcnt(0)
	v_lshlrev_b32_e32 v2, 16, v2
	v_mul_f32_e64 v10, |v2|, s19
	v_exp_f32_e32 v10, v10
	v_lshlrev_b32_e32 v3, 16, v3
	v_mul_f32_e64 v12, |v3|, s19
	v_exp_f32_e32 v12, v12
	v_add_f32_e32 v10, 1.0, v10
	v_cmp_gt_f32_e32 vcc, s96, v10
	v_max_f32_e32 v2, v2, v2
	v_min_f32_e32 v2, 0, v2
	v_cndmask_b32_e64 v11, 0, 32, vcc
	v_ldexp_f32 v10, v10, v11
	v_log_f32_e32 v10, v10
	v_lshlrev_b32_e32 v4, 16, v4
	v_max_f32_e32 v3, v3, v3
	v_min_f32_e32 v3, 0, v3
	v_mul_f32_e32 v11, 0x3f317217, v10
	v_fma_f32 v11, v10, s97, -v11
	v_fmac_f32_e32 v11, 0x3377d1cf, v10
	v_fmac_f32_e32 v11, 0x3f317217, v10
	v_cmp_lt_f32_e64 s[38:39], |v10|, s15
	v_lshlrev_b32_e32 v5, 16, v5
	v_lshlrev_b32_e32 v6, 16, v6
	v_cndmask_b32_e64 v10, v10, v11, s[38:39]
	v_cndmask_b32_e32 v11, 0, v179, vcc
	v_sub_f32_e32 v10, v10, v11
	v_add_f32_e32 v11, 1.0, v12
	v_cmp_gt_f32_e32 vcc, s96, v11
	v_sub_f32_e32 v2, v2, v10
	v_lshlrev_b32_e32 v7, 16, v7
	v_cndmask_b32_e64 v12, 0, 32, vcc
	v_ldexp_f32 v11, v11, v12
	v_log_f32_e32 v11, v11
	v_mul_f32_e64 v12, |v4|, s19
	v_exp_f32_e32 v12, v12
	v_max_f32_e32 v4, v4, v4
	v_mul_f32_e32 v10, 0x3f317217, v11
	v_fma_f32 v10, v11, s97, -v10
	v_fmac_f32_e32 v10, 0x3377d1cf, v11
	v_fmac_f32_e32 v10, 0x3f317217, v11
	v_cmp_lt_f32_e64 s[38:39], |v11|, s15
	v_min_f32_e32 v4, 0, v4
	v_lshlrev_b32_e32 v8, 16, v8
	v_cndmask_b32_e64 v10, v11, v10, s[38:39]
	v_cndmask_b32_e32 v11, 0, v179, vcc
	v_sub_f32_e32 v10, v10, v11
	v_sub_f32_e32 v3, v3, v10
	v_add_f32_e32 v10, 1.0, v12
	v_cmp_gt_f32_e32 vcc, s96, v10
	v_mul_f32_e64 v12, |v5|, s19
	v_exp_f32_e32 v12, v12
	v_cndmask_b32_e64 v11, 0, 32, vcc
	v_ldexp_f32 v10, v10, v11
	v_log_f32_e32 v10, v10
	v_max_f32_e32 v5, v5, v5
	v_min_f32_e32 v5, 0, v5
	v_lshlrev_b32_e32 v9, 16, v9
	v_mul_f32_e32 v11, 0x3f317217, v10
	v_fma_f32 v11, v10, s97, -v11
	v_fmac_f32_e32 v11, 0x3377d1cf, v10
	v_fmac_f32_e32 v11, 0x3f317217, v10
	v_cmp_lt_f32_e64 s[38:39], |v10|, s15
	v_fma_f32 v2, v2, s2, 0
	v_fmamk_f32 v3, v3, 0x3d800000, v2
	v_cndmask_b32_e64 v10, v10, v11, s[38:39]
	v_cndmask_b32_e32 v11, 0, v179, vcc
	v_sub_f32_e32 v10, v10, v11
	v_add_f32_e32 v11, 1.0, v12
	v_cmp_gt_f32_e32 vcc, s96, v11
	v_sub_f32_e32 v4, v4, v10
	v_fmamk_f32 v4, v4, 0x3d800000, v3
	v_cndmask_b32_e64 v12, 0, 32, vcc
	v_ldexp_f32 v11, v11, v12
	v_log_f32_e32 v11, v11
	v_mul_f32_e64 v12, |v6|, s19
	v_exp_f32_e32 v12, v12
	v_max_f32_e32 v6, v6, v6
	v_mul_f32_e32 v10, 0x3f317217, v11
	v_fma_f32 v10, v11, s97, -v10
	v_fmac_f32_e32 v10, 0x3377d1cf, v11
	v_fmac_f32_e32 v10, 0x3f317217, v11
	v_cmp_lt_f32_e64 s[38:39], |v11|, s15
	v_min_f32_e32 v6, 0, v6
	s_movk_i32 s2, 0xff
	v_cndmask_b32_e64 v10, v11, v10, s[38:39]
	v_cndmask_b32_e32 v11, 0, v179, vcc
	v_sub_f32_e32 v10, v10, v11
	v_sub_f32_e32 v5, v5, v10
	v_add_f32_e32 v10, 1.0, v12
	v_cmp_gt_f32_e32 vcc, s96, v10
	v_mul_f32_e64 v12, |v7|, s19
	v_exp_f32_e32 v12, v12
	v_cndmask_b32_e64 v11, 0, 32, vcc
	v_ldexp_f32 v10, v10, v11
	v_log_f32_e32 v10, v10
	v_max_f32_e32 v7, v7, v7
	v_min_f32_e32 v7, 0, v7
	v_fmamk_f32 v5, v5, 0x3d800000, v4
	v_mul_f32_e32 v11, 0x3f317217, v10
	v_fma_f32 v11, v10, s97, -v11
	v_fmac_f32_e32 v11, 0x3377d1cf, v10
	v_fmac_f32_e32 v11, 0x3f317217, v10
	v_cmp_lt_f32_e64 s[38:39], |v10|, s15
	s_nop 1
	v_cndmask_b32_e64 v10, v10, v11, s[38:39]
	v_cndmask_b32_e32 v11, 0, v179, vcc
	v_sub_f32_e32 v10, v10, v11
	v_add_f32_e32 v11, 1.0, v12
	v_cmp_gt_f32_e32 vcc, s96, v11
	v_sub_f32_e32 v6, v6, v10
	v_fmamk_f32 v6, v6, 0x3d800000, v5
	v_cndmask_b32_e64 v12, 0, 32, vcc
	v_ldexp_f32 v11, v11, v12
	v_log_f32_e32 v11, v11
	v_mul_f32_e64 v12, |v8|, s19
	v_exp_f32_e32 v12, v12
	v_max_f32_e32 v8, v8, v8
	v_mul_f32_e32 v10, 0x3f317217, v11
	v_fma_f32 v10, v11, s97, -v10
	v_fmac_f32_e32 v10, 0x3377d1cf, v11
	v_fmac_f32_e32 v10, 0x3f317217, v11
	v_cmp_lt_f32_e64 s[38:39], |v11|, s15
	v_min_f32_e32 v8, 0, v8
	s_nop 0
	v_cndmask_b32_e64 v10, v11, v10, s[38:39]
	v_cndmask_b32_e32 v11, 0, v179, vcc
	v_sub_f32_e32 v10, v10, v11
	v_sub_f32_e32 v7, v7, v10
	v_add_f32_e32 v10, 1.0, v12
	v_cmp_gt_f32_e32 vcc, s96, v10
	v_mul_f32_e64 v12, |v9|, s19
	v_exp_f32_e32 v12, v12
	v_cndmask_b32_e64 v11, 0, 32, vcc
	v_ldexp_f32 v10, v10, v11
	v_log_f32_e32 v10, v10
	v_max_f32_e32 v9, v9, v9
	v_min_f32_e32 v9, 0, v9
	v_fmamk_f32 v7, v7, 0x3d800000, v6
	v_mul_f32_e32 v11, 0x3f317217, v10
	v_fma_f32 v11, v10, s97, -v11
	v_fmac_f32_e32 v11, 0x3377d1cf, v10
	v_fmac_f32_e32 v11, 0x3f317217, v10
	v_cmp_lt_f32_e64 s[38:39], |v10|, s15
	s_nop 1
	v_cndmask_b32_e64 v10, v10, v11, s[38:39]
	v_cndmask_b32_e32 v11, 0, v179, vcc
	v_sub_f32_e32 v10, v10, v11
	v_add_f32_e32 v11, 1.0, v12
	v_cmp_gt_f32_e32 vcc, s96, v11
	v_sub_f32_e32 v8, v8, v10
	v_fmamk_f32 v8, v8, 0x3d800000, v7
	v_cndmask_b32_e64 v12, 0, 32, vcc
	v_ldexp_f32 v11, v11, v12
	v_log_f32_e32 v11, v11
	ds_read_u16 v12, v24 offset:4224
	ds_read_u16 v13, v24 offset:4752
	ds_read_u16 v14, v24 offset:5280
	ds_read_u16 v15, v24 offset:5808
	ds_read_u16 v16, v24 offset:6336
	ds_read_u16 v17, v24 offset:6864
	ds_read_u16 v18, v24 offset:7392
	ds_read_u16 v19, v24 offset:7920
	s_waitcnt lgkmcnt(0)
	v_lshlrev_b32_e32 v12, 16, v12
	v_mul_f32_e64 v20, |v12|, s19
	v_mul_f32_e32 v10, 0x3f317217, v11
	v_fma_f32 v10, v11, s97, -v10
	v_fmac_f32_e32 v10, 0x3377d1cf, v11
	v_exp_f32_e32 v20, v20
	v_fmac_f32_e32 v10, 0x3f317217, v11
	v_cmp_lt_f32_e64 s[38:39], |v11|, s15
	v_lshlrev_b32_e32 v13, 16, v13
	v_lshlrev_b32_e32 v14, 16, v14
	v_cndmask_b32_e64 v10, v11, v10, s[38:39]
	v_cndmask_b32_e32 v11, 0, v179, vcc
	v_sub_f32_e32 v10, v10, v11
	v_sub_f32_e32 v9, v9, v10
	v_add_f32_e32 v10, 1.0, v20
	v_cmp_gt_f32_e32 vcc, s96, v10
	v_mul_f32_e64 v20, |v13|, s19
	v_exp_f32_e32 v20, v20
	v_cndmask_b32_e64 v11, 0, 32, vcc
	v_ldexp_f32 v10, v10, v11
	v_log_f32_e32 v10, v10
	v_max_f32_e32 v11, v12, v12
	v_min_f32_e32 v11, 0, v11
	v_lshlrev_b32_e32 v15, 16, v15
	v_mul_f32_e32 v12, 0x3f317217, v10
	v_fma_f32 v12, v10, s97, -v12
	v_fmac_f32_e32 v12, 0x3377d1cf, v10
	v_fmac_f32_e32 v12, 0x3f317217, v10
	v_cmp_lt_f32_e64 s[38:39], |v10|, s15
	v_lshlrev_b32_e32 v16, 16, v16
	v_lshlrev_b32_e32 v17, 16, v17
	v_cndmask_b32_e64 v10, v10, v12, s[38:39]
	v_cndmask_b32_e32 v12, 0, v179, vcc
	v_sub_f32_e32 v10, v10, v12
	v_add_f32_e32 v12, 1.0, v20
	v_cmp_gt_f32_e32 vcc, s96, v12
	v_sub_f32_e32 v10, v11, v10
	v_max_f32_e32 v11, v13, v13
	v_cndmask_b32_e64 v20, 0, 32, vcc
	v_ldexp_f32 v12, v12, v20
	v_log_f32_e32 v12, v12
	v_mul_f32_e64 v20, |v14|, s19
	v_exp_f32_e32 v20, v20
	v_min_f32_e32 v11, 0, v11
	v_mul_f32_e32 v13, 0x3f317217, v12
	v_fma_f32 v13, v12, s97, -v13
	v_fmac_f32_e32 v13, 0x3377d1cf, v12
	v_fmac_f32_e32 v13, 0x3f317217, v12
	v_cmp_lt_f32_e64 s[38:39], |v12|, s15
	v_lshlrev_b32_e32 v18, 16, v18
	v_lshlrev_b32_e32 v19, 16, v19
	v_cndmask_b32_e64 v12, v12, v13, s[38:39]
	v_cndmask_b32_e32 v13, 0, v179, vcc
	v_sub_f32_e32 v12, v12, v13
	v_sub_f32_e32 v11, v11, v12
	v_add_f32_e32 v12, 1.0, v20
	v_cmp_gt_f32_e32 vcc, s96, v12
	v_mul_f32_e64 v20, |v15|, s19
	v_exp_f32_e32 v20, v20
	v_cndmask_b32_e64 v13, 0, 32, vcc
	v_ldexp_f32 v12, v12, v13
	v_log_f32_e32 v12, v12
	v_max_f32_e32 v13, v14, v14
	v_min_f32_e32 v13, 0, v13
	v_fmamk_f32 v9, v9, 0x3d800000, v8
	v_mul_f32_e32 v14, 0x3f317217, v12
	v_fma_f32 v14, v12, s97, -v14
	v_fmac_f32_e32 v14, 0x3377d1cf, v12
	v_fmac_f32_e32 v14, 0x3f317217, v12
	v_cmp_lt_f32_e64 s[38:39], |v12|, s15
	v_fmamk_f32 v10, v10, 0x3d800000, v9
	v_fmamk_f32 v11, v11, 0x3d800000, v10
	v_cndmask_b32_e64 v12, v12, v14, s[38:39]
	v_cndmask_b32_e32 v14, 0, v179, vcc
	v_sub_f32_e32 v12, v12, v14
	v_add_f32_e32 v14, 1.0, v20
	v_cmp_gt_f32_e32 vcc, s96, v14
	v_sub_f32_e32 v12, v13, v12
	v_max_f32_e32 v13, v15, v15
	v_cndmask_b32_e64 v20, 0, 32, vcc
	v_ldexp_f32 v14, v14, v20
	v_log_f32_e32 v14, v14
	v_mul_f32_e64 v20, |v16|, s19
	v_exp_f32_e32 v20, v20
	v_min_f32_e32 v13, 0, v13
	v_mul_f32_e32 v15, 0x3f317217, v14
	v_fma_f32 v15, v14, s97, -v15
	v_fmac_f32_e32 v15, 0x3377d1cf, v14
	v_fmac_f32_e32 v15, 0x3f317217, v14
	v_cmp_lt_f32_e64 s[38:39], |v14|, s15
	v_fmamk_f32 v12, v12, 0x3d800000, v11
	s_nop 0
	v_cndmask_b32_e64 v14, v14, v15, s[38:39]
	v_cndmask_b32_e32 v15, 0, v179, vcc
	v_sub_f32_e32 v14, v14, v15
	v_sub_f32_e32 v13, v13, v14
	v_add_f32_e32 v14, 1.0, v20
	v_cmp_gt_f32_e32 vcc, s96, v14
	v_mul_f32_e64 v20, |v17|, s19
	v_exp_f32_e32 v20, v20
	v_cndmask_b32_e64 v15, 0, 32, vcc
	v_ldexp_f32 v14, v14, v15
	v_log_f32_e32 v14, v14
	v_max_f32_e32 v15, v16, v16
	v_min_f32_e32 v15, 0, v15
	v_fmamk_f32 v13, v13, 0x3d800000, v12
	v_mul_f32_e32 v16, 0x3f317217, v14
	v_fma_f32 v16, v14, s97, -v16
	v_fmac_f32_e32 v16, 0x3377d1cf, v14
	v_fmac_f32_e32 v16, 0x3f317217, v14
	v_cmp_lt_f32_e64 s[38:39], |v14|, s15
	s_nop 1
	v_cndmask_b32_e64 v14, v14, v16, s[38:39]
	v_cndmask_b32_e32 v16, 0, v179, vcc
	v_sub_f32_e32 v14, v14, v16
	v_add_f32_e32 v16, 1.0, v20
	v_cmp_gt_f32_e32 vcc, s96, v16
	v_sub_f32_e32 v14, v15, v14
	v_max_f32_e32 v15, v17, v17
	v_cndmask_b32_e64 v20, 0, 32, vcc
	v_ldexp_f32 v16, v16, v20
	v_log_f32_e32 v16, v16
	v_mul_f32_e64 v20, |v18|, s19
	v_exp_f32_e32 v20, v20
	v_min_f32_e32 v15, 0, v15
	v_mul_f32_e32 v17, 0x3f317217, v16
	v_fma_f32 v17, v16, s97, -v17
	v_fmac_f32_e32 v17, 0x3377d1cf, v16
	v_fmac_f32_e32 v17, 0x3f317217, v16
	v_cmp_lt_f32_e64 s[38:39], |v16|, s15
	v_fmamk_f32 v14, v14, 0x3d800000, v13
	s_nop 0
	v_cndmask_b32_e64 v16, v16, v17, s[38:39]
	v_cndmask_b32_e32 v17, 0, v179, vcc
	v_sub_f32_e32 v16, v16, v17
	v_sub_f32_e32 v15, v15, v16
	v_add_f32_e32 v16, 1.0, v20
	v_cmp_gt_f32_e32 vcc, s96, v16
	v_mul_f32_e64 v20, |v19|, s19
	v_exp_f32_e32 v20, v20
	v_cndmask_b32_e64 v17, 0, 32, vcc
	v_ldexp_f32 v16, v16, v17
	v_log_f32_e32 v16, v16
	v_max_f32_e32 v17, v18, v18
	v_min_f32_e32 v17, 0, v17
	v_fmamk_f32 v15, v15, 0x3d800000, v14
	v_mul_f32_e32 v18, 0x3f317217, v16
	v_fma_f32 v18, v16, s97, -v18
	v_fmac_f32_e32 v18, 0x3377d1cf, v16
	v_fmac_f32_e32 v18, 0x3f317217, v16
	v_cmp_lt_f32_e64 s[38:39], |v16|, s15
	s_nop 1
	v_cndmask_b32_e64 v16, v16, v18, s[38:39]
	v_cndmask_b32_e32 v18, 0, v179, vcc
	v_sub_f32_e32 v16, v16, v18
	v_add_f32_e32 v18, 1.0, v20
	v_cmp_gt_f32_e32 vcc, s96, v18
	v_sub_f32_e32 v16, v17, v16
	v_max_f32_e32 v17, v19, v19
	v_cndmask_b32_e64 v20, 0, 32, vcc
	v_ldexp_f32 v18, v18, v20
	v_log_f32_e32 v18, v18
	ds_read_u16 v20, v24 offset:8448
	ds_read_u16 v21, v24 offset:8976
	ds_read_u16 v22, v24 offset:9504
	ds_read_u16 v23, v24 offset:10032
	ds_read_u16 v25, v24 offset:10560
	ds_read_u16 v26, v24 offset:11088
	ds_read_u16 v27, v24 offset:11616
	ds_read_u16 v28, v24 offset:12144
	s_waitcnt lgkmcnt(0)
	v_lshlrev_b32_e32 v20, 16, v20
	v_mul_f32_e64 v29, |v20|, s19
	v_mul_f32_e32 v19, 0x3f317217, v18
	v_fma_f32 v19, v18, s97, -v19
	v_fmac_f32_e32 v19, 0x3377d1cf, v18
	v_exp_f32_e32 v29, v29
	v_fmac_f32_e32 v19, 0x3f317217, v18
	v_cmp_lt_f32_e64 s[38:39], |v18|, s15
	v_min_f32_e32 v17, 0, v17
	v_lshlrev_b32_e32 v21, 16, v21
	v_cndmask_b32_e64 v18, v18, v19, s[38:39]
	v_cndmask_b32_e32 v19, 0, v179, vcc
	v_sub_f32_e32 v18, v18, v19
	v_sub_f32_e32 v17, v17, v18
	v_add_f32_e32 v18, 1.0, v29
	v_cmp_gt_f32_e32 vcc, s96, v18
	v_mul_f32_e64 v29, |v21|, s19
	v_exp_f32_e32 v29, v29
	v_cndmask_b32_e64 v19, 0, 32, vcc
	v_ldexp_f32 v18, v18, v19
	v_log_f32_e32 v18, v18
	v_max_f32_e32 v19, v20, v20
	v_min_f32_e32 v19, 0, v19
	v_lshlrev_b32_e32 v22, 16, v22
	v_mul_f32_e32 v20, 0x3f317217, v18
	v_fma_f32 v20, v18, s97, -v20
	v_fmac_f32_e32 v20, 0x3377d1cf, v18
	v_fmac_f32_e32 v20, 0x3f317217, v18
	v_cmp_lt_f32_e64 s[38:39], |v18|, s15
	v_lshlrev_b32_e32 v23, 16, v23
	v_lshlrev_b32_e32 v25, 16, v25
	v_cndmask_b32_e64 v18, v18, v20, s[38:39]
	v_cndmask_b32_e32 v20, 0, v179, vcc
	v_sub_f32_e32 v18, v18, v20
	v_add_f32_e32 v20, 1.0, v29
	v_cmp_gt_f32_e32 vcc, s96, v20
	v_sub_f32_e32 v18, v19, v18
	v_max_f32_e32 v19, v21, v21
	v_cndmask_b32_e64 v29, 0, 32, vcc
	v_ldexp_f32 v20, v20, v29
	v_log_f32_e32 v20, v20
	v_mul_f32_e64 v29, |v22|, s19
	v_exp_f32_e32 v29, v29
	v_min_f32_e32 v19, 0, v19
	v_mul_f32_e32 v21, 0x3f317217, v20
	v_fma_f32 v21, v20, s97, -v21
	v_fmac_f32_e32 v21, 0x3377d1cf, v20
	v_fmac_f32_e32 v21, 0x3f317217, v20
	v_cmp_lt_f32_e64 s[38:39], |v20|, s15
	v_lshlrev_b32_e32 v26, 16, v26
	v_lshlrev_b32_e32 v27, 16, v27
	v_cndmask_b32_e64 v20, v20, v21, s[38:39]
	v_cndmask_b32_e32 v21, 0, v179, vcc
	v_sub_f32_e32 v20, v20, v21
	v_sub_f32_e32 v19, v19, v20
	v_add_f32_e32 v20, 1.0, v29
	v_cmp_gt_f32_e32 vcc, s96, v20
	v_mul_f32_e64 v29, |v23|, s19
	v_exp_f32_e32 v29, v29
	v_cndmask_b32_e64 v21, 0, 32, vcc
	v_ldexp_f32 v20, v20, v21
	v_log_f32_e32 v20, v20
	v_max_f32_e32 v21, v22, v22
	v_min_f32_e32 v21, 0, v21
	v_lshlrev_b32_e32 v28, 16, v28
	v_mul_f32_e32 v22, 0x3f317217, v20
	v_fma_f32 v22, v20, s97, -v22
	v_fmac_f32_e32 v22, 0x3377d1cf, v20
	v_fmac_f32_e32 v22, 0x3f317217, v20
	v_cmp_lt_f32_e64 s[38:39], |v20|, s15
	v_fmamk_f32 v16, v16, 0x3d800000, v15
	v_fmamk_f32 v17, v17, 0x3d800000, v16
	v_cndmask_b32_e64 v20, v20, v22, s[38:39]
	v_cndmask_b32_e32 v22, 0, v179, vcc
	v_sub_f32_e32 v20, v20, v22
	v_add_f32_e32 v22, 1.0, v29
	v_cmp_gt_f32_e32 vcc, s96, v22
	v_sub_f32_e32 v20, v21, v20
	v_max_f32_e32 v21, v23, v23
	v_cndmask_b32_e64 v29, 0, 32, vcc
	v_ldexp_f32 v22, v22, v29
	v_log_f32_e32 v22, v22
	v_mul_f32_e64 v29, |v25|, s19
	v_exp_f32_e32 v29, v29
	v_min_f32_e32 v21, 0, v21
	v_mul_f32_e32 v23, 0x3f317217, v22
	v_fma_f32 v23, v22, s97, -v23
	v_fmac_f32_e32 v23, 0x3377d1cf, v22
	v_fmac_f32_e32 v23, 0x3f317217, v22
	v_cmp_lt_f32_e64 s[38:39], |v22|, s15
	v_fmamk_f32 v18, v18, 0x3d800000, v17
	v_fmamk_f32 v19, v19, 0x3d800000, v18
	v_cndmask_b32_e64 v22, v22, v23, s[38:39]
	v_cndmask_b32_e32 v23, 0, v179, vcc
	v_sub_f32_e32 v22, v22, v23
	v_sub_f32_e32 v21, v21, v22
	v_add_f32_e32 v22, 1.0, v29
	v_cmp_gt_f32_e32 vcc, s96, v22
	v_mul_f32_e64 v29, |v26|, s19
	v_exp_f32_e32 v29, v29
	v_cndmask_b32_e64 v23, 0, 32, vcc
	v_ldexp_f32 v22, v22, v23
	v_log_f32_e32 v22, v22
	v_max_f32_e32 v23, v25, v25
	v_min_f32_e32 v23, 0, v23
	v_fmamk_f32 v20, v20, 0x3d800000, v19
	v_mul_f32_e32 v25, 0x3f317217, v22
	v_fma_f32 v25, v22, s97, -v25
	v_fmac_f32_e32 v25, 0x3377d1cf, v22
	v_fmac_f32_e32 v25, 0x3f317217, v22
	v_cmp_lt_f32_e64 s[38:39], |v22|, s15
	v_fmamk_f32 v21, v21, 0x3d800000, v20
	s_nop 0
	v_cndmask_b32_e64 v22, v22, v25, s[38:39]
	v_cndmask_b32_e32 v25, 0, v179, vcc
	v_sub_f32_e32 v22, v22, v25
	v_add_f32_e32 v25, 1.0, v29
	v_cmp_gt_f32_e32 vcc, s96, v25
	v_sub_f32_e32 v22, v23, v22
	v_max_f32_e32 v23, v26, v26
	v_cndmask_b32_e64 v29, 0, 32, vcc
	v_ldexp_f32 v25, v25, v29
	v_log_f32_e32 v25, v25
	v_mul_f32_e64 v29, |v27|, s19
	v_exp_f32_e32 v29, v29
	v_min_f32_e32 v23, 0, v23
	v_mul_f32_e32 v26, 0x3f317217, v25
	v_fma_f32 v26, v25, s97, -v26
	v_fmac_f32_e32 v26, 0x3377d1cf, v25
	v_fmac_f32_e32 v26, 0x3f317217, v25
	v_cmp_lt_f32_e64 s[38:39], |v25|, s15
	v_fmamk_f32 v22, v22, 0x3d800000, v21
	s_nop 0
	v_cndmask_b32_e64 v25, v25, v26, s[38:39]
	v_cndmask_b32_e32 v26, 0, v179, vcc
	v_sub_f32_e32 v25, v25, v26
	v_sub_f32_e32 v23, v23, v25
	v_add_f32_e32 v25, 1.0, v29
	v_cmp_gt_f32_e32 vcc, s96, v25
	v_mul_f32_e64 v29, |v28|, s19
	v_exp_f32_e32 v29, v29
	v_cndmask_b32_e64 v26, 0, 32, vcc
	v_ldexp_f32 v25, v25, v26
	v_log_f32_e32 v25, v25
	v_max_f32_e32 v26, v27, v27
	v_min_f32_e32 v26, 0, v26
	v_fmamk_f32 v23, v23, 0x3d800000, v22
	v_mul_f32_e32 v27, 0x3f317217, v25
	v_fma_f32 v27, v25, s97, -v27
	v_fmac_f32_e32 v27, 0x3377d1cf, v25
	v_fmac_f32_e32 v27, 0x3f317217, v25
	v_cmp_lt_f32_e64 s[38:39], |v25|, s15
	s_nop 1
	v_cndmask_b32_e64 v25, v25, v27, s[38:39]
	v_cndmask_b32_e32 v27, 0, v179, vcc
	v_sub_f32_e32 v25, v25, v27
	v_add_f32_e32 v27, 1.0, v29
	v_cmp_gt_f32_e32 vcc, s96, v27
	v_sub_f32_e32 v25, v26, v25
	v_max_f32_e32 v26, v28, v28
	v_cndmask_b32_e64 v29, 0, 32, vcc
	v_ldexp_f32 v27, v27, v29
	v_log_f32_e32 v27, v27
	ds_read_u16 v29, v24 offset:12672
	ds_read_u16 v30, v24 offset:13200
	ds_read_u16 v31, v24 offset:13728
	ds_read_u16 v32, v24 offset:14256
	ds_read_u16 v33, v24 offset:14784
	ds_read_u16 v189, v24 offset:15312
	ds_read_u16 v190, v24 offset:15840
	ds_read_u16 v191, v24 offset:16368
	s_waitcnt lgkmcnt(0)
	v_lshlrev_b32_e32 v29, 16, v29
	v_mul_f32_e64 v24, |v29|, s19
	v_mul_f32_e32 v28, 0x3f317217, v27
	v_fma_f32 v28, v27, s97, -v28
	v_fmac_f32_e32 v28, 0x3377d1cf, v27
	v_exp_f32_e32 v192, v24
	v_fmac_f32_e32 v28, 0x3f317217, v27
	v_cmp_lt_f32_e64 s[38:39], |v27|, s15
	v_min_f32_e32 v26, 0, v26
	s_nop 0
	v_cndmask_b32_e64 v27, v27, v28, s[38:39]
	v_cndmask_b32_e32 v28, 0, v179, vcc
	v_sub_f32_e32 v24, v27, v28
	v_sub_f32_e32 v26, v26, v24
	v_fmamk_f32 v24, v25, 0x3d800000, v23
	v_add_f32_e32 v25, 1.0, v192
	v_cmp_gt_f32_e32 vcc, s96, v25
	s_nop 1
	v_cndmask_b32_e64 v27, 0, 32, vcc
	v_ldexp_f32 v25, v25, v27
	v_log_f32_e32 v27, v25
	v_fmamk_f32 v25, v26, 0x3d800000, v24
	v_max_f32_e32 v26, v29, v29
	v_lshlrev_b32_e32 v29, 16, v30
	v_mul_f32_e32 v28, 0x3f317217, v27
	v_mul_f32_e64 v30, |v29|, s19
	v_fma_f32 v28, v27, s97, -v28
	v_exp_f32_e32 v30, v30
	v_fmac_f32_e32 v28, 0x3377d1cf, v27
	v_fmac_f32_e32 v28, 0x3f317217, v27
	v_cmp_lt_f32_e64 s[38:39], |v27|, s15
	v_min_f32_e32 v26, 0, v26
	s_nop 0
	v_cndmask_b32_e64 v27, v27, v28, s[38:39]
	v_cndmask_b32_e32 v28, 0, v179, vcc
	v_sub_f32_e32 v27, v27, v28
	v_add_f32_e32 v28, 1.0, v30
	v_cmp_gt_f32_e32 vcc, s96, v28
	v_sub_f32_e32 v26, v26, v27
	v_max_f32_e32 v27, v29, v29
	v_cndmask_b32_e64 v30, 0, 32, vcc
	v_ldexp_f32 v28, v28, v30
	v_log_f32_e32 v28, v28
	v_lshlrev_b32_e32 v30, 16, v31
	v_mul_f32_e64 v31, |v30|, s19
	v_exp_f32_e32 v31, v31
	v_mul_f32_e32 v29, 0x3f317217, v28
	v_fma_f32 v29, v28, s97, -v29
	v_fmac_f32_e32 v29, 0x3377d1cf, v28
	v_fmac_f32_e32 v29, 0x3f317217, v28
	v_cmp_lt_f32_e64 s[38:39], |v28|, s15
	v_min_f32_e32 v27, 0, v27
	v_fmamk_f32 v26, v26, 0x3d800000, v25
	v_cndmask_b32_e64 v28, v28, v29, s[38:39]
	v_cndmask_b32_e32 v29, 0, v179, vcc
	v_sub_f32_e32 v28, v28, v29
	v_sub_f32_e32 v27, v27, v28
	v_add_f32_e32 v28, 1.0, v31
	v_cmp_gt_f32_e32 vcc, s96, v28
	v_lshlrev_b32_e32 v31, 16, v32
	v_mul_f32_e64 v32, |v31|, s19
	v_cndmask_b32_e64 v29, 0, 32, vcc
	v_ldexp_f32 v28, v28, v29
	v_log_f32_e32 v28, v28
	v_max_f32_e32 v29, v30, v30
	v_exp_f32_e32 v32, v32
	v_min_f32_e32 v29, 0, v29
	v_mul_f32_e32 v30, 0x3f317217, v28
	v_fma_f32 v30, v28, s97, -v30
	v_fmac_f32_e32 v30, 0x3377d1cf, v28
	v_fmac_f32_e32 v30, 0x3f317217, v28
	v_cmp_lt_f32_e64 s[38:39], |v28|, s15
	v_fmamk_f32 v27, v27, 0x3d800000, v26
	s_nop 0
	v_cndmask_b32_e64 v28, v28, v30, s[38:39]
	v_cndmask_b32_e32 v30, 0, v179, vcc
	v_sub_f32_e32 v28, v28, v30
	v_add_f32_e32 v30, 1.0, v32
	v_cmp_gt_f32_e32 vcc, s96, v30
	v_sub_f32_e32 v28, v29, v28
	v_max_f32_e32 v29, v31, v31
	v_cndmask_b32_e64 v32, 0, 32, vcc
	v_ldexp_f32 v30, v30, v32
	v_log_f32_e32 v30, v30
	v_lshlrev_b32_e32 v32, 16, v33
	v_mul_f32_e64 v33, |v32|, s19
	v_exp_f32_e32 v33, v33
	v_mul_f32_e32 v31, 0x3f317217, v30
	v_fma_f32 v31, v30, s97, -v31
	v_fmac_f32_e32 v31, 0x3377d1cf, v30
	v_fmac_f32_e32 v31, 0x3f317217, v30
	v_cmp_lt_f32_e64 s[38:39], |v30|, s15
	v_min_f32_e32 v29, 0, v29
	v_fmamk_f32 v28, v28, 0x3d800000, v27
	v_cndmask_b32_e64 v30, v30, v31, s[38:39]
	v_cndmask_b32_e32 v31, 0, v179, vcc
	v_sub_f32_e32 v30, v30, v31
	v_sub_f32_e32 v29, v29, v30
	v_add_f32_e32 v30, 1.0, v33
	v_cmp_gt_f32_e32 vcc, s96, v30
	v_lshlrev_b32_e32 v33, 16, v189
	v_mul_f32_e64 v189, |v33|, s19
	v_cndmask_b32_e64 v31, 0, 32, vcc
	v_ldexp_f32 v30, v30, v31
	v_log_f32_e32 v30, v30
	v_max_f32_e32 v31, v32, v32
	v_exp_f32_e32 v189, v189
	v_min_f32_e32 v31, 0, v31
	v_mul_f32_e32 v32, 0x3f317217, v30
	v_fma_f32 v32, v30, s97, -v32
	v_fmac_f32_e32 v32, 0x3377d1cf, v30
	v_fmac_f32_e32 v32, 0x3f317217, v30
	v_cmp_lt_f32_e64 s[38:39], |v30|, s15
	v_fmamk_f32 v29, v29, 0x3d800000, v28
	s_nop 0
	v_cndmask_b32_e64 v30, v30, v32, s[38:39]
	v_cndmask_b32_e32 v32, 0, v179, vcc
	v_sub_f32_e32 v30, v30, v32
	v_add_f32_e32 v32, 1.0, v189
	v_cmp_gt_f32_e32 vcc, s96, v32
	v_sub_f32_e32 v30, v31, v30
	v_max_f32_e32 v31, v33, v33
	v_cndmask_b32_e64 v189, 0, 32, vcc
	v_ldexp_f32 v32, v32, v189
	v_log_f32_e32 v32, v32
	v_lshlrev_b32_e32 v189, 16, v190
	v_mul_f32_e64 v190, |v189|, s19
	v_exp_f32_e32 v190, v190
	v_mul_f32_e32 v33, 0x3f317217, v32
	v_fma_f32 v33, v32, s97, -v33
	v_fmac_f32_e32 v33, 0x3377d1cf, v32
	v_fmac_f32_e32 v33, 0x3f317217, v32
	v_cmp_lt_f32_e64 s[38:39], |v32|, s15
	v_min_f32_e32 v31, 0, v31
	v_fmamk_f32 v30, v30, 0x3d800000, v29
	v_cndmask_b32_e64 v32, v32, v33, s[38:39]
	v_cndmask_b32_e32 v33, 0, v179, vcc
	v_sub_f32_e32 v32, v32, v33
	v_sub_f32_e32 v31, v31, v32
	v_add_f32_e32 v32, 1.0, v190
	v_cmp_gt_f32_e32 vcc, s96, v32
	v_lshlrev_b32_e32 v190, 16, v191
	v_mul_f32_e64 v191, |v190|, s19
	v_cndmask_b32_e64 v33, 0, 32, vcc
	v_ldexp_f32 v32, v32, v33
	v_log_f32_e32 v32, v32
	v_max_f32_e32 v33, v189, v189
	v_exp_f32_e32 v191, v191
	v_min_f32_e32 v33, 0, v33
	v_mul_f32_e32 v189, 0x3f317217, v32
	v_fma_f32 v189, v32, s97, -v189
	v_fmac_f32_e32 v189, 0x3377d1cf, v32
	v_fmac_f32_e32 v189, 0x3f317217, v32
	v_cmp_lt_f32_e64 s[38:39], |v32|, s15
	v_fmamk_f32 v31, v31, 0x3d800000, v30
	s_nop 0
	v_cndmask_b32_e64 v32, v32, v189, s[38:39]
	v_cndmask_b32_e32 v189, 0, v179, vcc
	v_sub_f32_e32 v32, v32, v189
	v_add_f32_e32 v189, 1.0, v191
	v_cmp_gt_f32_e32 vcc, s96, v189
	v_sub_f32_e32 v32, v33, v32
	v_max_f32_e32 v33, v190, v190
	v_cndmask_b32_e64 v191, 0, 32, vcc
	v_ldexp_f32 v189, v189, v191
	v_log_f32_e32 v189, v189
	v_min_f32_e32 v33, 0, v33
	v_fmamk_f32 v32, v32, 0x3d800000, v31
	v_mul_f32_e32 v190, 0x3f317217, v189
	v_fma_f32 v190, v189, s97, -v190
	v_fmac_f32_e32 v190, 0x3377d1cf, v189
	v_fmac_f32_e32 v190, 0x3f317217, v189
	v_cmp_lt_f32_e64 s[38:39], |v189|, s15
	s_nop 1
	v_cndmask_b32_e64 v189, v189, v190, s[38:39]
	v_cndmask_b32_e32 v190, 0, v179, vcc
	v_sub_f32_e32 v189, v189, v190
	v_sub_f32_e32 v33, v33, v189
	v_mov_b32_e32 v189, 2
	v_lshlrev_b32_e32 v190, 10, v160
	v_lshlrev_b32_sdwa v189, v189, v109 dst_sel:DWORD dst_unused:UNUSED_PAD src0_sel:DWORD src1_sel:BYTE_0
	v_fmamk_f32 v33, v33, 0x3d800000, v32
	v_add3_u32 v190, v187, v190, v189
	v_cmp_lt_u32_e32 vcc, s2, v109
	ds_write_b32 v190, v33
	s_waitcnt lgkmcnt(0)
	s_barrier
	s_and_saveexec_b64 s[2:3], vcc
	s_cbranch_execz .LBB0_168
	v_add_u32_e32 v187, v187, v189
	ds_read_b32 v190, v187
	s_waitcnt lgkmcnt(0)
	v_pk_add_f32 v[32:33], v[32:33], v[190:191] op_sel_hi:[1,0]
	v_pk_add_f32 v[30:31], v[30:31], v[190:191] op_sel_hi:[1,0]
	v_pk_add_f32 v[28:29], v[28:29], v[190:191] op_sel_hi:[1,0]
	v_pk_add_f32 v[26:27], v[26:27], v[190:191] op_sel_hi:[1,0]
	v_pk_add_f32 v[24:25], v[24:25], v[190:191] op_sel_hi:[1,0]
	v_pk_add_f32 v[22:23], v[22:23], v[190:191] op_sel_hi:[1,0]
	v_pk_add_f32 v[20:21], v[20:21], v[190:191] op_sel_hi:[1,0]
	v_pk_add_f32 v[18:19], v[18:19], v[190:191] op_sel_hi:[1,0]
	v_pk_add_f32 v[16:17], v[16:17], v[190:191] op_sel_hi:[1,0]
	v_pk_add_f32 v[14:15], v[14:15], v[190:191] op_sel_hi:[1,0]
	v_pk_add_f32 v[12:13], v[12:13], v[190:191] op_sel_hi:[1,0]
	v_pk_add_f32 v[10:11], v[10:11], v[190:191] op_sel_hi:[1,0]
	v_pk_add_f32 v[8:9], v[8:9], v[190:191] op_sel_hi:[1,0]
	v_pk_add_f32 v[6:7], v[6:7], v[190:191] op_sel_hi:[1,0]
	v_pk_add_f32 v[4:5], v[4:5], v[190:191] op_sel_hi:[1,0]
	v_pk_add_f32 v[2:3], v[2:3], v[190:191] op_sel_hi:[1,0]
.LBB0_168:
	s_or_b64 exec, exec, s[2:3]
	v_mul_u32_u24_sdwa v109, v109, s89 dst_sel:DWORD dst_unused:UNUSED_PAD src0_sel:BYTE_0 src1_sel:DWORD
	v_lshlrev_b32_e32 v160, 6, v160
	v_add3_u32 v109, v87, v109, v160
	v_mul_f32_e32 v160, 0x3fb8aa3b, v2
	v_mul_f32_e32 v2, 0xbfb8aa3b, v2
	v_exp_f32_e32 v160, v160
	v_exp_f32_e32 v2, v2
	v_lshlrev_b32_e32 v185, 16, v185
	v_mul_f32_e32 v185, 0x3e000000, v185
	v_lshlrev_b32_e32 v169, 16, v169
	v_mul_f32_e32 v160, v185, v160
	v_mul_f32_e32 v2, v2, v169
	v_or_b32_e32 v0, v188, v0
	v_cvt_pk_bf16_f32 v160, v160, s0
	v_add_u32_e32 v169, v66, v0
	v_cvt_pk_bf16_f32 v2, v2, s0
	v_add_u32_e32 v0, v85, v0
	ds_write_b16 v169, v160
	ds_write_b16 v0, v2
	v_mul_f32_e32 v2, 0x3fb8aa3b, v3
	v_exp_f32_e32 v2, v2
	v_mul_f32_e32 v3, 0xbfb8aa3b, v3
	v_exp_f32_e32 v3, v3
	v_lshlrev_b32_e32 v160, 16, v161
	v_mul_f32_e32 v160, 0x3e000000, v160
	v_mul_f32_e32 v2, v160, v2
	v_lshlrev_b32_e32 v156, 16, v156
	v_mul_f32_e32 v3, v3, v156
	v_cvt_pk_bf16_f32 v2, v2, s0
	ds_write_b16 v169, v2 offset:528
	v_cvt_pk_bf16_f32 v2, v3, s0
	ds_write_b16 v0, v2 offset:528
	v_mul_f32_e32 v2, 0x3fb8aa3b, v4
	v_exp_f32_e32 v2, v2
	v_mul_f32_e32 v3, 0xbfb8aa3b, v4
	v_exp_f32_e32 v3, v3
	v_lshlrev_b32_e32 v4, 16, v148
	v_mul_f32_e32 v4, 0x3e000000, v4
	v_mul_f32_e32 v2, v4, v2
	v_lshlrev_b32_e32 v4, 16, v144
	v_mul_f32_e32 v3, v3, v4
	v_cvt_pk_bf16_f32 v2, v2, s0
	ds_write_b16 v169, v2 offset:1056
	v_cvt_pk_bf16_f32 v2, v3, s0
	ds_write_b16 v0, v2 offset:1056
	v_mul_f32_e32 v2, 0x3fb8aa3b, v5
	v_exp_f32_e32 v2, v2
	v_mul_f32_e32 v3, 0xbfb8aa3b, v5
	v_exp_f32_e32 v3, v3
	v_lshlrev_b32_e32 v5, 16, v152
	v_mul_f32_e32 v5, 0x3e000000, v5
	v_mul_f32_e32 v2, v5, v2
	v_lshlrev_b32_e32 v5, 16, v151
	v_mul_f32_e32 v3, v3, v5
	v_cvt_pk_bf16_f32 v2, v2, s0
	ds_write_b16 v169, v2 offset:1584
	v_cvt_pk_bf16_f32 v2, v3, s0
	ds_write_b16 v0, v2 offset:1584
	v_mul_f32_e32 v2, 0x3fb8aa3b, v6
	v_exp_f32_e32 v2, v2
	v_mul_f32_e32 v3, 0xbfb8aa3b, v6
	v_exp_f32_e32 v3, v3
	v_lshlrev_b32_e32 v6, 16, v141
	v_mul_f32_e32 v6, 0x3e000000, v6
	v_mul_f32_e32 v2, v6, v2
	v_lshlrev_b32_e32 v6, 16, v139
	v_mul_f32_e32 v3, v3, v6
	v_cvt_pk_bf16_f32 v2, v2, s0
	ds_write_b16 v169, v2 offset:2112
	v_cvt_pk_bf16_f32 v2, v3, s0
	ds_write_b16 v0, v2 offset:2112
	v_mul_f32_e32 v2, 0x3fb8aa3b, v7
	v_exp_f32_e32 v2, v2
	v_mul_f32_e32 v3, 0xbfb8aa3b, v7
	v_exp_f32_e32 v3, v3
	v_lshlrev_b32_e32 v7, 16, v132
	v_mul_f32_e32 v7, 0x3e000000, v7
	v_mul_f32_e32 v2, v7, v2
	v_lshlrev_b32_e32 v7, 16, v140
	v_mul_f32_e32 v3, v3, v7
	v_cvt_pk_bf16_f32 v2, v2, s0
	ds_write_b16 v169, v2 offset:2640
	v_cvt_pk_bf16_f32 v2, v3, s0
	ds_write_b16 v0, v2 offset:2640
	v_mul_f32_e32 v2, 0x3fb8aa3b, v8
	v_exp_f32_e32 v2, v2
	v_mul_f32_e32 v3, 0xbfb8aa3b, v8
	v_exp_f32_e32 v3, v3
	v_lshlrev_b32_e32 v8, 16, v133
	v_mul_f32_e32 v8, 0x3e000000, v8
	v_mul_f32_e32 v2, v8, v2
	v_lshlrev_b32_e32 v8, 16, v131
	v_mul_f32_e32 v3, v3, v8
	v_cvt_pk_bf16_f32 v2, v2, s0
	ds_write_b16 v169, v2 offset:3168
	v_cvt_pk_bf16_f32 v2, v3, s0
	ds_write_b16 v0, v2 offset:3168
	v_mul_f32_e32 v2, 0x3fb8aa3b, v9
	v_exp_f32_e32 v2, v2
	v_mul_f32_e32 v3, 0xbfb8aa3b, v9
	v_exp_f32_e32 v3, v3
	v_lshlrev_b32_e32 v9, 16, v126
	v_mul_f32_e32 v9, 0x3e000000, v9
	v_mul_f32_e32 v2, v9, v2
	v_lshlrev_b32_e32 v9, 16, v124
	v_mul_f32_e32 v3, v3, v9
	v_cvt_pk_bf16_f32 v2, v2, s0
	v_lshlrev_b32_e32 v168, 16, v168
	v_lshlrev_b32_e32 v155, 16, v155
	v_lshlrev_b32_e32 v4, 16, v163
	v_lshlrev_b32_e32 v5, 16, v150
	v_lshlrev_b32_e32 v6, 16, v137
	v_lshlrev_b32_e32 v7, 16, v138
	v_lshlrev_b32_e32 v8, 16, v130
	v_lshlrev_b32_e32 v9, 16, v123
	ds_write_b16 v169, v2 offset:3696
	v_cvt_pk_bf16_f32 v2, v3, s0
	ds_write_b16 v0, v2 offset:3696
	v_cvt_pk_bf16_f32 v2, v168, v155
	v_cvt_pk_bf16_f32 v3, v4, v5
	v_cvt_pk_bf16_f32 v4, v6, v7
	v_cvt_pk_bf16_f32 v5, v8, v9
	ds_write_b128 v109, v[2:5]
	v_mul_f32_e32 v2, 0x3fb8aa3b, v10
	v_exp_f32_e32 v2, v2
	v_mul_f32_e32 v3, 0xbfb8aa3b, v10
	v_exp_f32_e32 v3, v3
	v_lshlrev_b32_e32 v4, 16, v122
	v_mul_f32_e32 v4, 0x3e000000, v4
	v_mul_f32_e32 v2, v4, v2
	v_lshlrev_b32_e32 v4, 16, v120
	v_mul_f32_e32 v3, v3, v4
	v_cvt_pk_bf16_f32 v2, v2, s0
	ds_write_b16 v169, v2 offset:4224
	v_cvt_pk_bf16_f32 v2, v3, s0
	ds_write_b16 v0, v2 offset:4224
	v_mul_f32_e32 v2, 0x3fb8aa3b, v11
	v_exp_f32_e32 v2, v2
	v_mul_f32_e32 v3, 0xbfb8aa3b, v11
	v_exp_f32_e32 v3, v3
	v_lshlrev_b32_e32 v5, 16, v113
	v_mul_f32_e32 v5, 0x3e000000, v5
	v_mul_f32_e32 v2, v5, v2
	v_lshlrev_b32_e32 v5, 16, v112
	v_mul_f32_e32 v3, v3, v5
	v_cvt_pk_bf16_f32 v2, v2, s0
	ds_write_b16 v169, v2 offset:4752
	v_cvt_pk_bf16_f32 v2, v3, s0
	ds_write_b16 v0, v2 offset:4752
	v_mul_f32_e32 v2, 0x3fb8aa3b, v12
	v_exp_f32_e32 v2, v2
	v_mul_f32_e32 v3, 0xbfb8aa3b, v12
	v_exp_f32_e32 v3, v3
	v_lshlrev_b32_e32 v6, 16, v101
	v_mul_f32_e32 v6, 0x3e000000, v6
	v_mul_f32_e32 v2, v6, v2
	v_lshlrev_b32_e32 v6, 16, v100
	v_mul_f32_e32 v3, v3, v6
	v_cvt_pk_bf16_f32 v2, v2, s0
	ds_write_b16 v169, v2 offset:5280
	v_cvt_pk_bf16_f32 v2, v3, s0
	ds_write_b16 v0, v2 offset:5280
	v_mul_f32_e32 v2, 0x3fb8aa3b, v13
	v_exp_f32_e32 v2, v2
	v_mul_f32_e32 v3, 0xbfb8aa3b, v13
	v_exp_f32_e32 v3, v3
	v_lshlrev_b32_e32 v7, 16, v106
	v_mul_f32_e32 v7, 0x3e000000, v7
	v_mul_f32_e32 v2, v7, v2
	v_lshlrev_b32_e32 v7, 16, v103
	v_mul_f32_e32 v3, v3, v7
	v_cvt_pk_bf16_f32 v2, v2, s0
	ds_write_b16 v169, v2 offset:5808
	v_cvt_pk_bf16_f32 v2, v3, s0
	ds_write_b16 v0, v2 offset:5808
	v_mul_f32_e32 v2, 0x3fb8aa3b, v14
	v_exp_f32_e32 v2, v2
	v_mul_f32_e32 v3, 0xbfb8aa3b, v14
	v_exp_f32_e32 v3, v3
	v_lshlrev_b32_e32 v8, 16, v96
	v_mul_f32_e32 v8, 0x3e000000, v8
	v_mul_f32_e32 v2, v8, v2
	v_lshlrev_b32_e32 v8, 16, v92
	v_mul_f32_e32 v3, v3, v8
	v_cvt_pk_bf16_f32 v2, v2, s0
	ds_write_b16 v169, v2 offset:6336
	v_cvt_pk_bf16_f32 v2, v3, s0
	ds_write_b16 v0, v2 offset:6336
	v_mul_f32_e32 v2, 0x3fb8aa3b, v15
	v_exp_f32_e32 v2, v2
	v_mul_f32_e32 v3, 0xbfb8aa3b, v15
	v_exp_f32_e32 v3, v3
	v_lshlrev_b32_e32 v9, 16, v81
	v_mul_f32_e32 v9, 0x3e000000, v9
	v_mul_f32_e32 v2, v9, v2
	v_lshlrev_b32_e32 v9, 16, v94
	v_mul_f32_e32 v3, v3, v9
	v_cvt_pk_bf16_f32 v2, v2, s0
	ds_write_b16 v169, v2 offset:6864
	v_cvt_pk_bf16_f32 v2, v3, s0
	ds_write_b16 v0, v2 offset:6864
	v_mul_f32_e32 v2, 0x3fb8aa3b, v16
	v_exp_f32_e32 v2, v2
	v_mul_f32_e32 v3, 0xbfb8aa3b, v16
	v_exp_f32_e32 v3, v3
	v_lshlrev_b32_e32 v10, 16, v86
	v_mul_f32_e32 v10, 0x3e000000, v10
	v_mul_f32_e32 v2, v10, v2
	v_lshlrev_b32_e32 v10, 16, v79
	v_mul_f32_e32 v3, v3, v10
	v_cvt_pk_bf16_f32 v2, v2, s0
	ds_write_b16 v169, v2 offset:7392
	v_cvt_pk_bf16_f32 v2, v3, s0
	ds_write_b16 v0, v2 offset:7392
	v_mul_f32_e32 v2, 0x3fb8aa3b, v17
	v_exp_f32_e32 v2, v2
	v_mul_f32_e32 v3, 0xbfb8aa3b, v17
	v_exp_f32_e32 v3, v3
	v_lshlrev_b32_e32 v11, 16, v77
	v_mul_f32_e32 v11, 0x3e000000, v11
	v_mul_f32_e32 v2, v11, v2
	v_lshlrev_b32_e32 v11, 16, v76
	v_mul_f32_e32 v3, v3, v11
	v_cvt_pk_bf16_f32 v2, v2, s0
	v_lshlrev_b32_e32 v4, 16, v119
	v_lshlrev_b32_e32 v5, 16, v111
	v_lshlrev_b32_e32 v6, 16, v114
	v_lshlrev_b32_e32 v7, 16, v102
	v_lshlrev_b32_e32 v8, 16, v90
	v_lshlrev_b32_e32 v9, 16, v91
	v_lshlrev_b32_e32 v10, 16, v78
	v_lshlrev_b32_e32 v11, 16, v75
	ds_write_b16 v169, v2 offset:7920
	v_cvt_pk_bf16_f32 v2, v3, s0
	ds_write_b16 v0, v2 offset:7920
	v_cvt_pk_bf16_f32 v2, v4, v5
	v_cvt_pk_bf16_f32 v3, v6, v7
	v_cvt_pk_bf16_f32 v4, v8, v9
	v_cvt_pk_bf16_f32 v5, v10, v11
	ds_write_b128 v109, v[2:5] offset:16
	v_mul_f32_e32 v2, 0x3fb8aa3b, v18
	v_exp_f32_e32 v2, v2
	v_mul_f32_e32 v3, 0xbfb8aa3b, v18
	v_exp_f32_e32 v3, v3
	v_lshlrev_b32_e32 v4, 16, v74
	v_mul_f32_e32 v4, 0x3e000000, v4
	v_mul_f32_e32 v2, v4, v2
	v_lshlrev_b32_e32 v4, 16, v73
	v_mul_f32_e32 v3, v3, v4
	v_cvt_pk_bf16_f32 v2, v2, s0
	ds_write_b16 v169, v2 offset:8448
	v_cvt_pk_bf16_f32 v2, v3, s0
	ds_write_b16 v0, v2 offset:8448
	v_mul_f32_e32 v2, 0x3fb8aa3b, v19
	v_exp_f32_e32 v2, v2
	v_mul_f32_e32 v3, 0xbfb8aa3b, v19
	v_exp_f32_e32 v3, v3
	v_lshlrev_b32_e32 v5, 16, v71
	v_mul_f32_e32 v5, 0x3e000000, v5
	v_mul_f32_e32 v2, v5, v2
	v_lshlrev_b32_e32 v5, 16, v70
	v_mul_f32_e32 v3, v3, v5
	v_cvt_pk_bf16_f32 v2, v2, s0
	ds_write_b16 v169, v2 offset:8976
	v_cvt_pk_bf16_f32 v2, v3, s0
	ds_write_b16 v0, v2 offset:8976
	v_mul_f32_e32 v2, 0x3fb8aa3b, v20
	v_exp_f32_e32 v2, v2
	v_mul_f32_e32 v3, 0xbfb8aa3b, v20
	v_exp_f32_e32 v3, v3
	v_lshlrev_b32_e32 v6, 16, v68
	v_mul_f32_e32 v6, 0x3e000000, v6
	v_mul_f32_e32 v2, v6, v2
	v_lshlrev_b32_e32 v6, 16, v67
	v_mul_f32_e32 v3, v3, v6
	v_cvt_pk_bf16_f32 v2, v2, s0
	ds_write_b16 v169, v2 offset:9504
	v_cvt_pk_bf16_f32 v2, v3, s0
	ds_write_b16 v0, v2 offset:9504
	v_mul_f32_e32 v2, 0x3fb8aa3b, v21
	v_exp_f32_e32 v2, v2
	v_mul_f32_e32 v3, 0xbfb8aa3b, v21
	v_exp_f32_e32 v3, v3
	v_lshlrev_b32_e32 v7, 16, v184
	v_mul_f32_e32 v7, 0x3e000000, v7
	v_mul_f32_e32 v2, v7, v2
	v_lshlrev_b32_e32 v7, 16, v167
	v_mul_f32_e32 v3, v3, v7
	v_cvt_pk_bf16_f32 v2, v2, s0
	ds_write_b16 v169, v2 offset:10032
	v_cvt_pk_bf16_f32 v2, v3, s0
	ds_write_b16 v0, v2 offset:10032
	v_mul_f32_e32 v2, 0x3fb8aa3b, v22
	v_exp_f32_e32 v2, v2
	v_mul_f32_e32 v3, 0xbfb8aa3b, v22
	v_exp_f32_e32 v3, v3
	v_lshlrev_b32_e32 v8, 16, v162
	v_mul_f32_e32 v8, 0x3e000000, v8
	v_mul_f32_e32 v2, v8, v2
	v_lshlrev_b32_e32 v8, 16, v159
	v_mul_f32_e32 v3, v3, v8
	v_cvt_pk_bf16_f32 v2, v2, s0
	ds_write_b16 v169, v2 offset:10560
	v_cvt_pk_bf16_f32 v2, v3, s0
	ds_write_b16 v0, v2 offset:10560
	v_mul_f32_e32 v2, 0x3fb8aa3b, v23
	v_exp_f32_e32 v2, v2
	v_mul_f32_e32 v3, 0xbfb8aa3b, v23
	v_exp_f32_e32 v3, v3
	v_lshlrev_b32_e32 v9, 16, v149
	v_mul_f32_e32 v9, 0x3e000000, v9
	v_mul_f32_e32 v2, v9, v2
	v_lshlrev_b32_e32 v9, 16, v165
	v_mul_f32_e32 v3, v3, v9
	v_cvt_pk_bf16_f32 v2, v2, s0
	ds_write_b16 v169, v2 offset:11088
	v_cvt_pk_bf16_f32 v2, v3, s0
	ds_write_b16 v0, v2 offset:11088
	v_mul_f32_e32 v2, 0x3fb8aa3b, v24
	v_exp_f32_e32 v2, v2
	v_mul_f32_e32 v3, 0xbfb8aa3b, v24
	v_exp_f32_e32 v3, v3
	v_lshlrev_b32_e32 v10, 16, v158
	v_mul_f32_e32 v10, 0x3e000000, v10
	v_mul_f32_e32 v2, v10, v2
	v_lshlrev_b32_e32 v10, 16, v154
	v_mul_f32_e32 v3, v3, v10
	v_cvt_pk_bf16_f32 v2, v2, s0
	ds_write_b16 v169, v2 offset:11616
	v_cvt_pk_bf16_f32 v2, v3, s0
	ds_write_b16 v0, v2 offset:11616
	v_mul_f32_e32 v2, 0x3fb8aa3b, v25
	v_exp_f32_e32 v2, v2
	v_mul_f32_e32 v3, 0xbfb8aa3b, v25
	v_exp_f32_e32 v3, v3
	v_lshlrev_b32_e32 v11, 16, v147
	v_mul_f32_e32 v11, 0x3e000000, v11
	v_mul_f32_e32 v2, v11, v2
	v_lshlrev_b32_e32 v11, 16, v143
	v_mul_f32_e32 v3, v3, v11
	v_cvt_pk_bf16_f32 v2, v2, s0
	v_lshlrev_b32_e32 v4, 16, v72
	v_lshlrev_b32_e32 v5, 16, v69
	v_lshlrev_b32_e32 v6, 16, v186
	v_lshlrev_b32_e32 v7, 16, v166
	v_lshlrev_b32_e32 v8, 16, v157
	v_lshlrev_b32_e32 v9, 16, v164
	v_lshlrev_b32_e32 v10, 16, v153
	v_lshlrev_b32_e32 v11, 16, v142
	ds_write_b16 v169, v2 offset:12144
	v_cvt_pk_bf16_f32 v2, v3, s0
	ds_write_b16 v0, v2 offset:12144
	v_cvt_pk_bf16_f32 v2, v4, v5
	v_cvt_pk_bf16_f32 v3, v6, v7
	v_cvt_pk_bf16_f32 v4, v8, v9
	v_cvt_pk_bf16_f32 v5, v10, v11
	ds_write_b128 v109, v[2:5] offset:32
	v_mul_f32_e32 v2, 0x3fb8aa3b, v26
	v_exp_f32_e32 v2, v2
	v_mul_f32_e32 v3, 0xbfb8aa3b, v26
	v_exp_f32_e32 v3, v3
	v_lshlrev_b32_e32 v4, 16, v136
	v_mul_f32_e32 v4, 0x3e000000, v4
	v_mul_f32_e32 v2, v4, v2
	v_lshlrev_b32_e32 v4, 16, v135
	v_mul_f32_e32 v3, v3, v4
	v_cvt_pk_bf16_f32 v2, v2, s0
	ds_write_b16 v169, v2 offset:12672
	v_cvt_pk_bf16_f32 v2, v3, s0
	ds_write_b16 v0, v2 offset:12672
	v_mul_f32_e32 v2, 0x3fb8aa3b, v27
	v_exp_f32_e32 v2, v2
	v_mul_f32_e32 v3, 0xbfb8aa3b, v27
	v_exp_f32_e32 v3, v3
	v_lshlrev_b32_e32 v5, 16, v129
	v_mul_f32_e32 v5, 0x3e000000, v5
	v_mul_f32_e32 v2, v5, v2
	v_lshlrev_b32_e32 v5, 16, v128
	v_mul_f32_e32 v3, v3, v5
	v_cvt_pk_bf16_f32 v2, v2, s0
	ds_write_b16 v169, v2 offset:13200
	v_cvt_pk_bf16_f32 v2, v3, s0
	ds_write_b16 v0, v2 offset:13200
	v_mul_f32_e32 v2, 0x3fb8aa3b, v28
	v_exp_f32_e32 v2, v2
	v_mul_f32_e32 v3, 0xbfb8aa3b, v28
	v_exp_f32_e32 v3, v3
	v_lshlrev_b32_e32 v6, 16, v121
	v_mul_f32_e32 v6, 0x3e000000, v6
	v_mul_f32_e32 v2, v6, v2
	v_lshlrev_b32_e32 v6, 16, v117
	v_mul_f32_e32 v3, v3, v6
	v_cvt_pk_bf16_f32 v2, v2, s0
	ds_write_b16 v169, v2 offset:13728
	v_cvt_pk_bf16_f32 v2, v3, s0
	ds_write_b16 v0, v2 offset:13728
	v_mul_f32_e32 v2, 0x3fb8aa3b, v29
	v_exp_f32_e32 v2, v2
	v_mul_f32_e32 v3, 0xbfb8aa3b, v29
	v_exp_f32_e32 v3, v3
	v_lshlrev_b32_e32 v7, 16, v118
	v_mul_f32_e32 v7, 0x3e000000, v7
	v_mul_f32_e32 v2, v7, v2
	v_lshlrev_b32_e32 v7, 16, v116
	v_mul_f32_e32 v3, v3, v7
	v_cvt_pk_bf16_f32 v2, v2, s0
	ds_write_b16 v169, v2 offset:14256
	v_cvt_pk_bf16_f32 v2, v3, s0
	ds_write_b16 v0, v2 offset:14256
	v_mul_f32_e32 v2, 0x3fb8aa3b, v30
	v_exp_f32_e32 v2, v2
	v_mul_f32_e32 v3, 0xbfb8aa3b, v30
	v_exp_f32_e32 v3, v3
	v_lshlrev_b32_e32 v8, 16, v110
	v_mul_f32_e32 v8, 0x3e000000, v8
	v_mul_f32_e32 v2, v8, v2
	v_lshlrev_b32_e32 v8, 16, v107
	v_mul_f32_e32 v3, v3, v8
	v_cvt_pk_bf16_f32 v2, v2, s0
	ds_write_b16 v169, v2 offset:14784
	v_cvt_pk_bf16_f32 v2, v3, s0
	ds_write_b16 v0, v2 offset:14784
	v_mul_f32_e32 v2, 0x3fb8aa3b, v31
	v_exp_f32_e32 v2, v2
	v_mul_f32_e32 v3, 0xbfb8aa3b, v31
	v_exp_f32_e32 v3, v3
	v_lshlrev_b32_e32 v9, 16, v98
	v_mul_f32_e32 v9, 0x3e000000, v9
	v_mul_f32_e32 v2, v9, v2
	s_waitcnt vmcnt(0)
	v_lshlrev_b32_e32 v9, 16, v108
	v_mul_f32_e32 v3, v3, v9
	v_cvt_pk_bf16_f32 v2, v2, s0
	ds_write_b16 v169, v2 offset:15312
	v_cvt_pk_bf16_f32 v2, v3, s0
	ds_write_b16 v0, v2 offset:15312
	v_mul_f32_e32 v2, 0x3fb8aa3b, v32
	v_exp_f32_e32 v2, v2
	v_mul_f32_e32 v3, 0xbfb8aa3b, v32
	v_exp_f32_e32 v3, v3
	v_lshlrev_b32_e32 v10, 16, v99
	v_mul_f32_e32 v10, 0x3e000000, v10
	v_mul_f32_e32 v2, v10, v2
	v_lshlrev_b32_e32 v10, 16, v97
	v_mul_f32_e32 v3, v3, v10
	v_cvt_pk_bf16_f32 v2, v2, s0
	ds_write_b16 v169, v2 offset:15840
	v_cvt_pk_bf16_f32 v2, v3, s0
	ds_write_b16 v0, v2 offset:15840
	v_mul_f32_e32 v2, 0x3fb8aa3b, v33
	v_exp_f32_e32 v2, v2
	v_mul_f32_e32 v3, 0xbfb8aa3b, v33
	v_exp_f32_e32 v3, v3
	v_lshlrev_b32_e32 v11, 16, v88
	v_mul_f32_e32 v11, 0x3e000000, v11
	v_mul_f32_e32 v2, v11, v2
	v_lshlrev_b32_e32 v11, 16, v83
	v_mul_f32_e32 v3, v3, v11
	v_cvt_pk_bf16_f32 v2, v2, s0
	s_bfe_u32 s80, s11, 0x10006
	ds_write_b16 v169, v2 offset:16368
	v_cvt_pk_bf16_f32 v2, v3, s0
	s_lshl_b32 s2, s80, 5
	ds_write_b16 v0, v2 offset:16368
	v_or_b32_e32 v0, s2, v89
	s_movk_i32 s94, 0x210
	v_lshlrev_b32_e32 v4, 16, v134
	v_lshlrev_b32_e32 v5, 16, v127
	v_lshlrev_b32_e32 v6, 16, v125
	v_lshlrev_b32_e32 v7, 16, v115
	v_lshlrev_b32_e32 v8, 16, v104
	v_lshlrev_b32_e32 v9, 16, v105
	v_lshlrev_b32_e32 v10, 16, v95
	v_lshlrev_b32_e32 v11, 16, v80
	s_and_b32 s11, s11, 0xffffff80
	v_mad_u32_u24 v0, v0, s94, v66
	v_cvt_pk_bf16_f32 v2, v4, v5
	v_cvt_pk_bf16_f32 v3, v6, v7
	v_cvt_pk_bf16_f32 v4, v8, v9
	v_cvt_pk_bf16_f32 v5, v10, v11
	v_add3_u32 v0, v0, v82, s11
	ds_write_b128 v109, v[2:5] offset:48
	s_waitcnt lgkmcnt(0)
	s_barrier
	ds_read_b128 v[66:69], v0
	ds_read_b128 v[70:73], v0 offset:32
	s_waitcnt lgkmcnt(1)
	v_mfma_f32_32x32x16_bf16 v[2:17], v[62:65], v[66:69], 0
	ds_read_b128 v[74:77], v0 offset:64
	ds_read_b128 v[78:81], v0 offset:96
	v_lshrrev_b32_e32 v83, 3, v84
	s_or_b32 s2, s2, s7
	v_or_b32_e32 v90, s2, v83
	s_lshl_b32 s2, s10, 6
	s_ashr_i32 s3, s2, 31
	v_lshlrev_b32_e32 v0, 3, v84
	s_waitcnt lgkmcnt(2)
	v_mfma_f32_32x32x16_bf16 v[2:17], v[58:61], v[70:73], v[2:17]
	v_and_b32_e32 v92, 56, v0
	s_lshl_b64 s[76:77], s[2:3], 1
	v_lshlrev_b32_e32 v0, 1, v92
	v_or_b32_e32 v88, 8, v90
	v_or_b32_e32 v86, 16, v90
	v_or_b32_e32 v84, 24, v90
	s_mul_i32 s7, s10, 0x2400
	s_waitcnt lgkmcnt(1)
	v_mfma_f32_32x32x16_bf16 v[2:17], v[54:57], v[74:77], v[2:17]
	v_mov_b64_e32 v[54:55], s[26:27]
	v_mad_i64_i32 v[18:19], s[38:39], v90, s18, v[54:55]
	v_lshl_add_u64 v[18:19], v[18:19], 0, s[76:77]
	v_ashrrev_i32_e32 v91, 31, v90
	s_waitcnt lgkmcnt(0)
	v_mfma_f32_32x32x16_bf16 v[2:17], v[50:53], v[78:81], v[2:17]
	v_lshl_add_u64 v[50:51], v[18:19], 0, v[0:1]
	v_mad_i64_i32 v[52:53], s[38:39], v88, s18, v[54:55]
	v_mfma_f32_32x32x16_bf16 v[18:33], v[46:49], v[66:69], 0
	v_lshl_add_u64 v[46:47], v[52:53], 0, s[76:77]
	v_lshl_add_u64 v[46:47], v[46:47], 0, v[0:1]
	global_load_dwordx4 v[62:65], v[50:51], off offset:1536
	global_load_dwordx4 v[58:61], v[46:47], off offset:1536
	v_mad_i64_i32 v[46:47], s[38:39], v86, s18, v[54:55]
	v_mfma_f32_32x32x16_bf16 v[18:33], v[42:45], v[70:73], v[18:33]
	v_lshl_add_u64 v[42:43], v[46:47], 0, s[76:77]
	v_mad_i64_i32 v[44:45], s[38:39], v84, s18, v[54:55]
	v_lshl_add_u64 v[42:43], v[42:43], 0, v[0:1]
	v_lshl_add_u64 v[44:45], v[44:45], 0, s[76:77]
	v_lshl_add_u64 v[44:45], v[44:45], 0, v[0:1]
	global_load_dwordx4 v[54:57], v[42:43], off offset:1536
	global_load_dwordx4 v[50:53], v[44:45], off offset:1536
	v_mfma_f32_32x32x16_bf16 v[18:33], v[38:41], v[74:77], v[18:33]
	v_lshlrev_b32_e32 v0, 3, v93
	v_mfma_f32_32x32x16_bf16 v[18:33], v[34:37], v[78:81], v[18:33]
	v_lshlrev_b32_e32 v34, 2, v93
	v_or_b32_e32 v35, 2, v34
	v_cmp_gt_u32_e64 s[40:41], v35, v89
	v_or_b32_e32 v35, 3, v34
	v_cmp_gt_u32_e64 s[42:43], v35, v89
	v_or_b32_e32 v35, 8, v34
	v_cmp_gt_u32_e64 s[44:45], v35, v89
	v_or_b32_e32 v35, 9, v34
	v_cmp_gt_u32_e64 s[46:47], v35, v89
	v_or_b32_e32 v35, 10, v34
	v_cmp_gt_u32_e64 s[48:49], v35, v89
	v_or_b32_e32 v35, 11, v34
	v_cmp_gt_u32_e64 s[50:51], v35, v89
	v_or_b32_e32 v35, 16, v34
	v_cmp_gt_u32_e64 s[52:53], v35, v89
	v_or_b32_e32 v35, 17, v34
	v_cmp_gt_u32_e64 s[54:55], v35, v89
	v_or_b32_e32 v35, 18, v34
	v_cmp_gt_u32_e64 s[56:57], v35, v89
	v_or_b32_e32 v35, 19, v34
	v_cmp_gt_u32_e64 s[58:59], v35, v89
	v_or_b32_e32 v35, 24, v34
	v_cmp_gt_u32_e64 s[60:61], v35, v89
	v_or_b32_e32 v35, 25, v34
	v_cmp_gt_u32_e32 vcc, v34, v89
	v_cmp_lt_u32_e64 s[38:39], v34, v89
	v_cmp_gt_u32_e64 s[62:63], v35, v89
	v_or_b32_e32 v35, 26, v34
	v_or_b32_e32 v34, 27, v34
	v_cmp_gt_u32_e64 s[66:67], v34, v89
	v_mov_b32_e32 v34, s7
	v_mad_u32_u24 v34, v89, s89, v34
	v_or_b32_e32 v34, v34, v0
	v_add_u32_e32 v87, v87, v34
	v_mov_b32_e32 v34, s11
	v_mad_u32_u24 v34, v89, s94, v34
	v_cmp_gt_u32_e64 s[64:65], v35, v89
	s_sub_i32 s7, 0, s80
	v_add3_u32 v82, v34, v82, v85
	s_branch .LBB0_170

.LBB0_173:
	s_and_b64 vcc, exec, s[2:3]
	s_cbranch_vccz .LBB0_253
	s_add_i32 s2, s85, 0xfffffe00
	s_lshr_b32 s2, s2, 7
	s_bfe_u32 s3, s85, 0x60001
	s_and_b32 s6, s85, 1
	s_lshl_b32 s7, s3, 7
	s_lshl_b32 s10, s2, 8
	s_lshl_b32 s3, s3, 2
	s_lshl_b32 s2, s2, 13
	s_lshl_b32 s54, s6, 1
	s_or_b32 s3, s3, s10
	s_or_b32 s52, s7, s2
	s_mov_b32 s2, 14
	s_or_b32 s38, s3, s54
	s_ashr_i32 s3, s2, 31
	s_lshl_b32 s53, s6, 7
	s_add_i32 s58, s52, -3
	s_sub_i32 s57, 0, s7
	s_lshl_b64 s[2:3], s[2:3], 3
	s_add_u32 s2, s0, s2
	s_mov_b32 s6, 15
	s_addc_u32 s3, s1, s3
	s_ashr_i32 s7, s6, 31
	s_lshl_b64 s[6:7], s[6:7], 3
	s_add_u32 s6, s0, s6
	s_mov_b32 s10, 16
	s_addc_u32 s7, s1, s7
	s_ashr_i32 s11, s10, 31
	s_lshl_b64 s[10:11], s[10:11], 3
	s_add_u32 s10, s0, s10
	s_mov_b32 s20, 17
	s_addc_u32 s11, s1, s11
	s_ashr_i32 s21, s20, 31
	s_lshl_b64 s[20:21], s[20:21], 3
	s_add_u32 s40, s0, s20
	s_mov_b32 s20, 18
	s_addc_u32 s41, s1, s21
	s_ashr_i32 s21, s20, 31
	s_lshl_b64 s[20:21], s[20:21], 3
	s_add_u32 s42, s0, s20
	s_mov_b32 s20, 19
	s_addc_u32 s43, s1, s21
	s_ashr_i32 s21, s20, 31
	s_lshl_b64 s[20:21], s[20:21], 3
	s_add_u32 s50, s0, s20
	v_mov_b32_e32 v104, v183
	v_readlane_b32 s20, v254, 53
	s_addc_u32 s51, s1, s21
	v_readfirstlane_b32 s55, v104
	s_bitcmp1_b32 s55, 8
	s_cselect_b32 s21, 0xc0, 0
	s_xor_b32 s55, s55, s21
	v_mov_b32_e32 v99, s20
	v_readlane_b32 s20, v254, 54
	s_ashr_i32 s56, s55, 8
	v_lshrrev_b32_e32 v0, 1, v104
	v_mov_b32_e32 v103, s20
	v_readlane_b32 s20, v254, 55
	v_and_b32_e32 v0, 16, v0
	v_and_b32_e32 v98, 63, v104
	v_mov_b32_e32 v101, s20
	s_add_i32 s20, s38, s56
	s_ashr_i32 s21, s20, 31
	s_lshl_b64 s[20:21], s[20:21], 14
	v_readlane_b32 s38, v254, 62
	v_readlane_b32 s39, v254, 63
	s_add_u32 s20, s38, s20
	s_addc_u32 s21, s39, s21
	v_lshl_add_u64 v[6:7], s[20:21], 0, v[0:1]
	v_lshlrev_b32_e32 v0, 8, v104
	v_and_b32_e32 v0, 0x1f00, v0
	v_lshl_add_u64 v[8:9], v[6:7], 0, v[0:1]
	v_mov_b32_e32 v0, 0x2000
	v_lshl_or_b32 v0, v98, 8, v0
	v_mov_b32_e32 v102, v1
	v_lshl_add_u64 v[6:7], v[6:7], 0, v[0:1]
	s_waitcnt lgkmcnt(0)
	s_barrier
	global_load_dwordx4 v[2:5], v[8:9], off
	global_load_dwordx4 v[78:81], v[8:9], off offset:32
	global_load_dwordx4 v[74:77], v[8:9], off offset:64
	global_load_dwordx4 v[66:69], v[8:9], off offset:96
	global_load_dwordx4 v[58:61], v[8:9], off offset:128
	global_load_dwordx4 v[54:57], v[8:9], off offset:160
	global_load_dwordx4 v[46:49], v[8:9], off offset:192
	global_load_dwordx4 v[38:41], v[8:9], off offset:224
	global_load_dwordx4 v[18:21], v[6:7], off
	global_load_dwordx4 v[86:89], v[6:7], off offset:32
	global_load_dwordx4 v[82:85], v[6:7], off offset:64
	global_load_dwordx4 v[70:73], v[6:7], off offset:96
	global_load_dwordx4 v[62:65], v[6:7], off offset:128
	global_load_dwordx4 v[50:53], v[6:7], off offset:160
	global_load_dwordx4 v[42:45], v[6:7], off offset:192
	global_load_dwordx4 v[34:37], v[6:7], off offset:224
	s_mov_b32 s20, 0x2aaaaaab
	v_mul_hi_i32 v0, v104, s20
	v_lshrrev_b32_e32 v6, 31, v0
	v_ashrrev_i32_e32 v0, 6, v0
	v_add_u32_e32 v25, v0, v6
	v_mul_i32_i24_e32 v0, 0x180, v25
	v_sub_u32_e32 v14, v104, v0
	v_lshlrev_b32_e32 v213, 1, v14
	v_and_b32_e32 v27, 0x7f, v14
	v_and_b32_e32 v0, 0xffffff00, v213
	v_lshlrev_b32_e32 v10, 5, v25
	v_or3_b32 v6, s53, v0, v27
	v_add_u32_e32 v0, s58, v10
	v_mov_b64_e32 v[8:9], s[26:27]
	v_mad_i64_i32 v[8:9], s[20:21], v0, s18, v[8:9]
	v_ashrrev_i32_e32 v7, 31, v6
	v_lshl_add_u64 v[6:7], v[6:7], 1, v[8:9]
	v_cmp_lt_i32_e64 s[38:39], s57, v10
	v_mov_b32_e32 v15, 0
	v_mov_b32_e32 v16, 0
	v_mov_b32_e32 v17, 0
	v_mov_b32_e32 v228, 0
	v_mov_b32_e32 v229, 0
	s_and_saveexec_b64 s[20:21], s[38:39]
	s_cbranch_execz .LBB0_176
	v_add_co_u32_e32 v8, vcc, 0x2000, v6
	s_nop 1
	v_addc_co_u32_e32 v9, vcc, 0, v7, vcc
	global_load_ushort v228, v[8:9], off offset:3584
	v_add_co_u32_e32 v8, vcc, 0x1000, v6
	s_nop 0
	s_nop 0
	v_addc_co_u32_e32 v9, vcc, 0, v7, vcc
	global_load_ushort v229, v[8:9], off
	s_nop 0
	s_nop 0
.LBB0_176:
	s_or_b64 exec, exec, s[20:21]
	s_load_dwordx2 s[46:47], s[2:3], 0x0
	s_load_dwordx2 s[44:45], s[6:7], 0x0
	s_load_dwordx2 s[20:21], s[10:11], 0x0
	s_load_dwordx2 s[48:49], s[40:41], 0x0
	s_nop 0
	s_load_dwordx2 s[42:43], s[42:43], 0x0
	s_nop 0
	s_load_dwordx2 s[40:41], s[50:51], 0x0
	v_mov_b32_e32 v230, 0
	s_and_saveexec_b64 s[2:3], s[38:39]
	s_cbranch_execz .LBB0_178
	v_add_co_u32_e32 v8, vcc, 0x4000, v6
	s_nop 1
	v_addc_co_u32_e32 v9, vcc, 0, v7, vcc
	global_load_ushort v230, v[8:9], off offset:3072
	s_nop 0
	s_nop 0
.LBB0_178:
	s_or_b64 exec, exec, s[2:3]
	v_add_co_u32_e32 v8, vcc, 0x6000, v6
	s_mov_b32 s2, 0xc000
	s_nop 0
	v_addc_co_u32_e32 v9, vcc, 0, v7, vcc
	global_load_ushort v92, v[8:9], off offset:2560
	v_add_co_u32_e32 v8, vcc, 0x8000, v6
	v_add_u32_e32 v0, 0x200, v104
	s_nop 0
	v_addc_co_u32_e32 v9, vcc, 0, v7, vcc
	global_load_ushort v93, v[8:9], off offset:2048
	v_add_co_u32_e32 v8, vcc, 0xa000, v6
	v_mov_b32_e32 v11, 0
	s_nop 0
	v_addc_co_u32_e32 v9, vcc, 0, v7, vcc
	global_load_ushort v30, v[8:9], off offset:1536
	v_add_co_u32_e32 v8, vcc, s2, v6
	s_mov_b32 s2, 0x11000
	s_nop 0
	v_addc_co_u32_e32 v9, vcc, 0, v7, vcc
	global_load_ushort v31, v[8:9], off offset:1024
	v_add_co_u32_e32 v8, vcc, 0xe000, v6
	v_mov_b32_e32 v12, 0
	s_nop 0
	v_addc_co_u32_e32 v9, vcc, 0, v7, vcc
	global_load_ushort v32, v[8:9], off offset:512
	v_add_co_u32_e32 v8, vcc, s28, v6
	v_mov_b32_e32 v13, 0
	s_nop 0
	v_addc_co_u32_e32 v9, vcc, 0, v7, vcc
	global_load_ushort v90, v[8:9], off
	v_add_co_u32_e32 v8, vcc, s2, v6
	s_mov_b32 s2, 0x20000
	s_nop 0
	v_addc_co_u32_e32 v9, vcc, 0, v7, vcc
	global_load_ushort v33, v[8:9], off offset:3584
	v_add_co_u32_e32 v8, vcc, 0x13000, v6
	s_nop 1
	v_addc_co_u32_e32 v9, vcc, 0, v7, vcc
	global_load_ushort v91, v[8:9], off offset:3072
	v_add_co_u32_e32 v8, vcc, 0x15000, v6
	s_nop 1
	v_addc_co_u32_e32 v9, vcc, 0, v7, vcc
	global_load_ushort v214, v[8:9], off offset:2560
	v_add_co_u32_e32 v8, vcc, 0x17000, v6
	s_nop 1
	v_addc_co_u32_e32 v9, vcc, 0, v7, vcc
	global_load_ushort v215, v[8:9], off offset:2048
	v_add_co_u32_e32 v8, vcc, 0x19000, v6
	s_nop 1
	v_addc_co_u32_e32 v9, vcc, 0, v7, vcc
	global_load_ushort v211, v[8:9], off offset:1536
	v_add_co_u32_e32 v8, vcc, 0x1b000, v6
	s_nop 1
	v_addc_co_u32_e32 v9, vcc, 0, v7, vcc
	global_load_ushort v212, v[8:9], off offset:1024
	v_add_co_u32_e32 v8, vcc, 0x1d000, v6
	s_nop 1
	v_addc_co_u32_e32 v9, vcc, 0, v7, vcc
	global_load_ushort v94, v[8:9], off offset:512
	v_add_co_u32_e32 v8, vcc, 0x1f000, v6
	s_nop 1
	v_addc_co_u32_e32 v9, vcc, 0, v7, vcc
	global_load_ushort v95, v[8:9], off
	v_add_co_u32_e32 v8, vcc, s2, v6
	s_mov_b32 s2, 0x28000
	s_nop 0
	v_addc_co_u32_e32 v9, vcc, 0, v7, vcc
	global_load_ushort v96, v[8:9], off offset:3584
	v_add_co_u32_e32 v8, vcc, 0x22000, v6
	s_nop 1
	v_addc_co_u32_e32 v9, vcc, 0, v7, vcc
	global_load_ushort v97, v[8:9], off offset:3072
	v_add_co_u32_e32 v8, vcc, 0x24000, v6
	s_nop 1
	v_addc_co_u32_e32 v9, vcc, 0, v7, vcc
	global_load_ushort v209, v[8:9], off offset:2560
	v_add_co_u32_e32 v8, vcc, 0x26000, v6
	s_nop 1
	v_addc_co_u32_e32 v9, vcc, 0, v7, vcc
	global_load_ushort v210, v[8:9], off offset:2048
	v_add_co_u32_e32 v8, vcc, s2, v6
	s_mov_b32 s2, 0x2aaaaaab
	s_nop 0
	v_addc_co_u32_e32 v9, vcc, 0, v7, vcc
	global_load_ushort v207, v[8:9], off offset:1536
	v_add_co_u32_e32 v8, vcc, 0x2a000, v6
	s_nop 1
	v_addc_co_u32_e32 v9, vcc, 0, v7, vcc
	global_load_ushort v208, v[8:9], off offset:1024
	v_add_co_u32_e32 v8, vcc, 0x2c000, v6
	s_nop 1
	v_addc_co_u32_e32 v9, vcc, 0, v7, vcc
	global_load_ushort v203, v[8:9], off offset:512
	v_add_co_u32_e32 v8, vcc, 0x2e000, v6
	s_nop 1
	v_addc_co_u32_e32 v9, vcc, 0, v7, vcc
	global_load_ushort v204, v[8:9], off
	v_add_co_u32_e32 v8, vcc, 0x2f000, v6
	s_nop 1
	v_addc_co_u32_e32 v9, vcc, 0, v7, vcc
	global_load_ushort v205, v[8:9], off offset:3584
	v_add_co_u32_e32 v8, vcc, 0x31000, v6
	s_nop 1
	v_addc_co_u32_e32 v9, vcc, 0, v7, vcc
	global_load_ushort v206, v[8:9], off offset:3072
	v_add_co_u32_e32 v8, vcc, 0x33000, v6
	s_nop 1
	v_addc_co_u32_e32 v9, vcc, 0, v7, vcc
	global_load_ushort v201, v[8:9], off offset:2560
	v_add_co_u32_e32 v8, vcc, 0x35000, v6
	s_nop 1
	v_addc_co_u32_e32 v9, vcc, 0, v7, vcc
	global_load_ushort v202, v[8:9], off offset:2048
	v_add_co_u32_e32 v8, vcc, 0x37000, v6
	s_nop 1
	v_addc_co_u32_e32 v9, vcc, 0, v7, vcc
	global_load_ushort v199, v[8:9], off offset:1536
	v_add_co_u32_e32 v8, vcc, 0x39000, v6
	s_nop 1
	v_addc_co_u32_e32 v9, vcc, 0, v7, vcc
	global_load_ushort v200, v[8:9], off offset:1024
	v_add_co_u32_e32 v8, vcc, 0x3b000, v6
	s_nop 1
	v_addc_co_u32_e32 v9, vcc, 0, v7, vcc
	global_load_ushort v197, v[8:9], off offset:512
	v_add_co_u32_e32 v8, vcc, 0x3d000, v6
	s_nop 1
	v_addc_co_u32_e32 v9, vcc, 0, v7, vcc
	global_load_ushort v198, v[8:9], off
	v_add_co_u32_e32 v8, vcc, 0x3e000, v6
	s_nop 1
	v_addc_co_u32_e32 v9, vcc, 0, v7, vcc
	v_add_co_u32_e32 v6, vcc, s29, v6
	global_load_ushort v195, v[8:9], off offset:3584
	s_nop 0
	v_addc_co_u32_e32 v7, vcc, 0, v7, vcc
	global_load_ushort v196, v[6:7], off offset:3072
	v_mul_hi_i32 v6, v0, s2
	v_lshrrev_b32_e32 v7, 31, v6
	v_ashrrev_i32_e32 v6, 6, v6
	v_add_u32_e32 v161, v6, v7
	v_mul_i32_i24_e32 v6, 0x180, v161
	v_sub_u32_e32 v192, v0, v6
	v_lshlrev_b32_e32 v185, 1, v192
	v_and_b32_e32 v169, 0x7f, v192
	v_and_b32_e32 v0, 0xffffff00, v185
	v_lshlrev_b32_e32 v135, 5, v161
	v_or3_b32 v6, s53, v0, v169
	v_add_u32_e32 v0, s58, v135
	v_mov_b64_e32 v[8:9], s[26:27]
	v_mad_i64_i32 v[8:9], s[2:3], v0, s18, v[8:9]
	v_ashrrev_i32_e32 v7, 31, v6
	v_lshl_add_u64 v[6:7], v[6:7], 1, v[8:9]
	v_cmp_lt_i32_e64 s[38:39], s57, v135
	v_mov_b32_e32 v231, 0
	v_mov_b32_e32 v232, 0
	s_and_saveexec_b64 s[2:3], s[38:39]
	s_cbranch_execz .LBB0_180
	v_add_co_u32_e32 v8, vcc, 0x2000, v6
	s_nop 1
	v_addc_co_u32_e32 v9, vcc, 0, v7, vcc
	global_load_ushort v231, v[8:9], off offset:3584
	v_add_co_u32_e32 v8, vcc, 0x1000, v6
	s_nop 0
	s_nop 0
	v_addc_co_u32_e32 v9, vcc, 0, v7, vcc
	global_load_ushort v232, v[8:9], off
	s_nop 0
	s_nop 0
.LBB0_180:
	s_or_b64 exec, exec, s[2:3]
	v_mov_b32_e32 v233, 0
	s_and_saveexec_b64 s[2:3], s[38:39]
	s_cbranch_execz .LBB0_182
	v_add_co_u32_e32 v8, vcc, 0x4000, v6
	s_nop 1
	v_addc_co_u32_e32 v9, vcc, 0, v7, vcc
	global_load_ushort v233, v[8:9], off offset:3072
	s_nop 0
	s_nop 0
.LBB0_182:
	s_or_b64 exec, exec, s[2:3]
	v_add_co_u32_e32 v8, vcc, 0x6000, v6
	s_mov_b32 s2, 0xc000
	s_nop 0
	v_addc_co_u32_e32 v9, vcc, 0, v7, vcc
	global_load_ushort v193, v[8:9], off offset:2560
	v_add_co_u32_e32 v8, vcc, 0x8000, v6
	v_add_u32_e32 v0, 0x400, v104
	s_nop 0
	v_addc_co_u32_e32 v9, vcc, 0, v7, vcc
	global_load_ushort v194, v[8:9], off offset:2048
	v_add_co_u32_e32 v8, vcc, 0xa000, v6
	s_nop 1
	v_addc_co_u32_e32 v9, vcc, 0, v7, vcc
	global_load_ushort v190, v[8:9], off offset:1536
	v_add_co_u32_e32 v8, vcc, s2, v6
	s_mov_b32 s2, 0x11000
	s_nop 0
	v_addc_co_u32_e32 v9, vcc, 0, v7, vcc
	global_load_ushort v191, v[8:9], off offset:1024
	v_add_co_u32_e32 v8, vcc, 0xe000, v6
	s_nop 1
	v_addc_co_u32_e32 v9, vcc, 0, v7, vcc
	global_load_ushort v186, v[8:9], off offset:512
	v_add_co_u32_e32 v8, vcc, s28, v6
	s_nop 1
	v_addc_co_u32_e32 v9, vcc, 0, v7, vcc
	global_load_ushort v187, v[8:9], off
	v_add_co_u32_e32 v8, vcc, s2, v6
	s_mov_b32 s2, 0x20000
	s_nop 0
	v_addc_co_u32_e32 v9, vcc, 0, v7, vcc
	global_load_ushort v188, v[8:9], off offset:3584
	v_add_co_u32_e32 v8, vcc, 0x13000, v6
	s_nop 1
	v_addc_co_u32_e32 v9, vcc, 0, v7, vcc
	global_load_ushort v189, v[8:9], off offset:3072
	v_add_co_u32_e32 v8, vcc, 0x15000, v6
	s_nop 1
	v_addc_co_u32_e32 v9, vcc, 0, v7, vcc
	global_load_ushort v168, v[8:9], off offset:2560
	v_add_co_u32_e32 v8, vcc, 0x17000, v6
	s_nop 1
	v_addc_co_u32_e32 v9, vcc, 0, v7, vcc
	global_load_ushort v184, v[8:9], off offset:2048
	v_add_co_u32_e32 v8, vcc, 0x19000, v6
	s_nop 1
	v_addc_co_u32_e32 v9, vcc, 0, v7, vcc
	global_load_ushort v166, v[8:9], off offset:1536
	v_add_co_u32_e32 v8, vcc, 0x1b000, v6
	s_nop 1
	v_addc_co_u32_e32 v9, vcc, 0, v7, vcc
	global_load_ushort v167, v[8:9], off offset:1024
	v_add_co_u32_e32 v8, vcc, 0x1d000, v6
	s_nop 1
	v_addc_co_u32_e32 v9, vcc, 0, v7, vcc
	global_load_ushort v162, v[8:9], off offset:512
	v_add_co_u32_e32 v8, vcc, 0x1f000, v6
	s_nop 1
	v_addc_co_u32_e32 v9, vcc, 0, v7, vcc
	global_load_ushort v163, v[8:9], off
	v_add_co_u32_e32 v8, vcc, s2, v6
	s_mov_b32 s2, 0x28000
	s_nop 0
	v_addc_co_u32_e32 v9, vcc, 0, v7, vcc
	global_load_ushort v164, v[8:9], off offset:3584
	v_add_co_u32_e32 v8, vcc, 0x22000, v6
	s_nop 1
	v_addc_co_u32_e32 v9, vcc, 0, v7, vcc
	global_load_ushort v165, v[8:9], off offset:3072
	v_add_co_u32_e32 v8, vcc, 0x24000, v6
	s_nop 1
	v_addc_co_u32_e32 v9, vcc, 0, v7, vcc
	s_nop 0
	global_load_ushort v159, v[8:9], off offset:2560
	v_add_co_u32_e32 v8, vcc, 0x26000, v6
	s_nop 1
	v_addc_co_u32_e32 v9, vcc, 0, v7, vcc
	global_load_ushort v160, v[8:9], off offset:2048
	v_add_co_u32_e32 v8, vcc, s2, v6
	s_mov_b32 s2, 0x2aaaaaab
	s_nop 0
	v_addc_co_u32_e32 v9, vcc, 0, v7, vcc
	global_load_ushort v157, v[8:9], off offset:1536
	v_add_co_u32_e32 v8, vcc, 0x2a000, v6
	s_nop 1
	v_addc_co_u32_e32 v9, vcc, 0, v7, vcc
	global_load_ushort v158, v[8:9], off offset:1024
	v_add_co_u32_e32 v8, vcc, 0x2c000, v6
	s_nop 1
	v_addc_co_u32_e32 v9, vcc, 0, v7, vcc
	global_load_ushort v153, v[8:9], off offset:512
	v_add_co_u32_e32 v8, vcc, 0x2e000, v6
	s_nop 1
	v_addc_co_u32_e32 v9, vcc, 0, v7, vcc
	global_load_ushort v154, v[8:9], off
	v_add_co_u32_e32 v8, vcc, 0x2f000, v6
	s_nop 1
	v_addc_co_u32_e32 v9, vcc, 0, v7, vcc
	global_load_ushort v155, v[8:9], off offset:3584
	v_add_co_u32_e32 v8, vcc, 0x31000, v6
	s_nop 1
	v_addc_co_u32_e32 v9, vcc, 0, v7, vcc
	global_load_ushort v156, v[8:9], off offset:3072
	v_add_co_u32_e32 v8, vcc, 0x33000, v6
	s_nop 1
	v_addc_co_u32_e32 v9, vcc, 0, v7, vcc
	global_load_ushort v151, v[8:9], off offset:2560
	v_add_co_u32_e32 v8, vcc, 0x35000, v6
	s_nop 1
	v_addc_co_u32_e32 v9, vcc, 0, v7, vcc
	global_load_ushort v152, v[8:9], off offset:2048
	v_add_co_u32_e32 v8, vcc, 0x37000, v6
	s_nop 1
	v_addc_co_u32_e32 v9, vcc, 0, v7, vcc
	global_load_ushort v149, v[8:9], off offset:1536
	v_add_co_u32_e32 v8, vcc, 0x39000, v6
	s_nop 1
	v_addc_co_u32_e32 v9, vcc, 0, v7, vcc
	global_load_ushort v150, v[8:9], off offset:1024
	v_add_co_u32_e32 v8, vcc, 0x3b000, v6
	s_nop 1
	v_addc_co_u32_e32 v9, vcc, 0, v7, vcc
	global_load_ushort v147, v[8:9], off offset:512
	v_add_co_u32_e32 v8, vcc, 0x3d000, v6
	s_nop 1
	v_addc_co_u32_e32 v9, vcc, 0, v7, vcc
	global_load_ushort v148, v[8:9], off
	v_add_co_u32_e32 v8, vcc, 0x3e000, v6
	s_nop 1
	v_addc_co_u32_e32 v9, vcc, 0, v7, vcc
	v_add_co_u32_e32 v6, vcc, s29, v6
	global_load_ushort v143, v[8:9], off offset:3584
	s_nop 0
	v_addc_co_u32_e32 v7, vcc, 0, v7, vcc
	global_load_ushort v144, v[6:7], off offset:3072
	v_mul_hi_i32 v6, v0, s2
	v_lshrrev_b32_e32 v7, 31, v6
	v_ashrrev_i32_e32 v6, 6, v6
	v_add_u32_e32 v122, v6, v7
	v_mul_i32_i24_e32 v6, 0x180, v122
	v_sub_u32_e32 v140, v0, v6
	v_lshlrev_b32_e32 v132, 1, v140
	v_and_b32_e32 v130, 0x7f, v140
	v_and_b32_e32 v0, 0xffffff00, v132
	v_lshlrev_b32_e32 v100, 5, v122
	v_or3_b32 v6, s53, v0, v130
	v_add_u32_e32 v0, s58, v100
	v_mov_b64_e32 v[8:9], s[26:27]
	v_mad_i64_i32 v[8:9], s[2:3], v0, s18, v[8:9]
	v_ashrrev_i32_e32 v7, 31, v6
	v_lshl_add_u64 v[22:23], v[6:7], 1, v[8:9]
	v_cmp_lt_i32_e64 s[38:39], s57, v100
	v_mov_b32_e32 v7, 0
	v_mov_b32_e32 v8, 0
	v_mov_b32_e32 v9, 0
	v_mov_b32_e32 v234, 0
	v_mov_b32_e32 v235, 0
	s_and_saveexec_b64 s[2:3], s[38:39]
	s_cbranch_execz .LBB0_184
	v_add_co_u32_e32 v8, vcc, 0x2000, v22
	s_nop 1
	v_addc_co_u32_e32 v9, vcc, 0, v23, vcc
	global_load_ushort v234, v[8:9], off offset:3584
	v_add_co_u32_e32 v8, vcc, 0x1000, v22
	s_nop 1
	v_addc_co_u32_e32 v9, vcc, 0, v23, vcc
	global_load_ushort v235, v[8:9], off
	s_nop 0
	s_nop 0
	s_nop 0
.LBB0_184:
	s_or_b64 exec, exec, s[2:3]
	v_mov_b32_e32 v236, 0
	s_and_saveexec_b64 s[2:3], s[38:39]
	s_cbranch_execz .LBB0_186
	v_add_co_u32_e32 v6, vcc, 0x4000, v22
	s_nop 1
	v_addc_co_u32_e32 v7, vcc, 0, v23, vcc
	global_load_ushort v236, v[6:7], off offset:3072
	s_nop 0
	s_nop 0
.LBB0_186:
	s_or_b64 exec, exec, s[2:3]
	v_add_co_u32_e32 v28, vcc, 0x6000, v22
	s_mov_b32 s2, 0xc000
	s_nop 0
	v_addc_co_u32_e32 v29, vcc, 0, v23, vcc
	global_load_ushort v141, v[28:29], off offset:2560
	v_add_co_u32_e32 v28, vcc, 0x8000, v22
	v_lshlrev_b32_e32 v0, 2, v104
	s_nop 0
	v_addc_co_u32_e32 v29, vcc, 0, v23, vcc
	global_load_ushort v142, v[28:29], off offset:2048
	v_add_co_u32_e32 v28, vcc, 0xa000, v22
	v_bfe_u32 v6, v104, 7, 1
	s_nop 0
	v_addc_co_u32_e32 v29, vcc, 0, v23, vcc
	global_load_ushort v138, v[28:29], off offset:1536
	v_add_co_u32_e32 v28, vcc, s2, v22
	s_mov_b32 s2, 0x11000
	s_nop 0
	v_addc_co_u32_e32 v29, vcc, 0, v23, vcc
	global_load_ushort v139, v[28:29], off offset:1024
	v_add_co_u32_e32 v28, vcc, 0xe000, v22
	s_nop 1
	v_addc_co_u32_e32 v29, vcc, 0, v23, vcc
	global_load_ushort v133, v[28:29], off offset:512
	v_add_co_u32_e32 v28, vcc, s28, v22
	s_nop 1
	v_addc_co_u32_e32 v29, vcc, 0, v23, vcc
	global_load_ushort v134, v[28:29], off
	v_add_co_u32_e32 v28, vcc, s2, v22
	s_mov_b32 s2, 0x20000
	s_nop 0
	v_addc_co_u32_e32 v29, vcc, 0, v23, vcc
	global_load_ushort v136, v[28:29], off offset:3584
	v_add_co_u32_e32 v28, vcc, 0x13000, v22
	s_nop 1
	v_addc_co_u32_e32 v29, vcc, 0, v23, vcc
	global_load_ushort v137, v[28:29], off offset:3072
	v_add_co_u32_e32 v28, vcc, 0x15000, v22
	s_nop 1
	v_addc_co_u32_e32 v29, vcc, 0, v23, vcc
	global_load_ushort v129, v[28:29], off offset:2560
	v_add_co_u32_e32 v28, vcc, 0x17000, v22
	s_nop 1
	v_addc_co_u32_e32 v29, vcc, 0, v23, vcc
	global_load_ushort v131, v[28:29], off offset:2048
	v_add_co_u32_e32 v28, vcc, 0x19000, v22
	s_nop 1
	v_addc_co_u32_e32 v29, vcc, 0, v23, vcc
	global_load_ushort v127, v[28:29], off offset:1536
	v_add_co_u32_e32 v28, vcc, 0x1b000, v22
	s_nop 1
	v_addc_co_u32_e32 v29, vcc, 0, v23, vcc
	global_load_ushort v128, v[28:29], off offset:1024
	v_add_co_u32_e32 v28, vcc, 0x1d000, v22
	s_nop 1
	v_addc_co_u32_e32 v29, vcc, 0, v23, vcc
	global_load_ushort v123, v[28:29], off offset:512
	v_add_co_u32_e32 v28, vcc, 0x1f000, v22
	s_nop 1
	v_addc_co_u32_e32 v29, vcc, 0, v23, vcc
	global_load_ushort v124, v[28:29], off
	v_add_co_u32_e32 v28, vcc, s2, v22
	s_mov_b32 s2, 0x28000
	s_nop 0
	v_addc_co_u32_e32 v29, vcc, 0, v23, vcc
	global_load_ushort v125, v[28:29], off offset:3584
	v_add_co_u32_e32 v28, vcc, 0x22000, v22
	s_nop 1
	v_addc_co_u32_e32 v29, vcc, 0, v23, vcc
	global_load_ushort v126, v[28:29], off offset:3072
	v_add_co_u32_e32 v28, vcc, 0x24000, v22
	s_nop 1
	v_addc_co_u32_e32 v29, vcc, 0, v23, vcc
	global_load_ushort v120, v[28:29], off offset:2560
	v_add_co_u32_e32 v28, vcc, 0x26000, v22
	s_nop 1
	v_addc_co_u32_e32 v29, vcc, 0, v23, vcc
	global_load_ushort v121, v[28:29], off offset:2048
	v_add_co_u32_e32 v28, vcc, s2, v22
	s_movk_i32 s2, 0x100
	s_nop 0
	v_addc_co_u32_e32 v29, vcc, 0, v23, vcc
	global_load_ushort v118, v[28:29], off offset:1536
	v_add_co_u32_e32 v28, vcc, 0x2a000, v22
	s_nop 1
	v_addc_co_u32_e32 v29, vcc, 0, v23, vcc
	global_load_ushort v119, v[28:29], off offset:1024
	v_add_co_u32_e32 v28, vcc, 0x2c000, v22
	s_nop 1
	v_addc_co_u32_e32 v29, vcc, 0, v23, vcc
	global_load_ushort v114, v[28:29], off offset:512
	v_add_co_u32_e32 v28, vcc, 0x2e000, v22
	s_nop 1
	v_addc_co_u32_e32 v29, vcc, 0, v23, vcc
	global_load_ushort v115, v[28:29], off
	v_add_co_u32_e32 v28, vcc, 0x2f000, v22
	s_nop 1
	v_addc_co_u32_e32 v29, vcc, 0, v23, vcc
	global_load_ushort v116, v[28:29], off offset:3584
	v_add_co_u32_e32 v28, vcc, 0x31000, v22
	s_nop 1
	v_addc_co_u32_e32 v29, vcc, 0, v23, vcc
	global_load_ushort v117, v[28:29], off offset:3072
	v_add_co_u32_e32 v28, vcc, 0x33000, v22
	s_nop 1
	v_addc_co_u32_e32 v29, vcc, 0, v23, vcc
	global_load_ushort v112, v[28:29], off offset:2560
	v_add_co_u32_e32 v28, vcc, 0x35000, v22
	s_nop 1
	v_addc_co_u32_e32 v29, vcc, 0, v23, vcc
	global_load_ushort v113, v[28:29], off offset:2048
	v_add_co_u32_e32 v28, vcc, 0x37000, v22
	s_nop 1
	v_addc_co_u32_e32 v29, vcc, 0, v23, vcc
	global_load_ushort v110, v[28:29], off offset:1536
	v_add_co_u32_e32 v28, vcc, 0x39000, v22
	s_nop 1
	v_addc_co_u32_e32 v29, vcc, 0, v23, vcc
	global_load_ushort v111, v[28:29], off offset:1024
	v_add_co_u32_e32 v28, vcc, 0x3b000, v22
	s_nop 1
	v_addc_co_u32_e32 v29, vcc, 0, v23, vcc
	global_load_ushort v108, v[28:29], off offset:512
	v_add_co_u32_e32 v28, vcc, 0x3d000, v22
	s_nop 1
	v_addc_co_u32_e32 v29, vcc, 0, v23, vcc
	global_load_ushort v109, v[28:29], off
	v_add_co_u32_e32 v28, vcc, 0x3e000, v22
	s_nop 1
	v_addc_co_u32_e32 v29, vcc, 0, v23, vcc
	v_add_co_u32_e32 v22, vcc, 0x40000, v22
	global_load_ushort v106, v[28:29], off offset:3584
	s_nop 0
	v_addc_co_u32_e32 v23, vcc, 0, v23, vcc
	global_load_ushort v107, v[22:23], off offset:3072
	v_cmp_gt_i32_e32 vcc, s2, v104
	v_and_b32_e32 v23, 0x7f, v104
	v_and_b32_e32 v22, 0x3fc, v0
	s_and_saveexec_b64 s[50:51], vcc
	s_cbranch_execz .LBB0_188
	s_lshl_b64 s[2:3], s[36:37], 2
	s_waitcnt lgkmcnt(0)
	s_add_u32 s6, s20, s2
	s_addc_u32 s7, s21, s3
	s_add_u32 s20, s48, s2
	v_or_b32_e32 v0, s52, v23
	s_movk_i32 s2, 0xf00
	v_or_b32_e32 v24, s54, v6
	v_mul_lo_u32 v0, v0, s2
	v_or_b32_e32 v0, v0, v24
	v_add_u32_e32 v0, 0xe14, v0
	v_lshl_add_u64 v[28:29], v[0:1], 1, s[26:27]
	global_load_ushort v0, v[28:29], off
	v_lshlrev_b32_e32 v26, 2, v24
	global_load_dword v24, v26, s[6:7]
	s_addc_u32 s21, s49, s3
	global_load_dword v26, v26, s[20:21]
	s_waitcnt vmcnt(0) lgkmcnt(0)
	v_lshlrev_b32_e32 v0, 16, v0
	v_add_f32_e32 v0, v24, v0
	v_max_f32_e32 v24, 0, v0
	v_mul_f32_e64 v0, |v0|, s19
	v_exp_f32_e32 v0, v0
	v_mul_f32_e32 v26, 0x3fb8aa3b, v26
	v_exp_f32_e32 v26, v26
	v_add_f32_e32 v105, 1.0, v0
	v_add_f32_e32 v28, -1.0, v105
	v_sub_f32_e32 v29, v28, v105
	v_add_f32_e32 v29, 1.0, v29
	v_sub_f32_e32 v28, v0, v28
	v_add_f32_e32 v216, v28, v29
	v_frexp_mant_f32_e32 v28, v105
	v_cmp_gt_f32_e64 s[38:39], s86, v28
	v_cvt_f64_f32_e32 v[28:29], v105
	v_frexp_exp_i32_f64_e32 v28, v[28:29]
	v_subbrev_co_u32_e64 v28, s[38:39], 0, v28, s[38:39]
	v_sub_u32_e32 v29, 0, v28
	v_ldexp_f32 v105, v105, v29
	v_ldexp_f32 v29, v216, v29
	v_add_f32_e32 v216, -1.0, v105
	v_add_f32_e32 v217, 1.0, v216
	v_sub_f32_e32 v217, v105, v217
	v_add_f32_e32 v217, v29, v217
	v_add_f32_e32 v218, v216, v217
	v_sub_f32_e32 v216, v218, v216
	v_sub_f32_e32 v216, v217, v216
	v_add_f32_e32 v217, 1.0, v105
	v_add_f32_e32 v219, -1.0, v217
	v_sub_f32_e32 v105, v105, v219
	v_add_f32_e32 v29, v29, v105
	v_add_f32_e32 v105, v217, v29
	v_sub_f32_e32 v217, v105, v217
	v_sub_f32_e32 v29, v29, v217
	v_rcp_f32_e32 v217, v105
	v_cvt_f32_i32_e32 v28, v28
	v_cmp_neq_f32_e64 s[38:39], s15, v0
	v_mul_f32_e32 v219, v218, v217
	v_mul_f32_e32 v224, v105, v219
	v_fma_f32 v225, v219, v105, -v224
	v_fmac_f32_e32 v225, v219, v29
	v_add_f32_e32 v226, v224, v225
	v_sub_f32_e32 v227, v218, v226
	v_sub_f32_e32 v218, v218, v227
	v_sub_f32_e32 v224, v226, v224
	v_sub_f32_e32 v218, v218, v226
	v_add_f32_e32 v216, v216, v218
	v_sub_f32_e32 v218, v224, v225
	v_add_f32_e32 v216, v218, v216
	v_add_f32_e32 v218, v227, v216
	v_mul_f32_e32 v224, v217, v218
	v_mul_f32_e32 v225, v105, v224
	v_fma_f32 v105, v224, v105, -v225
	v_fmac_f32_e32 v105, v224, v29
	v_sub_f32_e32 v29, v227, v218
	v_add_f32_e32 v29, v216, v29
	v_add_f32_e32 v216, v225, v105
	v_sub_f32_e32 v226, v218, v216
	v_sub_f32_e32 v218, v218, v226
	v_sub_f32_e32 v225, v216, v225
	v_sub_f32_e32 v216, v218, v216
	v_add_f32_e32 v29, v29, v216
	v_sub_f32_e32 v105, v225, v105
	v_add_f32_e32 v29, v105, v29
	v_add_f32_e32 v105, v219, v224
	v_add_f32_e32 v29, v226, v29
	v_sub_f32_e32 v216, v105, v219
	v_mul_f32_e32 v29, v217, v29
	v_sub_f32_e32 v216, v224, v216
	v_add_f32_e32 v29, v216, v29
	v_mul_f32_e32 v219, 0x3f317218, v28
	v_add_f32_e32 v216, v105, v29
	v_fma_f32 v224, v28, s87, -v219
	v_mul_f32_e32 v217, v216, v216
	v_fmac_f32_e32 v224, 0xb102e308, v28
	v_sub_f32_e32 v28, v216, v105
	v_fmamk_f32 v218, v217, 0x3e9b6dac, v172
	v_sub_f32_e32 v28, v29, v28
	v_add_f32_e32 v29, v219, v224
	v_fmaak_f32 v218, v217, v218, 0x3f2aaada
	v_sub_f32_e32 v105, v29, v219
	v_ldexp_f32 v219, v216, 1
	v_mul_f32_e32 v216, v216, v217
	v_mul_f32_e32 v216, v216, v218
	v_add_f32_e32 v217, v219, v216
	v_sub_f32_e32 v218, v217, v219
	v_ldexp_f32 v28, v28, 1
	v_sub_f32_e32 v216, v216, v218
	v_add_f32_e32 v28, v28, v216
	v_add_f32_e32 v216, v217, v28
	v_sub_f32_e32 v217, v216, v217
	v_sub_f32_e32 v28, v28, v217
	v_add_f32_e32 v217, v29, v216
	v_sub_f32_e32 v218, v217, v29
	v_sub_f32_e32 v219, v217, v218
	v_sub_f32_e32 v105, v224, v105
	v_sub_f32_e32 v29, v29, v219
	v_sub_f32_e32 v216, v216, v218
	v_add_f32_e32 v29, v216, v29
	v_add_f32_e32 v216, v105, v28
	v_sub_f32_e32 v218, v216, v105
	v_sub_f32_e32 v219, v216, v218
	v_sub_f32_e32 v105, v105, v219
	v_sub_f32_e32 v28, v28, v218
	v_add_f32_e32 v29, v216, v29
	v_add_f32_e32 v28, v28, v105
	v_add_f32_e32 v105, v217, v29
	v_sub_f32_e32 v216, v105, v217
	v_sub_f32_e32 v29, v29, v216
	v_add_f32_e32 v28, v28, v29
	v_add_f32_e32 v28, v105, v28
	v_cndmask_b32_e64 v28, v175, v28, s[38:39]
	v_cmp_ngt_f32_e64 s[38:39], -1.0, v0
	s_nop 1
	v_cndmask_b32_e64 v28, v176, v28, s[38:39]
	v_cmp_neq_f32_e64 s[38:39], -1.0, v0
	s_nop 1
	v_cndmask_b32_e64 v28, v177, v28, s[38:39]
	v_cmp_lt_f32_e64 s[38:39], |v0|, s88
	s_nop 1
	v_cndmask_b32_e64 v0, v28, v0, s[38:39]
	v_add_f32_e32 v0, v24, v0
	v_add_u32_e32 v24, v101, v22
	v_mul_f32_e64 v26, v0, -v26
	ds_write2st64_b32 v24, v26, v0 offset1:4

.LBB0_242:
	s_or_b64 exec, exec, s[2:3]
	s_bfe_u32 s3, s55, 0x20006
	v_and_b32_e32 v108, 31, v104
	s_lshl_b32 s6, s3, 5
	v_lshrrev_b32_e32 v112, 5, v98
	v_or_b32_e32 v100, s6, v108
	v_mul_u32_u24_e32 v109, 0x110, v100
	v_lshlrev_b32_e32 v114, 4, v112
	v_add3_u32 v99, v99, v109, v114
	s_waitcnt lgkmcnt(0)
	s_barrier
	ds_read_b128 v[90:93], v99
	ds_read_b128 v[94:97], v99 offset:32
	s_waitcnt lgkmcnt(1)
	v_mfma_f32_32x32x16_bf16 v[2:17], v[2:5], v[90:93], 0
	v_lshrrev_b32_e32 v106, 3, v98
	v_or_b32_e32 v107, s6, v106
	v_or_b32_e32 v0, s52, v107
	v_mul_lo_u32 v0, v0, s18
	s_lshl_b32 s44, s56, 6
	s_lshl_b32 s80, s53, 1
	s_ashr_i32 s45, s44, 31
	v_mfma_f32_32x32x16_bf16 v[18:33], v[18:21], v[90:93], 0
	s_mov_b32 s2, 0xf000
	v_lshlrev_b32_e32 v111, 2, v112
	s_add_i32 s3, s3, 1
	v_mov_b32_e32 v115, v111
	s_waitcnt lgkmcnt(0)
	v_mfma_f32_32x32x16_bf16 v[2:17], v[78:81], v[94:97], v[2:17]
	ds_read_b128 v[78:81], v99 offset:64
	v_mfma_f32_32x32x16_bf16 v[18:33], v[86:89], v[94:97], v[18:33]
	s_waitcnt lgkmcnt(0)
	v_mfma_f32_32x32x16_bf16 v[2:17], v[74:77], v[78:81], v[2:17]
	ds_read_b128 v[74:77], v99 offset:96
	v_mfma_f32_32x32x16_bf16 v[18:33], v[82:85], v[78:81], v[18:33]
	s_waitcnt lgkmcnt(0)
	v_mfma_f32_32x32x16_bf16 v[2:17], v[66:69], v[74:77], v[2:17]
	v_mfma_f32_32x32x16_bf16 v[18:33], v[70:73], v[74:77], v[18:33]
	ds_read_b128 v[66:69], v99 offset:128
	ds_read_b128 v[70:73], v99 offset:160
	s_waitcnt lgkmcnt(1)
	v_mfma_f32_32x32x16_bf16 v[2:17], v[58:61], v[66:69], v[2:17]
	v_lshlrev_b32_e32 v58, 3, v98
	v_and_b32_e32 v98, 56, v58
	v_lshl_add_u64 v[58:59], s[26:27], 0, v[0:1]
	v_lshl_add_u64 v[58:59], v[58:59], 0, s[80:81]
	v_lshl_add_u64 v[58:59], s[44:45], 1, v[58:59]
	v_lshlrev_b32_e32 v0, 1, v98
	v_lshl_add_u64 v[86:87], v[58:59], 0, v[0:1]
	v_mfma_f32_32x32x16_bf16 v[18:33], v[62:65], v[66:69], v[18:33]
	s_waitcnt lgkmcnt(0)
	v_mfma_f32_32x32x16_bf16 v[2:17], v[54:57], v[70:73], v[2:17]
	v_add_co_u32_e32 v54, vcc, s2, v86
	s_mov_b32 s2, 0x1e000
	s_nop 0
	v_addc_co_u32_e32 v55, vcc, 0, v87, vcc
	global_load_dwordx4 v[62:65], v[86:87], off offset:3584
	global_load_dwordx4 v[58:61], v[54:55], off offset:3584
	v_add_co_u32_e32 v54, vcc, s2, v86
	s_mov_b32 s2, 0x2d000
	s_nop 0
	v_addc_co_u32_e32 v55, vcc, 0, v87, vcc
	v_mfma_f32_32x32x16_bf16 v[18:33], v[50:53], v[70:73], v[18:33]
	v_add_co_u32_e32 v50, vcc, s2, v86
	global_load_dwordx4 v[54:57], v[54:55], off offset:3584
	s_nop 0
	v_addc_co_u32_e32 v51, vcc, 0, v87, vcc
	global_load_dwordx4 v[50:53], v[50:51], off offset:3584
	ds_read_b128 v[82:85], v99 offset:192
	ds_read_b128 v[86:89], v99 offset:224
	s_waitcnt lgkmcnt(0)
	v_mfma_f32_32x32x16_bf16 v[2:17], v[46:49], v[82:85], v[2:17]
	s_lshl_b32 s2, s56, 7
	s_or_b32 s7, s2, s6
	v_or_b32_e32 v0, s7, v108
	v_lshl_add_u32 v0, v0, 2, v101
	ds_read_b32 v110, v0 offset:2048
	s_mul_i32 s7, s56, 0x4400
	v_mov_b32_e32 v99, v100
	v_mfma_f32_32x32x16_bf16 v[18:33], v[42:45], v[82:85], v[18:33]
	s_waitcnt lgkmcnt(0)
	v_mul_f32_e32 v0, 0x3fb8aa3b, v110
	v_exp_f32_e32 v0, v0
	v_mfma_f32_32x32x16_bf16 v[2:17], v[38:41], v[86:89], v[2:17]
	v_mfma_f32_32x32x16_bf16 v[18:33], v[34:37], v[86:89], v[18:33]
	v_mov_b32_e32 v35, s7
	s_movk_i32 s7, 0x110
	s_nop 8
	v_mul_f32_e64 v16, v0, v16
	v_mul_f32_e64 v17, v0, v17
	v_mul_f32_e64 v14, v0, v14
	v_mul_f32_e64 v15, v0, v15
	v_pk_mul_f32 v[12:13], v[0:1], v[12:13] op_sel_hi:[0,1]
	v_pk_mul_f32 v[10:11], v[0:1], v[10:11] op_sel_hi:[0,1]
	v_pk_mul_f32 v[8:9], v[0:1], v[8:9] op_sel_hi:[0,1]
	v_pk_mul_f32 v[6:7], v[0:1], v[6:7] op_sel_hi:[0,1]
	v_pk_mul_f32 v[4:5], v[0:1], v[4:5] op_sel_hi:[0,1]
	v_pk_mul_f32 v[2:3], v[0:1], v[2:3] op_sel_hi:[0,1]
	v_pk_mul_f32 v[32:33], v[0:1], v[32:33] op_sel_hi:[0,1]
	v_pk_mul_f32 v[30:31], v[0:1], v[30:31] op_sel_hi:[0,1]
	v_pk_mul_f32 v[28:29], v[0:1], v[28:29] op_sel_hi:[0,1]
	v_pk_mul_f32 v[26:27], v[0:1], v[26:27] op_sel_hi:[0,1]
	v_pk_mul_f32 v[24:25], v[0:1], v[24:25] op_sel_hi:[0,1]
	v_pk_mul_f32 v[22:23], v[0:1], v[22:23] op_sel_hi:[0,1]
	v_pk_mul_f32 v[20:21], v[0:1], v[20:21] op_sel_hi:[0,1]
	v_pk_mul_f32 v[18:19], v[0:1], v[18:19] op_sel_hi:[0,1]
	v_lshlrev_b32_e32 v0, 3, v112
	v_mul_u32_u24_e32 v34, 0x110, v108
	v_mad_u32_u24 v35, v108, s7, v35
	v_or_b32_e32 v35, v35, v0
	v_add3_u32 v113, v34, v114, v102
	v_lshl_or_b32 v34, s56, 9, v114
	s_movk_i32 s7, 0x800
	v_add_u32_e32 v112, v103, v35
	v_add3_u32 v114, v101, v34, s7

.LBB0_254:
	s_ashr_i32 s44, s85, 5
	s_and_b32 s46, s85, 31
	s_lshl_b32 s47, s46, 8
	s_ashr_i32 s45, s44, 31
	s_add_i32 s42, s47, 0x100
	s_lshl_b64 s[2:3], s[44:45], 15
	v_readlane_b32 s6, v255, 9
	v_readlane_b32 s7, v255, 10
	s_add_u32 s10, s6, s2
	s_mov_b32 s2, 11
	s_addc_u32 s11, s7, s3
	s_ashr_i32 s3, s2, 31
	s_lshl_b64 s[2:3], s[2:3], 3
	s_add_u32 s2, s0, s2
	s_mov_b32 s6, 12
	s_addc_u32 s3, s1, s3
	s_ashr_i32 s7, s6, 31
	s_lshl_b64 s[6:7], s[6:7], 3
	s_add_u32 s20, s0, s6
	s_mov_b32 s6, 13
	s_addc_u32 s21, s1, s7
	s_ashr_i32 s7, s6, 31
	s_lshl_b64 s[6:7], s[6:7], 3
	v_mov_b32_e32 v24, v183
	s_add_u32 s38, s0, s6
	s_addc_u32 s39, s1, s7
	v_lshlrev_b32_e32 v14, 2, v24
	v_readfirstlane_b32 s45, v24
	s_load_dwordx2 s[50:51], s[2:3], 0x0
	s_load_dwordx2 s[52:53], s[20:21], 0x0
	v_cmp_gt_i32_e32 vcc, s42, v14
	s_waitcnt lgkmcnt(0)
	s_barrier
	s_add_u32 s50, s50, s70
	s_addc_u32 s51, s51, s71
	s_add_u32 s52, s52, s70
	s_addc_u32 s53, s53, s71
	v_and_b32_e32 v30, 63, v24
	v_lshlrev_b32_e32 v30, 2, v30
	global_load_dword v31, v30, s[50:51]
	global_load_dword v32, v30, s[52:53]
	s_and_saveexec_b64 s[6:7], vcc
	s_cbranch_execz .LBB0_256
	v_ashrrev_i32_e32 v15, 31, v14
	v_lshl_add_u64 v[2:3], v[14:15], 2, s[10:11]
	global_load_dwordx4 v[2:5], v[2:3], off
.LBB0_256:
	s_or_b64 exec, exec, s[6:7]
	s_load_dwordx2 s[6:7], s[2:3], 0x0
	s_nop 0
	s_load_dwordx2 s[2:3], s[20:21], 0x0
	s_load_dwordx2 s[48:49], s[38:39], 0x0
	v_add_u32_e32 v18, 0x800, v14
	v_cmp_gt_i32_e64 s[38:39], s42, v18
	s_and_saveexec_b64 s[20:21], s[38:39]
	s_cbranch_execz .LBB0_258
	v_ashrrev_i32_e32 v19, 31, v18
	v_lshl_add_u64 v[6:7], v[18:19], 2, s[10:11]
	global_load_dwordx4 v[6:9], v[6:7], off
.LBB0_258:
	s_or_b64 exec, exec, s[20:21]
	v_add_u32_e32 v20, 0x1000, v14
	v_cmp_gt_i32_e64 s[40:41], s42, v20
	s_and_saveexec_b64 s[20:21], s[40:41]
	s_cbranch_execz .LBB0_260
	v_ashrrev_i32_e32 v21, 31, v20
	v_lshl_add_u64 v[10:11], v[20:21], 2, s[10:11]
	global_load_dwordx4 v[10:13], v[10:11], off

.LBB0_274:
	v_ashrrev_i32_e32 v23, 31, v22
	v_lshl_add_u64 v[14:15], v[22:23], 2, s[10:11]
	global_load_dwordx4 v[14:17], v[14:15], off
	s_or_b64 exec, exec, s[20:21]
	s_and_saveexec_b64 s[10:11], vcc
	s_cbranch_execz .LBB0_262

.LBB0_279:
	s_ashr_i32 s2, s85, 7
	s_ashr_i32 s3, s2, 31
	s_lshl_b32 s7, s44, 6
	v_and_b32_e32 v188, 31, v24
	s_lshl_b64 s[38:39], s[2:3], 13
	s_and_b32 s57, s7, 0xc0
	v_or_b32_e32 v189, s58, v188
	s_ashr_i32 s2, s58, 31
	v_lshl_add_u32 v0, v189, 2, 0
	s_add_u32 s55, s38, s58
	ds_read_b32 v16, v0
	v_or_b32_e32 v0, s55, v188
	v_mov_b64_e32 v[2:3], s[26:27]
	s_addc_u32 s56, s39, s2
	v_mad_u64_u32 v[2:3], s[2:3], v0, s18, v[2:3]
	v_mov_b32_e32 v0, 0x1e00
	v_lshrrev_b32_e32 v144, 5, v185
	v_mad_i32_i24 v3, s56, v0, v3
	s_lshl_b32 s80, s57, 1
	v_lshl_add_u64 v[2:3], v[2:3], 0, s[80:81]
	v_lshlrev_b32_e32 v148, 4, v144
	v_mov_b32_e32 v149, v1
	v_lshl_add_u64 v[14:15], v[2:3], 0, v[148:149]
	v_and_b32_e32 v0, 32, v185
	s_add_i32 s2, 0, 0x8000
	v_mov_b32_e32 v149, s2
	v_cmp_eq_u32_e32 vcc, 0, v24
	s_waitcnt vmcnt(0) lgkmcnt(0)
	v_mov_b64_e32 v[2:3], v[96:97]
	v_mov_b64_e32 v[4:5], v[98:99]
	v_mov_b64_e32 v[6:7], v[100:101]
	v_mov_b64_e32 v[8:9], v[102:103]
	v_mov_b64_e32 v[10:11], v[104:105]
	v_mov_b64_e32 v[12:13], v[106:107]
	v_mov_b64_e32 v[18:19], v[108:109]
	v_mov_b64_e32 v[20:21], v[110:111]
	v_mov_b64_e32 v[74:75], v[112:113]
	v_mov_b64_e32 v[76:77], v[114:115]
	v_mov_b64_e32 v[78:79], v[116:117]
	v_mov_b64_e32 v[80:81], v[118:119]
	v_mov_b64_e32 v[58:59], v[120:121]
	v_mov_b64_e32 v[60:61], v[122:123]
	v_mov_b64_e32 v[66:67], v[124:125]
	v_mov_b64_e32 v[68:69], v[126:127]
	v_mov_b64_e32 v[50:51], v[128:129]
	v_mov_b64_e32 v[52:53], v[130:131]
	v_mov_b64_e32 v[54:55], v[132:133]
	v_mov_b64_e32 v[56:57], v[134:135]
	v_mov_b64_e32 v[62:63], v[136:137]
	v_mov_b64_e32 v[64:65], v[138:139]
	v_mov_b64_e32 v[70:71], v[140:141]
	v_mov_b64_e32 v[72:73], v[142:143]
	v_lshlrev_b32_e32 v162, 16, v2
	v_and_b32_e32 v163, 0xffff0000, v2
	v_lshlrev_b32_e32 v160, 16, v3
	v_and_b32_e32 v161, 0xffff0000, v3
	v_pk_mul_f32 v[2:3], v[162:163], v[162:163]
	v_pk_mul_f32 v[36:37], v[160:161], v[160:161]
	v_add_f32_e32 v0, v2, v3
	v_lshlrev_b32_e32 v130, 16, v4
	v_and_b32_e32 v131, 0xffff0000, v4
	v_add_f32_e32 v0, v36, v0
	v_lshlrev_b32_e32 v128, 16, v5
	v_and_b32_e32 v129, 0xffff0000, v5
	v_pk_mul_f32 v[4:5], v[130:131], v[130:131]
	v_add_f32_e32 v0, v37, v0
	v_add_f32_e32 v0, v4, v0
	v_pk_mul_f32 v[34:35], v[128:129], v[128:129]
	v_add_f32_e32 v0, v5, v0
	v_lshlrev_b32_e32 v142, 16, v6
	v_and_b32_e32 v143, 0xffff0000, v6
	v_add_f32_e32 v0, v34, v0
	v_lshlrev_b32_e32 v140, 16, v7
	v_and_b32_e32 v141, 0xffff0000, v7
	v_pk_mul_f32 v[6:7], v[142:143], v[142:143]
	v_add_f32_e32 v0, v35, v0
	v_add_f32_e32 v0, v6, v0
	v_pk_mul_f32 v[32:33], v[140:141], v[140:141]
	v_add_f32_e32 v0, v7, v0
	v_lshlrev_b32_e32 v134, 16, v8
	v_and_b32_e32 v135, 0xffff0000, v8
	v_add_f32_e32 v0, v32, v0
	v_lshlrev_b32_e32 v132, 16, v9
	v_and_b32_e32 v133, 0xffff0000, v9
	v_pk_mul_f32 v[8:9], v[134:135], v[134:135]
	v_add_f32_e32 v0, v33, v0
	v_add_f32_e32 v0, v8, v0
	v_pk_mul_f32 v[30:31], v[132:133], v[132:133]
	v_add_f32_e32 v0, v9, v0
	v_lshlrev_b32_e32 v138, 16, v10
	v_and_b32_e32 v139, 0xffff0000, v10
	v_add_f32_e32 v0, v30, v0
	v_lshlrev_b32_e32 v136, 16, v11
	v_and_b32_e32 v137, 0xffff0000, v11
	v_pk_mul_f32 v[10:11], v[138:139], v[138:139]
	v_add_f32_e32 v0, v31, v0
	v_add_f32_e32 v0, v10, v0
	v_pk_mul_f32 v[28:29], v[136:137], v[136:137]
	v_add_f32_e32 v0, v11, v0
	v_lshlrev_b32_e32 v94, 16, v12
	v_and_b32_e32 v95, 0xffff0000, v12
	v_add_f32_e32 v0, v28, v0
	v_lshlrev_b32_e32 v92, 16, v13
	v_and_b32_e32 v93, 0xffff0000, v13
	v_pk_mul_f32 v[12:13], v[94:95], v[94:95]
	v_add_f32_e32 v0, v29, v0
	v_add_f32_e32 v0, v12, v0
	v_pk_mul_f32 v[26:27], v[92:93], v[92:93]
	v_add_f32_e32 v0, v13, v0
	v_lshlrev_b32_e32 v90, 16, v18
	v_and_b32_e32 v91, 0xffff0000, v18
	v_add_f32_e32 v0, v26, v0
	v_lshlrev_b32_e32 v88, 16, v19
	v_and_b32_e32 v89, 0xffff0000, v19
	v_pk_mul_f32 v[18:19], v[90:91], v[90:91]
	v_add_f32_e32 v0, v27, v0
	v_add_f32_e32 v0, v18, v0
	v_pk_mul_f32 v[22:23], v[88:89], v[88:89]
	v_add_f32_e32 v0, v19, v0
	v_lshlrev_b32_e32 v86, 16, v20
	v_and_b32_e32 v87, 0xffff0000, v20
	v_add_f32_e32 v0, v22, v0
	v_lshlrev_b32_e32 v84, 16, v21
	v_and_b32_e32 v85, 0xffff0000, v21
	v_pk_mul_f32 v[20:21], v[86:87], v[86:87]
	v_add_f32_e32 v0, v23, v0
	v_add_f32_e32 v0, v20, v0
	v_pk_mul_f32 v[14:15], v[84:85], v[84:85]
	v_add_f32_e32 v0, v21, v0
	v_add_f32_e32 v0, v14, v0
	v_and_b32_e32 v6, 7, v24
	v_add_f32_e32 v164, v15, v0
	v_lshlrev_b32_e32 v0, 5, v6
	global_load_dwordx4 v[96:99], v0, s[20:21] offset:16
	global_load_dwordx4 v[100:103], v0, s[20:21]
	ds_bpermute_b32 v165, v187, v164
	s_and_saveexec_b64 s[2:3], vcc
	s_add_i32 s10, 0, 0x22000
	v_mov_b32_e32 v0, s10
	ds_write_b32 v0, v1
	s_or_b64 exec, exec, s[2:3]
	v_sub_u32_e32 v2, s6, v82
	v_add_u32_e32 v7, 6, v2
	s_mov_b32 s2, 0x55555556
	v_mul_hi_i32 v2, v7, s2
	v_ashrrev_i32_e32 v168, 3, v24
	v_lshrrev_b32_e32 v3, 31, v2
	v_ashrrev_i32_e32 v169, 31, v168
	v_add_u32_e32 v190, v2, v3
	v_lshl_add_u64 v[2:3], s[38:39], 0, v[168:169]
	v_mov_b64_e32 v[4:5], s[26:27]
	v_mad_u64_u32 v[4:5], s[2:3], v2, s18, v[4:5]
	v_lshlrev_b32_e32 v0, 3, v6
	v_mad_i32_i24 v5, v3, s18, v5
	v_lshl_add_u64 v[2:3], v[4:5], 0, s[80:81]
	v_lshlrev_b32_e32 v0, 1, v0
	v_add_u32_e32 v169, -1, v190
	v_lshl_add_u64 v[150:151], v[2:3], 0, v[0:1]
	s_or_b32 s60, s6, 3
	v_mad_u64_u32 v[2:3], s[2:3], v169, 3, v[82:83]
	v_cmp_ge_i32_e64 s[46:47], s60, v2
	v_lshlrev_b32_e32 v4, 6, v2
	s_and_saveexec_b64 s[2:3], s[46:47]
	s_cbranch_execz .LBB0_283
	v_mad_i64_i32 v[8:9], s[10:11], v4, s18, v[150:151]
	global_load_dwordx4 v[104:107], v[8:9], off offset:2560
.LBB0_283:
	s_or_b64 exec, exec, s[2:3]
	v_cmp_gt_i32_e64 s[44:45], s60, v2
	s_and_saveexec_b64 s[2:3], s[44:45]
	s_cbranch_execz .LBB0_285
	v_lshl_add_u32 v0, v2, 6, 64
	v_mad_i64_i32 v[8:9], s[10:11], v0, s18, v[150:151]
	global_load_dwordx4 v[108:111], v[8:9], off offset:2560
.LBB0_285:
	s_or_b64 exec, exec, s[2:3]
	v_add_u32_e32 v0, 2, v2
	v_cmp_ge_i32_e64 s[42:43], s60, v0
	s_and_saveexec_b64 s[2:3], s[42:43]
	s_cbranch_execz .LBB0_287
	v_lshlrev_b32_e32 v0, 6, v0
	v_mad_i64_i32 v[8:9], s[10:11], v0, s18, v[150:151]
	global_load_dwordx4 v[112:115], v[8:9], off offset:2560
.LBB0_287:
	s_or_b64 exec, exec, s[2:3]
	s_mov_b32 s2, 0x2aaaaaab
	v_mul_hi_i32 v0, v24, s2
	v_lshrrev_b32_e32 v3, 31, v0
	v_ashrrev_i32_e32 v8, 2, v0
	v_add_u32_e32 v166, v8, v3
	v_mul_lo_u32 v0, v166, 24
	v_sub_u32_e32 v0, v24, v0
	v_ashrrev_i32_e32 v167, 3, v0
	v_ashrrev_i32_e32 v5, 31, v4
	v_add_u32_e32 v9, v2, v167
	v_lshlrev_b32_e32 v152, 3, v0
	v_lshl_add_u64 v[4:5], v[4:5], 1, s[30:31]
	v_cmp_ge_i32_e32 vcc, s60, v9
	v_ashrrev_i32_e32 v153, 31, v152
	s_and_saveexec_b64 s[2:3], vcc
	s_cbranch_execz .LBB0_289
	v_add3_u32 v8, v8, v3, s7
	v_ashrrev_i32_e32 v9, 31, v8
	v_lshlrev_b64 v[8:9], 14, v[8:9]
	v_lshl_add_u64 v[8:9], v[4:5], 0, v[8:9]
	v_lshl_add_u64 v[8:9], v[152:153], 1, v[8:9]
	global_load_dwordx4 v[116:119], v[8:9], off
.LBB0_289:
	s_or_b64 exec, exec, s[2:3]
	v_add_u32_e32 v3, 0x200, v24
	s_mov_b32 s2, 0x2aaaaaab
	v_mul_hi_i32 v9, v3, s2
	v_lshrrev_b32_e32 v8, 31, v9
	v_ashrrev_i32_e32 v9, 2, v9
	v_add_u32_e32 v201, v9, v8
	v_mul_lo_u32 v10, v201, 24
	v_sub_u32_e32 v3, v3, v10
	v_ashrrev_i32_e32 v200, 3, v3
	v_add_u32_e32 v10, v2, v200
	v_lshlrev_b32_e32 v154, 3, v3
	v_cmp_ge_i32_e64 s[38:39], s60, v10
	v_ashrrev_i32_e32 v155, 31, v154
	s_and_saveexec_b64 s[2:3], s[38:39]
	s_cbranch_execz .LBB0_291
	v_add3_u32 v8, v9, v8, s7
	v_ashrrev_i32_e32 v9, 31, v8
	v_lshlrev_b64 v[8:9], 14, v[8:9]
	v_lshl_add_u64 v[8:9], v[4:5], 0, v[8:9]
	v_lshl_add_u64 v[8:9], v[154:155], 1, v[8:9]
	global_load_dwordx4 v[120:123], v[8:9], off

.LBB0_305:
	v_subrev_u32_e32 v0, s61, v169
	v_cmp_lt_i32_e64 s[38:39], 0, v0
	v_lshl_add_u32 v0, v0, 1, v0
	v_add_u32_e32 v209, v0, v198
	s_and_saveexec_b64 s[2:3], s[38:39]
	s_cbranch_execz .LBB0_317
	v_cmp_ge_i32_e64 s[40:41], s60, v209
	v_lshlrev_b32_e32 v2, 6, v209
	s_and_saveexec_b64 s[6:7], s[40:41]
	s_cbranch_execz .LBB0_308
	v_mad_i64_i32 v[4:5], s[10:11], v2, s18, v[150:151]
	s_waitcnt vmcnt(0)
	global_load_dwordx4 v[104:107], v[4:5], off offset:2560
.LBB0_308:
	s_or_b64 exec, exec, s[6:7]
	v_cmp_gt_i32_e64 s[40:41], s60, v209
	s_and_saveexec_b64 s[6:7], s[40:41]
	s_cbranch_execz .LBB0_310
	v_lshl_add_u32 v0, v209, 6, 64
	v_mad_i64_i32 v[4:5], s[10:11], v0, s18, v[150:151]
	s_nop 0
	global_load_dwordx4 v[108:111], v[4:5], off offset:2560
.LBB0_310:
	s_or_b64 exec, exec, s[6:7]
	v_add_u32_e32 v0, 2, v209
	v_cmp_ge_i32_e64 s[40:41], s60, v0
	s_and_saveexec_b64 s[6:7], s[40:41]
	s_cbranch_execz .LBB0_312
	v_lshlrev_b32_e32 v0, 6, v0
	v_mad_i64_i32 v[4:5], s[10:11], v0, s18, v[150:151]
	s_nop 0
	global_load_dwordx4 v[112:115], v[4:5], off offset:2560

.LBB0_315:
	v_lshl_add_u64 v[2:3], v[2:3], 0, v[166:167]
	v_lshl_add_u64 v[2:3], v[156:157], 1, v[2:3]
	s_nop 0
	global_load_dwordx4 v[124:127], v[2:3], off

.LBB0_340:
	v_lshl_add_u64 v[4:5], v[2:3], 0, v[162:163]
	v_lshl_add_u64 v[4:5], v[152:153], 1, v[4:5]
	s_nop 0
	global_load_dwordx4 v[116:119], v[4:5], off
	s_or_b64 exec, exec, s[6:7]
	v_cmp_le_i32_e64 s[40:41], v209, v200
	s_and_saveexec_b64 s[6:7], s[40:41]
	s_cbranch_execz .LBB0_314
.LBB0_341:
	v_lshl_add_u64 v[4:5], v[2:3], 0, v[164:165]
	v_lshl_add_u64 v[4:5], v[154:155], 1, v[4:5]
	s_nop 0
	global_load_dwordx4 v[120:123], v[4:5], off
	s_or_b64 exec, exec, s[6:7]
	v_cmp_le_i32_e64 s[40:41], v209, v201
	s_and_saveexec_b64 s[6:7], s[40:41]
	s_cbranch_execnz .LBB0_315
	s_branch .LBB0_316

.LBB0_347:
	v_add3_u32 v10, v10, v9, s7
	v_ashrrev_i32_e32 v11, 31, v10
	v_lshlrev_b64 v[10:11], 14, v[10:11]
	v_lshl_add_u64 v[4:5], v[4:5], 0, v[10:11]
	v_lshl_add_u64 v[4:5], v[156:157], 1, v[4:5]
	global_load_dwordx4 v[124:127], v[4:5], off
	s_or_b64 exec, exec, s[2:3]
	v_lshl_add_u32 v158, v6, 4, v149
	s_and_saveexec_b64 s[2:3], s[46:47]
	s_cbranch_execz .LBB0_293

.LBB0_387:
	v_lshl_add_u32 v140, s67, 8, v144
	v_lshl_or_b32 v148, s68, 8, v158
	v_ashrrev_i32_e32 v141, 31, v140
	v_ashrrev_i32_e32 v149, 31, v148
	v_lshlrev_b64 v[142:143], 10, v[140:141]
	v_lshl_add_u64 v[142:143], v[142:143], 0, v[148:149]
	v_lshl_add_u64 v[150:151], v[142:143], 1, s[24:25]
	global_load_dwordx2 v[160:161], v[150:151], off
	global_load_dwordx2 v[156:157], v[150:151], off offset:32
	global_load_dwordx2 v[154:155], v[150:151], off offset:256
	global_load_dwordx2 v[152:153], v[150:151], off offset:288
	v_cndmask_b32_e64 v162, 0, 1, s[34:35]
	v_mov_b32_e32 v133, v132
	v_cmp_ne_u32_e64 s[42:43], 1, v162
	s_andn2_b64 vcc, exec, s[34:35]
	s_mov_b64 s[2:3], -1
	s_waitcnt vmcnt(0) lgkmcnt(0)
	v_lshlrev_b32_e32 v162, 16, v160
	v_and_b32_e32 v163, 0xffff0000, v160
	v_lshlrev_b32_e32 v160, 16, v161
	v_and_b32_e32 v161, 0xffff0000, v161
	v_pk_fma_f32 v[128:129], v[132:133], v[128:129], v[160:161]
	v_pk_fma_f32 v[126:127], v[134:135], v[126:127], v[162:163]
	s_cbranch_vccnz .LBB0_389
	v_lshl_add_u64 v[160:161], v[142:143], 2, s[74:75]
	s_mov_b64 s[2:3], 0
	global_store_dwordx4 v[160:161], v[126:129], off
.LBB0_389:
	s_andn2_b64 vcc, exec, s[2:3]
	v_mov_b32_e32 v160, 0
	s_cbranch_vccnz .LBB0_391
	v_cvt_pk_bf16_f32 v126, v126, v127
	v_cvt_pk_bf16_f32 v127, v128, v129
	global_store_dwordx2 v[150:151], v[126:127], off
	v_lshlrev_b32_e32 v128, 16, v126
	v_lshlrev_b32_e32 v129, 16, v127
	v_and_b32_e32 v127, 0xffff0000, v127
	v_and_b32_e32 v126, 0xffff0000, v126
	v_pk_mul_f32 v[126:127], v[126:127], v[126:127]
	s_nop 0
	v_pk_fma_f32 v[126:127], v[128:129], v[128:129], v[126:127]
	s_nop 0
	v_add_f32_e32 v160, v126, v127

.LBB0_393:
	s_andn2_b64 vcc, exec, s[2:3]
	s_cbranch_vccnz .LBB0_395
	v_cvt_pk_bf16_f32 v122, v122, v123
	v_cvt_pk_bf16_f32 v123, v124, v125
	global_store_dwordx2 v[150:151], v[122:123], off offset:32
	v_lshlrev_b32_e32 v124, 16, v122
	v_lshlrev_b32_e32 v125, 16, v123
	v_and_b32_e32 v123, 0xffff0000, v123
	v_and_b32_e32 v122, 0xffff0000, v122
	v_pk_mul_f32 v[122:123], v[122:123], v[122:123]
	s_nop 0
	v_pk_fma_f32 v[122:123], v[124:125], v[124:125], v[122:123]
	s_nop 0
	v_add_f32_e32 v122, v122, v123
	v_add_f32_e32 v160, v160, v122

.LBB0_397:
	s_andn2_b64 vcc, exec, s[2:3]
	s_cbranch_vccnz .LBB0_399
	v_cvt_pk_bf16_f32 v118, v118, v119
	v_cvt_pk_bf16_f32 v119, v120, v121
	global_store_dwordx2 v[150:151], v[118:119], off offset:256
	v_lshlrev_b32_e32 v120, 16, v118
	v_lshlrev_b32_e32 v121, 16, v119
	v_and_b32_e32 v119, 0xffff0000, v119
	v_and_b32_e32 v118, 0xffff0000, v118
	v_pk_mul_f32 v[118:119], v[118:119], v[118:119]
	s_nop 0
	v_pk_fma_f32 v[118:119], v[120:121], v[120:121], v[118:119]
	s_nop 0
	v_add_f32_e32 v118, v118, v119
	v_add_f32_e32 v160, v160, v118

.LBB0_403:
	s_nop 0
	v_cvt_pk_bf16_f32 v114, v114, v115
	v_cvt_pk_bf16_f32 v115, v116, v117
	global_store_dwordx2 v[150:151], v[114:115], off offset:288
	v_lshlrev_b32_e32 v116, 16, v114
	v_lshlrev_b32_e32 v117, 16, v115
	v_and_b32_e32 v115, 0xffff0000, v115
	v_and_b32_e32 v114, 0xffff0000, v114
	v_pk_mul_f32 v[114:115], v[114:115], v[114:115]
	s_nop 0
	v_pk_fma_f32 v[114:115], v[116:117], v[116:117], v[114:115]
	s_nop 0
	v_add_f32_e32 v114, v114, v115
	v_add_f32_e32 v160, v160, v114
	v_cndmask_b32_e64 v114, 0, 1, s[36:37]
	v_cmp_ne_u32_e64 s[44:45], 1, v114
	s_andn2_b64 vcc, exec, s[36:37]
	s_cbranch_vccnz .LBB0_407
.LBB0_404:
	v_and_b32_e32 v115, 64, v174
	v_xor_b32_e32 v114, 16, v174
	v_add_u32_e32 v115, 64, v115
	v_cmp_lt_i32_e32 vcc, v114, v115
	v_xor_b32_e32 v116, 32, v174
	s_nop 0
	v_cndmask_b32_e32 v114, v174, v114, vcc
	v_lshlrev_b32_e32 v114, 2, v114
	ds_bpermute_b32 v114, v114, v160
	v_cmp_lt_i32_e32 vcc, v116, v115
	s_waitcnt lgkmcnt(0)
	v_add_f32_e32 v114, v160, v114
	v_cndmask_b32_e32 v115, v174, v116, vcc
	v_lshlrev_b32_e32 v115, 2, v115
	ds_bpermute_b32 v115, v115, v114
	s_and_saveexec_b64 s[2:3], s[38:39]
	s_cbranch_execz .LBB0_406
	s_waitcnt lgkmcnt(0)
	v_add_f32_e32 v114, v114, v115
	s_mov_b32 s20, 0x49800000
	v_fma_f32 v114, v114, s20, 0.5
	v_trunc_f32_e32 v114, v114
	v_mul_f32_e32 v115, 0x2f800000, v114
	v_floor_f32_e32 v115, v115
	v_fmac_f32_e32 v114, 0xcf800000, v115
	v_cvt_u32_f32_e32 v114, v114
	v_cvt_u32_f32_e32 v115, v115
	v_lshl_add_u64 v[116:117], v[140:141], 3, s[4:5]
	global_atomic_add_x2 v[116:117], v[114:115], off

.LBB0_407:
	v_or_b32_e32 v114, 16, v140
	s_waitcnt lgkmcnt(0)
	v_ashrrev_i32_e32 v115, 31, v114
	v_lshlrev_b64 v[114:115], 10, v[114:115]
	v_lshl_add_u64 v[116:117], v[114:115], 0, v[148:149]
	v_lshl_add_u64 v[114:115], v[116:117], 1, s[24:25]
	global_load_dwordx2 v[124:125], v[114:115], off
	global_load_dwordx2 v[122:123], v[114:115], off offset:32
	global_load_dwordx2 v[120:121], v[114:115], off offset:256
	global_load_dwordx2 v[118:119], v[114:115], off offset:288
	v_mov_b32_e32 v133, v132
	s_and_b64 vcc, exec, s[42:43]
	s_mov_b64 s[2:3], -1
	s_waitcnt vmcnt(0) lgkmcnt(0)
	v_lshlrev_b32_e32 v126, 16, v124
	v_and_b32_e32 v127, 0xffff0000, v124
	v_lshlrev_b32_e32 v124, 16, v125
	v_and_b32_e32 v125, 0xffff0000, v125
	v_pk_fma_f32 v[112:113], v[132:133], v[112:113], v[124:125]
	v_pk_fma_f32 v[110:111], v[134:135], v[110:111], v[126:127]
	s_cbranch_vccnz .LBB0_409
	v_lshl_add_u64 v[124:125], v[116:117], 2, s[74:75]
	s_mov_b64 s[2:3], 0
	global_store_dwordx4 v[124:125], v[110:113], off
.LBB0_409:
	s_andn2_b64 vcc, exec, s[2:3]
	v_mov_b32_e32 v124, 0
	s_cbranch_vccnz .LBB0_411
	v_cvt_pk_bf16_f32 v110, v110, v111
	v_cvt_pk_bf16_f32 v111, v112, v113
	global_store_dwordx2 v[114:115], v[110:111], off
	v_lshlrev_b32_e32 v112, 16, v110
	v_lshlrev_b32_e32 v113, 16, v111
	v_and_b32_e32 v111, 0xffff0000, v111
	v_and_b32_e32 v110, 0xffff0000, v110
	v_pk_mul_f32 v[110:111], v[110:111], v[110:111]
	s_nop 0
	v_pk_fma_f32 v[110:111], v[112:113], v[112:113], v[110:111]
	s_nop 0
	v_add_f32_e32 v124, v110, v111

.LBB0_413:
	s_andn2_b64 vcc, exec, s[2:3]
	s_cbranch_vccnz .LBB0_415
	v_cvt_pk_bf16_f32 v106, v106, v107
	v_cvt_pk_bf16_f32 v107, v108, v109
	global_store_dwordx2 v[114:115], v[106:107], off offset:32
	v_lshlrev_b32_e32 v108, 16, v106
	v_lshlrev_b32_e32 v109, 16, v107
	v_and_b32_e32 v107, 0xffff0000, v107
	v_and_b32_e32 v106, 0xffff0000, v106
	v_pk_mul_f32 v[106:107], v[106:107], v[106:107]
	s_nop 0
	v_pk_fma_f32 v[106:107], v[108:109], v[108:109], v[106:107]
	s_nop 0
	v_add_f32_e32 v106, v106, v107
	v_add_f32_e32 v124, v124, v106

.LBB0_417:
	s_andn2_b64 vcc, exec, s[2:3]
	s_cbranch_vccnz .LBB0_419
	v_cvt_pk_bf16_f32 v102, v102, v103
	v_cvt_pk_bf16_f32 v103, v104, v105
	global_store_dwordx2 v[114:115], v[102:103], off offset:256
	v_lshlrev_b32_e32 v104, 16, v102
	v_lshlrev_b32_e32 v105, 16, v103
	v_and_b32_e32 v103, 0xffff0000, v103
	v_and_b32_e32 v102, 0xffff0000, v102
	v_pk_mul_f32 v[102:103], v[102:103], v[102:103]
	s_nop 0
	v_pk_fma_f32 v[102:103], v[104:105], v[104:105], v[102:103]
	s_nop 0
	v_add_f32_e32 v102, v102, v103
	v_add_f32_e32 v124, v124, v102

.LBB0_423:
	s_nop 0
	v_cvt_pk_bf16_f32 v98, v98, v99
	v_cvt_pk_bf16_f32 v99, v100, v101
	global_store_dwordx2 v[114:115], v[98:99], off offset:288
	v_lshlrev_b32_e32 v100, 16, v98
	v_lshlrev_b32_e32 v101, 16, v99
	v_and_b32_e32 v99, 0xffff0000, v99
	v_and_b32_e32 v98, 0xffff0000, v98
	v_pk_mul_f32 v[98:99], v[98:99], v[98:99]
	s_nop 0
	v_pk_fma_f32 v[98:99], v[100:101], v[100:101], v[98:99]
	s_nop 0
	v_add_f32_e32 v98, v98, v99
	v_add_f32_e32 v124, v124, v98
	s_and_b64 vcc, exec, s[44:45]
	s_cbranch_vccnz .LBB0_427
.LBB0_424:
	v_and_b32_e32 v99, 64, v174
	v_xor_b32_e32 v98, 16, v174
	v_add_u32_e32 v99, 64, v99
	v_cmp_lt_i32_e32 vcc, v98, v99
	v_xor_b32_e32 v100, 32, v174
	s_nop 0
	v_cndmask_b32_e32 v98, v174, v98, vcc
	v_lshlrev_b32_e32 v98, 2, v98
	ds_bpermute_b32 v98, v98, v124
	v_cmp_lt_i32_e32 vcc, v100, v99
	s_waitcnt lgkmcnt(0)
	v_add_f32_e32 v98, v124, v98
	v_cndmask_b32_e32 v99, v174, v100, vcc
	v_lshlrev_b32_e32 v99, 2, v99
	ds_bpermute_b32 v99, v99, v98
	s_and_saveexec_b64 s[2:3], s[38:39]
	s_cbranch_execz .LBB0_426
	s_waitcnt lgkmcnt(0)
	v_add_f32_e32 v98, v98, v99
	s_mov_b32 s20, 0x49800000
	v_fma_f32 v98, v98, s20, 0.5
	v_trunc_f32_e32 v98, v98
	v_mul_f32_e32 v99, 0x2f800000, v98
	v_floor_f32_e32 v99, v99
	v_fmac_f32_e32 v98, 0xcf800000, v99
	v_cvt_u32_f32_e32 v98, v98
	v_cvt_u32_f32_e32 v99, v99
	v_lshl_add_u64 v[100:101], v[140:141], 3, s[4:5]
	global_atomic_add_x2 v[100:101], v[98:99], off offset:128

.LBB0_427:
	v_or_b32_e32 v98, 32, v140
	s_waitcnt lgkmcnt(0)
	v_ashrrev_i32_e32 v99, 31, v98
	v_lshlrev_b64 v[98:99], 10, v[98:99]
	v_lshl_add_u64 v[100:101], v[98:99], 0, v[148:149]
	v_lshl_add_u64 v[98:99], v[100:101], 1, s[24:25]
	global_load_dwordx2 v[108:109], v[98:99], off
	global_load_dwordx2 v[106:107], v[98:99], off offset:32
	global_load_dwordx2 v[104:105], v[98:99], off offset:256
	global_load_dwordx2 v[102:103], v[98:99], off offset:288
	v_mov_b32_e32 v133, v132
	s_and_b64 vcc, exec, s[42:43]
	s_mov_b64 s[2:3], -1
	s_waitcnt vmcnt(0) lgkmcnt(0)
	v_lshlrev_b32_e32 v110, 16, v108
	v_and_b32_e32 v111, 0xffff0000, v108
	v_lshlrev_b32_e32 v108, 16, v109
	v_and_b32_e32 v109, 0xffff0000, v109
	v_pk_fma_f32 v[96:97], v[132:133], v[96:97], v[108:109]
	v_pk_fma_f32 v[94:95], v[134:135], v[94:95], v[110:111]
	s_cbranch_vccnz .LBB0_429
	v_lshl_add_u64 v[108:109], v[100:101], 2, s[74:75]
	s_mov_b64 s[2:3], 0
	global_store_dwordx4 v[108:109], v[94:97], off
.LBB0_429:
	s_andn2_b64 vcc, exec, s[2:3]
	v_mov_b32_e32 v108, 0
	s_cbranch_vccnz .LBB0_431
	v_cvt_pk_bf16_f32 v94, v94, v95
	v_cvt_pk_bf16_f32 v95, v96, v97
	global_store_dwordx2 v[98:99], v[94:95], off
	v_lshlrev_b32_e32 v96, 16, v94
	v_lshlrev_b32_e32 v97, 16, v95
	v_and_b32_e32 v95, 0xffff0000, v95
	v_and_b32_e32 v94, 0xffff0000, v94
	v_pk_mul_f32 v[94:95], v[94:95], v[94:95]
	s_nop 0
	v_pk_fma_f32 v[94:95], v[96:97], v[96:97], v[94:95]
	s_nop 0
	v_add_f32_e32 v108, v94, v95

.LBB0_433:
	s_andn2_b64 vcc, exec, s[2:3]
	s_cbranch_vccnz .LBB0_435
	v_cvt_pk_bf16_f32 v90, v90, v91
	v_cvt_pk_bf16_f32 v91, v92, v93
	global_store_dwordx2 v[98:99], v[90:91], off offset:32
	v_lshlrev_b32_e32 v92, 16, v90
	v_lshlrev_b32_e32 v93, 16, v91
	v_and_b32_e32 v91, 0xffff0000, v91
	v_and_b32_e32 v90, 0xffff0000, v90
	v_pk_mul_f32 v[90:91], v[90:91], v[90:91]
	s_nop 0
	v_pk_fma_f32 v[90:91], v[92:93], v[92:93], v[90:91]
	s_nop 0
	v_add_f32_e32 v90, v90, v91
	v_add_f32_e32 v108, v108, v90

.LBB0_437:
	s_andn2_b64 vcc, exec, s[2:3]
	s_cbranch_vccnz .LBB0_439
	v_cvt_pk_bf16_f32 v86, v86, v87
	v_cvt_pk_bf16_f32 v87, v88, v89
	global_store_dwordx2 v[98:99], v[86:87], off offset:256
	v_lshlrev_b32_e32 v88, 16, v86
	v_lshlrev_b32_e32 v89, 16, v87
	v_and_b32_e32 v87, 0xffff0000, v87
	v_and_b32_e32 v86, 0xffff0000, v86
	v_pk_mul_f32 v[86:87], v[86:87], v[86:87]
	s_nop 0
	v_pk_fma_f32 v[86:87], v[88:89], v[88:89], v[86:87]
	s_nop 0
	v_add_f32_e32 v86, v86, v87
	v_add_f32_e32 v108, v108, v86

.LBB0_443:
	s_nop 0
	v_cvt_pk_bf16_f32 v82, v82, v83
	v_cvt_pk_bf16_f32 v83, v84, v85
	global_store_dwordx2 v[98:99], v[82:83], off offset:288
	v_lshlrev_b32_e32 v84, 16, v82
	v_lshlrev_b32_e32 v85, 16, v83
	v_and_b32_e32 v83, 0xffff0000, v83
	v_and_b32_e32 v82, 0xffff0000, v82
	v_pk_mul_f32 v[82:83], v[82:83], v[82:83]
	s_nop 0
	v_pk_fma_f32 v[82:83], v[84:85], v[84:85], v[82:83]
	s_nop 0
	v_add_f32_e32 v82, v82, v83
	v_add_f32_e32 v108, v108, v82
	s_and_b64 vcc, exec, s[44:45]
	s_cbranch_vccnz .LBB0_447
.LBB0_444:
	v_and_b32_e32 v83, 64, v174
	v_xor_b32_e32 v82, 16, v174
	v_add_u32_e32 v83, 64, v83
	v_cmp_lt_i32_e32 vcc, v82, v83
	v_xor_b32_e32 v84, 32, v174
	s_nop 0
	v_cndmask_b32_e32 v82, v174, v82, vcc
	v_lshlrev_b32_e32 v82, 2, v82
	ds_bpermute_b32 v82, v82, v108
	v_cmp_lt_i32_e32 vcc, v84, v83
	s_waitcnt lgkmcnt(0)
	v_add_f32_e32 v82, v108, v82
	v_cndmask_b32_e32 v83, v174, v84, vcc
	v_lshlrev_b32_e32 v83, 2, v83
	ds_bpermute_b32 v83, v83, v82
	s_and_saveexec_b64 s[2:3], s[38:39]
	s_cbranch_execz .LBB0_446
	s_waitcnt lgkmcnt(0)
	v_add_f32_e32 v82, v82, v83
	s_mov_b32 s20, 0x49800000
	v_fma_f32 v82, v82, s20, 0.5
	v_trunc_f32_e32 v82, v82
	v_mul_f32_e32 v83, 0x2f800000, v82
	v_floor_f32_e32 v83, v83
	v_fmac_f32_e32 v82, 0xcf800000, v83
	v_cvt_u32_f32_e32 v82, v82
	v_cvt_u32_f32_e32 v83, v83
	v_lshl_add_u64 v[84:85], v[140:141], 3, s[4:5]
	global_atomic_add_x2 v[84:85], v[82:83], off offset:256

.LBB0_447:
	v_or_b32_e32 v82, 48, v140
	s_waitcnt lgkmcnt(0)
	v_ashrrev_i32_e32 v83, 31, v82
	v_lshlrev_b64 v[82:83], 10, v[82:83]
	v_lshl_add_u64 v[84:85], v[82:83], 0, v[148:149]
	v_lshl_add_u64 v[82:83], v[84:85], 1, s[24:25]
	global_load_dwordx2 v[92:93], v[82:83], off
	global_load_dwordx2 v[90:91], v[82:83], off offset:32
	global_load_dwordx2 v[88:89], v[82:83], off offset:256
	global_load_dwordx2 v[86:87], v[82:83], off offset:288
	v_mov_b32_e32 v133, v132
	s_and_b64 vcc, exec, s[42:43]
	s_mov_b64 s[2:3], -1
	s_waitcnt vmcnt(0) lgkmcnt(0)
	v_lshlrev_b32_e32 v94, 16, v92
	v_and_b32_e32 v95, 0xffff0000, v92
	v_lshlrev_b32_e32 v92, 16, v93
	v_and_b32_e32 v93, 0xffff0000, v93
	v_pk_fma_f32 v[80:81], v[132:133], v[80:81], v[92:93]
	v_pk_fma_f32 v[78:79], v[134:135], v[78:79], v[94:95]
	s_cbranch_vccnz .LBB0_449
	v_lshl_add_u64 v[92:93], v[84:85], 2, s[74:75]
	s_mov_b64 s[2:3], 0
	global_store_dwordx4 v[92:93], v[78:81], off
.LBB0_449:
	s_andn2_b64 vcc, exec, s[2:3]
	v_mov_b32_e32 v92, 0
	s_cbranch_vccnz .LBB0_451
	v_cvt_pk_bf16_f32 v78, v78, v79
	v_cvt_pk_bf16_f32 v79, v80, v81
	global_store_dwordx2 v[82:83], v[78:79], off
	v_lshlrev_b32_e32 v80, 16, v78
	v_lshlrev_b32_e32 v81, 16, v79
	v_and_b32_e32 v79, 0xffff0000, v79
	v_and_b32_e32 v78, 0xffff0000, v78
	v_pk_mul_f32 v[78:79], v[78:79], v[78:79]
	s_nop 0
	v_pk_fma_f32 v[78:79], v[80:81], v[80:81], v[78:79]
	s_nop 0
	v_add_f32_e32 v92, v78, v79

.LBB0_453:
	s_andn2_b64 vcc, exec, s[2:3]
	s_cbranch_vccnz .LBB0_455
	v_cvt_pk_bf16_f32 v74, v74, v75
	v_cvt_pk_bf16_f32 v75, v76, v77
	global_store_dwordx2 v[82:83], v[74:75], off offset:32
	v_lshlrev_b32_e32 v76, 16, v74
	v_lshlrev_b32_e32 v77, 16, v75
	v_and_b32_e32 v75, 0xffff0000, v75
	v_and_b32_e32 v74, 0xffff0000, v74
	v_pk_mul_f32 v[74:75], v[74:75], v[74:75]
	s_nop 0
	v_pk_fma_f32 v[74:75], v[76:77], v[76:77], v[74:75]
	s_nop 0
	v_add_f32_e32 v74, v74, v75
	v_add_f32_e32 v92, v92, v74

.LBB0_457:
	s_andn2_b64 vcc, exec, s[2:3]
	s_cbranch_vccnz .LBB0_459
	v_cvt_pk_bf16_f32 v70, v70, v71
	v_cvt_pk_bf16_f32 v71, v72, v73
	global_store_dwordx2 v[82:83], v[70:71], off offset:256
	v_lshlrev_b32_e32 v72, 16, v70
	v_lshlrev_b32_e32 v73, 16, v71
	v_and_b32_e32 v71, 0xffff0000, v71
	v_and_b32_e32 v70, 0xffff0000, v70
	v_pk_mul_f32 v[70:71], v[70:71], v[70:71]
	s_nop 0
	v_pk_fma_f32 v[70:71], v[72:73], v[72:73], v[70:71]
	s_nop 0
	v_add_f32_e32 v70, v70, v71
	v_add_f32_e32 v92, v92, v70

.LBB0_463:
	s_nop 0
	v_cvt_pk_bf16_f32 v66, v66, v67
	v_cvt_pk_bf16_f32 v67, v68, v69
	global_store_dwordx2 v[82:83], v[66:67], off offset:288
	v_lshlrev_b32_e32 v68, 16, v66
	v_lshlrev_b32_e32 v69, 16, v67
	v_and_b32_e32 v67, 0xffff0000, v67
	v_and_b32_e32 v66, 0xffff0000, v66
	v_pk_mul_f32 v[66:67], v[66:67], v[66:67]
	s_nop 0
	v_pk_fma_f32 v[66:67], v[68:69], v[68:69], v[66:67]
	s_nop 0
	v_add_f32_e32 v66, v66, v67
	v_add_f32_e32 v92, v92, v66
	s_and_b64 vcc, exec, s[44:45]
	s_cbranch_vccnz .LBB0_467
.LBB0_464:
	v_and_b32_e32 v67, 64, v174
	v_xor_b32_e32 v66, 16, v174
	v_add_u32_e32 v67, 64, v67
	v_cmp_lt_i32_e32 vcc, v66, v67
	v_xor_b32_e32 v68, 32, v174
	s_nop 0
	v_cndmask_b32_e32 v66, v174, v66, vcc
	v_lshlrev_b32_e32 v66, 2, v66
	ds_bpermute_b32 v66, v66, v92
	v_cmp_lt_i32_e32 vcc, v68, v67
	s_waitcnt lgkmcnt(0)
	v_add_f32_e32 v66, v92, v66
	v_cndmask_b32_e32 v67, v174, v68, vcc
	v_lshlrev_b32_e32 v67, 2, v67
	ds_bpermute_b32 v67, v67, v66
	s_and_saveexec_b64 s[2:3], s[38:39]
	s_cbranch_execz .LBB0_466
	s_waitcnt lgkmcnt(0)
	v_add_f32_e32 v66, v66, v67
	s_mov_b32 s20, 0x49800000
	v_fma_f32 v66, v66, s20, 0.5
	v_trunc_f32_e32 v66, v66
	v_mul_f32_e32 v67, 0x2f800000, v66
	v_floor_f32_e32 v67, v67
	v_fmac_f32_e32 v66, 0xcf800000, v67
	v_cvt_u32_f32_e32 v66, v66
	v_cvt_u32_f32_e32 v67, v67
	v_lshl_add_u64 v[68:69], v[140:141], 3, s[4:5]
	global_atomic_add_x2 v[68:69], v[66:67], off offset:384

.LBB0_467:
	s_mov_b64 s[2:3], 0x20000
	v_lshl_add_u64 v[68:69], v[142:143], 0, s[2:3]
	s_waitcnt lgkmcnt(0)
	v_lshl_add_u64 v[66:67], v[68:69], 1, s[24:25]
	global_load_dwordx2 v[76:77], v[66:67], off
	global_load_dwordx2 v[74:75], v[66:67], off offset:32
	global_load_dwordx2 v[72:73], v[66:67], off offset:256
	global_load_dwordx2 v[70:71], v[66:67], off offset:288
	v_mov_b32_e32 v133, v132
	s_and_b64 vcc, exec, s[42:43]
	s_mov_b64 s[2:3], -1
	s_waitcnt vmcnt(0) lgkmcnt(0)
	v_lshlrev_b32_e32 v78, 16, v76
	v_and_b32_e32 v79, 0xffff0000, v76
	v_lshlrev_b32_e32 v76, 16, v77
	v_and_b32_e32 v77, 0xffff0000, v77
	v_pk_fma_f32 v[64:65], v[132:133], v[64:65], v[76:77]
	v_pk_fma_f32 v[62:63], v[134:135], v[62:63], v[78:79]
	s_cbranch_vccnz .LBB0_469
	v_lshl_add_u64 v[76:77], v[68:69], 2, s[74:75]
	s_mov_b64 s[2:3], 0
	global_store_dwordx4 v[76:77], v[62:65], off
.LBB0_469:
	s_andn2_b64 vcc, exec, s[2:3]
	v_mov_b32_e32 v76, 0
	s_cbranch_vccnz .LBB0_471
	v_cvt_pk_bf16_f32 v62, v62, v63
	v_cvt_pk_bf16_f32 v63, v64, v65
	global_store_dwordx2 v[66:67], v[62:63], off
	v_lshlrev_b32_e32 v64, 16, v62
	v_lshlrev_b32_e32 v65, 16, v63
	v_and_b32_e32 v63, 0xffff0000, v63
	v_and_b32_e32 v62, 0xffff0000, v62
	v_pk_mul_f32 v[62:63], v[62:63], v[62:63]
	s_nop 0
	v_pk_fma_f32 v[62:63], v[64:65], v[64:65], v[62:63]
	s_nop 0
	v_add_f32_e32 v76, v62, v63

.LBB0_473:
	s_andn2_b64 vcc, exec, s[2:3]
	s_cbranch_vccnz .LBB0_475
	v_cvt_pk_bf16_f32 v58, v58, v59
	v_cvt_pk_bf16_f32 v59, v60, v61
	global_store_dwordx2 v[66:67], v[58:59], off offset:32
	v_lshlrev_b32_e32 v60, 16, v58
	v_lshlrev_b32_e32 v61, 16, v59
	v_and_b32_e32 v59, 0xffff0000, v59
	v_and_b32_e32 v58, 0xffff0000, v58
	v_pk_mul_f32 v[58:59], v[58:59], v[58:59]
	s_nop 0
	v_pk_fma_f32 v[58:59], v[60:61], v[60:61], v[58:59]
	s_nop 0
	v_add_f32_e32 v58, v58, v59
	v_add_f32_e32 v76, v76, v58

.LBB0_477:
	s_andn2_b64 vcc, exec, s[2:3]
	s_cbranch_vccnz .LBB0_479
	v_cvt_pk_bf16_f32 v54, v54, v55
	v_cvt_pk_bf16_f32 v55, v56, v57
	global_store_dwordx2 v[66:67], v[54:55], off offset:256
	v_lshlrev_b32_e32 v56, 16, v54
	v_lshlrev_b32_e32 v57, 16, v55
	v_and_b32_e32 v55, 0xffff0000, v55
	v_and_b32_e32 v54, 0xffff0000, v54
	v_pk_mul_f32 v[54:55], v[54:55], v[54:55]
	s_nop 0
	v_pk_fma_f32 v[54:55], v[56:57], v[56:57], v[54:55]
	s_nop 0
	v_add_f32_e32 v54, v54, v55
	v_add_f32_e32 v76, v76, v54

.LBB0_483:
	s_nop 0
	v_cvt_pk_bf16_f32 v50, v50, v51
	v_cvt_pk_bf16_f32 v51, v52, v53
	global_store_dwordx2 v[66:67], v[50:51], off offset:288
	v_lshlrev_b32_e32 v52, 16, v50
	v_lshlrev_b32_e32 v53, 16, v51
	v_and_b32_e32 v51, 0xffff0000, v51
	v_and_b32_e32 v50, 0xffff0000, v50
	v_pk_mul_f32 v[50:51], v[50:51], v[50:51]
	s_nop 0
	v_pk_fma_f32 v[50:51], v[52:53], v[52:53], v[50:51]
	s_nop 0
	v_add_f32_e32 v50, v50, v51
	v_add_f32_e32 v76, v76, v50
	s_and_b64 vcc, exec, s[44:45]
	s_cbranch_vccnz .LBB0_487
.LBB0_484:
	v_and_b32_e32 v51, 64, v174
	v_xor_b32_e32 v50, 16, v174
	v_add_u32_e32 v51, 64, v51
	v_cmp_lt_i32_e32 vcc, v50, v51
	v_xor_b32_e32 v52, 32, v174
	s_nop 0
	v_cndmask_b32_e32 v50, v174, v50, vcc
	v_lshlrev_b32_e32 v50, 2, v50
	ds_bpermute_b32 v50, v50, v76
	v_cmp_lt_i32_e32 vcc, v52, v51
	s_waitcnt lgkmcnt(0)
	v_add_f32_e32 v50, v76, v50
	v_cndmask_b32_e32 v51, v174, v52, vcc
	v_lshlrev_b32_e32 v51, 2, v51
	ds_bpermute_b32 v51, v51, v50
	s_and_saveexec_b64 s[2:3], s[38:39]
	s_cbranch_execz .LBB0_486
	s_waitcnt lgkmcnt(0)
	v_add_f32_e32 v50, v50, v51
	s_mov_b32 s20, 0x49800000
	v_fma_f32 v50, v50, s20, 0.5
	v_trunc_f32_e32 v50, v50
	v_mul_f32_e32 v51, 0x2f800000, v50
	v_floor_f32_e32 v51, v51
	v_fmac_f32_e32 v50, 0xcf800000, v51
	v_cvt_u32_f32_e32 v50, v50
	v_cvt_u32_f32_e32 v51, v51
	v_lshl_add_u64 v[52:53], v[140:141], 3, s[4:5]
	global_atomic_add_x2 v[52:53], v[50:51], off offset:1024

.LBB0_487:
	s_mov_b64 s[2:3], 0x24000
	v_lshl_add_u64 v[52:53], v[142:143], 0, s[2:3]
	s_waitcnt lgkmcnt(0)
	v_lshl_add_u64 v[50:51], v[52:53], 1, s[24:25]
	global_load_dwordx2 v[60:61], v[50:51], off
	global_load_dwordx2 v[58:59], v[50:51], off offset:32
	global_load_dwordx2 v[56:57], v[50:51], off offset:256
	global_load_dwordx2 v[54:55], v[50:51], off offset:288
	v_mov_b32_e32 v133, v132
	s_and_b64 vcc, exec, s[42:43]
	s_mov_b64 s[2:3], -1
	s_waitcnt vmcnt(0) lgkmcnt(0)
	v_lshlrev_b32_e32 v62, 16, v60
	v_and_b32_e32 v63, 0xffff0000, v60
	v_lshlrev_b32_e32 v60, 16, v61
	v_and_b32_e32 v61, 0xffff0000, v61
	v_pk_fma_f32 v[48:49], v[132:133], v[48:49], v[60:61]
	v_pk_fma_f32 v[46:47], v[134:135], v[46:47], v[62:63]
	s_cbranch_vccnz .LBB0_489
	v_lshl_add_u64 v[60:61], v[52:53], 2, s[74:75]
	s_mov_b64 s[2:3], 0
	global_store_dwordx4 v[60:61], v[46:49], off
.LBB0_489:
	s_andn2_b64 vcc, exec, s[2:3]
	v_mov_b32_e32 v60, 0
	s_cbranch_vccnz .LBB0_491
	v_cvt_pk_bf16_f32 v46, v46, v47
	v_cvt_pk_bf16_f32 v47, v48, v49
	global_store_dwordx2 v[50:51], v[46:47], off
	v_lshlrev_b32_e32 v48, 16, v46
	v_lshlrev_b32_e32 v49, 16, v47
	v_and_b32_e32 v47, 0xffff0000, v47
	v_and_b32_e32 v46, 0xffff0000, v46
	v_pk_mul_f32 v[46:47], v[46:47], v[46:47]
	s_nop 0
	v_pk_fma_f32 v[46:47], v[48:49], v[48:49], v[46:47]
	s_nop 0
	v_add_f32_e32 v60, v46, v47

.LBB0_493:
	s_andn2_b64 vcc, exec, s[2:3]
	s_cbranch_vccnz .LBB0_495
	v_cvt_pk_bf16_f32 v42, v42, v43
	v_cvt_pk_bf16_f32 v43, v44, v45
	global_store_dwordx2 v[50:51], v[42:43], off offset:32
	v_lshlrev_b32_e32 v44, 16, v42
	v_lshlrev_b32_e32 v45, 16, v43
	v_and_b32_e32 v43, 0xffff0000, v43
	v_and_b32_e32 v42, 0xffff0000, v42
	v_pk_mul_f32 v[42:43], v[42:43], v[42:43]
	s_nop 0
	v_pk_fma_f32 v[42:43], v[44:45], v[44:45], v[42:43]
	s_nop 0
	v_add_f32_e32 v42, v42, v43
	v_add_f32_e32 v60, v60, v42

.LBB0_497:
	s_andn2_b64 vcc, exec, s[2:3]
	s_cbranch_vccnz .LBB0_499
	v_cvt_pk_bf16_f32 v38, v38, v39
	v_cvt_pk_bf16_f32 v39, v40, v41
	global_store_dwordx2 v[50:51], v[38:39], off offset:256
	v_lshlrev_b32_e32 v40, 16, v38
	v_lshlrev_b32_e32 v41, 16, v39
	v_and_b32_e32 v39, 0xffff0000, v39
	v_and_b32_e32 v38, 0xffff0000, v38
	v_pk_mul_f32 v[38:39], v[38:39], v[38:39]
	s_nop 0
	v_pk_fma_f32 v[38:39], v[40:41], v[40:41], v[38:39]
	s_nop 0
	v_add_f32_e32 v38, v38, v39
	v_add_f32_e32 v60, v60, v38

.LBB0_503:
	s_nop 0
	v_cvt_pk_bf16_f32 v34, v34, v35
	v_cvt_pk_bf16_f32 v35, v36, v37
	global_store_dwordx2 v[50:51], v[34:35], off offset:288
	v_lshlrev_b32_e32 v36, 16, v34
	v_lshlrev_b32_e32 v37, 16, v35
	v_and_b32_e32 v35, 0xffff0000, v35
	v_and_b32_e32 v34, 0xffff0000, v34
	v_pk_mul_f32 v[34:35], v[34:35], v[34:35]
	s_nop 0
	v_pk_fma_f32 v[34:35], v[36:37], v[36:37], v[34:35]
	s_nop 0
	v_add_f32_e32 v34, v34, v35
	v_add_f32_e32 v60, v60, v34
	s_and_b64 vcc, exec, s[44:45]
	s_cbranch_vccnz .LBB0_507
.LBB0_504:
	v_and_b32_e32 v35, 64, v174
	v_xor_b32_e32 v34, 16, v174
	v_add_u32_e32 v35, 64, v35
	v_cmp_lt_i32_e32 vcc, v34, v35
	v_xor_b32_e32 v36, 32, v174
	s_nop 0
	v_cndmask_b32_e32 v34, v174, v34, vcc
	v_lshlrev_b32_e32 v34, 2, v34
	ds_bpermute_b32 v34, v34, v60
	v_cmp_lt_i32_e32 vcc, v36, v35
	s_waitcnt lgkmcnt(0)
	v_add_f32_e32 v34, v60, v34
	v_cndmask_b32_e32 v35, v174, v36, vcc
	v_lshlrev_b32_e32 v35, 2, v35
	ds_bpermute_b32 v35, v35, v34
	s_and_saveexec_b64 s[2:3], s[38:39]
	s_cbranch_execz .LBB0_506
	s_waitcnt lgkmcnt(0)
	v_add_f32_e32 v34, v34, v35
	s_mov_b32 s20, 0x49800000
	v_fma_f32 v34, v34, s20, 0.5
	v_trunc_f32_e32 v34, v34
	v_mul_f32_e32 v35, 0x2f800000, v34
	v_floor_f32_e32 v35, v35
	v_fmac_f32_e32 v34, 0xcf800000, v35
	v_cvt_u32_f32_e32 v34, v34
	v_cvt_u32_f32_e32 v35, v35
	v_lshl_add_u64 v[36:37], v[140:141], 3, s[4:5]
	global_atomic_add_x2 v[36:37], v[34:35], off offset:1152

.LBB0_507:
	s_mov_b64 s[2:3], 0x28000
	v_lshl_add_u64 v[36:37], v[142:143], 0, s[2:3]
	s_waitcnt lgkmcnt(0)
	v_lshl_add_u64 v[34:35], v[36:37], 1, s[24:25]
	global_load_dwordx2 v[44:45], v[34:35], off
	global_load_dwordx2 v[42:43], v[34:35], off offset:32
	global_load_dwordx2 v[40:41], v[34:35], off offset:256
	global_load_dwordx2 v[38:39], v[34:35], off offset:288
	v_mov_b32_e32 v133, v132
	s_and_b64 vcc, exec, s[42:43]
	s_mov_b64 s[2:3], -1
	s_waitcnt vmcnt(0) lgkmcnt(0)
	v_lshlrev_b32_e32 v46, 16, v44
	v_and_b32_e32 v47, 0xffff0000, v44
	v_lshlrev_b32_e32 v44, 16, v45
	v_and_b32_e32 v45, 0xffff0000, v45
	v_pk_fma_f32 v[32:33], v[132:133], v[32:33], v[44:45]
	v_pk_fma_f32 v[30:31], v[134:135], v[30:31], v[46:47]
	s_cbranch_vccnz .LBB0_509
	v_lshl_add_u64 v[44:45], v[36:37], 2, s[74:75]
	s_mov_b64 s[2:3], 0
	global_store_dwordx4 v[44:45], v[30:33], off
.LBB0_509:
	s_andn2_b64 vcc, exec, s[2:3]
	v_mov_b32_e32 v44, 0
	s_cbranch_vccnz .LBB0_511
	v_cvt_pk_bf16_f32 v30, v30, v31
	v_cvt_pk_bf16_f32 v31, v32, v33
	global_store_dwordx2 v[34:35], v[30:31], off
	v_lshlrev_b32_e32 v32, 16, v30
	v_lshlrev_b32_e32 v33, 16, v31
	v_and_b32_e32 v31, 0xffff0000, v31
	v_and_b32_e32 v30, 0xffff0000, v30
	v_pk_mul_f32 v[30:31], v[30:31], v[30:31]
	s_nop 0
	v_pk_fma_f32 v[30:31], v[32:33], v[32:33], v[30:31]
	s_nop 0
	v_add_f32_e32 v44, v30, v31

.LBB0_513:
	s_andn2_b64 vcc, exec, s[2:3]
	s_cbranch_vccnz .LBB0_515
	v_cvt_pk_bf16_f32 v26, v26, v27
	v_cvt_pk_bf16_f32 v27, v28, v29
	global_store_dwordx2 v[34:35], v[26:27], off offset:32
	v_lshlrev_b32_e32 v28, 16, v26
	v_lshlrev_b32_e32 v29, 16, v27
	v_and_b32_e32 v27, 0xffff0000, v27
	v_and_b32_e32 v26, 0xffff0000, v26
	v_pk_mul_f32 v[26:27], v[26:27], v[26:27]
	s_nop 0
	v_pk_fma_f32 v[26:27], v[28:29], v[28:29], v[26:27]
	s_nop 0
	v_add_f32_e32 v26, v26, v27
	v_add_f32_e32 v44, v44, v26

.LBB0_517:
	s_andn2_b64 vcc, exec, s[2:3]
	s_cbranch_vccnz .LBB0_519
	v_cvt_pk_bf16_f32 v22, v22, v23
	v_cvt_pk_bf16_f32 v23, v24, v25
	global_store_dwordx2 v[34:35], v[22:23], off offset:256
	v_lshlrev_b32_e32 v24, 16, v22
	v_lshlrev_b32_e32 v25, 16, v23
	v_and_b32_e32 v23, 0xffff0000, v23
	v_and_b32_e32 v22, 0xffff0000, v22
	v_pk_mul_f32 v[22:23], v[22:23], v[22:23]
	s_nop 0
	v_pk_fma_f32 v[22:23], v[24:25], v[24:25], v[22:23]
	s_nop 0
	v_add_f32_e32 v22, v22, v23
	v_add_f32_e32 v44, v44, v22

.LBB0_523:
	s_nop 0
	v_cvt_pk_bf16_f32 v18, v18, v19
	v_cvt_pk_bf16_f32 v19, v20, v21
	global_store_dwordx2 v[34:35], v[18:19], off offset:288
	v_lshlrev_b32_e32 v20, 16, v18
	v_lshlrev_b32_e32 v21, 16, v19
	v_and_b32_e32 v19, 0xffff0000, v19
	v_and_b32_e32 v18, 0xffff0000, v18
	v_pk_mul_f32 v[18:19], v[18:19], v[18:19]
	s_nop 0
	v_pk_fma_f32 v[18:19], v[20:21], v[20:21], v[18:19]
	s_nop 0
	v_add_f32_e32 v18, v18, v19
	v_add_f32_e32 v44, v44, v18
	s_and_b64 vcc, exec, s[44:45]
	s_cbranch_vccnz .LBB0_527
.LBB0_524:
	v_and_b32_e32 v19, 64, v174
	v_xor_b32_e32 v18, 16, v174
	v_add_u32_e32 v19, 64, v19
	v_cmp_lt_i32_e32 vcc, v18, v19
	v_xor_b32_e32 v20, 32, v174
	s_nop 0
	v_cndmask_b32_e32 v18, v174, v18, vcc
	v_lshlrev_b32_e32 v18, 2, v18
	ds_bpermute_b32 v18, v18, v44
	v_cmp_lt_i32_e32 vcc, v20, v19
	s_waitcnt lgkmcnt(0)
	v_add_f32_e32 v18, v44, v18
	v_cndmask_b32_e32 v19, v174, v20, vcc
	v_lshlrev_b32_e32 v19, 2, v19
	ds_bpermute_b32 v19, v19, v18
	s_and_saveexec_b64 s[2:3], s[38:39]
	s_cbranch_execz .LBB0_526
	s_waitcnt lgkmcnt(0)
	v_add_f32_e32 v18, v18, v19
	s_mov_b32 s20, 0x49800000
	v_fma_f32 v18, v18, s20, 0.5
	v_trunc_f32_e32 v18, v18
	v_mul_f32_e32 v19, 0x2f800000, v18
	v_floor_f32_e32 v19, v19
	v_fmac_f32_e32 v18, 0xcf800000, v19
	v_cvt_u32_f32_e32 v18, v18
	v_cvt_u32_f32_e32 v19, v19
	v_lshl_add_u64 v[20:21], v[140:141], 3, s[4:5]
	global_atomic_add_x2 v[20:21], v[18:19], off offset:1280

.LBB0_527:
	s_mov_b64 s[2:3], 0x2c000
	v_lshl_add_u64 v[20:21], v[142:143], 0, s[2:3]
	s_waitcnt lgkmcnt(0)
	v_lshl_add_u64 v[18:19], v[20:21], 1, s[24:25]
	global_load_dwordx2 v[28:29], v[18:19], off
	global_load_dwordx2 v[26:27], v[18:19], off offset:32
	global_load_dwordx2 v[24:25], v[18:19], off offset:256
	global_load_dwordx2 v[22:23], v[18:19], off offset:288
	v_mov_b32_e32 v133, v132
	s_and_b64 vcc, exec, s[42:43]
	s_mov_b64 s[2:3], -1
	s_waitcnt vmcnt(0) lgkmcnt(0)
	v_lshlrev_b32_e32 v30, 16, v28
	v_and_b32_e32 v31, 0xffff0000, v28
	v_lshlrev_b32_e32 v28, 16, v29
	v_and_b32_e32 v29, 0xffff0000, v29
	v_pk_fma_f32 v[16:17], v[132:133], v[16:17], v[28:29]
	v_pk_fma_f32 v[14:15], v[134:135], v[14:15], v[30:31]
	s_cbranch_vccnz .LBB0_529
	v_lshl_add_u64 v[28:29], v[20:21], 2, s[74:75]
	s_mov_b64 s[2:3], 0
	global_store_dwordx4 v[28:29], v[14:17], off
.LBB0_529:
	s_andn2_b64 vcc, exec, s[2:3]
	v_mov_b32_e32 v28, 0
	s_cbranch_vccnz .LBB0_531
	v_cvt_pk_bf16_f32 v14, v14, v15
	v_cvt_pk_bf16_f32 v15, v16, v17
	global_store_dwordx2 v[18:19], v[14:15], off
	v_lshlrev_b32_e32 v16, 16, v14
	v_lshlrev_b32_e32 v17, 16, v15
	v_and_b32_e32 v15, 0xffff0000, v15
	v_and_b32_e32 v14, 0xffff0000, v14
	v_pk_mul_f32 v[14:15], v[14:15], v[14:15]
	s_nop 0
	v_pk_fma_f32 v[14:15], v[16:17], v[16:17], v[14:15]
	s_nop 0
	v_add_f32_e32 v28, v14, v15

.LBB0_533:
	s_andn2_b64 vcc, exec, s[2:3]
	s_cbranch_vccnz .LBB0_535
	v_cvt_pk_bf16_f32 v10, v10, v11
	v_cvt_pk_bf16_f32 v11, v12, v13
	global_store_dwordx2 v[18:19], v[10:11], off offset:32
	v_lshlrev_b32_e32 v12, 16, v10
	v_lshlrev_b32_e32 v13, 16, v11
	v_and_b32_e32 v11, 0xffff0000, v11
	v_and_b32_e32 v10, 0xffff0000, v10
	v_pk_mul_f32 v[10:11], v[10:11], v[10:11]
	s_nop 0
	v_pk_fma_f32 v[10:11], v[12:13], v[12:13], v[10:11]
	s_nop 0
	v_add_f32_e32 v10, v10, v11
	v_add_f32_e32 v28, v28, v10

.LBB0_537:
	s_andn2_b64 vcc, exec, s[2:3]
	s_cbranch_vccnz .LBB0_539
	v_cvt_pk_bf16_f32 v6, v6, v7
	v_cvt_pk_bf16_f32 v7, v8, v9
	global_store_dwordx2 v[18:19], v[6:7], off offset:256
	v_lshlrev_b32_e32 v8, 16, v6
	v_lshlrev_b32_e32 v9, 16, v7
	v_and_b32_e32 v7, 0xffff0000, v7
	v_and_b32_e32 v6, 0xffff0000, v6
	v_pk_mul_f32 v[6:7], v[6:7], v[6:7]
	s_nop 0
	v_pk_fma_f32 v[6:7], v[8:9], v[8:9], v[6:7]
	s_nop 0
	v_add_f32_e32 v6, v6, v7
	v_add_f32_e32 v28, v28, v6

.LBB0_544:
	s_nop 0
	v_cvt_pk_bf16_f32 v2, v2, v3
	v_cvt_pk_bf16_f32 v3, v4, v5
	global_store_dwordx2 v[18:19], v[2:3], off offset:288
	v_lshlrev_b32_e32 v4, 16, v2
	v_lshlrev_b32_e32 v5, 16, v3
	v_and_b32_e32 v3, 0xffff0000, v3
	v_and_b32_e32 v2, 0xffff0000, v2
	v_pk_mul_f32 v[2:3], v[2:3], v[2:3]
	s_nop 0
	v_pk_fma_f32 v[2:3], v[4:5], v[4:5], v[2:3]
	s_nop 0
	v_add_f32_e32 v2, v2, v3
	v_add_f32_e32 v28, v28, v2
	s_and_b64 vcc, exec, s[44:45]
	s_cbranch_vccnz .LBB0_542
.LBB0_545:
	v_and_b32_e32 v3, 64, v174
	v_xor_b32_e32 v2, 16, v174
	v_add_u32_e32 v3, 64, v3
	v_cmp_lt_i32_e32 vcc, v2, v3
	v_xor_b32_e32 v4, 32, v174
	s_nop 0
	v_cndmask_b32_e32 v2, v174, v2, vcc
	v_lshlrev_b32_e32 v2, 2, v2
	ds_bpermute_b32 v2, v2, v28
	v_cmp_lt_i32_e32 vcc, v4, v3
	s_waitcnt lgkmcnt(0)
	v_add_f32_e32 v2, v28, v2
	v_cndmask_b32_e32 v3, v174, v4, vcc
	v_lshlrev_b32_e32 v3, 2, v3
	ds_bpermute_b32 v3, v3, v2
	s_and_saveexec_b64 s[2:3], s[38:39]
	s_cbranch_execz .LBB0_547
	s_waitcnt lgkmcnt(0)
	v_add_f32_e32 v2, v2, v3
	s_mov_b32 s20, 0x49800000
	v_fma_f32 v2, v2, s20, 0.5
	v_trunc_f32_e32 v2, v2
	v_mul_f32_e32 v3, 0x2f800000, v2
	v_floor_f32_e32 v3, v3
	v_fmac_f32_e32 v2, 0xcf800000, v3
	v_cvt_u32_f32_e32 v2, v2
	v_cvt_u32_f32_e32 v3, v3
	v_lshl_add_u64 v[4:5], v[140:141], 3, s[4:5]
	global_atomic_add_x2 v[4:5], v[2:3], off offset:1408

.LBB0_552:
	v_mov_b32_e32 v10, v170
	s_cmpk_gt_i32 s34, 0xaff
	s_nop 0
	v_readfirstlane_b32 s3, v10
	s_cbranch_scc1 .LBB0_568
	v_lshlrev_b32_e32 v0, 4, v10
	v_add_u32_e32 v2, 0x2000, v0
	s_waitcnt lgkmcnt(0)
	v_ashrrev_i32_e32 v3, 31, v2
	v_lshrrev_b32_e32 v3, 22, v3
	v_add_u32_e32 v3, v2, v3
	v_ashrrev_i32_e32 v11, 10, v3
	s_cmp_eq_u32 s11, 0
	v_mul_i32_i24_e32 v3, 0x400, v11
	s_cselect_b32 s2, 0, 0x1a00000
	v_readlane_b32 s5, v255, 4
	v_sub_u32_e32 v2, v2, v3
	s_cselect_b32 s4, 0, 2
	s_add_u32 s10, s5, s2
	v_readlane_b32 s2, v255, 5
	v_lshrrev_b32_e32 v3, 4, v2
	s_addc_u32 s11, s2, 0
	v_readlane_b32 s2, v255, 3
	v_bitop3_b32 v2, v3, v2, 32 bitop3:0x6c
	s_mul_i32 s2, s2, 3
	v_ashrrev_i32_e32 v3, 31, v2
	s_add_i32 s4, s4, s2
	v_lshrrev_b32_e32 v3, 26, v3
	s_ashr_i32 s5, s4, 31
	v_add_u32_e32 v3, v2, v3
	v_lshlrev_b32_e32 v4, 3, v11
	s_lshl_b64 s[4:5], s[4:5], 18
	v_readlane_b32 s2, v255, 6
	v_ashrrev_i32_e32 v13, 6, v3
	v_and_b32_e32 v4, -16, v4
	s_add_u32 s4, s2, s4
	v_readlane_b32 s2, v255, 7
	v_add_u32_e32 v4, v13, v4
	s_addc_u32 s5, s2, s5
	v_and_b32_e32 v5, 3, v13
	s_mov_b32 s2, 0x1fffe0
	v_lshrrev_b32_e32 v6, 2, v4
	v_lshlrev_b32_e32 v7, 1, v4
	v_and_b32_e32 v3, 0xc0, v3
	v_and_or_b32 v5, v4, s2, v5
	v_and_b32_e32 v6, 4, v6
	v_and_b32_e32 v7, 24, v7
	v_sub_u32_e32 v2, v2, v3
	v_or3_b32 v5, v5, v6, v7
	v_lshlrev_b32_e32 v6, 5, v11
	v_ashrrev_i16_sdwa v2, v180, sext(v2) dst_sel:DWORD dst_unused:UNUSED_PAD src0_sel:DWORD src1_sel:BYTE_0
	v_and_b32_e32 v6, 32, v6
	v_bfe_i32 v14, v2, 0, 16
	v_add_lshl_u32 v2, v6, v14, 1
	v_lshl_add_u32 v130, v5, 11, v2
	v_lshl_add_u32 v132, v4, 11, v2
	v_bfe_i32 v2, v10, 27, 1
	v_lshrrev_b32_e32 v2, 22, v2
	v_add_u32_e32 v2, v0, v2
	v_and_b32_e32 v2, 0xfffffc00, v2
	v_sub_u32_e32 v0, v0, v2
	v_lshrrev_b32_e32 v2, 4, v0
	v_ashrrev_i32_e32 v3, 31, v10
	v_bitop3_b32 v0, v2, v0, 32 bitop3:0x6c
	v_lshrrev_b32_e32 v3, 26, v3
	v_ashrrev_i32_e32 v2, 31, v0
	v_add_u32_e32 v3, v10, v3
	v_lshrrev_b32_e32 v2, 26, v2
	v_ashrrev_i32_e32 v16, 6, v3
	v_add_u32_e32 v2, v0, v2
	v_lshlrev_b32_e32 v3, 3, v16
	v_ashrrev_i32_e32 v15, 6, v2
	v_and_b32_e32 v3, -16, v3
	v_add_u32_e32 v3, v15, v3
	v_and_b32_e32 v4, 3, v15
	s_ashr_i32 s49, s34, 31
	v_and_or_b32 v4, v3, s2, v4
	s_lshr_b32 s2, s49, 29
	s_add_i32 s2, s34, s2
	s_ashr_i32 s30, s3, 8
	s_ashr_i32 s7, s3, 6
	s_ashr_i32 s20, s2, 3
	s_and_b32 s2, s2, -8
	s_lshl_b32 s48, s7, 10
	s_lshl_b32 s6, s30, 6
	s_sub_i32 s2, s34, s2
	s_cmp_lt_i32 s2, 0
	s_movk_i32 s21, 0x161
	s_cselect_b32 s21, s21, 0x160
	s_mul_i32 s2, s2, s21
	s_add_i32 s2, s2, s20
	s_mul_hi_i32 s20, s2, 0x2e8ba2e9
	s_lshr_b32 s21, s20, 31
	s_ashr_i32 s20, s20, 5
	s_add_i32 s20, s20, s21
	s_lshl_b32 s21, s20, 3
	s_mulk_i32 s20, 0xb0
	s_sub_i32 s20, s2, s20
	s_bfe_u32 s2, s20, 0x3001c
	s_add_i32 s28, s20, s2
	s_sext_i32_i16 s2, s28
	s_and_b32 s28, s28, 0xfff8
	v_lshrrev_b32_e32 v5, 2, v3
	v_lshlrev_b32_e32 v6, 1, v3
	v_and_b32_e32 v2, 0xc0, v2
	s_sub_i32 s20, s20, s28
	v_and_b32_e32 v5, 4, v5
	v_and_b32_e32 v6, 24, v6
	v_sub_u32_e32 v0, v0, v2
	s_sext_i32_i16 s20, s20
	v_or3_b32 v4, v4, v5, v6
	v_lshlrev_b32_e32 v5, 5, v16
	v_ashrrev_i16_sdwa v0, v180, sext(v0) dst_sel:DWORD dst_unused:UNUSED_PAD src0_sel:DWORD src1_sel:BYTE_0
	s_add_i32 s20, s21, s20
	v_and_b32_e32 v5, 32, v5
	v_bfe_i32 v17, v0, 0, 16
	s_lshl_b32 s21, s20, 8
	v_and_b32_e32 v12, 15, v10
	v_add_lshl_u32 v2, v5, v17, 1
	s_lshr_b32 s2, s2, 3
	s_add_i32 s21, s21, s6
	v_lshl_add_u32 v0, v4, 11, v2
	v_lshl_add_u32 v134, v3, 11, v2
	s_mov_b32 s66, s34
	v_or_b32_e32 v2, s21, v12
	s_ashr_i32 s21, s20, 31
	s_bfe_i64 s[34:35], s[2:3], 0x100000
	s_lshl_b64 s[28:29], s[20:21], 19
	s_lshl_b64 s[34:35], s[34:35], 19
	s_add_u32 s40, s10, s34
	v_ashrrev_i32_e32 v3, 31, v2
	s_addc_u32 s41, s11, s35
	s_add_i32 s21, s48, 0
	v_lshl_add_u64 v[2:3], v[2:3], 3, s[4:5]
	s_add_i32 m0, s21, 0x10000
	s_waitcnt vmcnt(0)
	global_load_dwordx2 v[158:159], v[2:3], off
	global_load_dwordx2 v[156:157], v[2:3], off offset:128
	global_load_dwordx2 v[154:155], v[2:3], off offset:256
	global_load_dwordx2 v[152:153], v[2:3], off offset:384
	global_load_dwordx2 v[150:151], v[2:3], off offset:1024
	global_load_dwordx2 v[148:149], v[2:3], off offset:1152
	global_load_dwordx2 v[142:143], v[2:3], off offset:1280
	global_load_dwordx2 v[140:141], v[2:3], off offset:1408
	v_mov_b32_e32 v131, v1
	global_load_lds_dwordx4 v0, s[40:41]
	s_add_i32 m0, s21, 0x12000
	s_add_u32 s34, s40, 0x40000
	global_load_lds_dwordx4 v130, s[40:41]
	s_addc_u32 s35, s41, 0
	s_add_i32 m0, s21, 0x14000
	v_mov_b32_e32 v135, v1
	global_load_lds_dwordx4 v0, s[34:35]
	s_add_i32 m0, s21, 0x16000
	s_add_u32 s46, s24, s28
	s_addc_u32 s47, s25, s29
	s_add_i32 s50, s21, 0x2000
	global_load_lds_dwordx4 v130, s[34:35]
	s_mov_b32 m0, s21
	s_add_u32 s28, s46, 0x40000
	global_load_lds_dwordx4 v134, s[46:47]
	s_mov_b32 m0, s50
	s_addc_u32 s29, s47, 0
	s_add_i32 s51, s21, 0x4000
	global_load_lds_dwordx4 v132, s[46:47]
	s_mov_b32 m0, s51
	s_add_i32 s52, s21, 0x6000
	global_load_lds_dwordx4 v134, s[28:29]
	s_mov_b32 m0, s52
	v_mov_b32_e32 v133, v1
	global_load_lds_dwordx4 v132, s[28:29]
	s_cmp_eq_u32 s30, 1
	v_lshl_add_u64 v[8:9], s[40:41], 0, v[0:1]
	v_lshl_add_u64 v[6:7], s[40:41], 0, v[130:131]
	v_lshl_add_u64 v[2:3], s[46:47], 0, v[134:135]
	s_cselect_b64 s[28:29], -1, 0
	s_cmp_lg_u32 s30, 1
	v_lshl_add_u64 v[4:5], s[46:47], 0, v[132:133]
	s_cbranch_scc1 .LBB0_555
	s_barrier

.LBB0_564:
	v_lshl_add_u32 v216, s20, 8, v144
	v_lshl_or_b32 v218, s57, 7, v162
	v_mov_b32_e32 v224, s26
	v_mov_b32_e32 v225, s27
	v_ashrrev_i32_e32 v219, 31, v218
	v_mov_b32_e32 v226, 0x358637bd
	v_lshlrev_b64 v[218:219], 1, v[218:219]
	v_mad_i64_i32 v[228:229], s[2:3], v216, s14, v[224:225]
	s_mov_b64 s[40:41], 0x16000
	s_mov_b64 s[6:7], 0xb0000
	v_ffbh_u32_e32 v208, v159
	v_ffbh_u32_e32 v209, v157
	v_ffbh_u32_e32 v210, v155
	v_ffbh_u32_e32 v211, v153
	v_ffbh_u32_e32 v212, v151
	v_ffbh_u32_e32 v213, v149
	v_ffbh_u32_e32 v214, v143
	v_ffbh_u32_e32 v215, v141
	v_min_u32_e32 v208, 32, v208
	v_min_u32_e32 v209, 32, v209
	v_min_u32_e32 v210, 32, v210
	v_min_u32_e32 v211, 32, v211
	v_min_u32_e32 v212, 32, v212
	v_min_u32_e32 v213, 32, v213
	v_min_u32_e32 v214, 32, v214
	v_min_u32_e32 v215, 32, v215
	v_lshlrev_b64 v[158:159], v208, v[158:159]
	v_lshlrev_b64 v[156:157], v209, v[156:157]
	v_lshlrev_b64 v[154:155], v210, v[154:155]
	v_lshlrev_b64 v[152:153], v211, v[152:153]
	v_lshlrev_b64 v[150:151], v212, v[150:151]
	v_lshlrev_b64 v[148:149], v213, v[148:149]
	v_lshlrev_b64 v[142:143], v214, v[142:143]
	v_lshlrev_b64 v[140:141], v215, v[140:141]
	v_min_u32_e32 v158, 1, v158
	v_min_u32_e32 v156, 1, v156
	v_min_u32_e32 v154, 1, v154
	v_min_u32_e32 v152, 1, v152
	v_min_u32_e32 v150, 1, v150
	v_min_u32_e32 v148, 1, v148
	v_min_u32_e32 v142, 1, v142
	v_min_u32_e32 v140, 1, v140
	v_or_b32_e32 v159, v159, v158
	v_or_b32_e32 v157, v157, v156
	v_or_b32_e32 v155, v155, v154
	v_or_b32_e32 v153, v153, v152
	v_or_b32_e32 v151, v151, v150
	v_or_b32_e32 v149, v149, v148
	v_or_b32_e32 v143, v143, v142
	v_or_b32_e32 v141, v141, v140
	v_cvt_f32_u32_e32 v159, v159
	v_cvt_f32_u32_e32 v157, v157
	v_cvt_f32_u32_e32 v155, v155
	v_cvt_f32_u32_e32 v153, v153
	v_cvt_f32_u32_e32 v151, v151
	v_cvt_f32_u32_e32 v149, v149
	v_cvt_f32_u32_e32 v143, v143
	v_cvt_f32_u32_e32 v141, v141
	v_sub_u32_e32 v208, 32, v208
	v_sub_u32_e32 v209, 32, v209
	v_sub_u32_e32 v210, 32, v210
	v_sub_u32_e32 v211, 32, v211
	v_sub_u32_e32 v212, 32, v212
	v_sub_u32_e32 v213, 32, v213
	v_sub_u32_e32 v214, 32, v214
	v_sub_u32_e32 v215, 32, v215
	v_ldexp_f32 v184, v159, v208
	v_ldexp_f32 v186, v157, v209
	v_ldexp_f32 v188, v155, v210
	v_ldexp_f32 v190, v153, v211
	v_ldexp_f32 v192, v151, v212
	v_ldexp_f32 v194, v149, v213
	v_ldexp_f32 v196, v143, v214
	v_ldexp_f32 v198, v141, v215
	v_mul_f32_e32 v184, 0x35800000, v184
	v_mul_f32_e32 v186, 0x35800000, v186
	v_mul_f32_e32 v188, 0x35800000, v188
	v_mul_f32_e32 v190, 0x35800000, v190
	v_mul_f32_e32 v192, 0x35800000, v192
	v_mul_f32_e32 v194, 0x35800000, v194
	v_mul_f32_e32 v196, 0x35800000, v196
	v_mul_f32_e32 v198, 0x35800000, v198
	s_mov_b32 s2, 0x3a800000
	v_fma_f32 v184, v184, s2, v226
	v_fma_f32 v186, v186, s2, v226
	v_fma_f32 v188, v188, s2, v226
	v_fma_f32 v190, v190, s2, v226
	v_fma_f32 v192, v192, s2, v226
	v_fma_f32 v194, v194, s2, v226
	v_fma_f32 v196, v196, s2, v226
	v_fma_f32 v198, v198, s2, v226
	v_rsq_f32_e32 v184, v184
	v_rsq_f32_e32 v186, v186
	v_rsq_f32_e32 v188, v188
	v_rsq_f32_e32 v190, v190
	v_rsq_f32_e32 v192, v192
	v_rsq_f32_e32 v194, v194
	v_rsq_f32_e32 v196, v196
	v_rsq_f32_e32 v198, v198
	v_lshl_add_u64 v[228:229], v[228:229], 0, v[218:219]
	v_lshl_add_u64 v[230:231], v[228:229], 0, s[40:41]
	v_lshl_add_u64 v[236:237], v[228:229], 0, s[6:7]
	v_lshl_add_u64 v[232:233], v[230:231], 0, s[40:41]
	v_lshl_add_u64 v[238:239], v[230:231], 0, s[6:7]
	v_lshl_add_u64 v[234:235], v[232:233], 0, s[40:41]
	v_lshl_add_u64 v[240:241], v[232:233], 0, s[6:7]
	v_lshl_add_u64 v[242:243], v[234:235], 0, s[6:7]
	s_mov_b32 s40, 0xbfb8aa3b
	s_mov_b32 s6, 1.0
	v_pk_mul_f32 v[126:127], v[184:185], v[126:127] op_sel_hi:[0,1]
	v_pk_mul_f32 v[128:129], v[184:185], v[128:129] op_sel_hi:[0,1]
	v_pk_mul_f32 v[122:123], v[184:185], v[122:123] op_sel_hi:[0,1]
	v_pk_mul_f32 v[124:125], v[184:185], v[124:125] op_sel_hi:[0,1]
	v_pk_mul_f32 v[118:119], v[184:185], v[118:119] op_sel_hi:[0,1]
	v_pk_mul_f32 v[120:121], v[184:185], v[120:121] op_sel_hi:[0,1]
	v_pk_mul_f32 v[114:115], v[184:185], v[114:115] op_sel_hi:[0,1]
	v_pk_mul_f32 v[116:117], v[184:185], v[116:117] op_sel_hi:[0,1]
	v_pk_mul_f32 v[200:201], v[126:127], s[40:41] op_sel_hi:[1,0]
	v_pk_mul_f32 v[202:203], v[128:129], s[40:41] op_sel_hi:[1,0]
	v_pk_mul_f32 v[204:205], v[122:123], s[40:41] op_sel_hi:[1,0]
	v_pk_mul_f32 v[206:207], v[124:125], s[40:41] op_sel_hi:[1,0]
	v_exp_f32_e32 v200, v200
	v_exp_f32_e32 v201, v201
	v_exp_f32_e32 v202, v202
	v_exp_f32_e32 v203, v203
	v_exp_f32_e32 v204, v204
	v_exp_f32_e32 v205, v205
	v_exp_f32_e32 v206, v206
	v_exp_f32_e32 v207, v207
	v_pk_add_f32 v[200:201], v[200:201], s[6:7] op_sel_hi:[1,0]
	v_pk_add_f32 v[202:203], v[202:203], s[6:7] op_sel_hi:[1,0]
	v_pk_add_f32 v[204:205], v[204:205], s[6:7] op_sel_hi:[1,0]
	v_pk_add_f32 v[206:207], v[206:207], s[6:7] op_sel_hi:[1,0]
	v_rcp_f32_e32 v200, v200
	v_rcp_f32_e32 v201, v201
	v_rcp_f32_e32 v202, v202
	v_rcp_f32_e32 v203, v203
	v_rcp_f32_e32 v204, v204
	v_rcp_f32_e32 v205, v205
	v_rcp_f32_e32 v206, v206
	v_rcp_f32_e32 v207, v207
	v_pk_mul_f32 v[126:127], v[126:127], v[200:201]
	v_pk_mul_f32 v[128:129], v[128:129], v[202:203]
	v_pk_mul_f32 v[122:123], v[122:123], v[204:205]
	v_pk_mul_f32 v[124:125], v[124:125], v[206:207]
	v_pk_mul_f32 v[126:127], v[126:127], v[118:119]
	v_pk_mul_f32 v[128:129], v[128:129], v[120:121]
	v_pk_mul_f32 v[122:123], v[122:123], v[114:115]
	v_pk_mul_f32 v[124:125], v[124:125], v[116:117]
	v_cvt_pk_bf16_f32 v126, v126, v127
	v_cvt_pk_bf16_f32 v127, v128, v129
	v_cvt_pk_bf16_f32 v128, v122, v123
	v_cvt_pk_bf16_f32 v129, v124, v125
	global_store_dwordx4 v[228:229], v[126:129], off
	v_pk_mul_f32 v[110:111], v[186:187], v[110:111] op_sel_hi:[0,1]
	v_pk_mul_f32 v[112:113], v[186:187], v[112:113] op_sel_hi:[0,1]
	v_pk_mul_f32 v[106:107], v[186:187], v[106:107] op_sel_hi:[0,1]
	v_pk_mul_f32 v[108:109], v[186:187], v[108:109] op_sel_hi:[0,1]
	v_pk_mul_f32 v[102:103], v[186:187], v[102:103] op_sel_hi:[0,1]
	v_pk_mul_f32 v[104:105], v[186:187], v[104:105] op_sel_hi:[0,1]
	v_pk_mul_f32 v[98:99], v[186:187], v[98:99] op_sel_hi:[0,1]
	v_pk_mul_f32 v[100:101], v[186:187], v[100:101] op_sel_hi:[0,1]
	v_pk_mul_f32 v[200:201], v[110:111], s[40:41] op_sel_hi:[1,0]
	v_pk_mul_f32 v[202:203], v[112:113], s[40:41] op_sel_hi:[1,0]
	v_pk_mul_f32 v[204:205], v[106:107], s[40:41] op_sel_hi:[1,0]
	v_pk_mul_f32 v[206:207], v[108:109], s[40:41] op_sel_hi:[1,0]
	v_exp_f32_e32 v200, v200
	v_exp_f32_e32 v201, v201
	v_exp_f32_e32 v202, v202
	v_exp_f32_e32 v203, v203
	v_exp_f32_e32 v204, v204
	v_exp_f32_e32 v205, v205
	v_exp_f32_e32 v206, v206
	v_exp_f32_e32 v207, v207
	v_pk_add_f32 v[200:201], v[200:201], s[6:7] op_sel_hi:[1,0]
	v_pk_add_f32 v[202:203], v[202:203], s[6:7] op_sel_hi:[1,0]
	v_pk_add_f32 v[204:205], v[204:205], s[6:7] op_sel_hi:[1,0]
	v_pk_add_f32 v[206:207], v[206:207], s[6:7] op_sel_hi:[1,0]
	v_rcp_f32_e32 v200, v200
	v_rcp_f32_e32 v201, v201
	v_rcp_f32_e32 v202, v202
	v_rcp_f32_e32 v203, v203
	v_rcp_f32_e32 v204, v204
	v_rcp_f32_e32 v205, v205
	v_rcp_f32_e32 v206, v206
	v_rcp_f32_e32 v207, v207
	v_pk_mul_f32 v[110:111], v[110:111], v[200:201]
	v_pk_mul_f32 v[112:113], v[112:113], v[202:203]
	v_pk_mul_f32 v[106:107], v[106:107], v[204:205]
	v_pk_mul_f32 v[108:109], v[108:109], v[206:207]
	v_pk_mul_f32 v[110:111], v[110:111], v[102:103]
	v_pk_mul_f32 v[112:113], v[112:113], v[104:105]
	v_pk_mul_f32 v[106:107], v[106:107], v[98:99]
	v_pk_mul_f32 v[108:109], v[108:109], v[100:101]
	v_cvt_pk_bf16_f32 v110, v110, v111
	v_cvt_pk_bf16_f32 v111, v112, v113
	v_cvt_pk_bf16_f32 v112, v106, v107
	v_cvt_pk_bf16_f32 v113, v108, v109
	global_store_dwordx4 v[230:231], v[110:113], off
	v_pk_mul_f32 v[94:95], v[188:189], v[94:95] op_sel_hi:[0,1]
	v_pk_mul_f32 v[96:97], v[188:189], v[96:97] op_sel_hi:[0,1]
	v_pk_mul_f32 v[90:91], v[188:189], v[90:91] op_sel_hi:[0,1]
	v_pk_mul_f32 v[92:93], v[188:189], v[92:93] op_sel_hi:[0,1]
	v_pk_mul_f32 v[86:87], v[188:189], v[86:87] op_sel_hi:[0,1]
	v_pk_mul_f32 v[88:89], v[188:189], v[88:89] op_sel_hi:[0,1]
	v_pk_mul_f32 v[82:83], v[188:189], v[82:83] op_sel_hi:[0,1]
	v_pk_mul_f32 v[84:85], v[188:189], v[84:85] op_sel_hi:[0,1]
	v_pk_mul_f32 v[200:201], v[94:95], s[40:41] op_sel_hi:[1,0]
	v_pk_mul_f32 v[202:203], v[96:97], s[40:41] op_sel_hi:[1,0]
	v_pk_mul_f32 v[204:205], v[90:91], s[40:41] op_sel_hi:[1,0]
	v_pk_mul_f32 v[206:207], v[92:93], s[40:41] op_sel_hi:[1,0]
	v_exp_f32_e32 v200, v200
	v_exp_f32_e32 v201, v201
	v_exp_f32_e32 v202, v202
	v_exp_f32_e32 v203, v203
	v_exp_f32_e32 v204, v204
	v_exp_f32_e32 v205, v205
	v_exp_f32_e32 v206, v206
	v_exp_f32_e32 v207, v207
	v_pk_add_f32 v[200:201], v[200:201], s[6:7] op_sel_hi:[1,0]
	v_pk_add_f32 v[202:203], v[202:203], s[6:7] op_sel_hi:[1,0]
	v_pk_add_f32 v[204:205], v[204:205], s[6:7] op_sel_hi:[1,0]
	v_pk_add_f32 v[206:207], v[206:207], s[6:7] op_sel_hi:[1,0]
	v_rcp_f32_e32 v200, v200
	v_rcp_f32_e32 v201, v201
	v_rcp_f32_e32 v202, v202
	v_rcp_f32_e32 v203, v203
	v_rcp_f32_e32 v204, v204
	v_rcp_f32_e32 v205, v205
	v_rcp_f32_e32 v206, v206
	v_rcp_f32_e32 v207, v207
	v_pk_mul_f32 v[94:95], v[94:95], v[200:201]
	v_pk_mul_f32 v[96:97], v[96:97], v[202:203]
	v_pk_mul_f32 v[90:91], v[90:91], v[204:205]
	v_pk_mul_f32 v[92:93], v[92:93], v[206:207]
	v_pk_mul_f32 v[94:95], v[94:95], v[86:87]
	v_pk_mul_f32 v[96:97], v[96:97], v[88:89]
	v_pk_mul_f32 v[90:91], v[90:91], v[82:83]
	v_pk_mul_f32 v[92:93], v[92:93], v[84:85]
	v_cvt_pk_bf16_f32 v94, v94, v95
	v_cvt_pk_bf16_f32 v95, v96, v97
	v_cvt_pk_bf16_f32 v96, v90, v91
	v_cvt_pk_bf16_f32 v97, v92, v93
	global_store_dwordx4 v[232:233], v[94:97], off
	v_pk_mul_f32 v[78:79], v[190:191], v[78:79] op_sel_hi:[0,1]
	v_pk_mul_f32 v[80:81], v[190:191], v[80:81] op_sel_hi:[0,1]
	v_pk_mul_f32 v[74:75], v[190:191], v[74:75] op_sel_hi:[0,1]
	v_pk_mul_f32 v[76:77], v[190:191], v[76:77] op_sel_hi:[0,1]
	v_pk_mul_f32 v[70:71], v[190:191], v[70:71] op_sel_hi:[0,1]
	v_pk_mul_f32 v[72:73], v[190:191], v[72:73] op_sel_hi:[0,1]
	v_pk_mul_f32 v[66:67], v[190:191], v[66:67] op_sel_hi:[0,1]
	v_pk_mul_f32 v[68:69], v[190:191], v[68:69] op_sel_hi:[0,1]
	v_pk_mul_f32 v[200:201], v[78:79], s[40:41] op_sel_hi:[1,0]
	v_pk_mul_f32 v[202:203], v[80:81], s[40:41] op_sel_hi:[1,0]
	v_pk_mul_f32 v[204:205], v[74:75], s[40:41] op_sel_hi:[1,0]
	v_pk_mul_f32 v[206:207], v[76:77], s[40:41] op_sel_hi:[1,0]
	v_exp_f32_e32 v200, v200
	v_exp_f32_e32 v201, v201
	v_exp_f32_e32 v202, v202
	v_exp_f32_e32 v203, v203
	v_exp_f32_e32 v204, v204
	v_exp_f32_e32 v205, v205
	v_exp_f32_e32 v206, v206
	v_exp_f32_e32 v207, v207
	v_pk_add_f32 v[200:201], v[200:201], s[6:7] op_sel_hi:[1,0]
	v_pk_add_f32 v[202:203], v[202:203], s[6:7] op_sel_hi:[1,0]
	v_pk_add_f32 v[204:205], v[204:205], s[6:7] op_sel_hi:[1,0]
	v_pk_add_f32 v[206:207], v[206:207], s[6:7] op_sel_hi:[1,0]
	v_rcp_f32_e32 v200, v200
	v_rcp_f32_e32 v201, v201
	v_rcp_f32_e32 v202, v202
	v_rcp_f32_e32 v203, v203
	v_rcp_f32_e32 v204, v204
	v_rcp_f32_e32 v205, v205
	v_rcp_f32_e32 v206, v206
	v_rcp_f32_e32 v207, v207
	v_pk_mul_f32 v[78:79], v[78:79], v[200:201]
	v_pk_mul_f32 v[80:81], v[80:81], v[202:203]
	v_pk_mul_f32 v[74:75], v[74:75], v[204:205]
	v_pk_mul_f32 v[76:77], v[76:77], v[206:207]
	v_pk_mul_f32 v[78:79], v[78:79], v[70:71]
	v_pk_mul_f32 v[80:81], v[80:81], v[72:73]
	v_pk_mul_f32 v[74:75], v[74:75], v[66:67]
	v_pk_mul_f32 v[76:77], v[76:77], v[68:69]
	v_cvt_pk_bf16_f32 v78, v78, v79
	v_cvt_pk_bf16_f32 v79, v80, v81
	v_cvt_pk_bf16_f32 v80, v74, v75
	v_cvt_pk_bf16_f32 v81, v76, v77
	global_store_dwordx4 v[234:235], v[78:81], off
	v_pk_mul_f32 v[62:63], v[192:193], v[62:63] op_sel_hi:[0,1]
	v_pk_mul_f32 v[64:65], v[192:193], v[64:65] op_sel_hi:[0,1]
	v_pk_mul_f32 v[58:59], v[192:193], v[58:59] op_sel_hi:[0,1]
	v_pk_mul_f32 v[60:61], v[192:193], v[60:61] op_sel_hi:[0,1]
	v_pk_mul_f32 v[54:55], v[192:193], v[54:55] op_sel_hi:[0,1]
	v_pk_mul_f32 v[56:57], v[192:193], v[56:57] op_sel_hi:[0,1]
	v_pk_mul_f32 v[50:51], v[192:193], v[50:51] op_sel_hi:[0,1]
	v_pk_mul_f32 v[52:53], v[192:193], v[52:53] op_sel_hi:[0,1]
	v_pk_mul_f32 v[200:201], v[62:63], s[40:41] op_sel_hi:[1,0]
	v_pk_mul_f32 v[202:203], v[64:65], s[40:41] op_sel_hi:[1,0]
	v_pk_mul_f32 v[204:205], v[58:59], s[40:41] op_sel_hi:[1,0]
	v_pk_mul_f32 v[206:207], v[60:61], s[40:41] op_sel_hi:[1,0]
	v_exp_f32_e32 v200, v200
	v_exp_f32_e32 v201, v201
	v_exp_f32_e32 v202, v202
	v_exp_f32_e32 v203, v203
	v_exp_f32_e32 v204, v204
	v_exp_f32_e32 v205, v205
	v_exp_f32_e32 v206, v206
	v_exp_f32_e32 v207, v207
	v_pk_add_f32 v[200:201], v[200:201], s[6:7] op_sel_hi:[1,0]
	v_pk_add_f32 v[202:203], v[202:203], s[6:7] op_sel_hi:[1,0]
	v_pk_add_f32 v[204:205], v[204:205], s[6:7] op_sel_hi:[1,0]
	v_pk_add_f32 v[206:207], v[206:207], s[6:7] op_sel_hi:[1,0]
	v_rcp_f32_e32 v200, v200
	v_rcp_f32_e32 v201, v201
	v_rcp_f32_e32 v202, v202
	v_rcp_f32_e32 v203, v203
	v_rcp_f32_e32 v204, v204
	v_rcp_f32_e32 v205, v205
	v_rcp_f32_e32 v206, v206
	v_rcp_f32_e32 v207, v207
	v_pk_mul_f32 v[62:63], v[62:63], v[200:201]
	v_pk_mul_f32 v[64:65], v[64:65], v[202:203]
	v_pk_mul_f32 v[58:59], v[58:59], v[204:205]
	v_pk_mul_f32 v[60:61], v[60:61], v[206:207]
	v_pk_mul_f32 v[62:63], v[62:63], v[54:55]
	v_pk_mul_f32 v[64:65], v[64:65], v[56:57]
	v_pk_mul_f32 v[58:59], v[58:59], v[50:51]
	v_pk_mul_f32 v[60:61], v[60:61], v[52:53]
	v_cvt_pk_bf16_f32 v62, v62, v63
	v_cvt_pk_bf16_f32 v63, v64, v65
	v_cvt_pk_bf16_f32 v64, v58, v59
	v_cvt_pk_bf16_f32 v65, v60, v61
	global_store_dwordx4 v[236:237], v[62:65], off
	v_pk_mul_f32 v[46:47], v[194:195], v[46:47] op_sel_hi:[0,1]
	v_pk_mul_f32 v[48:49], v[194:195], v[48:49] op_sel_hi:[0,1]
	v_pk_mul_f32 v[42:43], v[194:195], v[42:43] op_sel_hi:[0,1]
	v_pk_mul_f32 v[44:45], v[194:195], v[44:45] op_sel_hi:[0,1]
	v_pk_mul_f32 v[38:39], v[194:195], v[38:39] op_sel_hi:[0,1]
	v_pk_mul_f32 v[40:41], v[194:195], v[40:41] op_sel_hi:[0,1]
	v_pk_mul_f32 v[34:35], v[194:195], v[34:35] op_sel_hi:[0,1]
	v_pk_mul_f32 v[36:37], v[194:195], v[36:37] op_sel_hi:[0,1]
	v_pk_mul_f32 v[200:201], v[46:47], s[40:41] op_sel_hi:[1,0]
	v_pk_mul_f32 v[202:203], v[48:49], s[40:41] op_sel_hi:[1,0]
	v_pk_mul_f32 v[204:205], v[42:43], s[40:41] op_sel_hi:[1,0]
	v_pk_mul_f32 v[206:207], v[44:45], s[40:41] op_sel_hi:[1,0]
	v_exp_f32_e32 v200, v200
	v_exp_f32_e32 v201, v201
	v_exp_f32_e32 v202, v202
	v_exp_f32_e32 v203, v203
	v_exp_f32_e32 v204, v204
	v_exp_f32_e32 v205, v205
	v_exp_f32_e32 v206, v206
	v_exp_f32_e32 v207, v207
	v_pk_add_f32 v[200:201], v[200:201], s[6:7] op_sel_hi:[1,0]
	v_pk_add_f32 v[202:203], v[202:203], s[6:7] op_sel_hi:[1,0]
	v_pk_add_f32 v[204:205], v[204:205], s[6:7] op_sel_hi:[1,0]
	v_pk_add_f32 v[206:207], v[206:207], s[6:7] op_sel_hi:[1,0]
	v_rcp_f32_e32 v200, v200
	v_rcp_f32_e32 v201, v201
	v_rcp_f32_e32 v202, v202
	v_rcp_f32_e32 v203, v203
	v_rcp_f32_e32 v204, v204
	v_rcp_f32_e32 v205, v205
	v_rcp_f32_e32 v206, v206
	v_rcp_f32_e32 v207, v207
	v_pk_mul_f32 v[46:47], v[46:47], v[200:201]
	v_pk_mul_f32 v[48:49], v[48:49], v[202:203]
	v_pk_mul_f32 v[42:43], v[42:43], v[204:205]
	v_pk_mul_f32 v[44:45], v[44:45], v[206:207]
	v_pk_mul_f32 v[46:47], v[46:47], v[38:39]
	v_pk_mul_f32 v[48:49], v[48:49], v[40:41]
	v_pk_mul_f32 v[42:43], v[42:43], v[34:35]
	v_pk_mul_f32 v[44:45], v[44:45], v[36:37]
	v_cvt_pk_bf16_f32 v46, v46, v47
	v_cvt_pk_bf16_f32 v47, v48, v49
	v_cvt_pk_bf16_f32 v48, v42, v43
	v_cvt_pk_bf16_f32 v49, v44, v45
	global_store_dwordx4 v[238:239], v[46:49], off
	v_pk_mul_f32 v[30:31], v[196:197], v[30:31] op_sel_hi:[0,1]
	v_pk_mul_f32 v[32:33], v[196:197], v[32:33] op_sel_hi:[0,1]
	v_pk_mul_f32 v[26:27], v[196:197], v[26:27] op_sel_hi:[0,1]
	v_pk_mul_f32 v[28:29], v[196:197], v[28:29] op_sel_hi:[0,1]
	v_pk_mul_f32 v[22:23], v[196:197], v[22:23] op_sel_hi:[0,1]
	v_pk_mul_f32 v[24:25], v[196:197], v[24:25] op_sel_hi:[0,1]
	v_pk_mul_f32 v[18:19], v[196:197], v[18:19] op_sel_hi:[0,1]
	v_pk_mul_f32 v[20:21], v[196:197], v[20:21] op_sel_hi:[0,1]
	v_pk_mul_f32 v[200:201], v[30:31], s[40:41] op_sel_hi:[1,0]
	v_pk_mul_f32 v[202:203], v[32:33], s[40:41] op_sel_hi:[1,0]
	v_pk_mul_f32 v[204:205], v[26:27], s[40:41] op_sel_hi:[1,0]
	v_pk_mul_f32 v[206:207], v[28:29], s[40:41] op_sel_hi:[1,0]
	v_exp_f32_e32 v200, v200
	v_exp_f32_e32 v201, v201
	v_exp_f32_e32 v202, v202
	v_exp_f32_e32 v203, v203
	v_exp_f32_e32 v204, v204
	v_exp_f32_e32 v205, v205
	v_exp_f32_e32 v206, v206
	v_exp_f32_e32 v207, v207
	v_pk_add_f32 v[200:201], v[200:201], s[6:7] op_sel_hi:[1,0]
	v_pk_add_f32 v[202:203], v[202:203], s[6:7] op_sel_hi:[1,0]
	v_pk_add_f32 v[204:205], v[204:205], s[6:7] op_sel_hi:[1,0]
	v_pk_add_f32 v[206:207], v[206:207], s[6:7] op_sel_hi:[1,0]
	v_rcp_f32_e32 v200, v200
	v_rcp_f32_e32 v201, v201
	v_rcp_f32_e32 v202, v202
	v_rcp_f32_e32 v203, v203
	v_rcp_f32_e32 v204, v204
	v_rcp_f32_e32 v205, v205
	v_rcp_f32_e32 v206, v206
	v_rcp_f32_e32 v207, v207
	v_pk_mul_f32 v[30:31], v[30:31], v[200:201]
	v_pk_mul_f32 v[32:33], v[32:33], v[202:203]
	v_pk_mul_f32 v[26:27], v[26:27], v[204:205]
	v_pk_mul_f32 v[28:29], v[28:29], v[206:207]
	v_pk_mul_f32 v[30:31], v[30:31], v[22:23]
	v_pk_mul_f32 v[32:33], v[32:33], v[24:25]
	v_pk_mul_f32 v[26:27], v[26:27], v[18:19]
	v_pk_mul_f32 v[28:29], v[28:29], v[20:21]
	v_cvt_pk_bf16_f32 v30, v30, v31
	v_cvt_pk_bf16_f32 v31, v32, v33
	v_cvt_pk_bf16_f32 v32, v26, v27
	v_cvt_pk_bf16_f32 v33, v28, v29
	global_store_dwordx4 v[240:241], v[30:33], off
	v_pk_mul_f32 v[14:15], v[198:199], v[14:15] op_sel_hi:[0,1]
	v_pk_mul_f32 v[16:17], v[198:199], v[16:17] op_sel_hi:[0,1]
	v_pk_mul_f32 v[10:11], v[198:199], v[10:11] op_sel_hi:[0,1]
	v_pk_mul_f32 v[12:13], v[198:199], v[12:13] op_sel_hi:[0,1]
	v_pk_mul_f32 v[6:7], v[198:199], v[6:7] op_sel_hi:[0,1]
	v_pk_mul_f32 v[8:9], v[198:199], v[8:9] op_sel_hi:[0,1]
	v_pk_mul_f32 v[2:3], v[198:199], v[2:3] op_sel_hi:[0,1]
	v_pk_mul_f32 v[4:5], v[198:199], v[4:5] op_sel_hi:[0,1]
	v_pk_mul_f32 v[200:201], v[14:15], s[40:41] op_sel_hi:[1,0]
	v_pk_mul_f32 v[202:203], v[16:17], s[40:41] op_sel_hi:[1,0]
	v_pk_mul_f32 v[204:205], v[10:11], s[40:41] op_sel_hi:[1,0]
	v_pk_mul_f32 v[206:207], v[12:13], s[40:41] op_sel_hi:[1,0]
	v_exp_f32_e32 v200, v200
	v_exp_f32_e32 v201, v201
	v_exp_f32_e32 v202, v202
	v_exp_f32_e32 v203, v203
	v_exp_f32_e32 v204, v204
	v_exp_f32_e32 v205, v205
	v_exp_f32_e32 v206, v206
	v_exp_f32_e32 v207, v207
	v_pk_add_f32 v[200:201], v[200:201], s[6:7] op_sel_hi:[1,0]
	v_pk_add_f32 v[202:203], v[202:203], s[6:7] op_sel_hi:[1,0]
	v_pk_add_f32 v[204:205], v[204:205], s[6:7] op_sel_hi:[1,0]
	v_pk_add_f32 v[206:207], v[206:207], s[6:7] op_sel_hi:[1,0]
	v_rcp_f32_e32 v200, v200
	v_rcp_f32_e32 v201, v201
	v_rcp_f32_e32 v202, v202
	v_rcp_f32_e32 v203, v203
	v_rcp_f32_e32 v204, v204
	v_rcp_f32_e32 v205, v205
	v_rcp_f32_e32 v206, v206
	v_rcp_f32_e32 v207, v207
	v_pk_mul_f32 v[14:15], v[14:15], v[200:201]
	v_pk_mul_f32 v[16:17], v[16:17], v[202:203]
	v_pk_mul_f32 v[10:11], v[10:11], v[204:205]
	v_pk_mul_f32 v[12:13], v[12:13], v[206:207]
	v_pk_mul_f32 v[14:15], v[14:15], v[6:7]
	v_pk_mul_f32 v[16:17], v[16:17], v[8:9]
	v_pk_mul_f32 v[10:11], v[10:11], v[2:3]
	v_pk_mul_f32 v[12:13], v[12:13], v[4:5]
	v_cvt_pk_bf16_f32 v14, v14, v15
	v_cvt_pk_bf16_f32 v15, v16, v17
	v_cvt_pk_bf16_f32 v16, v10, v11
	v_cvt_pk_bf16_f32 v17, v12, v13
	global_store_dwordx4 v[242:243], v[14:17], off
	s_mov_b64 s[2:3], -1
	s_andn2_b64 vcc, exec, s[38:39]
	s_cbranch_vccnz .LBB0_557
	s_nop 0
	v_lshl_add_u32 v2, s36, 8, v144
	v_ashrrev_i32_e32 v3, 31, v2
	v_lshl_add_u64 v[2:3], v[2:3], 3, s[4:5]
	global_load_dwordx2 v[158:159], v[2:3], off
	global_load_dwordx2 v[156:157], v[2:3], off offset:128
	global_load_dwordx2 v[154:155], v[2:3], off offset:256
	global_load_dwordx2 v[152:153], v[2:3], off offset:384
	global_load_dwordx2 v[150:151], v[2:3], off offset:1024
	global_load_dwordx2 v[148:149], v[2:3], off offset:1152
	global_load_dwordx2 v[142:143], v[2:3], off offset:1280
	global_load_dwordx2 v[140:141], v[2:3], off offset:1408
	s_andn2_b64 vcc, exec, s[28:29]
	s_cbranch_vccnz .LBB0_556
	s_barrier
	s_branch .LBB0_556

.LBB0_572:
	s_waitcnt vmcnt(0)
	v_mul_f32_e32 v0, v78, v127
	v_add_u32_e32 v6, s27, v48
	ds_write_b32 v6, v0
	s_waitcnt lgkmcnt(0)
	v_add_u32_e32 v49, s27, v11
	ds_read2_b32 v[6:7], v49 offset1:33
	ds_read2_b32 v[8:9], v49 offset0:66 offset1:99
	ds_read2_b32 v[50:51], v49 offset0:132 offset1:165
	ds_read2_b32 v[52:53], v49 offset0:198 offset1:231
	s_lshl_b64 s[2:3], s[20:21], 1
	s_add_u32 s2, s37, s2
	s_waitcnt lgkmcnt(3)
	v_cvt_pk_bf16_f32 v6, v6, v7
	s_waitcnt lgkmcnt(2)
	v_cvt_pk_bf16_f32 v7, v8, v9
	s_waitcnt lgkmcnt(1)
	v_cvt_pk_bf16_f32 v8, v50, v51
	v_or_b32_e32 v50, s5, v10
	s_addc_u32 s3, s40, s3
	v_lshlrev_b32_e32 v0, 1, v4
	v_ashrrev_i32_e32 v51, 31, v50
	v_lshl_add_u64 v[54:55], s[2:3], 0, v[0:1]
	v_lshlrev_b64 v[50:51], 11, v[50:51]
	s_waitcnt lgkmcnt(0)
	v_cvt_pk_bf16_f32 v9, v52, v53
	v_lshl_add_u64 v[50:51], v[54:55], 0, v[50:51]
	global_store_dwordx4 v[50:51], v[6:9], off
	v_add_u32_e32 v0, s27, v13
	ds_read2_b32 v[6:7], v0 offset1:33
	ds_read2_b32 v[8:9], v0 offset0:66 offset1:99
	ds_read2_b32 v[50:51], v0 offset0:132 offset1:165
	ds_read2_b32 v[52:53], v0 offset0:198 offset1:231
	v_add_u32_e32 v0, s27, v15
	s_waitcnt lgkmcnt(0)
	v_cvt_pk_bf16_f32 v6, v6, v7
	v_cvt_pk_bf16_f32 v7, v8, v9
	v_cvt_pk_bf16_f32 v8, v50, v51
	v_or_b32_e32 v50, s5, v12
	v_ashrrev_i32_e32 v51, 31, v50
	v_lshlrev_b64 v[50:51], 11, v[50:51]
	v_cvt_pk_bf16_f32 v9, v52, v53
	v_lshl_add_u64 v[50:51], v[54:55], 0, v[50:51]
	global_store_dwordx4 v[50:51], v[6:9], off
	ds_read2_b32 v[6:7], v0 offset1:33
	ds_read2_b32 v[8:9], v0 offset0:66 offset1:99
	ds_read2_b32 v[50:51], v0 offset0:132 offset1:165
	ds_read2_b32 v[52:53], v0 offset0:198 offset1:231
	v_add_u32_e32 v0, s27, v17
	s_waitcnt lgkmcnt(0)
	v_cvt_pk_bf16_f32 v6, v6, v7
	v_cvt_pk_bf16_f32 v7, v8, v9
	v_cvt_pk_bf16_f32 v8, v50, v51
	v_or_b32_e32 v50, s5, v14
	v_ashrrev_i32_e32 v51, 31, v50
	v_lshlrev_b64 v[50:51], 11, v[50:51]
	v_cvt_pk_bf16_f32 v9, v52, v53
	v_lshl_add_u64 v[50:51], v[54:55], 0, v[50:51]
	global_store_dwordx4 v[50:51], v[6:9], off
	ds_read2_b32 v[6:7], v0 offset1:33
	ds_read2_b32 v[8:9], v0 offset0:66 offset1:99
	ds_read2_b32 v[50:51], v0 offset0:132 offset1:165
	ds_read2_b32 v[52:53], v0 offset0:198 offset1:231
	s_waitcnt lgkmcnt(0)
	v_cvt_pk_bf16_f32 v6, v6, v7
	v_cvt_pk_bf16_f32 v7, v8, v9
	v_cvt_pk_bf16_f32 v8, v50, v51
	v_or_b32_e32 v50, s5, v16
	v_ashrrev_i32_e32 v51, 31, v50
	v_lshlrev_b64 v[50:51], 11, v[50:51]
	v_cvt_pk_bf16_f32 v9, v52, v53
	v_lshl_add_u64 v[50:51], v[54:55], 0, v[50:51]
	global_store_dwordx4 v[50:51], v[6:9], off
	s_waitcnt lgkmcnt(0)

.LBB0_574:
	s_mul_hi_i32 s2, s26, 0x60606061
	s_lshr_b32 s3, s2, 31
	s_ashr_i32 s2, s2, 12
	s_add_i32 s4, s2, s3
	s_mul_i32 s2, s4, 0xffffd580
	s_add_i32 s41, s26, s2
	s_ashr_i32 s5, s4, 31
	s_mul_i32 s3, s4, 0x2a80000
	s_mul_hi_i32 s2, s4, 0x2a80000
	s_add_u32 s37, s29, s3
	s_addc_u32 s40, s30, s2
	s_mul_hi_i32 s25, s4, 0x2c0000
	s_mul_i32 s24, s4, 0x2c0000
	s_cmpk_gt_i32 s41, 0xaff
	s_mov_b64 s[2:3], -1
	s_cbranch_scc0 .LBB0_808
	s_cmpk_gt_u32 s41, 0x107f
	s_cbranch_scc0 .LBB0_805
	s_cmpk_gt_u32 s41, 0x17ff
	s_cbranch_scc0 .LBB0_651
	s_cmpk_gt_u32 s41, 0x19ff
	s_cbranch_scc0 .LBB0_648
	s_cmpk_gt_u32 s41, 0x24ff
	s_cbranch_scc0 .LBB0_580
	s_mov_b32 s2, 26
	s_ashr_i32 s3, s2, 31
	s_lshl_b64 s[2:3], s[2:3], 3
	s_add_u32 s2, s0, s2
	s_addc_u32 s3, s1, s3
	s_load_dwordx2 s[2:3], s[2:3], 0x0
	s_lshl_b64 s[6:7], s[24:25], 2
	s_mul_i32 s10, s4, 0xffffab00
	s_waitcnt lgkmcnt(0)
	s_add_u32 s6, s2, s6
	s_addc_u32 s7, s3, s7
	s_add_i32 s3, s35, s10
	s_and_b32 s2, s31, 0x3e0
	s_addk_i32 s3, 0xcc00
	s_and_b32 s3, s3, 0x1ffc0
	v_or_b32_e32 v0, s2, v3
	v_or_b32_e32 v8, s3, v2
	v_lshlrev_b32_e32 v0, 2, v0
	v_lshl_add_u64 v[6:7], s[6:7], 0, v[0:1]
	v_lshlrev_b32_e32 v0, 12, v8
	v_lshl_add_u64 v[6:7], v[6:7], 0, v[0:1]
	s_movk_i32 s6, 0x2000
	v_add_co_u32_e32 v8, vcc, s6, v6
	s_movk_i32 s6, 0x4000
	s_nop 0
	v_addc_co_u32_e32 v9, vcc, 0, v7, vcc
	v_add_co_u32_e32 v50, vcc, s6, v6
	s_movk_i32 s6, 0x6000
	s_nop 0
	v_addc_co_u32_e32 v51, vcc, 0, v7, vcc
	v_add_co_u32_e32 v52, vcc, s6, v6
	s_mov_b32 s6, 0x8000
	s_nop 0
	v_addc_co_u32_e32 v53, vcc, 0, v7, vcc
	v_add_co_u32_e32 v54, vcc, s6, v6
	s_mov_b32 s6, 0xa000
	s_nop 0
	v_addc_co_u32_e32 v55, vcc, 0, v7, vcc
	v_add_co_u32_e32 v56, vcc, s6, v6
	s_mov_b32 s6, 0xc000
	s_nop 0
	v_addc_co_u32_e32 v57, vcc, 0, v7, vcc
	v_add_co_u32_e32 v58, vcc, s6, v6
	s_mov_b32 s6, 0xe000
	s_nop 0
	v_addc_co_u32_e32 v59, vcc, 0, v7, vcc
	v_add_co_u32_e32 v60, vcc, s6, v6
	s_mov_b32 s6, 0x12000
	s_nop 0
	v_addc_co_u32_e32 v61, vcc, 0, v7, vcc
	global_load_dword v0, v[6:7], off
	global_load_dword v49, v[8:9], off
	global_load_dword v64, v[50:51], off
	global_load_dword v65, v[52:53], off
	global_load_dword v66, v[54:55], off
	global_load_dword v67, v[56:57], off
	global_load_dword v68, v[58:59], off
	global_load_dword v69, v[60:61], off
	v_add_co_u32_e32 v8, vcc, s48, v6
	s_lshl_b32 s3, s3, 1
	s_nop 0
	v_addc_co_u32_e32 v9, vcc, 0, v7, vcc
	v_add_co_u32_e32 v50, vcc, s6, v6
	s_mov_b32 s6, 0x14000
	s_nop 0
	v_addc_co_u32_e32 v51, vcc, 0, v7, vcc
	v_add_co_u32_e32 v52, vcc, s6, v6
	s_mov_b32 s6, 0x16000
	s_nop 0
	v_addc_co_u32_e32 v53, vcc, 0, v7, vcc
	v_add_co_u32_e32 v54, vcc, s6, v6
	s_mov_b32 s6, 0x18000
	s_nop 0
	v_addc_co_u32_e32 v55, vcc, 0, v7, vcc
	v_add_co_u32_e32 v56, vcc, s6, v6
	s_mov_b32 s6, 0x1a000
	s_nop 0
	v_addc_co_u32_e32 v57, vcc, 0, v7, vcc
	v_add_co_u32_e32 v58, vcc, s6, v6
	s_mov_b32 s6, 0x1c000
	s_nop 0
	v_addc_co_u32_e32 v59, vcc, 0, v7, vcc
	v_add_co_u32_e32 v60, vcc, s6, v6
	s_mov_b32 s6, 0x1e000
	s_nop 0
	v_addc_co_u32_e32 v61, vcc, 0, v7, vcc
	v_add_co_u32_e32 v62, vcc, s6, v6
	s_mov_b32 s6, 0x22000
	s_nop 0
	v_addc_co_u32_e32 v63, vcc, 0, v7, vcc
	global_load_dword v70, v[8:9], off
	global_load_dword v71, v[50:51], off
	global_load_dword v72, v[52:53], off
	global_load_dword v73, v[54:55], off
	global_load_dword v74, v[56:57], off
	global_load_dword v75, v[58:59], off
	global_load_dword v76, v[60:61], off
	global_load_dword v77, v[62:63], off
	v_add_co_u32_e32 v8, vcc, s47, v6
	s_nop 1
	v_addc_co_u32_e32 v9, vcc, 0, v7, vcc
	v_add_co_u32_e32 v50, vcc, s6, v6
	s_mov_b32 s6, 0x24000
	s_nop 0
	v_addc_co_u32_e32 v51, vcc, 0, v7, vcc
	v_add_co_u32_e32 v52, vcc, s6, v6
	s_mov_b32 s6, 0x26000
	s_nop 0
	v_addc_co_u32_e32 v53, vcc, 0, v7, vcc
	v_add_co_u32_e32 v54, vcc, s6, v6
	s_mov_b32 s6, 0x28000
	s_nop 0
	v_addc_co_u32_e32 v55, vcc, 0, v7, vcc
	v_add_co_u32_e32 v56, vcc, s6, v6
	s_mov_b32 s6, 0x2a000
	s_nop 0
	v_addc_co_u32_e32 v57, vcc, 0, v7, vcc
	v_add_co_u32_e32 v58, vcc, s6, v6
	s_mov_b32 s6, 0x2c000
	s_nop 0
	v_addc_co_u32_e32 v59, vcc, 0, v7, vcc
	v_add_co_u32_e32 v60, vcc, s6, v6
	s_mov_b32 s6, 0x2e000
	s_nop 0
	v_addc_co_u32_e32 v61, vcc, 0, v7, vcc
	v_add_co_u32_e32 v62, vcc, s6, v6
	s_mov_b32 s6, 0x32000
	s_nop 0
	v_addc_co_u32_e32 v63, vcc, 0, v7, vcc
	global_load_dword v78, v[8:9], off
	global_load_dword v79, v[50:51], off
	global_load_dword v80, v[52:53], off
	global_load_dword v81, v[54:55], off
	global_load_dword v82, v[56:57], off
	global_load_dword v83, v[58:59], off
	global_load_dword v84, v[60:61], off
	s_nop 0
	global_load_dword v62, v[62:63], off
	v_add_co_u32_e32 v8, vcc, s49, v6
	s_nop 1
	v_addc_co_u32_e32 v9, vcc, 0, v7, vcc
	v_add_co_u32_e32 v50, vcc, s6, v6
	s_mov_b32 s6, 0x34000
	s_nop 0
	v_addc_co_u32_e32 v51, vcc, 0, v7, vcc
	v_add_co_u32_e32 v52, vcc, s6, v6
	s_mov_b32 s6, 0x36000
	s_nop 0
	v_addc_co_u32_e32 v53, vcc, 0, v7, vcc
	v_add_co_u32_e32 v54, vcc, s6, v6
	s_mov_b32 s6, 0x38000
	s_nop 0
	v_addc_co_u32_e32 v55, vcc, 0, v7, vcc
	v_add_co_u32_e32 v56, vcc, s6, v6
	s_mov_b32 s6, 0x3a000
	s_nop 0
	v_addc_co_u32_e32 v57, vcc, 0, v7, vcc
	v_add_co_u32_e32 v58, vcc, s6, v6
	s_mov_b32 s6, 0x3c000
	s_nop 0
	v_addc_co_u32_e32 v59, vcc, 0, v7, vcc
	v_add_co_u32_e32 v60, vcc, s6, v6
	s_mov_b32 s6, 0x3e000
	s_nop 0
	v_addc_co_u32_e32 v61, vcc, 0, v7, vcc
	v_add_co_u32_e32 v6, vcc, s6, v6
	s_add_u32 s6, s37, s3
	s_nop 0
	v_addc_co_u32_e32 v7, vcc, 0, v7, vcc
	global_load_dword v8, v[8:9], off
	s_nop 0
	global_load_dword v9, v[50:51], off
	s_nop 0
	global_load_dword v50, v[52:53], off
	global_load_dword v51, v[54:55], off
	s_nop 0
	global_load_dword v52, v[56:57], off
	global_load_dword v53, v[58:59], off
	global_load_dword v54, v[60:61], off
	s_nop 0
	global_load_dword v6, v[6:7], off
	s_waitcnt vmcnt(0)
	ds_write2_b32 v5, v0, v49 offset1:66
	ds_write2_b32 v5, v64, v65 offset0:132 offset1:198
	v_add_u32_e32 v0, 0x400, v5
	ds_write2_b32 v0, v66, v67 offset0:8 offset1:74
	ds_write2_b32 v0, v68, v69 offset0:140 offset1:206
	v_add_u32_e32 v0, 0x800, v5
	ds_write2_b32 v0, v70, v71 offset0:16 offset1:82
	ds_write2_b32 v0, v72, v73 offset0:148 offset1:214
	v_add_u32_e32 v0, 0xc00, v5
	ds_write2_b32 v0, v74, v75 offset0:24 offset1:90
	ds_write2_b32 v0, v76, v77 offset0:156 offset1:222
	v_add_u32_e32 v0, 0x1000, v5
	ds_write2_b32 v0, v78, v79 offset0:32 offset1:98
	ds_write2_b32 v0, v80, v81 offset0:164 offset1:230
	v_add_u32_e32 v0, 0x1400, v5
	ds_write2_b32 v0, v82, v83 offset0:40 offset1:106
	ds_write2_b32 v0, v84, v62 offset0:172 offset1:238
	v_add_u32_e32 v0, 0x1800, v5
	ds_write2_b32 v0, v8, v9 offset0:48 offset1:114
	ds_write2_b32 v0, v50, v51 offset0:180 offset1:246
	v_add_u32_e32 v0, 0x1c00, v5
	ds_write2_b32 v0, v52, v53 offset0:56 offset1:122
	ds_write2_b32 v0, v54, v6 offset0:188 offset1:254
	s_addc_u32 s7, s40, 0
	v_lshlrev_b32_e32 v0, 1, v4
	s_waitcnt lgkmcnt(0)
	v_lshl_add_u64 v[6:7], s[6:7], 0, v[0:1]
	v_add_u32_e32 v0, s27, v11
	ds_read2_b32 v[8:9], v0 offset1:33
	ds_read2_b32 v[50:51], v0 offset0:66 offset1:99
	ds_read2_b32 v[52:53], v0 offset0:132 offset1:165
	ds_read2_b32 v[54:55], v0 offset0:198 offset1:231
	s_mov_b64 s[6:7], 0x2500000
	v_or_b32_e32 v0, s2, v10
	v_lshl_add_u64 v[56:57], v[6:7], 0, s[6:7]
	v_mul_u32_u24_e32 v0, 0x1600, v0
	s_waitcnt lgkmcnt(3)
	v_cvt_pk_bf16_f32 v6, v8, v9
	s_waitcnt lgkmcnt(2)
	v_cvt_pk_bf16_f32 v7, v50, v51
	s_waitcnt lgkmcnt(1)
	v_cvt_pk_bf16_f32 v8, v52, v53
	s_waitcnt lgkmcnt(0)
	v_cvt_pk_bf16_f32 v9, v54, v55
	v_lshl_add_u64 v[50:51], v[56:57], 0, v[0:1]
	global_store_dwordx4 v[50:51], v[6:9], off
	v_add_u32_e32 v0, s27, v13
	ds_read2_b32 v[6:7], v0 offset1:33
	ds_read2_b32 v[8:9], v0 offset0:66 offset1:99
	ds_read2_b32 v[50:51], v0 offset0:132 offset1:165
	ds_read2_b32 v[52:53], v0 offset0:198 offset1:231
	v_or_b32_e32 v0, s2, v12
	v_mul_u32_u24_e32 v0, 0x1600, v0
	s_waitcnt lgkmcnt(0)
	v_cvt_pk_bf16_f32 v6, v6, v7
	v_cvt_pk_bf16_f32 v7, v8, v9
	v_cvt_pk_bf16_f32 v8, v50, v51
	v_cvt_pk_bf16_f32 v9, v52, v53
	v_lshl_add_u64 v[50:51], v[56:57], 0, v[0:1]
	global_store_dwordx4 v[50:51], v[6:9], off
	v_add_u32_e32 v0, s27, v15
	ds_read2_b32 v[6:7], v0 offset1:33
	ds_read2_b32 v[8:9], v0 offset0:66 offset1:99
	ds_read2_b32 v[50:51], v0 offset0:132 offset1:165
	ds_read2_b32 v[52:53], v0 offset0:198 offset1:231
	v_or_b32_e32 v0, s2, v14
	v_mul_u32_u24_e32 v0, 0x1600, v0
	s_waitcnt lgkmcnt(0)
	v_cvt_pk_bf16_f32 v6, v6, v7
	v_cvt_pk_bf16_f32 v7, v8, v9
	v_cvt_pk_bf16_f32 v8, v50, v51
	v_cvt_pk_bf16_f32 v9, v52, v53
	v_lshl_add_u64 v[50:51], v[56:57], 0, v[0:1]
	global_store_dwordx4 v[50:51], v[6:9], off
	v_add_u32_e32 v0, s27, v17
	ds_read2_b32 v[6:7], v0 offset1:33
	ds_read2_b32 v[8:9], v0 offset0:66 offset1:99
	ds_read2_b32 v[50:51], v0 offset0:132 offset1:165
	ds_read2_b32 v[52:53], v0 offset0:198 offset1:231
	v_or_b32_e32 v0, s2, v16
	v_mul_u32_u24_e32 v0, 0x1600, v0
	s_waitcnt lgkmcnt(0)
	v_cvt_pk_bf16_f32 v6, v6, v7
	v_cvt_pk_bf16_f32 v7, v8, v9
	v_cvt_pk_bf16_f32 v8, v50, v51
	v_cvt_pk_bf16_f32 v9, v52, v53
	v_lshl_add_u64 v[50:51], v[56:57], 0, v[0:1]
	global_store_dwordx4 v[50:51], v[6:9], off
	s_waitcnt lgkmcnt(0)
	s_mov_b64 s[2:3], 0

.LBB0_646:
	s_lshl_b32 s2, s11, 1
	s_waitcnt vmcnt(0)
	v_mul_f32_e32 v0, v8, v127
	v_add_u32_e32 v6, s27, v48
	s_add_u32 s2, s37, s2
	ds_write_b32 v6, v0
	s_addc_u32 s3, s40, 0
	v_lshlrev_b32_e32 v0, 1, v4
	s_waitcnt lgkmcnt(0)
	v_lshl_add_u64 v[6:7], s[2:3], 0, v[0:1]
	v_add_u32_e32 v0, s27, v11
	ds_read2_b32 v[8:9], v0 offset1:33
	ds_read2_b32 v[50:51], v0 offset0:66 offset1:99
	ds_read2_b32 v[52:53], v0 offset0:132 offset1:165
	ds_read2_b32 v[54:55], v0 offset0:198 offset1:231
	s_mov_b64 s[2:3], 0x1a00000
	v_or_b32_e32 v0, s10, v10
	v_lshl_add_u64 v[56:57], v[6:7], 0, s[2:3]
	v_lshlrev_b32_e32 v0, 11, v0
	s_waitcnt lgkmcnt(3)
	v_cvt_pk_bf16_f32 v6, v8, v9
	s_waitcnt lgkmcnt(2)
	v_cvt_pk_bf16_f32 v7, v50, v51
	s_waitcnt lgkmcnt(1)
	v_cvt_pk_bf16_f32 v8, v52, v53
	s_waitcnt lgkmcnt(0)
	v_cvt_pk_bf16_f32 v9, v54, v55
	v_lshl_add_u64 v[50:51], v[56:57], 0, v[0:1]
	global_store_dwordx4 v[50:51], v[6:9], off
	v_add_u32_e32 v0, s27, v13
	ds_read2_b32 v[6:7], v0 offset1:33
	ds_read2_b32 v[8:9], v0 offset0:66 offset1:99
	ds_read2_b32 v[50:51], v0 offset0:132 offset1:165
	ds_read2_b32 v[52:53], v0 offset0:198 offset1:231
	v_or_b32_e32 v0, s10, v12
	v_lshlrev_b32_e32 v0, 11, v0
	s_waitcnt lgkmcnt(0)
	v_cvt_pk_bf16_f32 v6, v6, v7
	v_cvt_pk_bf16_f32 v7, v8, v9
	v_cvt_pk_bf16_f32 v8, v50, v51
	v_cvt_pk_bf16_f32 v9, v52, v53
	v_lshl_add_u64 v[50:51], v[56:57], 0, v[0:1]
	global_store_dwordx4 v[50:51], v[6:9], off
	v_add_u32_e32 v0, s27, v15
	ds_read2_b32 v[6:7], v0 offset1:33
	ds_read2_b32 v[8:9], v0 offset0:66 offset1:99
	ds_read2_b32 v[50:51], v0 offset0:132 offset1:165
	ds_read2_b32 v[52:53], v0 offset0:198 offset1:231
	v_or_b32_e32 v0, s10, v14
	v_lshlrev_b32_e32 v0, 11, v0
	s_waitcnt lgkmcnt(0)
	v_cvt_pk_bf16_f32 v6, v6, v7
	v_cvt_pk_bf16_f32 v7, v8, v9
	v_cvt_pk_bf16_f32 v8, v50, v51
	v_cvt_pk_bf16_f32 v9, v52, v53
	v_lshl_add_u64 v[50:51], v[56:57], 0, v[0:1]
	global_store_dwordx4 v[50:51], v[6:9], off
	v_add_u32_e32 v0, s27, v17
	ds_read2_b32 v[6:7], v0 offset1:33
	ds_read2_b32 v[8:9], v0 offset0:66 offset1:99
	ds_read2_b32 v[50:51], v0 offset0:132 offset1:165
	ds_read2_b32 v[52:53], v0 offset0:198 offset1:231
	v_or_b32_e32 v0, s10, v16
	v_lshlrev_b32_e32 v0, 11, v0
	s_waitcnt lgkmcnt(0)
	v_cvt_pk_bf16_f32 v6, v6, v7
	v_cvt_pk_bf16_f32 v7, v8, v9
	v_cvt_pk_bf16_f32 v8, v50, v51
	v_cvt_pk_bf16_f32 v9, v52, v53
	v_lshl_add_u64 v[50:51], v[56:57], 0, v[0:1]
	global_store_dwordx4 v[50:51], v[6:9], off
	s_waitcnt lgkmcnt(0)

.LBB0_648:
	s_andn2_b64 vcc, exec, s[2:3]
	s_cbranch_vccnz .LBB0_650
	s_mov_b32 s2, 22
	s_ashr_i32 s3, s2, 31
	s_lshl_b64 s[2:3], s[2:3], 3
	s_add_u32 s2, s0, s2
	s_addc_u32 s3, s1, s3
	s_load_dwordx2 s[2:3], s[2:3], 0x0
	s_lshl_b64 s[6:7], s[4:5], 22
	s_mul_i32 s10, s4, 0xffffab00
	s_movk_i32 s5, 0x2000
	s_waitcnt lgkmcnt(0)
	s_add_u32 s6, s2, s6
	s_addc_u32 s7, s3, s7
	s_add_i32 s3, s35, s10
	s_and_b32 s2, s31, 0x3e0
	s_addk_i32 s3, 0xe600
	s_and_b32 s3, s3, 0x1ffc0
	v_or_b32_e32 v0, s2, v3
	v_or_b32_e32 v8, s3, v2
	v_lshlrev_b32_e32 v0, 2, v0
	v_lshl_add_u64 v[6:7], s[6:7], 0, v[0:1]
	v_lshlrev_b32_e32 v0, 12, v8
	v_lshl_add_u64 v[6:7], v[6:7], 0, v[0:1]
	v_add_co_u32_e32 v8, vcc, s5, v6
	s_movk_i32 s5, 0x4000
	s_nop 0
	v_addc_co_u32_e32 v9, vcc, 0, v7, vcc
	v_add_co_u32_e32 v50, vcc, s5, v6
	s_movk_i32 s5, 0x6000
	s_nop 0
	v_addc_co_u32_e32 v51, vcc, 0, v7, vcc
	v_add_co_u32_e32 v52, vcc, s5, v6
	s_mov_b32 s5, 0x8000
	s_nop 0
	v_addc_co_u32_e32 v53, vcc, 0, v7, vcc
	v_add_co_u32_e32 v54, vcc, s5, v6
	s_mov_b32 s5, 0xa000
	s_nop 0
	v_addc_co_u32_e32 v55, vcc, 0, v7, vcc
	v_add_co_u32_e32 v56, vcc, s5, v6
	s_mov_b32 s5, 0xc000
	s_nop 0
	v_addc_co_u32_e32 v57, vcc, 0, v7, vcc
	v_add_co_u32_e32 v58, vcc, s5, v6
	s_mov_b32 s5, 0xe000
	s_nop 0
	v_addc_co_u32_e32 v59, vcc, 0, v7, vcc
	v_add_co_u32_e32 v60, vcc, s5, v6
	s_mov_b32 s5, 0x12000
	s_nop 0
	v_addc_co_u32_e32 v61, vcc, 0, v7, vcc
	global_load_dword v0, v[6:7], off
	global_load_dword v49, v[8:9], off
	global_load_dword v64, v[50:51], off
	global_load_dword v65, v[52:53], off
	global_load_dword v66, v[54:55], off
	global_load_dword v67, v[56:57], off
	global_load_dword v68, v[58:59], off
	global_load_dword v69, v[60:61], off
	v_add_co_u32_e32 v8, vcc, s48, v6
	s_lshl_b32 s3, s3, 1
	s_nop 0
	v_addc_co_u32_e32 v9, vcc, 0, v7, vcc
	v_add_co_u32_e32 v50, vcc, s5, v6
	s_mov_b32 s5, 0x14000
	s_nop 0
	v_addc_co_u32_e32 v51, vcc, 0, v7, vcc
	v_add_co_u32_e32 v52, vcc, s5, v6
	s_mov_b32 s5, 0x16000
	s_nop 0
	v_addc_co_u32_e32 v53, vcc, 0, v7, vcc
	v_add_co_u32_e32 v54, vcc, s5, v6
	s_mov_b32 s5, 0x18000
	s_nop 0
	v_addc_co_u32_e32 v55, vcc, 0, v7, vcc
	v_add_co_u32_e32 v56, vcc, s5, v6
	s_mov_b32 s5, 0x1a000
	s_nop 0
	v_addc_co_u32_e32 v57, vcc, 0, v7, vcc
	v_add_co_u32_e32 v58, vcc, s5, v6
	s_mov_b32 s5, 0x1c000
	s_nop 0
	v_addc_co_u32_e32 v59, vcc, 0, v7, vcc
	v_add_co_u32_e32 v60, vcc, s5, v6
	s_mov_b32 s5, 0x1e000
	s_nop 0
	v_addc_co_u32_e32 v61, vcc, 0, v7, vcc
	v_add_co_u32_e32 v62, vcc, s5, v6
	s_mov_b32 s5, 0x22000
	s_nop 0
	v_addc_co_u32_e32 v63, vcc, 0, v7, vcc
	global_load_dword v70, v[8:9], off
	global_load_dword v71, v[50:51], off
	global_load_dword v72, v[52:53], off
	global_load_dword v73, v[54:55], off
	global_load_dword v74, v[56:57], off
	global_load_dword v75, v[58:59], off
	global_load_dword v76, v[60:61], off
	global_load_dword v77, v[62:63], off
	v_add_co_u32_e32 v8, vcc, s47, v6
	s_add_u32 s6, s37, s3
	s_nop 0
	v_addc_co_u32_e32 v9, vcc, 0, v7, vcc
	v_add_co_u32_e32 v50, vcc, s5, v6
	s_mov_b32 s5, 0x24000
	s_nop 0
	v_addc_co_u32_e32 v51, vcc, 0, v7, vcc
	v_add_co_u32_e32 v52, vcc, s5, v6
	s_mov_b32 s5, 0x26000
	s_nop 0
	v_addc_co_u32_e32 v53, vcc, 0, v7, vcc
	v_add_co_u32_e32 v54, vcc, s5, v6
	s_mov_b32 s5, 0x28000
	s_nop 0
	v_addc_co_u32_e32 v55, vcc, 0, v7, vcc
	v_add_co_u32_e32 v56, vcc, s5, v6
	s_mov_b32 s5, 0x2a000
	s_nop 0
	v_addc_co_u32_e32 v57, vcc, 0, v7, vcc
	v_add_co_u32_e32 v58, vcc, s5, v6
	s_mov_b32 s5, 0x2c000
	s_nop 0
	v_addc_co_u32_e32 v59, vcc, 0, v7, vcc
	v_add_co_u32_e32 v60, vcc, s5, v6
	s_mov_b32 s5, 0x2e000
	s_nop 0
	v_addc_co_u32_e32 v61, vcc, 0, v7, vcc
	v_add_co_u32_e32 v62, vcc, s5, v6
	s_mov_b32 s5, 0x32000
	s_nop 0
	v_addc_co_u32_e32 v63, vcc, 0, v7, vcc
	global_load_dword v78, v[8:9], off
	global_load_dword v79, v[50:51], off
	global_load_dword v80, v[52:53], off
	global_load_dword v81, v[54:55], off
	global_load_dword v82, v[56:57], off
	global_load_dword v83, v[58:59], off
	global_load_dword v84, v[60:61], off
	s_nop 0
	global_load_dword v62, v[62:63], off
	v_add_co_u32_e32 v8, vcc, s49, v6
	s_addc_u32 s7, s40, 0
	s_nop 0
	v_addc_co_u32_e32 v9, vcc, 0, v7, vcc
	v_add_co_u32_e32 v50, vcc, s5, v6
	s_mov_b32 s5, 0x34000
	s_nop 0
	v_addc_co_u32_e32 v51, vcc, 0, v7, vcc
	v_add_co_u32_e32 v52, vcc, s5, v6
	s_mov_b32 s5, 0x36000
	s_nop 0
	v_addc_co_u32_e32 v53, vcc, 0, v7, vcc
	v_add_co_u32_e32 v54, vcc, s5, v6
	s_mov_b32 s5, 0x38000
	s_nop 0
	v_addc_co_u32_e32 v55, vcc, 0, v7, vcc
	v_add_co_u32_e32 v56, vcc, s5, v6
	s_mov_b32 s5, 0x3a000
	s_nop 0
	v_addc_co_u32_e32 v57, vcc, 0, v7, vcc
	v_add_co_u32_e32 v58, vcc, s5, v6
	s_mov_b32 s5, 0x3c000
	s_nop 0
	v_addc_co_u32_e32 v59, vcc, 0, v7, vcc
	v_add_co_u32_e32 v60, vcc, s5, v6
	s_mov_b32 s5, 0x3e000
	s_nop 0
	v_addc_co_u32_e32 v61, vcc, 0, v7, vcc
	v_add_co_u32_e32 v6, vcc, s5, v6
	s_nop 1
	v_addc_co_u32_e32 v7, vcc, 0, v7, vcc
	global_load_dword v8, v[8:9], off
	s_nop 0
	global_load_dword v9, v[50:51], off
	s_nop 0
	global_load_dword v50, v[52:53], off
	global_load_dword v51, v[54:55], off
	s_nop 0
	global_load_dword v52, v[56:57], off
	global_load_dword v53, v[58:59], off
	global_load_dword v54, v[60:61], off
	s_nop 0
	global_load_dword v6, v[6:7], off
	s_waitcnt vmcnt(0)
	ds_write2_b32 v5, v0, v49 offset1:66
	ds_write2_b32 v5, v64, v65 offset0:132 offset1:198
	v_add_u32_e32 v0, 0x400, v5
	ds_write2_b32 v0, v66, v67 offset0:8 offset1:74
	ds_write2_b32 v0, v68, v69 offset0:140 offset1:206
	v_add_u32_e32 v0, 0x800, v5
	ds_write2_b32 v0, v70, v71 offset0:16 offset1:82
	ds_write2_b32 v0, v72, v73 offset0:148 offset1:214
	v_add_u32_e32 v0, 0xc00, v5
	ds_write2_b32 v0, v74, v75 offset0:24 offset1:90
	ds_write2_b32 v0, v76, v77 offset0:156 offset1:222
	v_add_u32_e32 v0, 0x1000, v5
	ds_write2_b32 v0, v78, v79 offset0:32 offset1:98
	ds_write2_b32 v0, v80, v81 offset0:164 offset1:230
	v_add_u32_e32 v0, 0x1400, v5
	ds_write2_b32 v0, v82, v83 offset0:40 offset1:106
	ds_write2_b32 v0, v84, v62 offset0:172 offset1:238
	v_add_u32_e32 v0, 0x1800, v5
	ds_write2_b32 v0, v8, v9 offset0:48 offset1:114
	ds_write2_b32 v0, v50, v51 offset0:180 offset1:246
	v_add_u32_e32 v0, 0x1c00, v5
	ds_write2_b32 v0, v52, v53 offset0:56 offset1:122
	ds_write2_b32 v0, v54, v6 offset0:188 offset1:254
	v_lshlrev_b32_e32 v0, 1, v4
	s_waitcnt lgkmcnt(0)
	v_lshl_add_u64 v[6:7], s[6:7], 0, v[0:1]
	v_add_u32_e32 v0, s27, v11
	ds_read2_b32 v[8:9], v0 offset1:33
	ds_read2_b32 v[50:51], v0 offset0:66 offset1:99
	ds_read2_b32 v[52:53], v0 offset0:132 offset1:165
	ds_read2_b32 v[54:55], v0 offset0:198 offset1:231
	s_mov_b64 s[6:7], 0x1800000
	v_or_b32_e32 v0, s2, v10
	v_lshl_add_u64 v[56:57], v[6:7], 0, s[6:7]
	v_lshlrev_b32_e32 v0, 11, v0
	s_waitcnt lgkmcnt(3)
	v_cvt_pk_bf16_f32 v6, v8, v9
	s_waitcnt lgkmcnt(2)
	v_cvt_pk_bf16_f32 v7, v50, v51
	s_waitcnt lgkmcnt(1)
	v_cvt_pk_bf16_f32 v8, v52, v53
	s_waitcnt lgkmcnt(0)
	v_cvt_pk_bf16_f32 v9, v54, v55
	v_lshl_add_u64 v[50:51], v[56:57], 0, v[0:1]
	global_store_dwordx4 v[50:51], v[6:9], off
	v_add_u32_e32 v0, s27, v13
	ds_read2_b32 v[6:7], v0 offset1:33
	ds_read2_b32 v[8:9], v0 offset0:66 offset1:99
	ds_read2_b32 v[50:51], v0 offset0:132 offset1:165
	ds_read2_b32 v[52:53], v0 offset0:198 offset1:231
	v_or_b32_e32 v0, s2, v12
	v_lshlrev_b32_e32 v0, 11, v0
	s_waitcnt lgkmcnt(0)
	v_cvt_pk_bf16_f32 v6, v6, v7
	v_cvt_pk_bf16_f32 v7, v8, v9
	v_cvt_pk_bf16_f32 v8, v50, v51
	v_cvt_pk_bf16_f32 v9, v52, v53
	v_lshl_add_u64 v[50:51], v[56:57], 0, v[0:1]
	global_store_dwordx4 v[50:51], v[6:9], off
	v_add_u32_e32 v0, s27, v15
	ds_read2_b32 v[6:7], v0 offset1:33
	ds_read2_b32 v[8:9], v0 offset0:66 offset1:99
	ds_read2_b32 v[50:51], v0 offset0:132 offset1:165
	ds_read2_b32 v[52:53], v0 offset0:198 offset1:231
	v_or_b32_e32 v0, s2, v14
	v_lshlrev_b32_e32 v0, 11, v0
	s_waitcnt lgkmcnt(0)
	v_cvt_pk_bf16_f32 v6, v6, v7
	v_cvt_pk_bf16_f32 v7, v8, v9
	v_cvt_pk_bf16_f32 v8, v50, v51
	v_cvt_pk_bf16_f32 v9, v52, v53
	v_lshl_add_u64 v[50:51], v[56:57], 0, v[0:1]
	global_store_dwordx4 v[50:51], v[6:9], off
	v_add_u32_e32 v0, s27, v17
	ds_read2_b32 v[6:7], v0 offset1:33
	ds_read2_b32 v[8:9], v0 offset0:66 offset1:99
	ds_read2_b32 v[50:51], v0 offset0:132 offset1:165
	ds_read2_b32 v[52:53], v0 offset0:198 offset1:231
	v_or_b32_e32 v0, s2, v16
	v_lshlrev_b32_e32 v0, 11, v0
	s_waitcnt lgkmcnt(0)
	v_cvt_pk_bf16_f32 v6, v6, v7
	v_cvt_pk_bf16_f32 v7, v8, v9
	v_cvt_pk_bf16_f32 v8, v50, v51
	v_cvt_pk_bf16_f32 v9, v52, v53
	v_lshl_add_u64 v[50:51], v[56:57], 0, v[0:1]
	global_store_dwordx4 v[50:51], v[6:9], off
	s_waitcnt lgkmcnt(0)

.LBB0_803:
	s_lshl_b32 s2, s6, 1
	s_waitcnt vmcnt(0)
	v_mul_f32_e32 v0, v77, v127
	v_add_u32_e32 v6, s27, v48
	s_add_u32 s2, s37, s2
	ds_write_b32 v6, v0
	s_addc_u32 s3, s40, 0
	v_lshlrev_b32_e32 v0, 1, v4
	s_waitcnt lgkmcnt(0)
	v_lshl_add_u64 v[6:7], s[2:3], 0, v[0:1]
	v_add_u32_e32 v0, s27, v11
	ds_read2_b32 v[8:9], v0 offset1:33
	ds_read2_b32 v[50:51], v0 offset0:66 offset1:99
	ds_read2_b32 v[52:53], v0 offset0:132 offset1:165
	ds_read2_b32 v[54:55], v0 offset0:198 offset1:231
	s_mov_b64 s[2:3], 0x1080000
	v_or_b32_e32 v0, s5, v10
	v_lshl_add_u64 v[56:57], v[6:7], 0, s[2:3]
	v_lshlrev_b32_e32 v0, 11, v0
	s_waitcnt lgkmcnt(3)
	v_cvt_pk_bf16_f32 v6, v8, v9
	s_waitcnt lgkmcnt(2)
	v_cvt_pk_bf16_f32 v7, v50, v51
	s_waitcnt lgkmcnt(1)
	v_cvt_pk_bf16_f32 v8, v52, v53
	s_waitcnt lgkmcnt(0)
	v_cvt_pk_bf16_f32 v9, v54, v55
	v_lshl_add_u64 v[50:51], v[56:57], 0, v[0:1]
	global_store_dwordx4 v[50:51], v[6:9], off
	v_add_u32_e32 v0, s27, v13
	ds_read2_b32 v[6:7], v0 offset1:33
	ds_read2_b32 v[8:9], v0 offset0:66 offset1:99
	ds_read2_b32 v[50:51], v0 offset0:132 offset1:165
	ds_read2_b32 v[52:53], v0 offset0:198 offset1:231
	v_or_b32_e32 v0, s5, v12
	v_lshlrev_b32_e32 v0, 11, v0
	s_waitcnt lgkmcnt(0)
	v_cvt_pk_bf16_f32 v6, v6, v7
	v_cvt_pk_bf16_f32 v7, v8, v9
	v_cvt_pk_bf16_f32 v8, v50, v51
	v_cvt_pk_bf16_f32 v9, v52, v53
	v_lshl_add_u64 v[50:51], v[56:57], 0, v[0:1]
	global_store_dwordx4 v[50:51], v[6:9], off
	v_add_u32_e32 v0, s27, v15
	ds_read2_b32 v[6:7], v0 offset1:33
	ds_read2_b32 v[8:9], v0 offset0:66 offset1:99
	ds_read2_b32 v[50:51], v0 offset0:132 offset1:165
	ds_read2_b32 v[52:53], v0 offset0:198 offset1:231
	v_or_b32_e32 v0, s5, v14
	v_lshlrev_b32_e32 v0, 11, v0
	s_waitcnt lgkmcnt(0)
	v_cvt_pk_bf16_f32 v6, v6, v7
	v_cvt_pk_bf16_f32 v7, v8, v9
	v_cvt_pk_bf16_f32 v8, v50, v51
	v_cvt_pk_bf16_f32 v9, v52, v53
	v_lshl_add_u64 v[50:51], v[56:57], 0, v[0:1]
	global_store_dwordx4 v[50:51], v[6:9], off
	v_add_u32_e32 v0, s27, v17
	ds_read2_b32 v[6:7], v0 offset1:33
	ds_read2_b32 v[8:9], v0 offset0:66 offset1:99
	ds_read2_b32 v[50:51], v0 offset0:132 offset1:165
	ds_read2_b32 v[52:53], v0 offset0:198 offset1:231
	v_or_b32_e32 v0, s5, v16
	v_lshlrev_b32_e32 v0, 11, v0
	s_waitcnt lgkmcnt(0)
	v_cvt_pk_bf16_f32 v6, v6, v7
	v_cvt_pk_bf16_f32 v7, v8, v9
	v_cvt_pk_bf16_f32 v8, v50, v51
	v_cvt_pk_bf16_f32 v9, v52, v53
	v_lshl_add_u64 v[50:51], v[56:57], 0, v[0:1]
	global_store_dwordx4 v[50:51], v[6:9], off
	s_waitcnt lgkmcnt(0)

.LBB0_805:
	s_andn2_b64 vcc, exec, s[2:3]
	s_cbranch_vccnz .LBB0_807
	s_mov_b32 s2, 4
	s_ashr_i32 s3, s2, 31
	s_lshl_b64 s[2:3], s[2:3], 3
	s_add_u32 s2, s0, s2
	s_addc_u32 s3, s1, s3
	s_load_dwordx2 s[2:3], s[2:3], 0x0
	s_lshl_b64 s[6:7], s[24:25], 2
	s_mul_i32 s5, s4, 0xffffab00
	s_waitcnt lgkmcnt(0)
	s_add_u32 s6, s2, s6
	s_addc_u32 s7, s3, s7
	s_add_i32 s3, s35, s5
	s_and_b32 s2, s31, 0x3e0
	s_and_b32 s3, s3, 0x1ffc0
	v_or_b32_e32 v0, s2, v3
	v_or_b32_e32 v8, s3, v2
	v_lshlrev_b32_e32 v0, 2, v0
	v_lshl_add_u64 v[6:7], s[6:7], 0, v[0:1]
	v_lshlrev_b32_e32 v0, 12, v8
	v_lshl_add_u64 v[6:7], v[6:7], 0, v[0:1]
	s_movk_i32 s5, 0x2000
	v_add_co_u32_e32 v8, vcc, s5, v6
	s_movk_i32 s5, 0x4000
	s_nop 0
	v_addc_co_u32_e32 v9, vcc, 0, v7, vcc
	v_add_co_u32_e32 v50, vcc, s5, v6
	s_movk_i32 s5, 0x6000
	s_nop 0
	v_addc_co_u32_e32 v51, vcc, 0, v7, vcc
	v_add_co_u32_e32 v52, vcc, s5, v6
	s_mov_b32 s5, 0x8000
	s_nop 0
	v_addc_co_u32_e32 v53, vcc, 0, v7, vcc
	v_add_co_u32_e32 v54, vcc, s5, v6
	s_mov_b32 s5, 0xa000
	s_nop 0
	v_addc_co_u32_e32 v55, vcc, 0, v7, vcc
	v_add_co_u32_e32 v56, vcc, s5, v6
	s_mov_b32 s5, 0xc000
	s_nop 0
	v_addc_co_u32_e32 v57, vcc, 0, v7, vcc
	v_add_co_u32_e32 v58, vcc, s5, v6
	s_mov_b32 s5, 0xe000
	s_nop 0
	v_addc_co_u32_e32 v59, vcc, 0, v7, vcc
	v_add_co_u32_e32 v60, vcc, s5, v6
	s_mov_b32 s5, 0x12000
	s_nop 0
	v_addc_co_u32_e32 v61, vcc, 0, v7, vcc
	global_load_dword v0, v[6:7], off
	global_load_dword v49, v[8:9], off
	global_load_dword v64, v[50:51], off
	global_load_dword v65, v[52:53], off
	global_load_dword v66, v[54:55], off
	global_load_dword v67, v[56:57], off
	global_load_dword v68, v[58:59], off
	global_load_dword v69, v[60:61], off
	v_add_co_u32_e32 v8, vcc, s48, v6
	s_lshl_b32 s3, s3, 1
	s_nop 0
	v_addc_co_u32_e32 v9, vcc, 0, v7, vcc
	v_add_co_u32_e32 v50, vcc, s5, v6
	s_mov_b32 s5, 0x14000
	s_nop 0
	v_addc_co_u32_e32 v51, vcc, 0, v7, vcc
	v_add_co_u32_e32 v52, vcc, s5, v6
	s_mov_b32 s5, 0x16000
	s_nop 0
	v_addc_co_u32_e32 v53, vcc, 0, v7, vcc
	v_add_co_u32_e32 v54, vcc, s5, v6
	s_mov_b32 s5, 0x18000
	s_nop 0
	v_addc_co_u32_e32 v55, vcc, 0, v7, vcc
	v_add_co_u32_e32 v56, vcc, s5, v6
	s_mov_b32 s5, 0x1a000
	s_nop 0
	v_addc_co_u32_e32 v57, vcc, 0, v7, vcc
	v_add_co_u32_e32 v58, vcc, s5, v6
	s_mov_b32 s5, 0x1c000
	s_nop 0
	v_addc_co_u32_e32 v59, vcc, 0, v7, vcc
	v_add_co_u32_e32 v60, vcc, s5, v6
	s_mov_b32 s5, 0x1e000
	s_nop 0
	v_addc_co_u32_e32 v61, vcc, 0, v7, vcc
	v_add_co_u32_e32 v62, vcc, s5, v6
	s_mov_b32 s5, 0x22000
	s_nop 0
	v_addc_co_u32_e32 v63, vcc, 0, v7, vcc
	global_load_dword v70, v[8:9], off
	global_load_dword v71, v[50:51], off
	global_load_dword v72, v[52:53], off
	global_load_dword v73, v[54:55], off
	global_load_dword v74, v[56:57], off
	global_load_dword v75, v[58:59], off
	global_load_dword v76, v[60:61], off
	global_load_dword v77, v[62:63], off
	v_add_co_u32_e32 v8, vcc, s47, v6
	s_add_u32 s6, s37, s3
	s_nop 0
	v_addc_co_u32_e32 v9, vcc, 0, v7, vcc
	v_add_co_u32_e32 v50, vcc, s5, v6
	s_mov_b32 s5, 0x24000
	s_nop 0
	v_addc_co_u32_e32 v51, vcc, 0, v7, vcc
	v_add_co_u32_e32 v52, vcc, s5, v6
	s_mov_b32 s5, 0x26000
	s_nop 0
	v_addc_co_u32_e32 v53, vcc, 0, v7, vcc
	v_add_co_u32_e32 v54, vcc, s5, v6
	s_mov_b32 s5, 0x28000
	s_nop 0
	v_addc_co_u32_e32 v55, vcc, 0, v7, vcc
	v_add_co_u32_e32 v56, vcc, s5, v6
	s_mov_b32 s5, 0x2a000
	s_nop 0
	v_addc_co_u32_e32 v57, vcc, 0, v7, vcc
	v_add_co_u32_e32 v58, vcc, s5, v6
	s_mov_b32 s5, 0x2c000
	s_nop 0
	v_addc_co_u32_e32 v59, vcc, 0, v7, vcc
	v_add_co_u32_e32 v60, vcc, s5, v6
	s_mov_b32 s5, 0x2e000
	s_nop 0
	v_addc_co_u32_e32 v61, vcc, 0, v7, vcc
	v_add_co_u32_e32 v62, vcc, s5, v6
	s_mov_b32 s5, 0x32000
	s_nop 0
	v_addc_co_u32_e32 v63, vcc, 0, v7, vcc
	global_load_dword v78, v[8:9], off
	global_load_dword v79, v[50:51], off
	global_load_dword v80, v[52:53], off
	global_load_dword v81, v[54:55], off
	global_load_dword v82, v[56:57], off
	global_load_dword v83, v[58:59], off
	global_load_dword v84, v[60:61], off
	s_nop 0
	global_load_dword v62, v[62:63], off
	v_add_co_u32_e32 v8, vcc, s49, v6
	s_addc_u32 s7, s40, 0
	s_nop 0
	v_addc_co_u32_e32 v9, vcc, 0, v7, vcc
	v_add_co_u32_e32 v50, vcc, s5, v6
	s_mov_b32 s5, 0x34000
	s_nop 0
	v_addc_co_u32_e32 v51, vcc, 0, v7, vcc
	v_add_co_u32_e32 v52, vcc, s5, v6
	s_mov_b32 s5, 0x36000
	s_nop 0
	v_addc_co_u32_e32 v53, vcc, 0, v7, vcc
	v_add_co_u32_e32 v54, vcc, s5, v6
	s_mov_b32 s5, 0x38000
	s_nop 0
	v_addc_co_u32_e32 v55, vcc, 0, v7, vcc
	v_add_co_u32_e32 v56, vcc, s5, v6
	s_mov_b32 s5, 0x3a000
	s_nop 0
	v_addc_co_u32_e32 v57, vcc, 0, v7, vcc
	v_add_co_u32_e32 v58, vcc, s5, v6
	s_mov_b32 s5, 0x3c000
	s_nop 0
	v_addc_co_u32_e32 v59, vcc, 0, v7, vcc
	v_add_co_u32_e32 v60, vcc, s5, v6
	s_mov_b32 s5, 0x3e000
	s_nop 0
	v_addc_co_u32_e32 v61, vcc, 0, v7, vcc
	v_add_co_u32_e32 v6, vcc, s5, v6
	s_nop 1
	v_addc_co_u32_e32 v7, vcc, 0, v7, vcc
	global_load_dword v8, v[8:9], off
	s_nop 0
	global_load_dword v9, v[50:51], off
	s_nop 0
	global_load_dword v50, v[52:53], off
	global_load_dword v51, v[54:55], off
	s_nop 0
	global_load_dword v52, v[56:57], off
	global_load_dword v53, v[58:59], off
	global_load_dword v54, v[60:61], off
	s_nop 0
	global_load_dword v6, v[6:7], off
	s_waitcnt vmcnt(0)
	ds_write2_b32 v5, v0, v49 offset1:66
	ds_write2_b32 v5, v64, v65 offset0:132 offset1:198
	v_add_u32_e32 v0, 0x400, v5
	ds_write2_b32 v0, v66, v67 offset0:8 offset1:74
	ds_write2_b32 v0, v68, v69 offset0:140 offset1:206
	v_add_u32_e32 v0, 0x800, v5
	ds_write2_b32 v0, v70, v71 offset0:16 offset1:82
	ds_write2_b32 v0, v72, v73 offset0:148 offset1:214
	v_add_u32_e32 v0, 0xc00, v5
	ds_write2_b32 v0, v74, v75 offset0:24 offset1:90
	ds_write2_b32 v0, v76, v77 offset0:156 offset1:222
	v_add_u32_e32 v0, 0x1000, v5
	ds_write2_b32 v0, v78, v79 offset0:32 offset1:98
	ds_write2_b32 v0, v80, v81 offset0:164 offset1:230
	v_add_u32_e32 v0, 0x1400, v5
	ds_write2_b32 v0, v82, v83 offset0:40 offset1:106
	ds_write2_b32 v0, v84, v62 offset0:172 offset1:238
	v_add_u32_e32 v0, 0x1800, v5
	ds_write2_b32 v0, v8, v9 offset0:48 offset1:114
	ds_write2_b32 v0, v50, v51 offset0:180 offset1:246
	v_add_u32_e32 v0, 0x1c00, v5
	ds_write2_b32 v0, v52, v53 offset0:56 offset1:122
	ds_write2_b32 v0, v54, v6 offset0:188 offset1:254
	v_lshlrev_b32_e32 v0, 1, v4
	s_waitcnt lgkmcnt(0)
	v_lshl_add_u64 v[6:7], s[6:7], 0, v[0:1]
	v_add_u32_e32 v0, s27, v11
	ds_read2_b32 v[8:9], v0 offset1:33
	ds_read2_b32 v[50:51], v0 offset0:66 offset1:99
	ds_read2_b32 v[52:53], v0 offset0:132 offset1:165
	ds_read2_b32 v[54:55], v0 offset0:198 offset1:231
	s_mov_b64 s[6:7], 0xb00000
	v_or_b32_e32 v0, s2, v10
	v_lshl_add_u64 v[56:57], v[6:7], 0, s[6:7]
	v_mul_u32_u24_e32 v0, 0x1600, v0
	s_waitcnt lgkmcnt(3)
	v_cvt_pk_bf16_f32 v6, v8, v9
	s_waitcnt lgkmcnt(2)
	v_cvt_pk_bf16_f32 v7, v50, v51
	s_waitcnt lgkmcnt(1)
	v_cvt_pk_bf16_f32 v8, v52, v53
	s_waitcnt lgkmcnt(0)
	v_cvt_pk_bf16_f32 v9, v54, v55
	v_lshl_add_u64 v[50:51], v[56:57], 0, v[0:1]
	global_store_dwordx4 v[50:51], v[6:9], off
	v_add_u32_e32 v0, s27, v13
	ds_read2_b32 v[6:7], v0 offset1:33
	ds_read2_b32 v[8:9], v0 offset0:66 offset1:99
	ds_read2_b32 v[50:51], v0 offset0:132 offset1:165
	ds_read2_b32 v[52:53], v0 offset0:198 offset1:231
	v_or_b32_e32 v0, s2, v12
	v_mul_u32_u24_e32 v0, 0x1600, v0
	s_waitcnt lgkmcnt(0)
	v_cvt_pk_bf16_f32 v6, v6, v7
	v_cvt_pk_bf16_f32 v7, v8, v9
	v_cvt_pk_bf16_f32 v8, v50, v51
	v_cvt_pk_bf16_f32 v9, v52, v53
	v_lshl_add_u64 v[50:51], v[56:57], 0, v[0:1]
	global_store_dwordx4 v[50:51], v[6:9], off
	v_add_u32_e32 v0, s27, v15
	ds_read2_b32 v[6:7], v0 offset1:33
	ds_read2_b32 v[8:9], v0 offset0:66 offset1:99
	ds_read2_b32 v[50:51], v0 offset0:132 offset1:165
	ds_read2_b32 v[52:53], v0 offset0:198 offset1:231
	v_or_b32_e32 v0, s2, v14
	v_mul_u32_u24_e32 v0, 0x1600, v0
	s_waitcnt lgkmcnt(0)
	v_cvt_pk_bf16_f32 v6, v6, v7
	v_cvt_pk_bf16_f32 v7, v8, v9
	v_cvt_pk_bf16_f32 v8, v50, v51
	v_cvt_pk_bf16_f32 v9, v52, v53
	v_lshl_add_u64 v[50:51], v[56:57], 0, v[0:1]
	global_store_dwordx4 v[50:51], v[6:9], off
	v_add_u32_e32 v0, s27, v17
	ds_read2_b32 v[6:7], v0 offset1:33
	ds_read2_b32 v[8:9], v0 offset0:66 offset1:99
	ds_read2_b32 v[50:51], v0 offset0:132 offset1:165
	ds_read2_b32 v[52:53], v0 offset0:198 offset1:231
	v_or_b32_e32 v0, s2, v16
	v_mul_u32_u24_e32 v0, 0x1600, v0
	s_waitcnt lgkmcnt(0)
	v_cvt_pk_bf16_f32 v6, v6, v7
	v_cvt_pk_bf16_f32 v7, v8, v9
	v_cvt_pk_bf16_f32 v8, v50, v51
	v_cvt_pk_bf16_f32 v9, v52, v53
	v_lshl_add_u64 v[50:51], v[56:57], 0, v[0:1]
	global_store_dwordx4 v[50:51], v[6:9], off
	s_waitcnt lgkmcnt(0)

.LBB0_940:
	v_add_u32_e32 v2, s4, v2
	s_mov_b32 s5, 0x13fff
	v_cmp_lt_i32_e32 vcc, s5, v2
	global_store_dwordx4 v[4:5], v[220:223], off
	s_or_b64 s[10:11], vcc, s[10:11]
	v_lshl_add_u64 v[4:5], v[4:5], 0, s[6:7]
	s_andn2_b64 exec, exec, s[10:11]
	s_cbranch_execnz .LBB0_940

.LBB0_944:
	s_waitcnt lgkmcnt(0)
	v_add_co_u32_e32 v2, vcc, 0xffffd000, v52
	s_mov_b32 s2, 0x5600000
	s_nop 0
	v_addc_co_u32_e32 v3, vcc, -1, v53, vcc
	global_load_dwordx4 v[62:65], v[2:3], off offset:-3072
	global_load_dwordx4 v[66:69], v[2:3], off offset:-2048
	global_load_dwordx4 v[70:73], v[2:3], off offset:-1024
	global_load_dwordx4 v[74:77], v[2:3], off
	global_load_dwordx4 v[14:17], v[52:53], off offset:-3072
	global_load_dwordx4 v[10:13], v[52:53], off offset:-2048
	global_load_dwordx4 v[6:9], v[52:53], off offset:-1024
	s_nop 0
	global_load_dwordx4 v[2:5], v[52:53], off
	v_add_co_u32_e32 v18, vcc, 0xffffe000, v52
	s_waitcnt vmcnt(0)
	v_cvt_pk_bf16_f32 v78, v62, v63
	v_addc_co_u32_e32 v19, vcc, -1, v53, vcc
	v_add_co_u32_e32 v20, vcc, 0xfffff000, v52
	global_load_dwordx4 v[46:49], v[18:19], off offset:-3072
	global_load_dwordx4 v[42:45], v[18:19], off offset:-2048
	global_load_dwordx4 v[38:41], v[18:19], off offset:-1024
	global_load_dwordx4 v[34:37], v[18:19], off
	v_addc_co_u32_e32 v21, vcc, -1, v53, vcc
	global_load_dwordx4 v[30:33], v[20:21], off offset:-3072
	global_load_dwordx4 v[26:29], v[20:21], off offset:-2048
	global_load_dwordx4 v[22:25], v[20:21], off offset:-1024
	s_nop 0
	global_load_dwordx4 v[18:21], v[52:53], off offset:-4096
	v_cvt_pk_bf16_f32 v79, v64, v65
	v_cvt_pk_bf16_f32 v64, v66, v67
	v_cvt_pk_bf16_f32 v65, v68, v69
	v_cvt_pk_bf16_f32 v66, v70, v71
	v_cvt_pk_bf16_f32 v67, v72, v73
	v_and_b32_e32 v54, 0xffff0000, v78
	v_and_b32_e32 v62, 0xffff0000, v79
	v_and_b32_e32 v70, 0xffff0000, v64
	v_and_b32_e32 v72, 0xffff0000, v65
	v_cvt_pk_bf16_f32 v68, v74, v75
	v_cvt_pk_bf16_f32 v69, v76, v77
	v_lshlrev_b32_e32 v0, 16, v78
	v_lshlrev_b32_e32 v55, 16, v79
	v_lshlrev_b32_e32 v63, 16, v64
	v_lshlrev_b32_e32 v71, 16, v65
	v_and_b32_e32 v74, 0xffff0000, v66
	v_and_b32_e32 v76, 0xffff0000, v67
	v_mul_f32_e32 v54, v54, v54
	v_mul_f32_e32 v62, v62, v62
	v_mul_f32_e32 v70, v70, v70
	v_mul_f32_e32 v72, v72, v72
	v_lshlrev_b32_e32 v73, 16, v66
	v_lshlrev_b32_e32 v75, 16, v67
	v_and_b32_e32 v80, 0xffff0000, v68
	v_and_b32_e32 v82, 0xffff0000, v69
	v_mul_f32_e32 v74, v74, v74
	v_mul_f32_e32 v76, v76, v76
	v_fmac_f32_e32 v54, v0, v0
	v_fmac_f32_e32 v62, v55, v55
	v_fmac_f32_e32 v70, v63, v63
	v_fmac_f32_e32 v72, v71, v71
	v_lshlrev_b32_e32 v77, 16, v68
	v_lshlrev_b32_e32 v81, 16, v69
	v_mul_f32_e32 v80, v80, v80
	v_mul_f32_e32 v82, v82, v82
	v_fmac_f32_e32 v74, v73, v73
	v_fmac_f32_e32 v76, v75, v75
	v_add_f32_e32 v0, v54, v62
	v_add_f32_e32 v54, v70, v72
	v_fmac_f32_e32 v80, v77, v77
	v_fmac_f32_e32 v82, v81, v81
	v_add_f32_e32 v55, v74, v76
	v_add_f32_e32 v0, v0, v54
	v_add_f32_e32 v62, v80, v82
	v_add_f32_e32 v0, v0, v55
	v_add_f32_e32 v0, v0, v62
	ds_bpermute_b32 v54, v56, v0
	s_waitcnt lgkmcnt(0)
	v_add_f32_e32 v0, v0, v54
	ds_bpermute_b32 v54, v57, v0
	s_waitcnt lgkmcnt(0)
	v_add_f32_e32 v0, v0, v54
	ds_bpermute_b32 v54, v58, v0
	s_waitcnt lgkmcnt(0)
	v_add_f32_e32 v0, v0, v54
	ds_bpermute_b32 v62, v59, v0
	v_lshl_add_u64 v[54:55], s[72:73], 0, v[50:51]
	v_add_co_u32_e32 v70, vcc, s2, v54
	s_waitcnt lgkmcnt(0)
	v_add_f32_e32 v0, v0, v62
	ds_bpermute_b32 v62, v60, v0
	v_addc_co_u32_e32 v71, vcc, 0, v55, vcc
	global_store_dwordx2 v[70:71], v[78:79], off
	global_store_dwordx2 v[70:71], v[64:65], off offset:512
	global_store_dwordx2 v[70:71], v[66:67], off offset:1024
	global_store_dwordx2 v[70:71], v[68:69], off offset:1536
	s_waitcnt lgkmcnt(0)
	v_add_f32_e32 v0, v0, v62
	ds_bpermute_b32 v62, v61, v0
	s_and_saveexec_b64 s[2:3], s[38:39]
	s_cbranch_execz .LBB0_946
	s_waitcnt lgkmcnt(0)
	v_add_f32_e32 v0, v0, v62
	v_fma_f32 v0, v0, s10, 0.5
	v_trunc_f32_e32 v0, v0
	v_mul_f32_e32 v62, 0x2f800000, v0
	v_floor_f32_e32 v63, v62
	v_fmac_f32_e32 v0, 0xcf800000, v63
	v_cvt_u32_f32_e32 v62, v0
	v_cvt_u32_f32_e32 v63, v63
	s_add_u32 s5, s72, s24
	s_addc_u32 s6, s73, s25
	v_mov_b32_e32 v0, s5
	v_add_co_u32_e32 v64, vcc, 0x1e900000, v0
	v_mov_b32_e32 v0, s6
	s_nop 0
	v_addc_co_u32_e32 v65, vcc, 0, v0, vcc
	global_store_dwordx2 v[64:65], v[62:63], off
.LBB0_946:
	s_or_b64 exec, exec, s[2:3]
	s_waitcnt vmcnt(0)
	v_cvt_pk_bf16_f32 v46, v46, v47
	v_cvt_pk_bf16_f32 v47, v48, v49
	v_and_b32_e32 v48, 0xffff0000, v46
	v_lshlrev_b32_e32 v0, 16, v46
	s_waitcnt lgkmcnt(0)
	v_and_b32_e32 v62, 0xffff0000, v47
	v_mul_f32_e32 v48, v48, v48
	v_cvt_pk_bf16_f32 v42, v42, v43
	v_lshlrev_b32_e32 v49, 16, v47
	v_fmac_f32_e32 v48, v0, v0
	v_mul_f32_e32 v0, v62, v62
	v_cvt_pk_bf16_f32 v43, v44, v45
	v_and_b32_e32 v45, 0xffff0000, v42
	v_fmac_f32_e32 v0, v49, v49
	v_lshlrev_b32_e32 v44, 16, v42
	v_and_b32_e32 v49, 0xffff0000, v43
	v_mul_f32_e32 v45, v45, v45
	v_add_f32_e32 v0, v48, v0
	v_lshlrev_b32_e32 v48, 16, v43
	v_fmac_f32_e32 v45, v44, v44
	v_mul_f32_e32 v44, v49, v49
	v_cvt_pk_bf16_f32 v38, v38, v39
	v_fmac_f32_e32 v44, v48, v48
	v_cvt_pk_bf16_f32 v39, v40, v41
	v_and_b32_e32 v41, 0xffff0000, v38
	v_add_f32_e32 v44, v45, v44
	v_lshlrev_b32_e32 v40, 16, v38
	v_and_b32_e32 v45, 0xffff0000, v39
	v_mul_f32_e32 v41, v41, v41
	v_add_f32_e32 v0, v0, v44
	v_lshlrev_b32_e32 v44, 16, v39
	v_fmac_f32_e32 v41, v40, v40
	v_mul_f32_e32 v40, v45, v45
	v_fmac_f32_e32 v40, v44, v44
	v_add_f32_e32 v40, v41, v40
	v_add_f32_e32 v0, v0, v40
	v_cvt_pk_bf16_f32 v40, v34, v35
	v_cvt_pk_bf16_f32 v41, v36, v37
	v_and_b32_e32 v35, 0xffff0000, v40
	v_lshlrev_b32_e32 v34, 16, v40
	v_and_b32_e32 v37, 0xffff0000, v41
	v_mul_f32_e32 v35, v35, v35
	v_lshlrev_b32_e32 v36, 16, v41
	v_fmac_f32_e32 v35, v34, v34
	v_mul_f32_e32 v34, v37, v37
	v_fmac_f32_e32 v34, v36, v36
	v_add_f32_e32 v34, v35, v34
	v_add_f32_e32 v0, v0, v34
	ds_bpermute_b32 v34, v56, v0
	v_add_co_u32_e32 v36, vcc, 0x5600000, v54
	s_waitcnt lgkmcnt(0)
	v_add_f32_e32 v0, v0, v34
	ds_bpermute_b32 v34, v57, v0
	v_addc_co_u32_e32 v37, vcc, 0, v55, vcc
	global_store_dwordx2 v[36:37], v[46:47], off offset:2048
	global_store_dwordx2 v[36:37], v[42:43], off offset:2560
	global_store_dwordx2 v[36:37], v[38:39], off offset:3072
	global_store_dwordx2 v[36:37], v[40:41], off offset:3584
	s_waitcnt lgkmcnt(0)
	v_add_f32_e32 v0, v0, v34
	ds_bpermute_b32 v34, v58, v0
	s_waitcnt lgkmcnt(0)
	v_add_f32_e32 v0, v0, v34
	ds_bpermute_b32 v34, v59, v0
	s_waitcnt lgkmcnt(0)
	v_add_f32_e32 v0, v0, v34
	ds_bpermute_b32 v34, v60, v0
	s_waitcnt lgkmcnt(0)
	v_add_f32_e32 v0, v0, v34
	ds_bpermute_b32 v34, v61, v0
	s_and_saveexec_b64 s[2:3], s[38:39]
	s_cbranch_execz .LBB0_948
	s_waitcnt lgkmcnt(0)
	v_add_f32_e32 v0, v0, v34
	v_fma_f32 v0, v0, s10, 0.5
	v_trunc_f32_e32 v0, v0
	v_mul_f32_e32 v34, 0x2f800000, v0
	v_floor_f32_e32 v35, v34
	v_fmac_f32_e32 v0, 0xcf800000, v35
	v_cvt_u32_f32_e32 v34, v0
	v_cvt_u32_f32_e32 v35, v35
	s_add_u32 s5, s72, s24
	s_addc_u32 s6, s73, s25
	v_mov_b32_e32 v0, s5
	v_add_co_u32_e32 v36, vcc, 0x1e900000, v0
	v_mov_b32_e32 v0, s6
	s_nop 0
	v_addc_co_u32_e32 v37, vcc, 0, v0, vcc
	global_store_dwordx2 v[36:37], v[34:35], off offset:8
.LBB0_948:
	s_or_b64 exec, exec, s[2:3]
	v_cvt_pk_bf16_f32 v30, v30, v31
	v_cvt_pk_bf16_f32 v31, v32, v33
	v_and_b32_e32 v32, 0xffff0000, v30
	v_lshlrev_b32_e32 v0, 16, v30
	s_waitcnt lgkmcnt(0)
	v_and_b32_e32 v34, 0xffff0000, v31
	v_mul_f32_e32 v32, v32, v32
	v_cvt_pk_bf16_f32 v26, v26, v27
	v_lshlrev_b32_e32 v33, 16, v31
	v_fmac_f32_e32 v32, v0, v0
	v_mul_f32_e32 v0, v34, v34
	v_cvt_pk_bf16_f32 v27, v28, v29
	v_and_b32_e32 v29, 0xffff0000, v26
	v_fmac_f32_e32 v0, v33, v33
	v_lshlrev_b32_e32 v28, 16, v26
	v_and_b32_e32 v33, 0xffff0000, v27
	v_mul_f32_e32 v29, v29, v29
	v_add_f32_e32 v0, v32, v0
	v_lshlrev_b32_e32 v32, 16, v27
	v_fmac_f32_e32 v29, v28, v28
	v_mul_f32_e32 v28, v33, v33
	v_cvt_pk_bf16_f32 v22, v22, v23
	v_fmac_f32_e32 v28, v32, v32
	v_cvt_pk_bf16_f32 v23, v24, v25
	v_and_b32_e32 v25, 0xffff0000, v22
	v_add_f32_e32 v28, v29, v28
	v_lshlrev_b32_e32 v24, 16, v22
	v_and_b32_e32 v29, 0xffff0000, v23
	v_mul_f32_e32 v25, v25, v25
	v_add_f32_e32 v0, v0, v28
	v_lshlrev_b32_e32 v28, 16, v23
	v_fmac_f32_e32 v25, v24, v24
	v_mul_f32_e32 v24, v29, v29
	v_fmac_f32_e32 v24, v28, v28
	v_add_f32_e32 v24, v25, v24
	v_add_f32_e32 v0, v0, v24
	v_cvt_pk_bf16_f32 v24, v18, v19
	v_cvt_pk_bf16_f32 v25, v20, v21
	v_and_b32_e32 v19, 0xffff0000, v24
	v_lshlrev_b32_e32 v18, 16, v24
	v_and_b32_e32 v21, 0xffff0000, v25
	v_mul_f32_e32 v19, v19, v19
	v_lshlrev_b32_e32 v20, 16, v25
	v_fmac_f32_e32 v19, v18, v18
	v_mul_f32_e32 v18, v21, v21
	v_fmac_f32_e32 v18, v20, v20
	v_add_f32_e32 v18, v19, v18
	v_add_f32_e32 v0, v0, v18
	ds_bpermute_b32 v18, v56, v0
	v_add_co_u32_e32 v20, vcc, 0x5601000, v54
	s_waitcnt lgkmcnt(0)
	v_add_f32_e32 v0, v0, v18
	ds_bpermute_b32 v18, v57, v0
	v_addc_co_u32_e32 v21, vcc, 0, v55, vcc
	global_store_dwordx2 v[20:21], v[30:31], off
	global_store_dwordx2 v[20:21], v[26:27], off offset:512
	global_store_dwordx2 v[20:21], v[22:23], off offset:1024
	global_store_dwordx2 v[20:21], v[24:25], off offset:1536
	s_waitcnt lgkmcnt(0)
	v_add_f32_e32 v0, v0, v18
	ds_bpermute_b32 v18, v58, v0
	s_waitcnt lgkmcnt(0)
	v_add_f32_e32 v0, v0, v18
	ds_bpermute_b32 v18, v59, v0
	s_waitcnt lgkmcnt(0)
	v_add_f32_e32 v0, v0, v18
	ds_bpermute_b32 v18, v60, v0
	s_waitcnt lgkmcnt(0)
	v_add_f32_e32 v0, v0, v18
	ds_bpermute_b32 v18, v61, v0
	s_and_saveexec_b64 s[2:3], s[38:39]
	s_cbranch_execz .LBB0_950
	s_waitcnt lgkmcnt(0)
	v_add_f32_e32 v0, v0, v18
	v_fma_f32 v0, v0, s10, 0.5
	v_trunc_f32_e32 v0, v0
	v_mul_f32_e32 v18, 0x2f800000, v0
	v_floor_f32_e32 v19, v18
	v_fmac_f32_e32 v0, 0xcf800000, v19
	v_cvt_u32_f32_e32 v18, v0
	v_cvt_u32_f32_e32 v19, v19
	s_add_u32 s5, s72, s24
	s_addc_u32 s6, s73, s25
	v_mov_b32_e32 v0, s5
	v_add_co_u32_e32 v20, vcc, 0x1e900000, v0
	v_mov_b32_e32 v0, s6
	s_nop 0
	v_addc_co_u32_e32 v21, vcc, 0, v0, vcc
	global_store_dwordx2 v[20:21], v[18:19], off offset:16
.LBB0_950:
	s_or_b64 exec, exec, s[2:3]
	v_cvt_pk_bf16_f32 v14, v14, v15
	v_cvt_pk_bf16_f32 v15, v16, v17
	v_and_b32_e32 v16, 0xffff0000, v14
	v_lshlrev_b32_e32 v0, 16, v14
	s_waitcnt lgkmcnt(0)
	v_and_b32_e32 v18, 0xffff0000, v15
	v_mul_f32_e32 v16, v16, v16
	v_cvt_pk_bf16_f32 v10, v10, v11
	v_lshlrev_b32_e32 v17, 16, v15
	v_fmac_f32_e32 v16, v0, v0
	v_mul_f32_e32 v0, v18, v18
	v_cvt_pk_bf16_f32 v11, v12, v13
	v_and_b32_e32 v13, 0xffff0000, v10
	v_fmac_f32_e32 v0, v17, v17
	v_lshlrev_b32_e32 v12, 16, v10
	v_and_b32_e32 v17, 0xffff0000, v11
	v_mul_f32_e32 v13, v13, v13
	v_add_f32_e32 v0, v16, v0
	v_lshlrev_b32_e32 v16, 16, v11
	v_fmac_f32_e32 v13, v12, v12
	v_mul_f32_e32 v12, v17, v17
	v_cvt_pk_bf16_f32 v6, v6, v7
	v_fmac_f32_e32 v12, v16, v16
	v_cvt_pk_bf16_f32 v7, v8, v9
	v_and_b32_e32 v9, 0xffff0000, v6
	v_add_f32_e32 v12, v13, v12
	v_lshlrev_b32_e32 v8, 16, v6
	v_and_b32_e32 v13, 0xffff0000, v7
	v_mul_f32_e32 v9, v9, v9
	v_add_f32_e32 v0, v0, v12
	v_lshlrev_b32_e32 v12, 16, v7
	v_fmac_f32_e32 v9, v8, v8
	v_mul_f32_e32 v8, v13, v13
	v_fmac_f32_e32 v8, v12, v12
	v_add_f32_e32 v8, v9, v8
	v_add_f32_e32 v0, v0, v8
	v_cvt_pk_bf16_f32 v8, v2, v3
	v_cvt_pk_bf16_f32 v9, v4, v5
	v_and_b32_e32 v3, 0xffff0000, v8
	v_lshlrev_b32_e32 v2, 16, v8
	v_and_b32_e32 v5, 0xffff0000, v9
	v_mul_f32_e32 v3, v3, v3
	v_lshlrev_b32_e32 v4, 16, v9
	v_fmac_f32_e32 v3, v2, v2
	v_mul_f32_e32 v2, v5, v5
	v_fmac_f32_e32 v2, v4, v4
	v_add_f32_e32 v2, v3, v2
	v_add_f32_e32 v0, v0, v2
	ds_bpermute_b32 v2, v56, v0
	v_add_co_u32_e32 v4, vcc, 0x5601000, v54
	s_waitcnt lgkmcnt(0)
	v_add_f32_e32 v0, v0, v2
	ds_bpermute_b32 v2, v57, v0
	v_addc_co_u32_e32 v5, vcc, 0, v55, vcc
	global_store_dwordx2 v[4:5], v[14:15], off offset:2048
	global_store_dwordx2 v[4:5], v[10:11], off offset:2560
	global_store_dwordx2 v[4:5], v[6:7], off offset:3072
	global_store_dwordx2 v[4:5], v[8:9], off offset:3584
	s_waitcnt lgkmcnt(0)
	v_add_f32_e32 v0, v0, v2
	ds_bpermute_b32 v2, v58, v0
	s_waitcnt lgkmcnt(0)
	v_add_f32_e32 v0, v0, v2
	ds_bpermute_b32 v2, v59, v0
	s_waitcnt lgkmcnt(0)
	v_add_f32_e32 v0, v0, v2
	ds_bpermute_b32 v2, v60, v0
	s_waitcnt lgkmcnt(0)
	v_add_f32_e32 v0, v0, v2
	ds_bpermute_b32 v2, v61, v0
	s_and_saveexec_b64 s[2:3], s[38:39]
	s_cbranch_execz .LBB0_943
	s_waitcnt lgkmcnt(0)
	v_add_f32_e32 v0, v0, v2
	v_fma_f32 v0, v0, s10, 0.5
	v_trunc_f32_e32 v0, v0
	v_mul_f32_e32 v2, 0x2f800000, v0
	v_floor_f32_e32 v3, v2
	v_fmac_f32_e32 v0, 0xcf800000, v3
	v_cvt_u32_f32_e32 v2, v0
	v_cvt_u32_f32_e32 v3, v3
	s_add_u32 s5, s72, s24
	s_addc_u32 s6, s73, s25
	v_mov_b32_e32 v0, s5
	v_add_co_u32_e32 v4, vcc, 0x1e900000, v0
	v_mov_b32_e32 v0, s6
	s_nop 0
	v_addc_co_u32_e32 v5, vcc, 0, v0, vcc
	global_store_dwordx2 v[4:5], v[2:3], off offset:24
	s_branch .LBB0_943
